# baseline (speedup 1.0000x reference)
;     DI size_t aoff(const Unit& u, size_t tstep) const { return (size_t)u.pm * tstep; }
;     DI size_t boff(const Unit& u, size_t tstep) const { return (size_t)u.pn * tstep; }
;     DI bool next(int i, Unit& u) const { const long L = (long)i * G + c; if (L >= np) return false; u.pm = pmv; u.pn = (int)(L % nN); u.ks = (int)(L / nN); return true; }
;     DI size_t aoff(const Unit& u, size_t) const { return (size_t)u.ks * kbytes; }
;     DI size_t boff(const Unit& u, size_t tstep) const { return (size_t)u.pn * tstep + (size_t)u.ks * kbytes; }
;     DI bool next(int i, Unit& u) const { Unit t; if (!S.next(i / 3, t)) return false; u.pm = t.pm; u.pn = t.pn; u.ks = i % 3; return true; }
;     DI size_t aoff(const Unit& u, size_t tstep) const { return (u.ks < 2 ? offU : offOA) + (size_t)u.pm * tstep; }
; #define PG8_LDA(dst, b, h) do { _Pragma("unroll") for (int m = 0; m < 4; ++m) _Pragma("unroll") for (int k = 0; k < 2; ++k) dst[m][k] = *(const LAS bf16x8*)(lds + PG8_SA(b, h) + aoff + m * 2048 + k * 1024); } while (0)
; template <class Epi, class Sched>
; DI void gemm_phase(LAS unsigned char* lds, const Gemm g, const Sched& S, const Epi& E) {
;     ...
;         const bool has_next = S.next(ui + 1, nxt);
;         const char* nA = has_next ? (const char*)g.A + S.aoff(nxt, tstep) : cA; const char* nB = has_next ? (const char*)g.Bt + S.boff(nxt, tstep) : cB;
;         for (int t = 0; t < nt; t += 2) {
;             if constexpr (Epi::HAS_MID) { if (t == E.mid_t(nt)) { int fr3 = fr, fq3 = fq; asm volatile("" : "+v"(fr3), "+v"(fq3)); E.mid(acc, cur, wr, wc, fr3, fq3); } }
;             const bool last = (t == nt - 2);
;             const char* a1 = cA + (size_t)(t + 1) * kstep;
;             const char* a2 = last ? nA : cA + (size_t)(t + 2) * kstep; const char* b2 = last ? nB : cB + (size_t)(t + 2) * kstep;
;             const char* a3 = a2 + kstep; const char* b3 = b2 + kstep;
;             PG8_LDB(B0, 0, 0); PG8_SCHED; PG8_LDA(At, 0, 0); PG8_STAGE(PG8_SA(1, 1), a1 + hstep, voffA);
;             PG8_WAIT_L(8); PG8_BAR; PG8_WAIT_L(0); PG8_MMA(0, 0, At, B0); PG8_BAR; PG8_SCHED;
;             PG8_LDB(B1, 0, 1); PG8_STAGE(PG8_SB(0, 0), b2, voffB);
;             PG8_BAR; PG8_WAIT_L(0); PG8_MMA(0, 1, At, B1); PG8_BAR;
;             PG8_LDA(At, 0, 1); PG8_STAGE(PG8_SA(0, 0), a2, voffA);
;             PG8_BAR; PG8_WAIT_L(0); PG8_MMA(1, 0, At, B0); PG8_BAR; PG8_SCHED;
.LBB0_218:
	s_ashr_i32 s17, s16, 31
	s_lshl_b64 s[0:1], s[16:17], 20
	v_cmp_lt_i64_e32 vcc, s[18:19], v[140:141]
	s_add_u32 s18, s47, s0
	s_addc_u32 s19, s48, s1
	s_and_b64 s[0:1], vcc, exec
	s_cselect_b32 s17, s19, s41
	s_cselect_b32 s65, s18, s40
	s_ashr_i32 s15, s14, 31
	s_lshl_b64 s[0:1], s[14:15], 20
	s_add_u32 s36, s49, s0
	s_addc_u32 s37, s50, s1
	s_and_b64 s[0:1], vcc, exec
	s_cselect_b32 s15, s37, s43
	s_cselect_b32 s66, s36, s42
	s_add_u32 s40, s40, 0x80080
	s_addc_u32 s41, s41, 0
	s_add_u32 s67, s42, 0x100
	v_mov_b32_e32 v0, 0
	s_addc_u32 s68, s43, 0
	s_mov_b32 s69, -2
	ds_read_b128 v[150:153], v147
	ds_read_b128 v[154:157], v147 offset:1024
	ds_read_b128 v[162:165], v147 offset:2048
	ds_read_b128 v[166:169], v147 offset:3072
	s_add_i32 m0, s39, 0xc000
	ds_read_b128 v[170:173], v148
	ds_read_b128 v[174:177], v148 offset:1024
	ds_read_b128 v[178:181], v148 offset:2048
	ds_read_b128 v[188:191], v148 offset:3072
	ds_read_b128 v[194:197], v148 offset:4096
	ds_read_b128 v[198:201], v148 offset:5120
	ds_read_b128 v[202:205], v148 offset:6144
	global_load_lds_dwordx4 v136, s[40:41]
	s_add_i32 m0, s39, 0xe000
	ds_read_b128 v[206:209], v148 offset:7168
	global_load_lds_dwordx4 v138, s[40:41]
	s_add_u32 s0, s40, 0xfff80080
	s_addc_u32 s1, s41, -1
	s_cmp_eq_u32 s69, 28
	s_cselect_b32 s45, s17, s1
	s_cselect_b32 s44, s65, s0
	s_cselect_b32 s43, s15, s68
	s_cselect_b32 s42, s66, s67
	s_waitcnt lgkmcnt(8)
	s_barrier
	s_waitcnt lgkmcnt(0)
	s_setprio 1
	v_mfma_f32_16x16x32_bf16 v[124:127], v[150:153], v[170:173], 0
	v_mfma_f32_16x16x32_bf16 v[120:123], v[162:165], v[170:173], 0
	v_mfma_f32_16x16x32_bf16 v[108:111], v[150:153], v[178:181], 0
	v_mfma_f32_16x16x32_bf16 v[104:107], v[162:165], v[178:181], 0
	v_mfma_f32_16x16x32_bf16 v[92:95], v[150:153], v[194:197], 0
	v_mfma_f32_16x16x32_bf16 v[88:91], v[162:165], v[194:197], 0
	v_mfma_f32_16x16x32_bf16 v[76:79], v[150:153], v[202:205], 0
	v_mfma_f32_16x16x32_bf16 v[72:75], v[162:165], v[202:205], 0
	v_mfma_f32_16x16x32_bf16 v[124:127], v[154:157], v[174:177], v[124:127]
	v_mfma_f32_16x16x32_bf16 v[120:123], v[166:169], v[174:177], v[120:123]
	v_mfma_f32_16x16x32_bf16 v[108:111], v[154:157], v[188:191], v[108:111]
	v_mfma_f32_16x16x32_bf16 v[104:107], v[166:169], v[188:191], v[104:107]
	v_mfma_f32_16x16x32_bf16 v[92:95], v[154:157], v[198:201], v[92:95]
	v_mfma_f32_16x16x32_bf16 v[88:91], v[166:169], v[198:201], v[88:91]
	v_mfma_f32_16x16x32_bf16 v[76:79], v[154:157], v[206:209], v[76:79]
	v_mfma_f32_16x16x32_bf16 v[72:75], v[166:169], v[206:209], v[72:75]
	s_setprio 0
	s_barrier
	s_add_i32 s0, s34, s52
	s_mov_b32 m0, s0
	ds_read_b128 v[210:213], v149
	ds_read_b128 v[214:217], v149 offset:1024
	ds_read_b128 v[218:221], v149 offset:2048
	global_load_lds_dwordx4 v130, s[42:43]
	s_add_i32 m0, s0, 0x2000
	ds_read_b128 v[222:225], v149 offset:3072
	global_load_lds_dwordx4 v134, s[42:43]
	s_barrier
	s_waitcnt lgkmcnt(0)
	s_setprio 1
	v_mfma_f32_16x16x32_bf16 v[116:119], v[210:213], v[170:173], 0
	v_mfma_f32_16x16x32_bf16 v[112:115], v[218:221], v[170:173], 0
	v_mfma_f32_16x16x32_bf16 v[100:103], v[210:213], v[178:181], 0
	v_mfma_f32_16x16x32_bf16 v[96:99], v[218:221], v[178:181], 0
	v_mfma_f32_16x16x32_bf16 v[84:87], v[210:213], v[194:197], 0
	v_mfma_f32_16x16x32_bf16 v[80:83], v[218:221], v[194:197], 0
	v_mfma_f32_16x16x32_bf16 v[68:71], v[210:213], v[202:205], 0
	v_mfma_f32_16x16x32_bf16 v[64:67], v[218:221], v[202:205], 0
	v_mfma_f32_16x16x32_bf16 v[116:119], v[214:217], v[174:177], v[116:119]
	v_mfma_f32_16x16x32_bf16 v[112:115], v[222:225], v[174:177], v[112:115]
	v_mfma_f32_16x16x32_bf16 v[100:103], v[214:217], v[188:191], v[100:103]
	v_mfma_f32_16x16x32_bf16 v[96:99], v[222:225], v[188:191], v[96:99]
	v_mfma_f32_16x16x32_bf16 v[84:87], v[214:217], v[198:201], v[84:87]
	v_mfma_f32_16x16x32_bf16 v[80:83], v[222:225], v[198:201], v[80:83]
	v_mfma_f32_16x16x32_bf16 v[68:71], v[214:217], v[206:209], v[68:71]
	v_mfma_f32_16x16x32_bf16 v[64:67], v[222:225], v[206:209], v[64:67]
	s_setprio 0
	s_mov_b32 m0, s39
	s_barrier
	ds_read_b128 v[170:173], v148 offset:16384
	ds_read_b128 v[174:177], v148 offset:17408
	ds_read_b128 v[178:181], v148 offset:18432
	ds_read_b128 v[188:191], v148 offset:19456
	ds_read_b128 v[194:197], v148 offset:20480
	ds_read_b128 v[198:201], v148 offset:21504
	ds_read_b128 v[202:205], v148 offset:22528
	global_load_lds_dwordx4 v128, s[44:45]
	s_mov_b32 m0, s53
	ds_read_b128 v[206:209], v148 offset:23552
	global_load_lds_dwordx4 v132, s[44:45]
	s_barrier
	s_waitcnt lgkmcnt(0)
	s_setprio 1
	v_mfma_f32_16x16x32_bf16 v[60:63], v[150:153], v[170:173], 0
	v_mfma_f32_16x16x32_bf16 v[56:59], v[162:165], v[170:173], 0
	v_mfma_f32_16x16x32_bf16 v[44:47], v[150:153], v[178:181], 0
	v_mfma_f32_16x16x32_bf16 v[40:43], v[162:165], v[178:181], 0
	v_mfma_f32_16x16x32_bf16 v[28:31], v[150:153], v[194:197], 0
	v_mfma_f32_16x16x32_bf16 v[24:27], v[162:165], v[194:197], 0
	v_mfma_f32_16x16x32_bf16 v[12:15], v[150:153], v[202:205], 0
	v_mfma_f32_16x16x32_bf16 v[8:11], v[162:165], v[202:205], 0
	v_mfma_f32_16x16x32_bf16 v[60:63], v[154:157], v[174:177], v[60:63]
	v_mfma_f32_16x16x32_bf16 v[56:59], v[166:169], v[174:177], v[56:59]
	v_mfma_f32_16x16x32_bf16 v[44:47], v[154:157], v[188:191], v[44:47]
	v_mfma_f32_16x16x32_bf16 v[40:43], v[166:169], v[188:191], v[40:43]
	v_mfma_f32_16x16x32_bf16 v[28:31], v[154:157], v[198:201], v[28:31]
	v_mfma_f32_16x16x32_bf16 v[24:27], v[166:169], v[198:201], v[24:27]
	v_mfma_f32_16x16x32_bf16 v[12:15], v[154:157], v[206:209], v[12:15]
	v_mfma_f32_16x16x32_bf16 v[8:11], v[166:169], v[206:209], v[8:11]
	s_setprio 0
	s_barrier
; #define PG8_STAGE(bufoff, gbase, voff) do { _Pragma("unroll") for (int _i = 0; _i < 2; ++_i) \
;         __builtin_amdgcn_global_load_lds((const unsigned*)((const char*)(gbase) + (voff)[_i]), (LAS unsigned*)(lds + (bufoff) + ldsw + _i * 8192), 16, 0, 0); } while (0)
; #define PG8_LDA(dst, b, h) do { _Pragma("unroll") for (int m = 0; m < 4; ++m) _Pragma("unroll") for (int k = 0; k < 2; ++k) dst[m][k] = *(const LAS bf16x8*)(lds + PG8_SA(b, h) + aoff + m * 2048 + k * 1024); } while (0)
; #define PG8_LDB(dst, b, h) do { _Pragma("unroll") for (int n = 0; n < 2; ++n) _Pragma("unroll") for (int k = 0; k < 2; ++k) dst[n][k] = *(const LAS bf16x8*)(lds + PG8_SB(b, h) + boff + n * 2048 + k * 1024); } while (0)
; #define PG8_MMA(ai, bj, At, Bt) do { __builtin_amdgcn_s_setprio(1); _Pragma("unroll") for (int m = 0; m < 4; ++m) _Pragma("unroll") for (int n = 0; n < 2; ++n) _Pragma("unroll") for (int k = 0; k < 2; ++k) \
;         acc[ai][bj][m][n] = __builtin_amdgcn_mfma_f32_16x16x32_bf16(Bt[n][k], At[m][k], acc[ai][bj][m][n], 0, 0, 0); __builtin_amdgcn_s_setprio(0); } while (0)
; #define PG8_WAIT_V(n) asm volatile("s_waitcnt vmcnt(" #n ")" ::: "memory")
; #define PG8_WAIT_L(n) asm volatile("s_waitcnt lgkmcnt(" #n ")" ::: "memory")
; #define PG8_BAR __builtin_amdgcn_s_barrier()
; #define PG8_SCHED __builtin_amdgcn_sched_barrier(0)
; template <class Epi, class Sched>
; DI void gemm_phase(LAS unsigned char* lds, const Gemm g, const Sched& S, const Epi& E) {
;     ...
;             PG8_STAGE(PG8_SB(0, 1), b2 + hstep, voffB);
;             PG8_WAIT_V(6); PG8_BAR; PG8_MMA(1, 1, At, B1); PG8_BAR;
;             PG8_LDB(B0, 1, 0); PG8_SCHED; PG8_LDA(At, 1, 0); PG8_STAGE(PG8_SA(0, 1), a2 + hstep, voffA);
;             PG8_WAIT_L(8); PG8_BAR; PG8_WAIT_L(0); PG8_MMA(0, 0, At, B0); PG8_BAR; PG8_SCHED;
;             PG8_LDB(B1, 1, 1); PG8_STAGE(PG8_SB(1, 0), b3, voffB);
	s_add_i32 s4, s35, s52
	s_mov_b32 m0, s4
	s_add_u32 s0, s42, 0x80000
	s_addc_u32 s1, s43, 0
	global_load_lds_dwordx4 v130, s[0:1]
	s_add_i32 m0, s4, 0x2000
	s_nop 0
	global_load_lds_dwordx4 v134, s[0:1]
	s_waitcnt vmcnt(6)
	s_barrier
	s_setprio 1
	v_mfma_f32_16x16x32_bf16 v[52:55], v[210:213], v[170:173], 0
	v_mfma_f32_16x16x32_bf16 v[48:51], v[218:221], v[170:173], 0
	v_mfma_f32_16x16x32_bf16 v[36:39], v[210:213], v[178:181], 0
	v_mfma_f32_16x16x32_bf16 v[32:35], v[218:221], v[178:181], 0
	v_mfma_f32_16x16x32_bf16 v[20:23], v[210:213], v[194:197], 0
	v_mfma_f32_16x16x32_bf16 v[16:19], v[218:221], v[194:197], 0
	v_mfma_f32_16x16x32_bf16 v[4:7], v[210:213], v[202:205], 0
	v_mfma_f32_16x16x32_bf16 v[0:3], v[218:221], v[202:205], 0
	v_mfma_f32_16x16x32_bf16 v[52:55], v[214:217], v[174:177], v[52:55]
	v_mfma_f32_16x16x32_bf16 v[48:51], v[222:225], v[174:177], v[48:51]
	v_mfma_f32_16x16x32_bf16 v[36:39], v[214:217], v[188:191], v[36:39]
	v_mfma_f32_16x16x32_bf16 v[32:35], v[222:225], v[188:191], v[32:35]
	v_mfma_f32_16x16x32_bf16 v[20:23], v[214:217], v[198:201], v[20:23]
	v_mfma_f32_16x16x32_bf16 v[16:19], v[222:225], v[198:201], v[16:19]
	v_mfma_f32_16x16x32_bf16 v[4:7], v[214:217], v[206:209], v[4:7]
	v_mfma_f32_16x16x32_bf16 v[0:3], v[222:225], v[206:209], v[0:3]
	s_setprio 0
	s_add_i32 s4, 0, 0x18000
	v_add_u32_e32 v158, s4, v146
	s_barrier
	ds_read_b128 v[150:153], v158
	ds_read_b128 v[154:157], v158 offset:1024
	ds_read_b128 v[162:165], v158 offset:2048
	ds_read_b128 v[166:169], v158 offset:3072
	s_add_u32 s0, s44, 0x80000
	s_addc_u32 s1, s45, 0
	s_mov_b32 m0, s54
	ds_read_b128 v[170:173], v148 offset:32768
	ds_read_b128 v[174:177], v148 offset:33792
	ds_read_b128 v[178:181], v148 offset:34816
	ds_read_b128 v[188:191], v148 offset:35840
	ds_read_b128 v[194:197], v148 offset:36864
	ds_read_b128 v[198:201], v148 offset:37888
	ds_read_b128 v[202:205], v148 offset:38912
	global_load_lds_dwordx4 v128, s[0:1]
	s_mov_b32 m0, s55
	ds_read_b128 v[206:209], v148 offset:39936
	global_load_lds_dwordx4 v132, s[0:1]
	s_waitcnt lgkmcnt(8)
	s_barrier
	s_waitcnt lgkmcnt(0)
	s_setprio 1
	v_mfma_f32_16x16x32_bf16 v[124:127], v[150:153], v[170:173], v[124:127]
	v_mfma_f32_16x16x32_bf16 v[120:123], v[162:165], v[170:173], v[120:123]
	v_mfma_f32_16x16x32_bf16 v[108:111], v[150:153], v[178:181], v[108:111]
	v_mfma_f32_16x16x32_bf16 v[104:107], v[162:165], v[178:181], v[104:107]
	v_mfma_f32_16x16x32_bf16 v[92:95], v[150:153], v[194:197], v[92:95]
	v_mfma_f32_16x16x32_bf16 v[88:91], v[162:165], v[194:197], v[88:91]
	v_mfma_f32_16x16x32_bf16 v[76:79], v[150:153], v[202:205], v[76:79]
	v_mfma_f32_16x16x32_bf16 v[72:75], v[162:165], v[202:205], v[72:75]
	v_mfma_f32_16x16x32_bf16 v[124:127], v[154:157], v[174:177], v[124:127]
	v_mfma_f32_16x16x32_bf16 v[120:123], v[166:169], v[174:177], v[120:123]
	v_mfma_f32_16x16x32_bf16 v[108:111], v[154:157], v[188:191], v[108:111]
	v_mfma_f32_16x16x32_bf16 v[104:107], v[166:169], v[188:191], v[104:107]
	v_mfma_f32_16x16x32_bf16 v[92:95], v[154:157], v[198:201], v[92:95]
	v_mfma_f32_16x16x32_bf16 v[88:91], v[166:169], v[198:201], v[88:91]
	v_mfma_f32_16x16x32_bf16 v[76:79], v[154:157], v[206:209], v[76:79]
	v_mfma_f32_16x16x32_bf16 v[72:75], v[166:169], v[206:209], v[72:75]
	s_setprio 0
	s_barrier
	s_add_i32 s5, 0, 0x1c000
	s_add_i32 s0, s4, s52
	v_add_u32_e32 v159, s5, v146
	s_add_i32 m0, s0, 0xffffff80
	ds_read_b128 v[210:213], v159
	ds_read_b128 v[214:217], v159 offset:1024
	ds_read_b128 v[218:221], v159 offset:2048
	global_load_lds_dwordx4 v130, s[42:43] offset:128
	s_add_i32 m0, s0, 0x1f80
	ds_read_b128 v[222:225], v159 offset:3072
	global_load_lds_dwordx4 v134, s[42:43] offset:128
	s_barrier
; #define PG8_STAGE(bufoff, gbase, voff) do { _Pragma("unroll") for (int _i = 0; _i < 2; ++_i) \
;         __builtin_amdgcn_global_load_lds((const unsigned*)((const char*)(gbase) + (voff)[_i]), (LAS unsigned*)(lds + (bufoff) + ldsw + _i * 8192), 16, 0, 0); } while (0)
; #define PG8_LDA(dst, b, h) do { _Pragma("unroll") for (int m = 0; m < 4; ++m) _Pragma("unroll") for (int k = 0; k < 2; ++k) dst[m][k] = *(const LAS bf16x8*)(lds + PG8_SA(b, h) + aoff + m * 2048 + k * 1024); } while (0)
; #define PG8_MMA(ai, bj, At, Bt) do { __builtin_amdgcn_s_setprio(1); _Pragma("unroll") for (int m = 0; m < 4; ++m) _Pragma("unroll") for (int n = 0; n < 2; ++n) _Pragma("unroll") for (int k = 0; k < 2; ++k) \
;         acc[ai][bj][m][n] = __builtin_amdgcn_mfma_f32_16x16x32_bf16(Bt[n][k], At[m][k], acc[ai][bj][m][n], 0, 0, 0); __builtin_amdgcn_s_setprio(0); } while (0)
; #define PG8_WAIT_V(n) asm volatile("s_waitcnt vmcnt(" #n ")" ::: "memory")
; #define PG8_WAIT_L(n) asm volatile("s_waitcnt lgkmcnt(" #n ")" ::: "memory")
; #define PG8_BAR __builtin_amdgcn_s_barrier()
; #define PG8_SCHED __builtin_amdgcn_sched_barrier(0)
; template <class Epi, class Sched>
; DI void gemm_phase(LAS unsigned char* lds, const Gemm g, const Sched& S, const Epi& E) {
;     ...
;             PG8_BAR; PG8_WAIT_L(0); PG8_MMA(0, 1, At, B1); PG8_BAR;
;             PG8_LDA(At, 1, 1); PG8_STAGE(PG8_SA(1, 0), a3, voffA);
;             PG8_BAR; PG8_WAIT_L(0); PG8_MMA(1, 0, At, B0); PG8_BAR; PG8_SCHED;
;             PG8_STAGE(PG8_SB(1, 1), b3 + hstep, voffB);
;             PG8_WAIT_V(6); PG8_BAR; PG8_MMA(1, 1, At, B1); PG8_BAR;
	s_waitcnt lgkmcnt(0)
	s_setprio 1
	v_mfma_f32_16x16x32_bf16 v[116:119], v[210:213], v[170:173], v[116:119]
	v_mfma_f32_16x16x32_bf16 v[112:115], v[218:221], v[170:173], v[112:115]
	v_mfma_f32_16x16x32_bf16 v[100:103], v[210:213], v[178:181], v[100:103]
	v_mfma_f32_16x16x32_bf16 v[96:99], v[218:221], v[178:181], v[96:99]
	v_mfma_f32_16x16x32_bf16 v[84:87], v[210:213], v[194:197], v[84:87]
	v_mfma_f32_16x16x32_bf16 v[80:83], v[218:221], v[194:197], v[80:83]
	v_mfma_f32_16x16x32_bf16 v[68:71], v[210:213], v[202:205], v[68:71]
	v_mfma_f32_16x16x32_bf16 v[64:67], v[218:221], v[202:205], v[64:67]
	v_mfma_f32_16x16x32_bf16 v[116:119], v[214:217], v[174:177], v[116:119]
	v_mfma_f32_16x16x32_bf16 v[112:115], v[222:225], v[174:177], v[112:115]
	v_mfma_f32_16x16x32_bf16 v[100:103], v[214:217], v[188:191], v[100:103]
	v_mfma_f32_16x16x32_bf16 v[96:99], v[222:225], v[188:191], v[96:99]
	v_mfma_f32_16x16x32_bf16 v[84:87], v[214:217], v[198:201], v[84:87]
	v_mfma_f32_16x16x32_bf16 v[80:83], v[222:225], v[198:201], v[80:83]
	v_mfma_f32_16x16x32_bf16 v[68:71], v[214:217], v[206:209], v[68:71]
	v_mfma_f32_16x16x32_bf16 v[64:67], v[222:225], v[206:209], v[64:67]
	s_setprio 0
	s_add_i32 m0, s59, 0xffffff80
	s_barrier
	ds_read_b128 v[170:173], v148 offset:49152
	ds_read_b128 v[174:177], v148 offset:50176
	ds_read_b128 v[178:181], v148 offset:51200
	ds_read_b128 v[188:191], v148 offset:52224
	ds_read_b128 v[194:197], v148 offset:53248
	ds_read_b128 v[198:201], v148 offset:54272
	ds_read_b128 v[202:205], v148 offset:55296
	global_load_lds_dwordx4 v128, s[44:45] offset:128
	s_add_i32 m0, s60, 0xffffff80
	ds_read_b128 v[206:209], v148 offset:56320
	global_load_lds_dwordx4 v132, s[44:45] offset:128
	s_barrier
	s_waitcnt lgkmcnt(0)
	s_setprio 1
	v_mfma_f32_16x16x32_bf16 v[60:63], v[150:153], v[170:173], v[60:63]
	v_mfma_f32_16x16x32_bf16 v[56:59], v[162:165], v[170:173], v[56:59]
	v_mfma_f32_16x16x32_bf16 v[44:47], v[150:153], v[178:181], v[44:47]
	v_mfma_f32_16x16x32_bf16 v[40:43], v[162:165], v[178:181], v[40:43]
	v_mfma_f32_16x16x32_bf16 v[28:31], v[150:153], v[194:197], v[28:31]
	v_mfma_f32_16x16x32_bf16 v[24:27], v[162:165], v[194:197], v[24:27]
	v_mfma_f32_16x16x32_bf16 v[12:15], v[150:153], v[202:205], v[12:15]
	v_mfma_f32_16x16x32_bf16 v[8:11], v[162:165], v[202:205], v[8:11]
	v_mfma_f32_16x16x32_bf16 v[60:63], v[154:157], v[174:177], v[60:63]
	v_mfma_f32_16x16x32_bf16 v[56:59], v[166:169], v[174:177], v[56:59]
	v_mfma_f32_16x16x32_bf16 v[44:47], v[154:157], v[188:191], v[44:47]
	v_mfma_f32_16x16x32_bf16 v[40:43], v[166:169], v[188:191], v[40:43]
	v_mfma_f32_16x16x32_bf16 v[28:31], v[154:157], v[198:201], v[28:31]
	v_mfma_f32_16x16x32_bf16 v[24:27], v[166:169], v[198:201], v[24:27]
	v_mfma_f32_16x16x32_bf16 v[12:15], v[154:157], v[206:209], v[12:15]
	v_mfma_f32_16x16x32_bf16 v[8:11], v[166:169], v[206:209], v[8:11]
	s_setprio 0
	s_barrier
	s_add_i32 s4, s5, s52
	s_mov_b32 m0, s4
	s_add_u32 s0, s42, 0x80080
	s_addc_u32 s1, s43, 0
	global_load_lds_dwordx4 v130, s[0:1]
	s_add_i32 m0, s4, 0x2000
	s_nop 0
	global_load_lds_dwordx4 v134, s[0:1]
	s_add_i32 s69, s69, 2
	s_add_u32 s40, s40, 0x100
	s_addc_u32 s41, s41, 0
	s_add_u32 s67, s67, 0x100
	s_addc_u32 s68, s68, 0
	s_cmp_gt_u32 s69, 29
	s_waitcnt vmcnt(6)
	s_barrier
	s_setprio 1
	v_mfma_f32_16x16x32_bf16 v[52:55], v[210:213], v[170:173], v[52:55]
	v_mfma_f32_16x16x32_bf16 v[48:51], v[218:221], v[170:173], v[48:51]
	v_mfma_f32_16x16x32_bf16 v[36:39], v[210:213], v[178:181], v[36:39]
	v_mfma_f32_16x16x32_bf16 v[32:35], v[218:221], v[178:181], v[32:35]
	v_mfma_f32_16x16x32_bf16 v[20:23], v[210:213], v[194:197], v[20:23]
	v_mfma_f32_16x16x32_bf16 v[16:19], v[218:221], v[194:197], v[16:19]
	v_mfma_f32_16x16x32_bf16 v[4:7], v[210:213], v[202:205], v[4:7]
	v_mfma_f32_16x16x32_bf16 v[0:3], v[218:221], v[202:205], v[0:3]
	v_mfma_f32_16x16x32_bf16 v[52:55], v[214:217], v[174:177], v[52:55]
	v_mfma_f32_16x16x32_bf16 v[48:51], v[222:225], v[174:177], v[48:51]
	v_mfma_f32_16x16x32_bf16 v[36:39], v[214:217], v[188:191], v[36:39]
	v_mfma_f32_16x16x32_bf16 v[32:35], v[222:225], v[188:191], v[32:35]
	v_mfma_f32_16x16x32_bf16 v[20:23], v[214:217], v[198:201], v[20:23]
	v_mfma_f32_16x16x32_bf16 v[16:19], v[222:225], v[198:201], v[16:19]
	v_mfma_f32_16x16x32_bf16 v[4:7], v[214:217], v[206:209], v[4:7]
	v_mfma_f32_16x16x32_bf16 v[0:3], v[222:225], v[206:209], v[0:3]
	s_setprio 0
	s_cbranch_scc0 .Lrot_219
	s_barrier
	s_branch .Lpeel_done_219

; #define PG8_STAGE(bufoff, gbase, voff) do { _Pragma("unroll") for (int _i = 0; _i < 2; ++_i) \
;         __builtin_amdgcn_global_load_lds((const unsigned*)((const char*)(gbase) + (voff)[_i]), (LAS unsigned*)(lds + (bufoff) + ldsw + _i * 8192), 16, 0, 0); } while (0)
; #define PG8_LDA(dst, b, h) do { _Pragma("unroll") for (int m = 0; m < 4; ++m) _Pragma("unroll") for (int k = 0; k < 2; ++k) dst[m][k] = *(const LAS bf16x8*)(lds + PG8_SA(b, h) + aoff + m * 2048 + k * 1024); } while (0)
; #define PG8_LDB(dst, b, h) do { _Pragma("unroll") for (int n = 0; n < 2; ++n) _Pragma("unroll") for (int k = 0; k < 2; ++k) dst[n][k] = *(const LAS bf16x8*)(lds + PG8_SB(b, h) + boff + n * 2048 + k * 1024); } while (0)
; #define PG8_MMA(ai, bj, At, Bt) do { __builtin_amdgcn_s_setprio(1); _Pragma("unroll") for (int m = 0; m < 4; ++m) _Pragma("unroll") for (int n = 0; n < 2; ++n) _Pragma("unroll") for (int k = 0; k < 2; ++k) \
;         acc[ai][bj][m][n] = __builtin_amdgcn_mfma_f32_16x16x32_bf16(Bt[n][k], At[m][k], acc[ai][bj][m][n], 0, 0, 0); __builtin_amdgcn_s_setprio(0); } while (0)
; #define PG8_WAIT_V(n) asm volatile("s_waitcnt vmcnt(" #n ")" ::: "memory")
; #define PG8_WAIT_L(n) asm volatile("s_waitcnt lgkmcnt(" #n ")" ::: "memory")
; #define PG8_BAR __builtin_amdgcn_s_barrier()
; #define PG8_SCHED __builtin_amdgcn_sched_barrier(0)
; template <class Epi, class Sched>
; DI void gemm_phase(LAS unsigned char* lds, const Gemm g, const Sched& S, const Epi& E) {
;     ...
;             PG8_LDB(B0, 0, 0); PG8_SCHED; PG8_LDA(At, 0, 0); PG8_STAGE(PG8_SA(1, 1), a1 + hstep, voffA);
;             PG8_WAIT_L(8); PG8_BAR; PG8_WAIT_L(0); PG8_MMA(0, 0, At, B0); PG8_BAR; PG8_SCHED;
;             PG8_LDB(B1, 0, 1); PG8_STAGE(PG8_SB(0, 0), b2, voffB);
;             PG8_BAR; PG8_WAIT_L(0); PG8_MMA(0, 1, At, B1); PG8_BAR;
;             PG8_LDA(At, 0, 1); PG8_STAGE(PG8_SA(0, 0), a2, voffA);
;             PG8_BAR; PG8_WAIT_L(0); PG8_MMA(1, 0, At, B0); PG8_BAR; PG8_SCHED;
;             PG8_STAGE(PG8_SB(0, 1), b2 + hstep, voffB);
;             PG8_WAIT_V(6); PG8_BAR; PG8_MMA(1, 1, At, B1); PG8_BAR;
.LBB0_219:
	ds_read_b128 v[150:153], v147
	ds_read_b128 v[154:157], v147 offset:1024
	ds_read_b128 v[162:165], v147 offset:2048
	ds_read_b128 v[166:169], v147 offset:3072
	s_add_i32 m0, s39, 0xc000
	ds_read_b128 v[170:173], v148
	ds_read_b128 v[174:177], v148 offset:1024
	ds_read_b128 v[178:181], v148 offset:2048
	ds_read_b128 v[188:191], v148 offset:3072
	ds_read_b128 v[194:197], v148 offset:4096
	ds_read_b128 v[198:201], v148 offset:5120
	ds_read_b128 v[202:205], v148 offset:6144
	global_load_lds_dwordx4 v136, s[40:41]
	s_add_i32 m0, s39, 0xe000
	ds_read_b128 v[206:209], v148 offset:7168
	global_load_lds_dwordx4 v138, s[40:41]
	s_add_u32 s0, s40, 0xfff80080
	s_addc_u32 s1, s41, -1
	s_cmp_eq_u32 s69, 28
	s_cselect_b32 s45, s17, s1
	s_cselect_b32 s44, s65, s0
	s_cselect_b32 s43, s15, s68
	s_cselect_b32 s42, s66, s67
	s_waitcnt lgkmcnt(8)
	s_barrier
	s_waitcnt lgkmcnt(0)
	s_setprio 1
	v_mfma_f32_16x16x32_bf16 v[124:127], v[150:153], v[170:173], v[124:127]
	v_mfma_f32_16x16x32_bf16 v[120:123], v[162:165], v[170:173], v[120:123]
	v_mfma_f32_16x16x32_bf16 v[108:111], v[150:153], v[178:181], v[108:111]
	v_mfma_f32_16x16x32_bf16 v[104:107], v[162:165], v[178:181], v[104:107]
	v_mfma_f32_16x16x32_bf16 v[92:95], v[150:153], v[194:197], v[92:95]
	v_mfma_f32_16x16x32_bf16 v[88:91], v[162:165], v[194:197], v[88:91]
	v_mfma_f32_16x16x32_bf16 v[76:79], v[150:153], v[202:205], v[76:79]
	v_mfma_f32_16x16x32_bf16 v[72:75], v[162:165], v[202:205], v[72:75]
	v_mfma_f32_16x16x32_bf16 v[124:127], v[154:157], v[174:177], v[124:127]
	v_mfma_f32_16x16x32_bf16 v[120:123], v[166:169], v[174:177], v[120:123]
	v_mfma_f32_16x16x32_bf16 v[108:111], v[154:157], v[188:191], v[108:111]
	v_mfma_f32_16x16x32_bf16 v[104:107], v[166:169], v[188:191], v[104:107]
	v_mfma_f32_16x16x32_bf16 v[92:95], v[154:157], v[198:201], v[92:95]
	v_mfma_f32_16x16x32_bf16 v[88:91], v[166:169], v[198:201], v[88:91]
	v_mfma_f32_16x16x32_bf16 v[76:79], v[154:157], v[206:209], v[76:79]
	v_mfma_f32_16x16x32_bf16 v[72:75], v[166:169], v[206:209], v[72:75]
	s_setprio 0
	s_barrier
	s_add_i32 s0, s34, s52
	s_mov_b32 m0, s0
	ds_read_b128 v[210:213], v149
	ds_read_b128 v[214:217], v149 offset:1024
	ds_read_b128 v[218:221], v149 offset:2048
	global_load_lds_dwordx4 v130, s[42:43]
	s_add_i32 m0, s0, 0x2000
	ds_read_b128 v[222:225], v149 offset:3072
	global_load_lds_dwordx4 v134, s[42:43]
	s_barrier
	s_waitcnt lgkmcnt(0)
	s_setprio 1
	v_mfma_f32_16x16x32_bf16 v[116:119], v[210:213], v[170:173], v[116:119]
	v_mfma_f32_16x16x32_bf16 v[112:115], v[218:221], v[170:173], v[112:115]
	v_mfma_f32_16x16x32_bf16 v[100:103], v[210:213], v[178:181], v[100:103]
	v_mfma_f32_16x16x32_bf16 v[96:99], v[218:221], v[178:181], v[96:99]
	v_mfma_f32_16x16x32_bf16 v[84:87], v[210:213], v[194:197], v[84:87]
	v_mfma_f32_16x16x32_bf16 v[80:83], v[218:221], v[194:197], v[80:83]
	v_mfma_f32_16x16x32_bf16 v[68:71], v[210:213], v[202:205], v[68:71]
	v_mfma_f32_16x16x32_bf16 v[64:67], v[218:221], v[202:205], v[64:67]
	v_mfma_f32_16x16x32_bf16 v[116:119], v[214:217], v[174:177], v[116:119]
	v_mfma_f32_16x16x32_bf16 v[112:115], v[222:225], v[174:177], v[112:115]
	v_mfma_f32_16x16x32_bf16 v[100:103], v[214:217], v[188:191], v[100:103]
	v_mfma_f32_16x16x32_bf16 v[96:99], v[222:225], v[188:191], v[96:99]
	v_mfma_f32_16x16x32_bf16 v[84:87], v[214:217], v[198:201], v[84:87]
	v_mfma_f32_16x16x32_bf16 v[80:83], v[222:225], v[198:201], v[80:83]
	v_mfma_f32_16x16x32_bf16 v[68:71], v[214:217], v[206:209], v[68:71]
	v_mfma_f32_16x16x32_bf16 v[64:67], v[222:225], v[206:209], v[64:67]
	s_setprio 0
	s_mov_b32 m0, s39
	s_barrier
	ds_read_b128 v[170:173], v148 offset:16384
	ds_read_b128 v[174:177], v148 offset:17408
	ds_read_b128 v[178:181], v148 offset:18432
	ds_read_b128 v[188:191], v148 offset:19456
	ds_read_b128 v[194:197], v148 offset:20480
	ds_read_b128 v[198:201], v148 offset:21504
	ds_read_b128 v[202:205], v148 offset:22528
	global_load_lds_dwordx4 v128, s[44:45]
	s_mov_b32 m0, s53
	ds_read_b128 v[206:209], v148 offset:23552
	global_load_lds_dwordx4 v132, s[44:45]
	s_barrier
	s_waitcnt lgkmcnt(0)
	s_setprio 1
	v_mfma_f32_16x16x32_bf16 v[60:63], v[150:153], v[170:173], v[60:63]
	v_mfma_f32_16x16x32_bf16 v[56:59], v[162:165], v[170:173], v[56:59]
	v_mfma_f32_16x16x32_bf16 v[44:47], v[150:153], v[178:181], v[44:47]
	v_mfma_f32_16x16x32_bf16 v[40:43], v[162:165], v[178:181], v[40:43]
	v_mfma_f32_16x16x32_bf16 v[28:31], v[150:153], v[194:197], v[28:31]
	v_mfma_f32_16x16x32_bf16 v[24:27], v[162:165], v[194:197], v[24:27]
	v_mfma_f32_16x16x32_bf16 v[12:15], v[150:153], v[202:205], v[12:15]
	v_mfma_f32_16x16x32_bf16 v[8:11], v[162:165], v[202:205], v[8:11]
	v_mfma_f32_16x16x32_bf16 v[60:63], v[154:157], v[174:177], v[60:63]
	v_mfma_f32_16x16x32_bf16 v[56:59], v[166:169], v[174:177], v[56:59]
	v_mfma_f32_16x16x32_bf16 v[44:47], v[154:157], v[188:191], v[44:47]
	v_mfma_f32_16x16x32_bf16 v[40:43], v[166:169], v[188:191], v[40:43]
	v_mfma_f32_16x16x32_bf16 v[28:31], v[154:157], v[198:201], v[28:31]
	v_mfma_f32_16x16x32_bf16 v[24:27], v[166:169], v[198:201], v[24:27]
	v_mfma_f32_16x16x32_bf16 v[12:15], v[154:157], v[206:209], v[12:15]
	v_mfma_f32_16x16x32_bf16 v[8:11], v[166:169], v[206:209], v[8:11]
	s_setprio 0
	s_barrier
	s_add_i32 s4, s35, s52
	s_mov_b32 m0, s4
	s_add_u32 s0, s42, 0x80000
	s_addc_u32 s1, s43, 0
	global_load_lds_dwordx4 v130, s[0:1]
	s_add_i32 m0, s4, 0x2000
	s_nop 0
	global_load_lds_dwordx4 v134, s[0:1]
	s_waitcnt vmcnt(6)
	s_barrier
; #define PG8_STAGE(bufoff, gbase, voff) do { _Pragma("unroll") for (int _i = 0; _i < 2; ++_i) \
;         __builtin_amdgcn_global_load_lds((const unsigned*)((const char*)(gbase) + (voff)[_i]), (LAS unsigned*)(lds + (bufoff) + ldsw + _i * 8192), 16, 0, 0); } while (0)
; #define PG8_LDA(dst, b, h) do { _Pragma("unroll") for (int m = 0; m < 4; ++m) _Pragma("unroll") for (int k = 0; k < 2; ++k) dst[m][k] = *(const LAS bf16x8*)(lds + PG8_SA(b, h) + aoff + m * 2048 + k * 1024); } while (0)
; #define PG8_LDB(dst, b, h) do { _Pragma("unroll") for (int n = 0; n < 2; ++n) _Pragma("unroll") for (int k = 0; k < 2; ++k) dst[n][k] = *(const LAS bf16x8*)(lds + PG8_SB(b, h) + boff + n * 2048 + k * 1024); } while (0)
; #define PG8_MMA(ai, bj, At, Bt) do { __builtin_amdgcn_s_setprio(1); _Pragma("unroll") for (int m = 0; m < 4; ++m) _Pragma("unroll") for (int n = 0; n < 2; ++n) _Pragma("unroll") for (int k = 0; k < 2; ++k) \
;         acc[ai][bj][m][n] = __builtin_amdgcn_mfma_f32_16x16x32_bf16(Bt[n][k], At[m][k], acc[ai][bj][m][n], 0, 0, 0); __builtin_amdgcn_s_setprio(0); } while (0)
; #define PG8_WAIT_V(n) asm volatile("s_waitcnt vmcnt(" #n ")" ::: "memory")
; #define PG8_WAIT_L(n) asm volatile("s_waitcnt lgkmcnt(" #n ")" ::: "memory")
; #define PG8_BAR __builtin_amdgcn_s_barrier()
; #define PG8_SCHED __builtin_amdgcn_sched_barrier(0)
; template <class Epi, class Sched>
; DI void gemm_phase(LAS unsigned char* lds, const Gemm g, const Sched& S, const Epi& E) {
;     ...
;             PG8_WAIT_V(6); PG8_BAR; PG8_MMA(1, 1, At, B1); PG8_BAR;
;             PG8_LDB(B0, 1, 0); PG8_SCHED; PG8_LDA(At, 1, 0); PG8_STAGE(PG8_SA(0, 1), a2 + hstep, voffA);
;             PG8_WAIT_L(8); PG8_BAR; PG8_WAIT_L(0); PG8_MMA(0, 0, At, B0); PG8_BAR; PG8_SCHED;
;             PG8_LDB(B1, 1, 1); PG8_STAGE(PG8_SB(1, 0), b3, voffB);
	s_setprio 1
	v_mfma_f32_16x16x32_bf16 v[52:55], v[210:213], v[170:173], v[52:55]
	v_mfma_f32_16x16x32_bf16 v[48:51], v[218:221], v[170:173], v[48:51]
	v_mfma_f32_16x16x32_bf16 v[36:39], v[210:213], v[178:181], v[36:39]
	v_mfma_f32_16x16x32_bf16 v[32:35], v[218:221], v[178:181], v[32:35]
	v_mfma_f32_16x16x32_bf16 v[20:23], v[210:213], v[194:197], v[20:23]
	v_mfma_f32_16x16x32_bf16 v[16:19], v[218:221], v[194:197], v[16:19]
	v_mfma_f32_16x16x32_bf16 v[4:7], v[210:213], v[202:205], v[4:7]
	v_mfma_f32_16x16x32_bf16 v[0:3], v[218:221], v[202:205], v[0:3]
	v_mfma_f32_16x16x32_bf16 v[52:55], v[214:217], v[174:177], v[52:55]
	v_mfma_f32_16x16x32_bf16 v[48:51], v[222:225], v[174:177], v[48:51]
	v_mfma_f32_16x16x32_bf16 v[36:39], v[214:217], v[188:191], v[36:39]
	v_mfma_f32_16x16x32_bf16 v[32:35], v[222:225], v[188:191], v[32:35]
	v_mfma_f32_16x16x32_bf16 v[20:23], v[214:217], v[198:201], v[20:23]
	v_mfma_f32_16x16x32_bf16 v[16:19], v[222:225], v[198:201], v[16:19]
	v_mfma_f32_16x16x32_bf16 v[4:7], v[214:217], v[206:209], v[4:7]
	v_mfma_f32_16x16x32_bf16 v[0:3], v[222:225], v[206:209], v[0:3]
	s_setprio 0
	s_add_i32 s4, 0, 0x18000
	s_barrier
	ds_read_b128 v[150:153], v158
	ds_read_b128 v[154:157], v158 offset:1024
	ds_read_b128 v[162:165], v158 offset:2048
	ds_read_b128 v[166:169], v158 offset:3072
	s_add_u32 s0, s44, 0x80000
	s_addc_u32 s1, s45, 0
	s_mov_b32 m0, s54
	ds_read_b128 v[170:173], v148 offset:32768
	ds_read_b128 v[174:177], v148 offset:33792
	ds_read_b128 v[178:181], v148 offset:34816
	ds_read_b128 v[188:191], v148 offset:35840
	ds_read_b128 v[194:197], v148 offset:36864
	ds_read_b128 v[198:201], v148 offset:37888
	ds_read_b128 v[202:205], v148 offset:38912
	global_load_lds_dwordx4 v128, s[0:1]
	s_mov_b32 m0, s55
	ds_read_b128 v[206:209], v148 offset:39936
	global_load_lds_dwordx4 v132, s[0:1]
	s_waitcnt lgkmcnt(8)
	s_barrier
	s_waitcnt lgkmcnt(0)
	s_setprio 1
	v_mfma_f32_16x16x32_bf16 v[124:127], v[150:153], v[170:173], v[124:127]
	v_mfma_f32_16x16x32_bf16 v[120:123], v[162:165], v[170:173], v[120:123]
	v_mfma_f32_16x16x32_bf16 v[108:111], v[150:153], v[178:181], v[108:111]
	v_mfma_f32_16x16x32_bf16 v[104:107], v[162:165], v[178:181], v[104:107]
	v_mfma_f32_16x16x32_bf16 v[92:95], v[150:153], v[194:197], v[92:95]
	v_mfma_f32_16x16x32_bf16 v[88:91], v[162:165], v[194:197], v[88:91]
	v_mfma_f32_16x16x32_bf16 v[76:79], v[150:153], v[202:205], v[76:79]
	v_mfma_f32_16x16x32_bf16 v[72:75], v[162:165], v[202:205], v[72:75]
	v_mfma_f32_16x16x32_bf16 v[124:127], v[154:157], v[174:177], v[124:127]
	v_mfma_f32_16x16x32_bf16 v[120:123], v[166:169], v[174:177], v[120:123]
	v_mfma_f32_16x16x32_bf16 v[108:111], v[154:157], v[188:191], v[108:111]
	v_mfma_f32_16x16x32_bf16 v[104:107], v[166:169], v[188:191], v[104:107]
	v_mfma_f32_16x16x32_bf16 v[92:95], v[154:157], v[198:201], v[92:95]
	v_mfma_f32_16x16x32_bf16 v[88:91], v[166:169], v[198:201], v[88:91]
	v_mfma_f32_16x16x32_bf16 v[76:79], v[154:157], v[206:209], v[76:79]
	v_mfma_f32_16x16x32_bf16 v[72:75], v[166:169], v[206:209], v[72:75]
	s_setprio 0
	s_barrier
	s_add_i32 s5, 0, 0x1c000
	s_add_i32 s0, s4, s52
	s_add_i32 m0, s0, 0xffffff80
	ds_read_b128 v[210:213], v159
	ds_read_b128 v[214:217], v159 offset:1024
	ds_read_b128 v[218:221], v159 offset:2048
	global_load_lds_dwordx4 v130, s[42:43] offset:128
	s_add_i32 m0, s0, 0x1f80
	ds_read_b128 v[222:225], v159 offset:3072
	global_load_lds_dwordx4 v134, s[42:43] offset:128
	s_barrier
; #define PG8_STAGE(bufoff, gbase, voff) do { _Pragma("unroll") for (int _i = 0; _i < 2; ++_i) \
;         __builtin_amdgcn_global_load_lds((const unsigned*)((const char*)(gbase) + (voff)[_i]), (LAS unsigned*)(lds + (bufoff) + ldsw + _i * 8192), 16, 0, 0); } while (0)
; #define PG8_LDA(dst, b, h) do { _Pragma("unroll") for (int m = 0; m < 4; ++m) _Pragma("unroll") for (int k = 0; k < 2; ++k) dst[m][k] = *(const LAS bf16x8*)(lds + PG8_SA(b, h) + aoff + m * 2048 + k * 1024); } while (0)
; #define PG8_MMA(ai, bj, At, Bt) do { __builtin_amdgcn_s_setprio(1); _Pragma("unroll") for (int m = 0; m < 4; ++m) _Pragma("unroll") for (int n = 0; n < 2; ++n) _Pragma("unroll") for (int k = 0; k < 2; ++k) \
;         acc[ai][bj][m][n] = __builtin_amdgcn_mfma_f32_16x16x32_bf16(Bt[n][k], At[m][k], acc[ai][bj][m][n], 0, 0, 0); __builtin_amdgcn_s_setprio(0); } while (0)
; #define PG8_WAIT_V(n) asm volatile("s_waitcnt vmcnt(" #n ")" ::: "memory")
; #define PG8_WAIT_L(n) asm volatile("s_waitcnt lgkmcnt(" #n ")" ::: "memory")
; #define PG8_BAR __builtin_amdgcn_s_barrier()
; #define PG8_SCHED __builtin_amdgcn_sched_barrier(0)
; template <class Epi, class Sched>
; DI void gemm_phase(LAS unsigned char* lds, const Gemm g, const Sched& S, const Epi& E) {
;     ...
;             PG8_BAR; PG8_WAIT_L(0); PG8_MMA(0, 1, At, B1); PG8_BAR;
;             PG8_LDA(At, 1, 1); PG8_STAGE(PG8_SA(1, 0), a3, voffA);
;             PG8_BAR; PG8_WAIT_L(0); PG8_MMA(1, 0, At, B0); PG8_BAR; PG8_SCHED;
;             PG8_STAGE(PG8_SB(1, 1), b3 + hstep, voffB);
;             PG8_WAIT_V(6); PG8_BAR; PG8_MMA(1, 1, At, B1); PG8_BAR;
	s_waitcnt lgkmcnt(0)
	s_setprio 1
	v_mfma_f32_16x16x32_bf16 v[116:119], v[210:213], v[170:173], v[116:119]
	v_mfma_f32_16x16x32_bf16 v[112:115], v[218:221], v[170:173], v[112:115]
	v_mfma_f32_16x16x32_bf16 v[100:103], v[210:213], v[178:181], v[100:103]
	v_mfma_f32_16x16x32_bf16 v[96:99], v[218:221], v[178:181], v[96:99]
	v_mfma_f32_16x16x32_bf16 v[84:87], v[210:213], v[194:197], v[84:87]
	v_mfma_f32_16x16x32_bf16 v[80:83], v[218:221], v[194:197], v[80:83]
	v_mfma_f32_16x16x32_bf16 v[68:71], v[210:213], v[202:205], v[68:71]
	v_mfma_f32_16x16x32_bf16 v[64:67], v[218:221], v[202:205], v[64:67]
	v_mfma_f32_16x16x32_bf16 v[116:119], v[214:217], v[174:177], v[116:119]
	v_mfma_f32_16x16x32_bf16 v[112:115], v[222:225], v[174:177], v[112:115]
	v_mfma_f32_16x16x32_bf16 v[100:103], v[214:217], v[188:191], v[100:103]
	v_mfma_f32_16x16x32_bf16 v[96:99], v[222:225], v[188:191], v[96:99]
	v_mfma_f32_16x16x32_bf16 v[84:87], v[214:217], v[198:201], v[84:87]
	v_mfma_f32_16x16x32_bf16 v[80:83], v[222:225], v[198:201], v[80:83]
	v_mfma_f32_16x16x32_bf16 v[68:71], v[214:217], v[206:209], v[68:71]
	v_mfma_f32_16x16x32_bf16 v[64:67], v[222:225], v[206:209], v[64:67]
	s_setprio 0
	s_add_i32 m0, s59, 0xffffff80
	s_barrier
	ds_read_b128 v[170:173], v148 offset:49152
	ds_read_b128 v[174:177], v148 offset:50176
	ds_read_b128 v[178:181], v148 offset:51200
	ds_read_b128 v[188:191], v148 offset:52224
	ds_read_b128 v[194:197], v148 offset:53248
	ds_read_b128 v[198:201], v148 offset:54272
	ds_read_b128 v[202:205], v148 offset:55296
	global_load_lds_dwordx4 v128, s[44:45] offset:128
	s_add_i32 m0, s60, 0xffffff80
	ds_read_b128 v[206:209], v148 offset:56320
	global_load_lds_dwordx4 v132, s[44:45] offset:128
	s_barrier
	s_waitcnt lgkmcnt(0)
	s_setprio 1
	v_mfma_f32_16x16x32_bf16 v[60:63], v[150:153], v[170:173], v[60:63]
	v_mfma_f32_16x16x32_bf16 v[56:59], v[162:165], v[170:173], v[56:59]
	v_mfma_f32_16x16x32_bf16 v[44:47], v[150:153], v[178:181], v[44:47]
	v_mfma_f32_16x16x32_bf16 v[40:43], v[162:165], v[178:181], v[40:43]
	v_mfma_f32_16x16x32_bf16 v[28:31], v[150:153], v[194:197], v[28:31]
	v_mfma_f32_16x16x32_bf16 v[24:27], v[162:165], v[194:197], v[24:27]
	v_mfma_f32_16x16x32_bf16 v[12:15], v[150:153], v[202:205], v[12:15]
	v_mfma_f32_16x16x32_bf16 v[8:11], v[162:165], v[202:205], v[8:11]
	v_mfma_f32_16x16x32_bf16 v[60:63], v[154:157], v[174:177], v[60:63]
	v_mfma_f32_16x16x32_bf16 v[56:59], v[166:169], v[174:177], v[56:59]
	v_mfma_f32_16x16x32_bf16 v[44:47], v[154:157], v[188:191], v[44:47]
	v_mfma_f32_16x16x32_bf16 v[40:43], v[166:169], v[188:191], v[40:43]
	v_mfma_f32_16x16x32_bf16 v[28:31], v[154:157], v[198:201], v[28:31]
	v_mfma_f32_16x16x32_bf16 v[24:27], v[166:169], v[198:201], v[24:27]
	v_mfma_f32_16x16x32_bf16 v[12:15], v[154:157], v[206:209], v[12:15]
	v_mfma_f32_16x16x32_bf16 v[8:11], v[166:169], v[206:209], v[8:11]
	s_setprio 0
	s_barrier
	s_add_i32 s4, s5, s52
	s_mov_b32 m0, s4
	s_add_u32 s0, s42, 0x80080
	s_addc_u32 s1, s43, 0
	global_load_lds_dwordx4 v130, s[0:1]
	s_add_i32 m0, s4, 0x2000
	s_nop 0
	global_load_lds_dwordx4 v134, s[0:1]
	s_add_i32 s69, s69, 2
	s_add_u32 s40, s40, 0x100
	s_addc_u32 s41, s41, 0
	s_add_u32 s67, s67, 0x100
	s_addc_u32 s68, s68, 0
	s_cmp_gt_u32 s69, 29
	s_waitcnt vmcnt(6)
	s_barrier
	s_setprio 1
	v_mfma_f32_16x16x32_bf16 v[52:55], v[210:213], v[170:173], v[52:55]
	v_mfma_f32_16x16x32_bf16 v[48:51], v[218:221], v[170:173], v[48:51]
	v_mfma_f32_16x16x32_bf16 v[36:39], v[210:213], v[178:181], v[36:39]
	v_mfma_f32_16x16x32_bf16 v[32:35], v[218:221], v[178:181], v[32:35]
	v_mfma_f32_16x16x32_bf16 v[20:23], v[210:213], v[194:197], v[20:23]
	v_mfma_f32_16x16x32_bf16 v[16:19], v[218:221], v[194:197], v[16:19]
	v_mfma_f32_16x16x32_bf16 v[4:7], v[210:213], v[202:205], v[4:7]
	v_mfma_f32_16x16x32_bf16 v[0:3], v[218:221], v[202:205], v[0:3]
	v_mfma_f32_16x16x32_bf16 v[52:55], v[214:217], v[174:177], v[52:55]
	v_mfma_f32_16x16x32_bf16 v[48:51], v[222:225], v[174:177], v[48:51]
	v_mfma_f32_16x16x32_bf16 v[36:39], v[214:217], v[188:191], v[36:39]
	v_mfma_f32_16x16x32_bf16 v[32:35], v[222:225], v[188:191], v[32:35]
	v_mfma_f32_16x16x32_bf16 v[20:23], v[214:217], v[198:201], v[20:23]
	v_mfma_f32_16x16x32_bf16 v[16:19], v[222:225], v[198:201], v[16:19]
	v_mfma_f32_16x16x32_bf16 v[4:7], v[214:217], v[206:209], v[4:7]
	v_mfma_f32_16x16x32_bf16 v[0:3], v[222:225], v[206:209], v[0:3]
	s_setprio 0
	s_cbranch_scc0 .Lrot_219
	s_barrier

;     DI size_t aoff(const Unit& u, size_t tstep) const { return (size_t)u.pm * tstep; }
;     DI size_t boff(const Unit& u, size_t tstep) const { return (size_t)u.pn * tstep; }
;     DI bool next(int i, Unit& u) const { const long L = (long)i * G + c; if (L >= np) return false; u.pm = pmv; u.pn = (int)(L % nN); u.ks = (int)(L / nN); return true; }
;     DI size_t aoff(const Unit& u, size_t) const { return (size_t)u.ks * kbytes; }
;     DI size_t boff(const Unit& u, size_t tstep) const { return (size_t)u.pn * tstep + (size_t)u.ks * kbytes; }
;     DI bool next(int i, Unit& u) const { Unit t; if (!S.next(i / 3, t)) return false; u.pm = t.pm; u.pn = t.pn; u.ks = i % 3; return true; }
;     DI size_t aoff(const Unit& u, size_t tstep) const { return (u.ks < 2 ? offU : offOA) + (size_t)u.pm * tstep; }
; #define PG8_WAIT_V(n) asm volatile("s_waitcnt vmcnt(" #n ")" ::: "memory")
; template <class Epi, class Sched>
; DI void gemm_phase(LAS unsigned char* lds, const Gemm g, const Sched& S, const Epi& E) {
;     ...
;         const bool has_next = S.next(ui + 1, nxt);
;         const char* nA = has_next ? (const char*)g.A + S.aoff(nxt, tstep) : cA; const char* nB = has_next ? (const char*)g.Bt + S.boff(nxt, tstep) : cB;
;         for (int t = 0; t < nt; t += 2) {
;             if constexpr (Epi::HAS_MID) { if (t == E.mid_t(nt)) { int fr3 = fr, fq3 = fq; asm volatile("" : "+v"(fr3), "+v"(fq3)); E.mid(acc, cur, wr, wc, fr3, fq3); } }
;             const bool last = (t == nt - 2);
;             const char* a1 = cA + (size_t)(t + 1) * kstep;
;             const char* a2 = last ? nA : cA + (size_t)(t + 2) * kstep; const char* b2 = last ? nB : cB + (size_t)(t + 2) * kstep;
;             const char* a3 = a2 + kstep; const char* b3 = b2 + kstep;
;             PG8_LDB(B0, 0, 0); PG8_SCHED; PG8_LDA(At, 0, 0); PG8_STAGE(PG8_SA(1, 1), a1 + hstep, voffA);
;             PG8_WAIT_L(8); PG8_BAR; PG8_WAIT_L(0); PG8_MMA(0, 0, At, B0); PG8_BAR; PG8_SCHED;
;             PG8_LDB(B1, 0, 1); PG8_STAGE(PG8_SB(0, 0), b2, voffB);
;             PG8_BAR; PG8_WAIT_L(0); PG8_MMA(0, 1, At, B1); PG8_BAR;
;             PG8_LDA(At, 0, 1); PG8_STAGE(PG8_SA(0, 0), a2, voffA);
;             PG8_BAR; PG8_WAIT_L(0); PG8_MMA(1, 0, At, B0); PG8_BAR; PG8_SCHED;
;             PG8_STAGE(PG8_SB(0, 1), b2 + hstep, voffB);
;             PG8_WAIT_V(6); PG8_BAR; PG8_MMA(1, 1, At, B1); PG8_BAR;
.LBB0_296:
	s_add_u32 s40, s40, 0x160080
	s_addc_u32 s41, s41, 0
	s_add_u32 s35, s42, 0x100
	v_mov_b32_e32 v0, 0
	s_addc_u32 s68, s43, 0
	s_mov_b32 s69, -2
	s_waitcnt lgkmcnt(0)
	ds_read_b128 v[144:147], v158
	ds_read_b128 v[164:167], v158 offset:1024
	ds_read_b128 v[168:171], v158 offset:2048
	ds_read_b128 v[172:175], v158 offset:3072
	s_add_u32 s0, s40, 0xffea0080
	s_addc_u32 s1, s41, -1
	s_cmpk_eq_i32 s69, 0x54
	s_cselect_b32 s45, s9, s1
	s_cselect_b32 s44, s8, s0
	s_cselect_b32 s43, s11, s68
	s_cselect_b32 s42, s10, s35
	s_add_i32 m0, s54, 0xc000
	ds_read_b128 v[176:179], v159
	ds_read_b128 v[180:183], v159 offset:1024
	ds_read_b128 v[188:191], v159 offset:2048
	ds_read_b128 v[194:197], v159 offset:3072
	ds_read_b128 v[198:201], v159 offset:4096
	ds_read_b128 v[202:205], v159 offset:5120
	ds_read_b128 v[206:209], v159 offset:6144
	global_load_lds_dwordx4 v136, s[40:41]
	s_add_i32 m0, s54, 0xe000
	ds_read_b128 v[210:213], v159 offset:7168
	global_load_lds_dwordx4 v138, s[40:41]
	s_waitcnt lgkmcnt(8)
	s_barrier
	s_waitcnt lgkmcnt(0)
	s_setprio 1
	v_mfma_f32_16x16x32_bf16 v[124:127], v[144:147], v[176:179], 0
	v_mfma_f32_16x16x32_bf16 v[120:123], v[168:171], v[176:179], 0
	v_mfma_f32_16x16x32_bf16 v[108:111], v[144:147], v[188:191], 0
	v_mfma_f32_16x16x32_bf16 v[104:107], v[168:171], v[188:191], 0
	v_mfma_f32_16x16x32_bf16 v[92:95], v[144:147], v[198:201], 0
	v_mfma_f32_16x16x32_bf16 v[88:91], v[168:171], v[198:201], 0
	v_mfma_f32_16x16x32_bf16 v[76:79], v[144:147], v[206:209], 0
	v_mfma_f32_16x16x32_bf16 v[72:75], v[168:171], v[206:209], 0
	v_mfma_f32_16x16x32_bf16 v[124:127], v[164:167], v[180:183], v[124:127]
	v_mfma_f32_16x16x32_bf16 v[120:123], v[172:175], v[180:183], v[120:123]
	v_mfma_f32_16x16x32_bf16 v[108:111], v[164:167], v[194:197], v[108:111]
	v_mfma_f32_16x16x32_bf16 v[104:107], v[172:175], v[194:197], v[104:107]
	v_mfma_f32_16x16x32_bf16 v[92:95], v[164:167], v[202:205], v[92:95]
	v_mfma_f32_16x16x32_bf16 v[88:91], v[172:175], v[202:205], v[88:91]
	v_mfma_f32_16x16x32_bf16 v[76:79], v[164:167], v[210:213], v[76:79]
	v_mfma_f32_16x16x32_bf16 v[72:75], v[172:175], v[210:213], v[72:75]
	s_setprio 0
	s_barrier
	s_add_i32 s0, s63, s53
	s_mov_b32 m0, s0
	ds_read_b128 v[214:217], v161
	ds_read_b128 v[218:221], v161 offset:1024
	ds_read_b128 v[222:225], v161 offset:2048
	global_load_lds_dwordx4 v130, s[42:43]
	s_add_i32 m0, s0, 0x2000
	ds_read_b128 v[226:229], v161 offset:3072
	global_load_lds_dwordx4 v134, s[42:43]
	s_barrier
	s_waitcnt lgkmcnt(0)
	s_setprio 1
	v_mfma_f32_16x16x32_bf16 v[116:119], v[214:217], v[176:179], 0
	v_mfma_f32_16x16x32_bf16 v[112:115], v[222:225], v[176:179], 0
	v_mfma_f32_16x16x32_bf16 v[100:103], v[214:217], v[188:191], 0
	v_mfma_f32_16x16x32_bf16 v[96:99], v[222:225], v[188:191], 0
	v_mfma_f32_16x16x32_bf16 v[84:87], v[214:217], v[198:201], 0
	v_mfma_f32_16x16x32_bf16 v[80:83], v[222:225], v[198:201], 0
	v_mfma_f32_16x16x32_bf16 v[68:71], v[214:217], v[206:209], 0
	v_mfma_f32_16x16x32_bf16 v[64:67], v[222:225], v[206:209], 0
	v_mfma_f32_16x16x32_bf16 v[116:119], v[218:221], v[180:183], v[116:119]
	v_mfma_f32_16x16x32_bf16 v[112:115], v[226:229], v[180:183], v[112:115]
	v_mfma_f32_16x16x32_bf16 v[100:103], v[218:221], v[194:197], v[100:103]
	v_mfma_f32_16x16x32_bf16 v[96:99], v[226:229], v[194:197], v[96:99]
	v_mfma_f32_16x16x32_bf16 v[84:87], v[218:221], v[202:205], v[84:87]
	v_mfma_f32_16x16x32_bf16 v[80:83], v[226:229], v[202:205], v[80:83]
	v_mfma_f32_16x16x32_bf16 v[68:71], v[218:221], v[210:213], v[68:71]
	v_mfma_f32_16x16x32_bf16 v[64:67], v[226:229], v[210:213], v[64:67]
	s_setprio 0
	s_mov_b32 m0, s54
	s_barrier
	ds_read_b128 v[176:179], v159 offset:16384
	ds_read_b128 v[180:183], v159 offset:17408
	ds_read_b128 v[188:191], v159 offset:18432
	ds_read_b128 v[194:197], v159 offset:19456
	ds_read_b128 v[198:201], v159 offset:20480
	ds_read_b128 v[202:205], v159 offset:21504
	ds_read_b128 v[206:209], v159 offset:22528
	global_load_lds_dwordx4 v128, s[44:45]
	s_mov_b32 m0, s55
	ds_read_b128 v[210:213], v159 offset:23552
	global_load_lds_dwordx4 v132, s[44:45]
	s_barrier
	s_waitcnt lgkmcnt(0)
	s_setprio 1
	v_mfma_f32_16x16x32_bf16 v[60:63], v[144:147], v[176:179], 0
	v_mfma_f32_16x16x32_bf16 v[56:59], v[168:171], v[176:179], 0
	v_mfma_f32_16x16x32_bf16 v[44:47], v[144:147], v[188:191], 0
	v_mfma_f32_16x16x32_bf16 v[40:43], v[168:171], v[188:191], 0
	v_mfma_f32_16x16x32_bf16 v[28:31], v[144:147], v[198:201], 0
	v_mfma_f32_16x16x32_bf16 v[24:27], v[168:171], v[198:201], 0
	v_mfma_f32_16x16x32_bf16 v[12:15], v[144:147], v[206:209], 0
	v_mfma_f32_16x16x32_bf16 v[8:11], v[168:171], v[206:209], 0
	v_mfma_f32_16x16x32_bf16 v[60:63], v[164:167], v[180:183], v[60:63]
	v_mfma_f32_16x16x32_bf16 v[56:59], v[172:175], v[180:183], v[56:59]
	v_mfma_f32_16x16x32_bf16 v[44:47], v[164:167], v[194:197], v[44:47]
	v_mfma_f32_16x16x32_bf16 v[40:43], v[172:175], v[194:197], v[40:43]
	v_mfma_f32_16x16x32_bf16 v[28:31], v[164:167], v[202:205], v[28:31]
	v_mfma_f32_16x16x32_bf16 v[24:27], v[172:175], v[202:205], v[24:27]
	v_mfma_f32_16x16x32_bf16 v[12:15], v[164:167], v[210:213], v[12:15]
	v_mfma_f32_16x16x32_bf16 v[8:11], v[172:175], v[210:213], v[8:11]
	s_setprio 0
	s_barrier
	s_add_i32 s4, s64, s53
	s_mov_b32 m0, s4
	s_add_u32 s0, s42, 0x160000
	s_addc_u32 s1, s43, 0
	global_load_lds_dwordx4 v130, s[0:1]
	s_add_i32 m0, s4, 0x2000
	s_nop 0
	global_load_lds_dwordx4 v134, s[0:1]
	s_waitcnt vmcnt(6)
	s_barrier
; #define PG8_STAGE(bufoff, gbase, voff) do { _Pragma("unroll") for (int _i = 0; _i < 2; ++_i) \
;         __builtin_amdgcn_global_load_lds((const unsigned*)((const char*)(gbase) + (voff)[_i]), (LAS unsigned*)(lds + (bufoff) + ldsw + _i * 8192), 16, 0, 0); } while (0)
; #define PG8_LDA(dst, b, h) do { _Pragma("unroll") for (int m = 0; m < 4; ++m) _Pragma("unroll") for (int k = 0; k < 2; ++k) dst[m][k] = *(const LAS bf16x8*)(lds + PG8_SA(b, h) + aoff + m * 2048 + k * 1024); } while (0)
; #define PG8_LDB(dst, b, h) do { _Pragma("unroll") for (int n = 0; n < 2; ++n) _Pragma("unroll") for (int k = 0; k < 2; ++k) dst[n][k] = *(const LAS bf16x8*)(lds + PG8_SB(b, h) + boff + n * 2048 + k * 1024); } while (0)
; #define PG8_MMA(ai, bj, At, Bt) do { __builtin_amdgcn_s_setprio(1); _Pragma("unroll") for (int m = 0; m < 4; ++m) _Pragma("unroll") for (int n = 0; n < 2; ++n) _Pragma("unroll") for (int k = 0; k < 2; ++k) \
;         acc[ai][bj][m][n] = __builtin_amdgcn_mfma_f32_16x16x32_bf16(Bt[n][k], At[m][k], acc[ai][bj][m][n], 0, 0, 0); __builtin_amdgcn_s_setprio(0); } while (0)
; #define PG8_WAIT_V(n) asm volatile("s_waitcnt vmcnt(" #n ")" ::: "memory")
; #define PG8_WAIT_L(n) asm volatile("s_waitcnt lgkmcnt(" #n ")" ::: "memory")
; #define PG8_BAR __builtin_amdgcn_s_barrier()
; #define PG8_SCHED __builtin_amdgcn_sched_barrier(0)
; template <class Epi, class Sched>
; DI void gemm_phase(LAS unsigned char* lds, const Gemm g, const Sched& S, const Epi& E) {
;     ...
;             PG8_WAIT_V(6); PG8_BAR; PG8_MMA(1, 1, At, B1); PG8_BAR;
;             PG8_LDB(B0, 1, 0); PG8_SCHED; PG8_LDA(At, 1, 0); PG8_STAGE(PG8_SA(0, 1), a2 + hstep, voffA);
;             PG8_WAIT_L(8); PG8_BAR; PG8_WAIT_L(0); PG8_MMA(0, 0, At, B0); PG8_BAR; PG8_SCHED;
;             PG8_LDB(B1, 1, 1); PG8_STAGE(PG8_SB(1, 0), b3, voffB);
	s_setprio 1
	v_mfma_f32_16x16x32_bf16 v[52:55], v[214:217], v[176:179], 0
	v_mfma_f32_16x16x32_bf16 v[48:51], v[222:225], v[176:179], 0
	v_mfma_f32_16x16x32_bf16 v[36:39], v[214:217], v[188:191], 0
	v_mfma_f32_16x16x32_bf16 v[32:35], v[222:225], v[188:191], 0
	v_mfma_f32_16x16x32_bf16 v[20:23], v[214:217], v[198:201], 0
	v_mfma_f32_16x16x32_bf16 v[16:19], v[222:225], v[198:201], 0
	v_mfma_f32_16x16x32_bf16 v[4:7], v[214:217], v[206:209], 0
	v_mfma_f32_16x16x32_bf16 v[0:3], v[222:225], v[206:209], 0
	v_mfma_f32_16x16x32_bf16 v[52:55], v[218:221], v[180:183], v[52:55]
	v_mfma_f32_16x16x32_bf16 v[48:51], v[226:229], v[180:183], v[48:51]
	v_mfma_f32_16x16x32_bf16 v[36:39], v[218:221], v[194:197], v[36:39]
	v_mfma_f32_16x16x32_bf16 v[32:35], v[226:229], v[194:197], v[32:35]
	v_mfma_f32_16x16x32_bf16 v[20:23], v[218:221], v[202:205], v[20:23]
	v_mfma_f32_16x16x32_bf16 v[16:19], v[226:229], v[202:205], v[16:19]
	v_mfma_f32_16x16x32_bf16 v[4:7], v[218:221], v[210:213], v[4:7]
	v_mfma_f32_16x16x32_bf16 v[0:3], v[226:229], v[210:213], v[0:3]
	s_setprio 0
	s_add_i32 s4, 0, 0x18000
	v_add_u32_e32 v230, s4, v157
	s_barrier
	ds_read_b128 v[144:147], v230
	ds_read_b128 v[164:167], v230 offset:1024
	ds_read_b128 v[168:171], v230 offset:2048
	ds_read_b128 v[172:175], v230 offset:3072
	s_add_u32 s0, s44, 0x160000
	s_addc_u32 s1, s45, 0
	s_mov_b32 m0, s56
	ds_read_b128 v[176:179], v159 offset:32768
	ds_read_b128 v[180:183], v159 offset:33792
	ds_read_b128 v[188:191], v159 offset:34816
	ds_read_b128 v[194:197], v159 offset:35840
	ds_read_b128 v[198:201], v159 offset:36864
	ds_read_b128 v[202:205], v159 offset:37888
	ds_read_b128 v[206:209], v159 offset:38912
	global_load_lds_dwordx4 v128, s[0:1]
	s_mov_b32 m0, s57
	ds_read_b128 v[210:213], v159 offset:39936
	global_load_lds_dwordx4 v132, s[0:1]
	s_waitcnt lgkmcnt(8)
	s_barrier
	s_waitcnt lgkmcnt(0)
	s_setprio 1
	v_mfma_f32_16x16x32_bf16 v[124:127], v[144:147], v[176:179], v[124:127]
	v_mfma_f32_16x16x32_bf16 v[120:123], v[168:171], v[176:179], v[120:123]
	v_mfma_f32_16x16x32_bf16 v[108:111], v[144:147], v[188:191], v[108:111]
	v_mfma_f32_16x16x32_bf16 v[104:107], v[168:171], v[188:191], v[104:107]
	v_mfma_f32_16x16x32_bf16 v[92:95], v[144:147], v[198:201], v[92:95]
	v_mfma_f32_16x16x32_bf16 v[88:91], v[168:171], v[198:201], v[88:91]
	v_mfma_f32_16x16x32_bf16 v[76:79], v[144:147], v[206:209], v[76:79]
	v_mfma_f32_16x16x32_bf16 v[72:75], v[168:171], v[206:209], v[72:75]
	v_mfma_f32_16x16x32_bf16 v[124:127], v[164:167], v[180:183], v[124:127]
	v_mfma_f32_16x16x32_bf16 v[120:123], v[172:175], v[180:183], v[120:123]
	v_mfma_f32_16x16x32_bf16 v[108:111], v[164:167], v[194:197], v[108:111]
	v_mfma_f32_16x16x32_bf16 v[104:107], v[172:175], v[194:197], v[104:107]
	v_mfma_f32_16x16x32_bf16 v[92:95], v[164:167], v[202:205], v[92:95]
	v_mfma_f32_16x16x32_bf16 v[88:91], v[172:175], v[202:205], v[88:91]
	v_mfma_f32_16x16x32_bf16 v[76:79], v[164:167], v[210:213], v[76:79]
	v_mfma_f32_16x16x32_bf16 v[72:75], v[172:175], v[210:213], v[72:75]
	s_setprio 0
	s_barrier
	s_add_i32 s5, 0, 0x1c000
	s_add_i32 s0, s4, s53
	v_add_u32_e32 v231, s5, v157
	s_add_i32 m0, s0, 0xffffff80
	ds_read_b128 v[214:217], v231
	ds_read_b128 v[218:221], v231 offset:1024
	ds_read_b128 v[222:225], v231 offset:2048
	global_load_lds_dwordx4 v130, s[42:43] offset:128
	s_add_i32 m0, s0, 0x1f80
	ds_read_b128 v[226:229], v231 offset:3072
	global_load_lds_dwordx4 v134, s[42:43] offset:128
	s_barrier
; #define PG8_STAGE(bufoff, gbase, voff) do { _Pragma("unroll") for (int _i = 0; _i < 2; ++_i) \
;         __builtin_amdgcn_global_load_lds((const unsigned*)((const char*)(gbase) + (voff)[_i]), (LAS unsigned*)(lds + (bufoff) + ldsw + _i * 8192), 16, 0, 0); } while (0)
; #define PG8_LDA(dst, b, h) do { _Pragma("unroll") for (int m = 0; m < 4; ++m) _Pragma("unroll") for (int k = 0; k < 2; ++k) dst[m][k] = *(const LAS bf16x8*)(lds + PG8_SA(b, h) + aoff + m * 2048 + k * 1024); } while (0)
; #define PG8_MMA(ai, bj, At, Bt) do { __builtin_amdgcn_s_setprio(1); _Pragma("unroll") for (int m = 0; m < 4; ++m) _Pragma("unroll") for (int n = 0; n < 2; ++n) _Pragma("unroll") for (int k = 0; k < 2; ++k) \
;         acc[ai][bj][m][n] = __builtin_amdgcn_mfma_f32_16x16x32_bf16(Bt[n][k], At[m][k], acc[ai][bj][m][n], 0, 0, 0); __builtin_amdgcn_s_setprio(0); } while (0)
; #define PG8_WAIT_V(n) asm volatile("s_waitcnt vmcnt(" #n ")" ::: "memory")
; #define PG8_WAIT_L(n) asm volatile("s_waitcnt lgkmcnt(" #n ")" ::: "memory")
; #define PG8_BAR __builtin_amdgcn_s_barrier()
; #define PG8_SCHED __builtin_amdgcn_sched_barrier(0)
; template <class Epi, class Sched>
; DI void gemm_phase(LAS unsigned char* lds, const Gemm g, const Sched& S, const Epi& E) {
;     ...
;             PG8_BAR; PG8_WAIT_L(0); PG8_MMA(0, 1, At, B1); PG8_BAR;
;             PG8_LDA(At, 1, 1); PG8_STAGE(PG8_SA(1, 0), a3, voffA);
;             PG8_BAR; PG8_WAIT_L(0); PG8_MMA(1, 0, At, B0); PG8_BAR; PG8_SCHED;
;             PG8_STAGE(PG8_SB(1, 1), b3 + hstep, voffB);
;             PG8_WAIT_V(6); PG8_BAR; PG8_MMA(1, 1, At, B1); PG8_BAR;
	s_waitcnt lgkmcnt(0)
	s_setprio 1
	v_mfma_f32_16x16x32_bf16 v[116:119], v[214:217], v[176:179], v[116:119]
	v_mfma_f32_16x16x32_bf16 v[112:115], v[222:225], v[176:179], v[112:115]
	v_mfma_f32_16x16x32_bf16 v[100:103], v[214:217], v[188:191], v[100:103]
	v_mfma_f32_16x16x32_bf16 v[96:99], v[222:225], v[188:191], v[96:99]
	v_mfma_f32_16x16x32_bf16 v[84:87], v[214:217], v[198:201], v[84:87]
	v_mfma_f32_16x16x32_bf16 v[80:83], v[222:225], v[198:201], v[80:83]
	v_mfma_f32_16x16x32_bf16 v[68:71], v[214:217], v[206:209], v[68:71]
	v_mfma_f32_16x16x32_bf16 v[64:67], v[222:225], v[206:209], v[64:67]
	v_mfma_f32_16x16x32_bf16 v[116:119], v[218:221], v[180:183], v[116:119]
	v_mfma_f32_16x16x32_bf16 v[112:115], v[226:229], v[180:183], v[112:115]
	v_mfma_f32_16x16x32_bf16 v[100:103], v[218:221], v[194:197], v[100:103]
	v_mfma_f32_16x16x32_bf16 v[96:99], v[226:229], v[194:197], v[96:99]
	v_mfma_f32_16x16x32_bf16 v[84:87], v[218:221], v[202:205], v[84:87]
	v_mfma_f32_16x16x32_bf16 v[80:83], v[226:229], v[202:205], v[80:83]
	v_mfma_f32_16x16x32_bf16 v[68:71], v[218:221], v[210:213], v[68:71]
	v_mfma_f32_16x16x32_bf16 v[64:67], v[226:229], v[210:213], v[64:67]
	s_setprio 0
	s_add_i32 m0, s61, 0xffffff80
	s_barrier
	ds_read_b128 v[176:179], v159 offset:49152
	ds_read_b128 v[180:183], v159 offset:50176
	ds_read_b128 v[188:191], v159 offset:51200
	ds_read_b128 v[194:197], v159 offset:52224
	ds_read_b128 v[198:201], v159 offset:53248
	ds_read_b128 v[202:205], v159 offset:54272
	ds_read_b128 v[206:209], v159 offset:55296
	global_load_lds_dwordx4 v128, s[44:45] offset:128
	s_add_i32 m0, s62, 0xffffff80
	ds_read_b128 v[210:213], v159 offset:56320
	global_load_lds_dwordx4 v132, s[44:45] offset:128
	s_barrier
	s_waitcnt lgkmcnt(0)
	s_setprio 1
	v_mfma_f32_16x16x32_bf16 v[60:63], v[144:147], v[176:179], v[60:63]
	v_mfma_f32_16x16x32_bf16 v[56:59], v[168:171], v[176:179], v[56:59]
	v_mfma_f32_16x16x32_bf16 v[44:47], v[144:147], v[188:191], v[44:47]
	v_mfma_f32_16x16x32_bf16 v[40:43], v[168:171], v[188:191], v[40:43]
	v_mfma_f32_16x16x32_bf16 v[28:31], v[144:147], v[198:201], v[28:31]
	v_mfma_f32_16x16x32_bf16 v[24:27], v[168:171], v[198:201], v[24:27]
	v_mfma_f32_16x16x32_bf16 v[12:15], v[144:147], v[206:209], v[12:15]
	v_mfma_f32_16x16x32_bf16 v[8:11], v[168:171], v[206:209], v[8:11]
	v_mfma_f32_16x16x32_bf16 v[60:63], v[164:167], v[180:183], v[60:63]
	v_mfma_f32_16x16x32_bf16 v[56:59], v[172:175], v[180:183], v[56:59]
	v_mfma_f32_16x16x32_bf16 v[44:47], v[164:167], v[194:197], v[44:47]
	v_mfma_f32_16x16x32_bf16 v[40:43], v[172:175], v[194:197], v[40:43]
	v_mfma_f32_16x16x32_bf16 v[28:31], v[164:167], v[202:205], v[28:31]
	v_mfma_f32_16x16x32_bf16 v[24:27], v[172:175], v[202:205], v[24:27]
	v_mfma_f32_16x16x32_bf16 v[12:15], v[164:167], v[210:213], v[12:15]
	v_mfma_f32_16x16x32_bf16 v[8:11], v[172:175], v[210:213], v[8:11]
	s_setprio 0
	s_barrier
	s_add_i32 s4, s5, s53
	s_mov_b32 m0, s4
	s_add_u32 s0, s42, 0x160080
	s_addc_u32 s1, s43, 0
	global_load_lds_dwordx4 v130, s[0:1]
	s_add_i32 m0, s4, 0x2000
	s_nop 0
	global_load_lds_dwordx4 v134, s[0:1]
	s_waitcnt vmcnt(6)
	s_barrier
	s_setprio 1
	v_mfma_f32_16x16x32_bf16 v[52:55], v[214:217], v[176:179], v[52:55]
	v_mfma_f32_16x16x32_bf16 v[48:51], v[222:225], v[176:179], v[48:51]
	v_mfma_f32_16x16x32_bf16 v[36:39], v[214:217], v[188:191], v[36:39]
	v_mfma_f32_16x16x32_bf16 v[32:35], v[222:225], v[188:191], v[32:35]
	v_mfma_f32_16x16x32_bf16 v[20:23], v[214:217], v[198:201], v[20:23]
	v_mfma_f32_16x16x32_bf16 v[16:19], v[222:225], v[198:201], v[16:19]
	v_mfma_f32_16x16x32_bf16 v[4:7], v[214:217], v[206:209], v[4:7]
	v_mfma_f32_16x16x32_bf16 v[0:3], v[222:225], v[206:209], v[0:3]
	v_mfma_f32_16x16x32_bf16 v[52:55], v[218:221], v[180:183], v[52:55]
	v_mfma_f32_16x16x32_bf16 v[48:51], v[226:229], v[180:183], v[48:51]
	v_mfma_f32_16x16x32_bf16 v[36:39], v[218:221], v[194:197], v[36:39]
	v_mfma_f32_16x16x32_bf16 v[32:35], v[226:229], v[194:197], v[32:35]
	v_mfma_f32_16x16x32_bf16 v[20:23], v[218:221], v[202:205], v[20:23]
	v_mfma_f32_16x16x32_bf16 v[16:19], v[226:229], v[202:205], v[16:19]
	v_mfma_f32_16x16x32_bf16 v[4:7], v[218:221], v[210:213], v[4:7]
	v_mfma_f32_16x16x32_bf16 v[0:3], v[226:229], v[210:213], v[0:3]
	s_setprio 0
	s_add_i32 s69, s69, 2
	s_add_u32 s40, s40, 0x100
	s_addc_u32 s41, s41, 0
	s_add_u32 s35, s35, 0x100
	s_addc_u32 s68, s68, 0
	s_cmpk_gt_u32 s69, 0x55
	s_cbranch_scc0 .Lrot_297
	s_barrier
	s_branch .Lpeel_done_297

; #define PG8_STAGE(bufoff, gbase, voff) do { _Pragma("unroll") for (int _i = 0; _i < 2; ++_i) \
;         __builtin_amdgcn_global_load_lds((const unsigned*)((const char*)(gbase) + (voff)[_i]), (LAS unsigned*)(lds + (bufoff) + ldsw + _i * 8192), 16, 0, 0); } while (0)
; #define PG8_LDA(dst, b, h) do { _Pragma("unroll") for (int m = 0; m < 4; ++m) _Pragma("unroll") for (int k = 0; k < 2; ++k) dst[m][k] = *(const LAS bf16x8*)(lds + PG8_SA(b, h) + aoff + m * 2048 + k * 1024); } while (0)
; #define PG8_LDB(dst, b, h) do { _Pragma("unroll") for (int n = 0; n < 2; ++n) _Pragma("unroll") for (int k = 0; k < 2; ++k) dst[n][k] = *(const LAS bf16x8*)(lds + PG8_SB(b, h) + boff + n * 2048 + k * 1024); } while (0)
; #define PG8_MMA(ai, bj, At, Bt) do { __builtin_amdgcn_s_setprio(1); _Pragma("unroll") for (int m = 0; m < 4; ++m) _Pragma("unroll") for (int n = 0; n < 2; ++n) _Pragma("unroll") for (int k = 0; k < 2; ++k) \
;         acc[ai][bj][m][n] = __builtin_amdgcn_mfma_f32_16x16x32_bf16(Bt[n][k], At[m][k], acc[ai][bj][m][n], 0, 0, 0); __builtin_amdgcn_s_setprio(0); } while (0)
; #define PG8_WAIT_V(n) asm volatile("s_waitcnt vmcnt(" #n ")" ::: "memory")
; #define PG8_WAIT_L(n) asm volatile("s_waitcnt lgkmcnt(" #n ")" ::: "memory")
; #define PG8_BAR __builtin_amdgcn_s_barrier()
; #define PG8_SCHED __builtin_amdgcn_sched_barrier(0)
; template <class Epi, class Sched>
; DI void gemm_phase(LAS unsigned char* lds, const Gemm g, const Sched& S, const Epi& E) {
;     ...
;             PG8_LDB(B0, 0, 0); PG8_SCHED; PG8_LDA(At, 0, 0); PG8_STAGE(PG8_SA(1, 1), a1 + hstep, voffA);
;             PG8_WAIT_L(8); PG8_BAR; PG8_WAIT_L(0); PG8_MMA(0, 0, At, B0); PG8_BAR; PG8_SCHED;
;             PG8_LDB(B1, 0, 1); PG8_STAGE(PG8_SB(0, 0), b2, voffB);
;             PG8_BAR; PG8_WAIT_L(0); PG8_MMA(0, 1, At, B1); PG8_BAR;
;             PG8_LDA(At, 0, 1); PG8_STAGE(PG8_SA(0, 0), a2, voffA);
;             PG8_BAR; PG8_WAIT_L(0); PG8_MMA(1, 0, At, B0); PG8_BAR; PG8_SCHED;
;             PG8_STAGE(PG8_SB(0, 1), b2 + hstep, voffB);
;             PG8_WAIT_V(6); PG8_BAR; PG8_MMA(1, 1, At, B1); PG8_BAR;
.LBB0_297:
	ds_read_b128 v[144:147], v158
	ds_read_b128 v[164:167], v158 offset:1024
	ds_read_b128 v[168:171], v158 offset:2048
	ds_read_b128 v[172:175], v158 offset:3072
	s_add_u32 s0, s40, 0xffea0080
	s_addc_u32 s1, s41, -1
	s_cmpk_eq_i32 s69, 0x54
	s_cselect_b32 s45, s9, s1
	s_cselect_b32 s44, s8, s0
	s_cselect_b32 s43, s11, s68
	s_cselect_b32 s42, s10, s35
	s_add_i32 m0, s54, 0xc000
	ds_read_b128 v[176:179], v159
	ds_read_b128 v[180:183], v159 offset:1024
	ds_read_b128 v[188:191], v159 offset:2048
	ds_read_b128 v[194:197], v159 offset:3072
	ds_read_b128 v[198:201], v159 offset:4096
	ds_read_b128 v[202:205], v159 offset:5120
	ds_read_b128 v[206:209], v159 offset:6144
	global_load_lds_dwordx4 v136, s[40:41]
	s_add_i32 m0, s54, 0xe000
	ds_read_b128 v[210:213], v159 offset:7168
	global_load_lds_dwordx4 v138, s[40:41]
	s_waitcnt lgkmcnt(8)
	s_barrier
	s_waitcnt lgkmcnt(0)
	s_setprio 1
	v_mfma_f32_16x16x32_bf16 v[124:127], v[144:147], v[176:179], v[124:127]
	v_mfma_f32_16x16x32_bf16 v[120:123], v[168:171], v[176:179], v[120:123]
	v_mfma_f32_16x16x32_bf16 v[108:111], v[144:147], v[188:191], v[108:111]
	v_mfma_f32_16x16x32_bf16 v[104:107], v[168:171], v[188:191], v[104:107]
	v_mfma_f32_16x16x32_bf16 v[92:95], v[144:147], v[198:201], v[92:95]
	v_mfma_f32_16x16x32_bf16 v[88:91], v[168:171], v[198:201], v[88:91]
	v_mfma_f32_16x16x32_bf16 v[76:79], v[144:147], v[206:209], v[76:79]
	v_mfma_f32_16x16x32_bf16 v[72:75], v[168:171], v[206:209], v[72:75]
	v_mfma_f32_16x16x32_bf16 v[124:127], v[164:167], v[180:183], v[124:127]
	v_mfma_f32_16x16x32_bf16 v[120:123], v[172:175], v[180:183], v[120:123]
	v_mfma_f32_16x16x32_bf16 v[108:111], v[164:167], v[194:197], v[108:111]
	v_mfma_f32_16x16x32_bf16 v[104:107], v[172:175], v[194:197], v[104:107]
	v_mfma_f32_16x16x32_bf16 v[92:95], v[164:167], v[202:205], v[92:95]
	v_mfma_f32_16x16x32_bf16 v[88:91], v[172:175], v[202:205], v[88:91]
	v_mfma_f32_16x16x32_bf16 v[76:79], v[164:167], v[210:213], v[76:79]
	v_mfma_f32_16x16x32_bf16 v[72:75], v[172:175], v[210:213], v[72:75]
	s_setprio 0
	s_barrier
	s_add_i32 s0, s63, s53
	s_mov_b32 m0, s0
	ds_read_b128 v[214:217], v161
	ds_read_b128 v[218:221], v161 offset:1024
	ds_read_b128 v[222:225], v161 offset:2048
	global_load_lds_dwordx4 v130, s[42:43]
	s_add_i32 m0, s0, 0x2000
	ds_read_b128 v[226:229], v161 offset:3072
	global_load_lds_dwordx4 v134, s[42:43]
	s_barrier
	s_waitcnt lgkmcnt(0)
	s_setprio 1
	v_mfma_f32_16x16x32_bf16 v[116:119], v[214:217], v[176:179], v[116:119]
	v_mfma_f32_16x16x32_bf16 v[112:115], v[222:225], v[176:179], v[112:115]
	v_mfma_f32_16x16x32_bf16 v[100:103], v[214:217], v[188:191], v[100:103]
	v_mfma_f32_16x16x32_bf16 v[96:99], v[222:225], v[188:191], v[96:99]
	v_mfma_f32_16x16x32_bf16 v[84:87], v[214:217], v[198:201], v[84:87]
	v_mfma_f32_16x16x32_bf16 v[80:83], v[222:225], v[198:201], v[80:83]
	v_mfma_f32_16x16x32_bf16 v[68:71], v[214:217], v[206:209], v[68:71]
	v_mfma_f32_16x16x32_bf16 v[64:67], v[222:225], v[206:209], v[64:67]
	v_mfma_f32_16x16x32_bf16 v[116:119], v[218:221], v[180:183], v[116:119]
	v_mfma_f32_16x16x32_bf16 v[112:115], v[226:229], v[180:183], v[112:115]
	v_mfma_f32_16x16x32_bf16 v[100:103], v[218:221], v[194:197], v[100:103]
	v_mfma_f32_16x16x32_bf16 v[96:99], v[226:229], v[194:197], v[96:99]
	v_mfma_f32_16x16x32_bf16 v[84:87], v[218:221], v[202:205], v[84:87]
	v_mfma_f32_16x16x32_bf16 v[80:83], v[226:229], v[202:205], v[80:83]
	v_mfma_f32_16x16x32_bf16 v[68:71], v[218:221], v[210:213], v[68:71]
	v_mfma_f32_16x16x32_bf16 v[64:67], v[226:229], v[210:213], v[64:67]
	s_setprio 0
	s_mov_b32 m0, s54
	s_barrier
	ds_read_b128 v[176:179], v159 offset:16384
	ds_read_b128 v[180:183], v159 offset:17408
	ds_read_b128 v[188:191], v159 offset:18432
	ds_read_b128 v[194:197], v159 offset:19456
	ds_read_b128 v[198:201], v159 offset:20480
	ds_read_b128 v[202:205], v159 offset:21504
	ds_read_b128 v[206:209], v159 offset:22528
	global_load_lds_dwordx4 v128, s[44:45]
	s_mov_b32 m0, s55
	ds_read_b128 v[210:213], v159 offset:23552
	global_load_lds_dwordx4 v132, s[44:45]
	s_barrier
	s_waitcnt lgkmcnt(0)
	s_setprio 1
	v_mfma_f32_16x16x32_bf16 v[60:63], v[144:147], v[176:179], v[60:63]
	v_mfma_f32_16x16x32_bf16 v[56:59], v[168:171], v[176:179], v[56:59]
	v_mfma_f32_16x16x32_bf16 v[44:47], v[144:147], v[188:191], v[44:47]
	v_mfma_f32_16x16x32_bf16 v[40:43], v[168:171], v[188:191], v[40:43]
	v_mfma_f32_16x16x32_bf16 v[28:31], v[144:147], v[198:201], v[28:31]
	v_mfma_f32_16x16x32_bf16 v[24:27], v[168:171], v[198:201], v[24:27]
	v_mfma_f32_16x16x32_bf16 v[12:15], v[144:147], v[206:209], v[12:15]
	v_mfma_f32_16x16x32_bf16 v[8:11], v[168:171], v[206:209], v[8:11]
	v_mfma_f32_16x16x32_bf16 v[60:63], v[164:167], v[180:183], v[60:63]
	v_mfma_f32_16x16x32_bf16 v[56:59], v[172:175], v[180:183], v[56:59]
	v_mfma_f32_16x16x32_bf16 v[44:47], v[164:167], v[194:197], v[44:47]
	v_mfma_f32_16x16x32_bf16 v[40:43], v[172:175], v[194:197], v[40:43]
	v_mfma_f32_16x16x32_bf16 v[28:31], v[164:167], v[202:205], v[28:31]
	v_mfma_f32_16x16x32_bf16 v[24:27], v[172:175], v[202:205], v[24:27]
	v_mfma_f32_16x16x32_bf16 v[12:15], v[164:167], v[210:213], v[12:15]
	v_mfma_f32_16x16x32_bf16 v[8:11], v[172:175], v[210:213], v[8:11]
	s_setprio 0
	s_barrier
	s_add_i32 s4, s64, s53
	s_mov_b32 m0, s4
	s_add_u32 s0, s42, 0x160000
	s_addc_u32 s1, s43, 0
	global_load_lds_dwordx4 v130, s[0:1]
	s_add_i32 m0, s4, 0x2000
	s_nop 0
	global_load_lds_dwordx4 v134, s[0:1]
	s_waitcnt vmcnt(6)
	s_barrier
; #define PG8_STAGE(bufoff, gbase, voff) do { _Pragma("unroll") for (int _i = 0; _i < 2; ++_i) \
;         __builtin_amdgcn_global_load_lds((const unsigned*)((const char*)(gbase) + (voff)[_i]), (LAS unsigned*)(lds + (bufoff) + ldsw + _i * 8192), 16, 0, 0); } while (0)
; #define PG8_LDA(dst, b, h) do { _Pragma("unroll") for (int m = 0; m < 4; ++m) _Pragma("unroll") for (int k = 0; k < 2; ++k) dst[m][k] = *(const LAS bf16x8*)(lds + PG8_SA(b, h) + aoff + m * 2048 + k * 1024); } while (0)
; #define PG8_LDB(dst, b, h) do { _Pragma("unroll") for (int n = 0; n < 2; ++n) _Pragma("unroll") for (int k = 0; k < 2; ++k) dst[n][k] = *(const LAS bf16x8*)(lds + PG8_SB(b, h) + boff + n * 2048 + k * 1024); } while (0)
; #define PG8_MMA(ai, bj, At, Bt) do { __builtin_amdgcn_s_setprio(1); _Pragma("unroll") for (int m = 0; m < 4; ++m) _Pragma("unroll") for (int n = 0; n < 2; ++n) _Pragma("unroll") for (int k = 0; k < 2; ++k) \
;         acc[ai][bj][m][n] = __builtin_amdgcn_mfma_f32_16x16x32_bf16(Bt[n][k], At[m][k], acc[ai][bj][m][n], 0, 0, 0); __builtin_amdgcn_s_setprio(0); } while (0)
; #define PG8_WAIT_V(n) asm volatile("s_waitcnt vmcnt(" #n ")" ::: "memory")
; #define PG8_WAIT_L(n) asm volatile("s_waitcnt lgkmcnt(" #n ")" ::: "memory")
; #define PG8_BAR __builtin_amdgcn_s_barrier()
; #define PG8_SCHED __builtin_amdgcn_sched_barrier(0)
; template <class Epi, class Sched>
; DI void gemm_phase(LAS unsigned char* lds, const Gemm g, const Sched& S, const Epi& E) {
;     ...
;             PG8_WAIT_V(6); PG8_BAR; PG8_MMA(1, 1, At, B1); PG8_BAR;
;             PG8_LDB(B0, 1, 0); PG8_SCHED; PG8_LDA(At, 1, 0); PG8_STAGE(PG8_SA(0, 1), a2 + hstep, voffA);
;             PG8_WAIT_L(8); PG8_BAR; PG8_WAIT_L(0); PG8_MMA(0, 0, At, B0); PG8_BAR; PG8_SCHED;
;             PG8_LDB(B1, 1, 1); PG8_STAGE(PG8_SB(1, 0), b3, voffB);
	s_setprio 1
	v_mfma_f32_16x16x32_bf16 v[52:55], v[214:217], v[176:179], v[52:55]
	v_mfma_f32_16x16x32_bf16 v[48:51], v[222:225], v[176:179], v[48:51]
	v_mfma_f32_16x16x32_bf16 v[36:39], v[214:217], v[188:191], v[36:39]
	v_mfma_f32_16x16x32_bf16 v[32:35], v[222:225], v[188:191], v[32:35]
	v_mfma_f32_16x16x32_bf16 v[20:23], v[214:217], v[198:201], v[20:23]
	v_mfma_f32_16x16x32_bf16 v[16:19], v[222:225], v[198:201], v[16:19]
	v_mfma_f32_16x16x32_bf16 v[4:7], v[214:217], v[206:209], v[4:7]
	v_mfma_f32_16x16x32_bf16 v[0:3], v[222:225], v[206:209], v[0:3]
	v_mfma_f32_16x16x32_bf16 v[52:55], v[218:221], v[180:183], v[52:55]
	v_mfma_f32_16x16x32_bf16 v[48:51], v[226:229], v[180:183], v[48:51]
	v_mfma_f32_16x16x32_bf16 v[36:39], v[218:221], v[194:197], v[36:39]
	v_mfma_f32_16x16x32_bf16 v[32:35], v[226:229], v[194:197], v[32:35]
	v_mfma_f32_16x16x32_bf16 v[20:23], v[218:221], v[202:205], v[20:23]
	v_mfma_f32_16x16x32_bf16 v[16:19], v[226:229], v[202:205], v[16:19]
	v_mfma_f32_16x16x32_bf16 v[4:7], v[218:221], v[210:213], v[4:7]
	v_mfma_f32_16x16x32_bf16 v[0:3], v[226:229], v[210:213], v[0:3]
	s_setprio 0
	s_add_i32 s4, 0, 0x18000
	s_barrier
	ds_read_b128 v[144:147], v230
	ds_read_b128 v[164:167], v230 offset:1024
	ds_read_b128 v[168:171], v230 offset:2048
	ds_read_b128 v[172:175], v230 offset:3072
	s_add_u32 s0, s44, 0x160000
	s_addc_u32 s1, s45, 0
	s_mov_b32 m0, s56
	ds_read_b128 v[176:179], v159 offset:32768
	ds_read_b128 v[180:183], v159 offset:33792
	ds_read_b128 v[188:191], v159 offset:34816
	ds_read_b128 v[194:197], v159 offset:35840
	ds_read_b128 v[198:201], v159 offset:36864
	ds_read_b128 v[202:205], v159 offset:37888
	ds_read_b128 v[206:209], v159 offset:38912
	global_load_lds_dwordx4 v128, s[0:1]
	s_mov_b32 m0, s57
	ds_read_b128 v[210:213], v159 offset:39936
	global_load_lds_dwordx4 v132, s[0:1]
	s_waitcnt lgkmcnt(8)
	s_barrier
	s_waitcnt lgkmcnt(0)
	s_setprio 1
	v_mfma_f32_16x16x32_bf16 v[124:127], v[144:147], v[176:179], v[124:127]
	v_mfma_f32_16x16x32_bf16 v[120:123], v[168:171], v[176:179], v[120:123]
	v_mfma_f32_16x16x32_bf16 v[108:111], v[144:147], v[188:191], v[108:111]
	v_mfma_f32_16x16x32_bf16 v[104:107], v[168:171], v[188:191], v[104:107]
	v_mfma_f32_16x16x32_bf16 v[92:95], v[144:147], v[198:201], v[92:95]
	v_mfma_f32_16x16x32_bf16 v[88:91], v[168:171], v[198:201], v[88:91]
	v_mfma_f32_16x16x32_bf16 v[76:79], v[144:147], v[206:209], v[76:79]
	v_mfma_f32_16x16x32_bf16 v[72:75], v[168:171], v[206:209], v[72:75]
	v_mfma_f32_16x16x32_bf16 v[124:127], v[164:167], v[180:183], v[124:127]
	v_mfma_f32_16x16x32_bf16 v[120:123], v[172:175], v[180:183], v[120:123]
	v_mfma_f32_16x16x32_bf16 v[108:111], v[164:167], v[194:197], v[108:111]
	v_mfma_f32_16x16x32_bf16 v[104:107], v[172:175], v[194:197], v[104:107]
	v_mfma_f32_16x16x32_bf16 v[92:95], v[164:167], v[202:205], v[92:95]
	v_mfma_f32_16x16x32_bf16 v[88:91], v[172:175], v[202:205], v[88:91]
	v_mfma_f32_16x16x32_bf16 v[76:79], v[164:167], v[210:213], v[76:79]
	v_mfma_f32_16x16x32_bf16 v[72:75], v[172:175], v[210:213], v[72:75]
	s_setprio 0
	s_barrier
	s_add_i32 s5, 0, 0x1c000
	s_add_i32 s0, s4, s53
	s_add_i32 m0, s0, 0xffffff80
	ds_read_b128 v[214:217], v231
	ds_read_b128 v[218:221], v231 offset:1024
	ds_read_b128 v[222:225], v231 offset:2048
	global_load_lds_dwordx4 v130, s[42:43] offset:128
	s_add_i32 m0, s0, 0x1f80
	ds_read_b128 v[226:229], v231 offset:3072
	global_load_lds_dwordx4 v134, s[42:43] offset:128
	s_barrier
; #define PG8_STAGE(bufoff, gbase, voff) do { _Pragma("unroll") for (int _i = 0; _i < 2; ++_i) \
;         __builtin_amdgcn_global_load_lds((const unsigned*)((const char*)(gbase) + (voff)[_i]), (LAS unsigned*)(lds + (bufoff) + ldsw + _i * 8192), 16, 0, 0); } while (0)
; #define PG8_LDA(dst, b, h) do { _Pragma("unroll") for (int m = 0; m < 4; ++m) _Pragma("unroll") for (int k = 0; k < 2; ++k) dst[m][k] = *(const LAS bf16x8*)(lds + PG8_SA(b, h) + aoff + m * 2048 + k * 1024); } while (0)
; #define PG8_MMA(ai, bj, At, Bt) do { __builtin_amdgcn_s_setprio(1); _Pragma("unroll") for (int m = 0; m < 4; ++m) _Pragma("unroll") for (int n = 0; n < 2; ++n) _Pragma("unroll") for (int k = 0; k < 2; ++k) \
;         acc[ai][bj][m][n] = __builtin_amdgcn_mfma_f32_16x16x32_bf16(Bt[n][k], At[m][k], acc[ai][bj][m][n], 0, 0, 0); __builtin_amdgcn_s_setprio(0); } while (0)
; #define PG8_WAIT_V(n) asm volatile("s_waitcnt vmcnt(" #n ")" ::: "memory")
; #define PG8_WAIT_L(n) asm volatile("s_waitcnt lgkmcnt(" #n ")" ::: "memory")
; #define PG8_BAR __builtin_amdgcn_s_barrier()
; #define PG8_SCHED __builtin_amdgcn_sched_barrier(0)
; template <class Epi, class Sched>
; DI void gemm_phase(LAS unsigned char* lds, const Gemm g, const Sched& S, const Epi& E) {
;     ...
;             PG8_BAR; PG8_WAIT_L(0); PG8_MMA(0, 1, At, B1); PG8_BAR;
;             PG8_LDA(At, 1, 1); PG8_STAGE(PG8_SA(1, 0), a3, voffA);
;             PG8_BAR; PG8_WAIT_L(0); PG8_MMA(1, 0, At, B0); PG8_BAR; PG8_SCHED;
;             PG8_STAGE(PG8_SB(1, 1), b3 + hstep, voffB);
;             PG8_WAIT_V(6); PG8_BAR; PG8_MMA(1, 1, At, B1); PG8_BAR;
	s_waitcnt lgkmcnt(0)
	s_setprio 1
	v_mfma_f32_16x16x32_bf16 v[116:119], v[214:217], v[176:179], v[116:119]
	v_mfma_f32_16x16x32_bf16 v[112:115], v[222:225], v[176:179], v[112:115]
	v_mfma_f32_16x16x32_bf16 v[100:103], v[214:217], v[188:191], v[100:103]
	v_mfma_f32_16x16x32_bf16 v[96:99], v[222:225], v[188:191], v[96:99]
	v_mfma_f32_16x16x32_bf16 v[84:87], v[214:217], v[198:201], v[84:87]
	v_mfma_f32_16x16x32_bf16 v[80:83], v[222:225], v[198:201], v[80:83]
	v_mfma_f32_16x16x32_bf16 v[68:71], v[214:217], v[206:209], v[68:71]
	v_mfma_f32_16x16x32_bf16 v[64:67], v[222:225], v[206:209], v[64:67]
	v_mfma_f32_16x16x32_bf16 v[116:119], v[218:221], v[180:183], v[116:119]
	v_mfma_f32_16x16x32_bf16 v[112:115], v[226:229], v[180:183], v[112:115]
	v_mfma_f32_16x16x32_bf16 v[100:103], v[218:221], v[194:197], v[100:103]
	v_mfma_f32_16x16x32_bf16 v[96:99], v[226:229], v[194:197], v[96:99]
	v_mfma_f32_16x16x32_bf16 v[84:87], v[218:221], v[202:205], v[84:87]
	v_mfma_f32_16x16x32_bf16 v[80:83], v[226:229], v[202:205], v[80:83]
	v_mfma_f32_16x16x32_bf16 v[68:71], v[218:221], v[210:213], v[68:71]
	v_mfma_f32_16x16x32_bf16 v[64:67], v[226:229], v[210:213], v[64:67]
	s_setprio 0
	s_add_i32 m0, s61, 0xffffff80
	s_barrier
	ds_read_b128 v[176:179], v159 offset:49152
	ds_read_b128 v[180:183], v159 offset:50176
	ds_read_b128 v[188:191], v159 offset:51200
	ds_read_b128 v[194:197], v159 offset:52224
	ds_read_b128 v[198:201], v159 offset:53248
	ds_read_b128 v[202:205], v159 offset:54272
	ds_read_b128 v[206:209], v159 offset:55296
	global_load_lds_dwordx4 v128, s[44:45] offset:128
	s_add_i32 m0, s62, 0xffffff80
	ds_read_b128 v[210:213], v159 offset:56320
	global_load_lds_dwordx4 v132, s[44:45] offset:128
	s_barrier
	s_waitcnt lgkmcnt(0)
	s_setprio 1
	v_mfma_f32_16x16x32_bf16 v[60:63], v[144:147], v[176:179], v[60:63]
	v_mfma_f32_16x16x32_bf16 v[56:59], v[168:171], v[176:179], v[56:59]
	v_mfma_f32_16x16x32_bf16 v[44:47], v[144:147], v[188:191], v[44:47]
	v_mfma_f32_16x16x32_bf16 v[40:43], v[168:171], v[188:191], v[40:43]
	v_mfma_f32_16x16x32_bf16 v[28:31], v[144:147], v[198:201], v[28:31]
	v_mfma_f32_16x16x32_bf16 v[24:27], v[168:171], v[198:201], v[24:27]
	v_mfma_f32_16x16x32_bf16 v[12:15], v[144:147], v[206:209], v[12:15]
	v_mfma_f32_16x16x32_bf16 v[8:11], v[168:171], v[206:209], v[8:11]
	v_mfma_f32_16x16x32_bf16 v[60:63], v[164:167], v[180:183], v[60:63]
	v_mfma_f32_16x16x32_bf16 v[56:59], v[172:175], v[180:183], v[56:59]
	v_mfma_f32_16x16x32_bf16 v[44:47], v[164:167], v[194:197], v[44:47]
	v_mfma_f32_16x16x32_bf16 v[40:43], v[172:175], v[194:197], v[40:43]
	v_mfma_f32_16x16x32_bf16 v[28:31], v[164:167], v[202:205], v[28:31]
	v_mfma_f32_16x16x32_bf16 v[24:27], v[172:175], v[202:205], v[24:27]
	v_mfma_f32_16x16x32_bf16 v[12:15], v[164:167], v[210:213], v[12:15]
	v_mfma_f32_16x16x32_bf16 v[8:11], v[172:175], v[210:213], v[8:11]
	s_setprio 0
	s_barrier
	s_add_i32 s4, s5, s53
	s_mov_b32 m0, s4
	s_add_u32 s0, s42, 0x160080
	s_addc_u32 s1, s43, 0
	global_load_lds_dwordx4 v130, s[0:1]
	s_add_i32 m0, s4, 0x2000
	s_nop 0
	global_load_lds_dwordx4 v134, s[0:1]
	s_waitcnt vmcnt(6)
	s_barrier
	s_setprio 1
	v_mfma_f32_16x16x32_bf16 v[52:55], v[214:217], v[176:179], v[52:55]
	v_mfma_f32_16x16x32_bf16 v[48:51], v[222:225], v[176:179], v[48:51]
	v_mfma_f32_16x16x32_bf16 v[36:39], v[214:217], v[188:191], v[36:39]
	v_mfma_f32_16x16x32_bf16 v[32:35], v[222:225], v[188:191], v[32:35]
	v_mfma_f32_16x16x32_bf16 v[20:23], v[214:217], v[198:201], v[20:23]
	v_mfma_f32_16x16x32_bf16 v[16:19], v[222:225], v[198:201], v[16:19]
	v_mfma_f32_16x16x32_bf16 v[4:7], v[214:217], v[206:209], v[4:7]
	v_mfma_f32_16x16x32_bf16 v[0:3], v[222:225], v[206:209], v[0:3]
	v_mfma_f32_16x16x32_bf16 v[52:55], v[218:221], v[180:183], v[52:55]
	v_mfma_f32_16x16x32_bf16 v[48:51], v[226:229], v[180:183], v[48:51]
	v_mfma_f32_16x16x32_bf16 v[36:39], v[218:221], v[194:197], v[36:39]
	v_mfma_f32_16x16x32_bf16 v[32:35], v[226:229], v[194:197], v[32:35]
	v_mfma_f32_16x16x32_bf16 v[20:23], v[218:221], v[202:205], v[20:23]
	v_mfma_f32_16x16x32_bf16 v[16:19], v[226:229], v[202:205], v[16:19]
	v_mfma_f32_16x16x32_bf16 v[4:7], v[218:221], v[210:213], v[4:7]
	v_mfma_f32_16x16x32_bf16 v[0:3], v[226:229], v[210:213], v[0:3]
	s_setprio 0
	s_add_i32 s69, s69, 2
	s_add_u32 s40, s40, 0x100
	s_addc_u32 s41, s41, 0
	s_add_u32 s35, s35, 0x100
	s_addc_u32 s68, s68, 0
	s_cmpk_gt_u32 s69, 0x55
	s_cbranch_scc0 .Lrot_297
	s_barrier

;     DI size_t aoff(const Unit& u, size_t tstep) const { return (size_t)u.pm * tstep; }
;     DI size_t boff(const Unit& u, size_t tstep) const { return (size_t)u.pn * tstep; }
;     DI bool next(int i, Unit& u) const { const long L = (long)i * G + c; if (L >= np) return false; u.pm = pmv; u.pn = (int)(L % nN); u.ks = (int)(L / nN); return true; }
;     DI size_t aoff(const Unit& u, size_t) const { return (size_t)u.ks * kbytes; }
;     DI size_t boff(const Unit& u, size_t tstep) const { return (size_t)u.pn * tstep + (size_t)u.ks * kbytes; }
;     DI bool next(int i, Unit& u) const { Unit t; if (!S.next(i / 3, t)) return false; u.pm = t.pm; u.pn = t.pn; u.ks = i % 3; return true; }
;     DI size_t aoff(const Unit& u, size_t tstep) const { return (u.ks < 2 ? offU : offOA) + (size_t)u.pm * tstep; }
; #define PG8_WAIT_V(n) asm volatile("s_waitcnt vmcnt(" #n ")" ::: "memory")
; template <class Epi, class Sched>
; DI void gemm_phase(LAS unsigned char* lds, const Gemm g, const Sched& S, const Epi& E) {
;     ...
;         const bool has_next = S.next(ui + 1, nxt);
;         const char* nA = has_next ? (const char*)g.A + S.aoff(nxt, tstep) : cA; const char* nB = has_next ? (const char*)g.Bt + S.boff(nxt, tstep) : cB;
;         for (int t = 0; t < nt; t += 2) {
;             if constexpr (Epi::HAS_MID) { if (t == E.mid_t(nt)) { int fr3 = fr, fq3 = fq; asm volatile("" : "+v"(fr3), "+v"(fq3)); E.mid(acc, cur, wr, wc, fr3, fq3); } }
;             const bool last = (t == nt - 2);
;             const char* a1 = cA + (size_t)(t + 1) * kstep;
;             const char* a2 = last ? nA : cA + (size_t)(t + 2) * kstep; const char* b2 = last ? nB : cB + (size_t)(t + 2) * kstep;
;             const char* a3 = a2 + kstep; const char* b3 = b2 + kstep;
;             PG8_LDB(B0, 0, 0); PG8_SCHED; PG8_LDA(At, 0, 0); PG8_STAGE(PG8_SA(1, 1), a1 + hstep, voffA);
;             PG8_WAIT_L(8); PG8_BAR; PG8_WAIT_L(0); PG8_MMA(0, 0, At, B0); PG8_BAR; PG8_SCHED;
;             PG8_LDB(B1, 0, 1); PG8_STAGE(PG8_SB(0, 0), b2, voffB);
;             PG8_BAR; PG8_WAIT_L(0); PG8_MMA(0, 1, At, B1); PG8_BAR;
;             PG8_LDA(At, 0, 1); PG8_STAGE(PG8_SA(0, 0), a2, voffA);
;             PG8_BAR; PG8_WAIT_L(0); PG8_MMA(1, 0, At, B0); PG8_BAR; PG8_SCHED;
;             PG8_STAGE(PG8_SB(0, 1), b2 + hstep, voffB);
;             PG8_WAIT_V(6); PG8_BAR; PG8_MMA(1, 1, At, B1); PG8_BAR;
.LBB0_325:
	s_add_u32 s28, s40, s28
	s_addc_u32 s29, s41, s29
	s_and_b64 s[0:1], s[8:9], exec
	s_cselect_b32 s15, s29, s39
	s_cselect_b32 s17, s28, s38
	s_add_u32 s8, s38, 0x160080
	s_addc_u32 s9, s39, 0
	s_add_u32 s66, s36, 0x100
	v_mov_b32_e32 v0, 0
	s_addc_u32 s67, s37, 0
	s_mov_b32 s68, -2
	ds_read_b128 v[150:153], v141
	ds_read_b128 v[154:157], v141 offset:1024
	ds_read_b128 v[162:165], v141 offset:2048
	ds_read_b128 v[166:169], v141 offset:3072
	s_mov_b32 m0, s58
	ds_read_b128 v[170:173], v142
	ds_read_b128 v[174:177], v142 offset:1024
	ds_read_b128 v[178:181], v142 offset:2048
	ds_read_b128 v[188:191], v142 offset:3072
	ds_read_b128 v[194:197], v142 offset:4096
	ds_read_b128 v[198:201], v142 offset:5120
	ds_read_b128 v[202:205], v142 offset:6144
	global_load_lds_dwordx4 v132, s[8:9]
	s_mov_b32 m0, s59
	ds_read_b128 v[206:209], v142 offset:7168
	global_load_lds_dwordx4 v134, s[8:9]
	s_add_u32 s0, s8, 0xffea0080
	s_addc_u32 s1, s9, -1
	s_cmp_eq_u32 s68, 4
	s_cselect_b32 s39, s15, s1
	s_cselect_b32 s38, s17, s0
	s_cselect_b32 s37, s19, s67
	s_cselect_b32 s36, s18, s66
	s_waitcnt lgkmcnt(8)
	s_barrier
	s_waitcnt lgkmcnt(0)
	s_setprio 1
	v_mfma_f32_16x16x32_bf16 v[124:127], v[150:153], v[170:173], 0
	v_mfma_f32_16x16x32_bf16 v[120:123], v[162:165], v[170:173], 0
	v_mfma_f32_16x16x32_bf16 v[116:119], v[150:153], v[178:181], 0
	v_mfma_f32_16x16x32_bf16 v[112:115], v[162:165], v[178:181], 0
	v_mfma_f32_16x16x32_bf16 v[104:107], v[150:153], v[194:197], 0
	v_mfma_f32_16x16x32_bf16 v[96:99], v[162:165], v[194:197], 0
	v_mfma_f32_16x16x32_bf16 v[88:91], v[150:153], v[202:205], 0
	v_mfma_f32_16x16x32_bf16 v[80:83], v[162:165], v[202:205], 0
	v_mfma_f32_16x16x32_bf16 v[124:127], v[154:157], v[174:177], v[124:127]
	v_mfma_f32_16x16x32_bf16 v[120:123], v[166:169], v[174:177], v[120:123]
	v_mfma_f32_16x16x32_bf16 v[116:119], v[154:157], v[188:191], v[116:119]
	v_mfma_f32_16x16x32_bf16 v[112:115], v[166:169], v[188:191], v[112:115]
	v_mfma_f32_16x16x32_bf16 v[104:107], v[154:157], v[198:201], v[104:107]
	v_mfma_f32_16x16x32_bf16 v[96:99], v[166:169], v[198:201], v[96:99]
	v_mfma_f32_16x16x32_bf16 v[88:91], v[154:157], v[206:209], v[88:91]
	v_mfma_f32_16x16x32_bf16 v[80:83], v[166:169], v[206:209], v[80:83]
	s_setprio 0
	s_barrier
	s_mov_b32 m0, s60
	ds_read_b128 v[210:213], v143
	ds_read_b128 v[214:217], v143 offset:1024
	ds_read_b128 v[218:221], v143 offset:2048
	global_load_lds_dwordx4 v130, s[36:37]
	s_mov_b32 m0, s61
	ds_read_b128 v[222:225], v143 offset:3072
	global_load_lds_dwordx4 v128, s[36:37]
	s_barrier
	s_waitcnt lgkmcnt(0)
	s_setprio 1
	v_mfma_f32_16x16x32_bf16 v[108:111], v[210:213], v[170:173], 0
	v_mfma_f32_16x16x32_bf16 v[100:103], v[218:221], v[170:173], 0
	v_mfma_f32_16x16x32_bf16 v[92:95], v[210:213], v[178:181], 0
	v_mfma_f32_16x16x32_bf16 v[84:87], v[218:221], v[178:181], 0
	v_mfma_f32_16x16x32_bf16 v[76:79], v[210:213], v[194:197], 0
	v_mfma_f32_16x16x32_bf16 v[72:75], v[218:221], v[194:197], 0
	v_mfma_f32_16x16x32_bf16 v[68:71], v[210:213], v[202:205], 0
	v_mfma_f32_16x16x32_bf16 v[64:67], v[218:221], v[202:205], 0
	v_mfma_f32_16x16x32_bf16 v[108:111], v[214:217], v[174:177], v[108:111]
	v_mfma_f32_16x16x32_bf16 v[100:103], v[222:225], v[174:177], v[100:103]
	v_mfma_f32_16x16x32_bf16 v[92:95], v[214:217], v[188:191], v[92:95]
	v_mfma_f32_16x16x32_bf16 v[84:87], v[222:225], v[188:191], v[84:87]
	v_mfma_f32_16x16x32_bf16 v[76:79], v[214:217], v[198:201], v[76:79]
	v_mfma_f32_16x16x32_bf16 v[72:75], v[222:225], v[198:201], v[72:75]
	v_mfma_f32_16x16x32_bf16 v[68:71], v[214:217], v[206:209], v[68:71]
	v_mfma_f32_16x16x32_bf16 v[64:67], v[222:225], v[206:209], v[64:67]
	s_setprio 0
	s_mov_b32 m0, s42
	s_barrier
	ds_read_b128 v[170:173], v142 offset:16384
	ds_read_b128 v[174:177], v142 offset:17408
	ds_read_b128 v[178:181], v142 offset:18432
	ds_read_b128 v[188:191], v142 offset:19456
	ds_read_b128 v[194:197], v142 offset:20480
	ds_read_b128 v[198:201], v142 offset:21504
	ds_read_b128 v[202:205], v142 offset:22528
	global_load_lds_dwordx4 v130, s[38:39]
	s_mov_b32 m0, s43
	ds_read_b128 v[206:209], v142 offset:23552
	global_load_lds_dwordx4 v128, s[38:39]
	s_barrier
	s_waitcnt lgkmcnt(0)
	s_setprio 1
	v_mfma_f32_16x16x32_bf16 v[60:63], v[150:153], v[170:173], 0
	v_mfma_f32_16x16x32_bf16 v[56:59], v[162:165], v[170:173], 0
	v_mfma_f32_16x16x32_bf16 v[52:55], v[150:153], v[178:181], 0
	v_mfma_f32_16x16x32_bf16 v[48:51], v[162:165], v[178:181], 0
	v_mfma_f32_16x16x32_bf16 v[40:43], v[150:153], v[194:197], 0
	v_mfma_f32_16x16x32_bf16 v[32:35], v[162:165], v[194:197], 0
	v_mfma_f32_16x16x32_bf16 v[24:27], v[150:153], v[202:205], 0
	v_mfma_f32_16x16x32_bf16 v[16:19], v[162:165], v[202:205], 0
	v_mfma_f32_16x16x32_bf16 v[60:63], v[154:157], v[174:177], v[60:63]
	v_mfma_f32_16x16x32_bf16 v[56:59], v[166:169], v[174:177], v[56:59]
	v_mfma_f32_16x16x32_bf16 v[52:55], v[154:157], v[188:191], v[52:55]
	v_mfma_f32_16x16x32_bf16 v[48:51], v[166:169], v[188:191], v[48:51]
	v_mfma_f32_16x16x32_bf16 v[40:43], v[154:157], v[198:201], v[40:43]
	v_mfma_f32_16x16x32_bf16 v[32:35], v[166:169], v[198:201], v[32:35]
	v_mfma_f32_16x16x32_bf16 v[24:27], v[154:157], v[206:209], v[24:27]
	v_mfma_f32_16x16x32_bf16 v[16:19], v[166:169], v[206:209], v[16:19]
	s_setprio 0
	s_barrier
	s_add_u32 s0, s36, 0x160000
	s_addc_u32 s1, s37, 0
	s_mov_b32 m0, s62
	s_nop 0
	global_load_lds_dwordx4 v130, s[0:1]
	s_mov_b32 m0, s63
	s_nop 0
	global_load_lds_dwordx4 v128, s[0:1]
	s_waitcnt vmcnt(6)
	s_barrier
; #define PG8_STAGE(bufoff, gbase, voff) do { _Pragma("unroll") for (int _i = 0; _i < 2; ++_i) \
;         __builtin_amdgcn_global_load_lds((const unsigned*)((const char*)(gbase) + (voff)[_i]), (LAS unsigned*)(lds + (bufoff) + ldsw + _i * 8192), 16, 0, 0); } while (0)
; #define PG8_LDA(dst, b, h) do { _Pragma("unroll") for (int m = 0; m < 4; ++m) _Pragma("unroll") for (int k = 0; k < 2; ++k) dst[m][k] = *(const LAS bf16x8*)(lds + PG8_SA(b, h) + aoff + m * 2048 + k * 1024); } while (0)
; #define PG8_LDB(dst, b, h) do { _Pragma("unroll") for (int n = 0; n < 2; ++n) _Pragma("unroll") for (int k = 0; k < 2; ++k) dst[n][k] = *(const LAS bf16x8*)(lds + PG8_SB(b, h) + boff + n * 2048 + k * 1024); } while (0)
; #define PG8_MMA(ai, bj, At, Bt) do { __builtin_amdgcn_s_setprio(1); _Pragma("unroll") for (int m = 0; m < 4; ++m) _Pragma("unroll") for (int n = 0; n < 2; ++n) _Pragma("unroll") for (int k = 0; k < 2; ++k) \
;         acc[ai][bj][m][n] = __builtin_amdgcn_mfma_f32_16x16x32_bf16(Bt[n][k], At[m][k], acc[ai][bj][m][n], 0, 0, 0); __builtin_amdgcn_s_setprio(0); } while (0)
; #define PG8_WAIT_V(n) asm volatile("s_waitcnt vmcnt(" #n ")" ::: "memory")
; #define PG8_WAIT_L(n) asm volatile("s_waitcnt lgkmcnt(" #n ")" ::: "memory")
; #define PG8_BAR __builtin_amdgcn_s_barrier()
; #define PG8_SCHED __builtin_amdgcn_sched_barrier(0)
; template <class Epi, class Sched>
; DI void gemm_phase(LAS unsigned char* lds, const Gemm g, const Sched& S, const Epi& E) {
;     ...
;             PG8_WAIT_V(6); PG8_BAR; PG8_MMA(1, 1, At, B1); PG8_BAR;
;             PG8_LDB(B0, 1, 0); PG8_SCHED; PG8_LDA(At, 1, 0); PG8_STAGE(PG8_SA(0, 1), a2 + hstep, voffA);
;             PG8_WAIT_L(8); PG8_BAR; PG8_WAIT_L(0); PG8_MMA(0, 0, At, B0); PG8_BAR; PG8_SCHED;
;             PG8_LDB(B1, 1, 1); PG8_STAGE(PG8_SB(1, 0), b3, voffB);
	s_setprio 1
	v_mfma_f32_16x16x32_bf16 v[44:47], v[210:213], v[170:173], 0
	v_mfma_f32_16x16x32_bf16 v[36:39], v[218:221], v[170:173], 0
	v_mfma_f32_16x16x32_bf16 v[28:31], v[210:213], v[178:181], 0
	v_mfma_f32_16x16x32_bf16 v[20:23], v[218:221], v[178:181], 0
	v_mfma_f32_16x16x32_bf16 v[12:15], v[210:213], v[194:197], 0
	v_mfma_f32_16x16x32_bf16 v[8:11], v[218:221], v[194:197], 0
	v_mfma_f32_16x16x32_bf16 v[4:7], v[210:213], v[202:205], 0
	v_mfma_f32_16x16x32_bf16 v[0:3], v[218:221], v[202:205], 0
	v_mfma_f32_16x16x32_bf16 v[44:47], v[214:217], v[174:177], v[44:47]
	v_mfma_f32_16x16x32_bf16 v[36:39], v[222:225], v[174:177], v[36:39]
	v_mfma_f32_16x16x32_bf16 v[28:31], v[214:217], v[188:191], v[28:31]
	v_mfma_f32_16x16x32_bf16 v[20:23], v[222:225], v[188:191], v[20:23]
	v_mfma_f32_16x16x32_bf16 v[12:15], v[214:217], v[198:201], v[12:15]
	v_mfma_f32_16x16x32_bf16 v[8:11], v[222:225], v[198:201], v[8:11]
	v_mfma_f32_16x16x32_bf16 v[4:7], v[214:217], v[206:209], v[4:7]
	v_mfma_f32_16x16x32_bf16 v[0:3], v[222:225], v[206:209], v[0:3]
	s_setprio 0
	s_barrier
	ds_read_b128 v[150:153], v144
	ds_read_b128 v[154:157], v144 offset:1024
	ds_read_b128 v[162:165], v144 offset:2048
	ds_read_b128 v[166:169], v144 offset:3072
	s_add_u32 s0, s38, 0x160000
	s_addc_u32 s1, s39, 0
	s_mov_b32 m0, s44
	ds_read_b128 v[170:173], v142 offset:32768
	ds_read_b128 v[174:177], v142 offset:33792
	ds_read_b128 v[178:181], v142 offset:34816
	ds_read_b128 v[188:191], v142 offset:35840
	ds_read_b128 v[194:197], v142 offset:36864
	ds_read_b128 v[198:201], v142 offset:37888
	ds_read_b128 v[202:205], v142 offset:38912
	global_load_lds_dwordx4 v130, s[0:1]
	s_mov_b32 m0, s45
	ds_read_b128 v[206:209], v142 offset:39936
	global_load_lds_dwordx4 v128, s[0:1]
	s_waitcnt lgkmcnt(8)
	s_barrier
	s_waitcnt lgkmcnt(0)
	s_setprio 1
	v_mfma_f32_16x16x32_bf16 v[124:127], v[150:153], v[170:173], v[124:127]
	v_mfma_f32_16x16x32_bf16 v[120:123], v[162:165], v[170:173], v[120:123]
	v_mfma_f32_16x16x32_bf16 v[116:119], v[150:153], v[178:181], v[116:119]
	v_mfma_f32_16x16x32_bf16 v[112:115], v[162:165], v[178:181], v[112:115]
	v_mfma_f32_16x16x32_bf16 v[104:107], v[150:153], v[194:197], v[104:107]
	v_mfma_f32_16x16x32_bf16 v[96:99], v[162:165], v[194:197], v[96:99]
	v_mfma_f32_16x16x32_bf16 v[88:91], v[150:153], v[202:205], v[88:91]
	v_mfma_f32_16x16x32_bf16 v[80:83], v[162:165], v[202:205], v[80:83]
	v_mfma_f32_16x16x32_bf16 v[124:127], v[154:157], v[174:177], v[124:127]
	v_mfma_f32_16x16x32_bf16 v[120:123], v[166:169], v[174:177], v[120:123]
	v_mfma_f32_16x16x32_bf16 v[116:119], v[154:157], v[188:191], v[116:119]
	v_mfma_f32_16x16x32_bf16 v[112:115], v[166:169], v[188:191], v[112:115]
	v_mfma_f32_16x16x32_bf16 v[104:107], v[154:157], v[198:201], v[104:107]
	v_mfma_f32_16x16x32_bf16 v[96:99], v[166:169], v[198:201], v[96:99]
	v_mfma_f32_16x16x32_bf16 v[88:91], v[154:157], v[206:209], v[88:91]
	v_mfma_f32_16x16x32_bf16 v[80:83], v[166:169], v[206:209], v[80:83]
	s_setprio 0
	s_barrier
	s_add_i32 s4, 0, 0x1c000
	s_add_i32 s0, s64, s35
	v_add_u32_e32 v145, s4, v140
	s_add_i32 m0, s0, 0xffffff80
	ds_read_b128 v[210:213], v145
	ds_read_b128 v[214:217], v145 offset:1024
	ds_read_b128 v[218:221], v145 offset:2048
	global_load_lds_dwordx4 v130, s[36:37] offset:128
	s_add_i32 m0, s0, 0x1f80
	ds_read_b128 v[222:225], v145 offset:3072
	global_load_lds_dwordx4 v128, s[36:37] offset:128
	s_barrier
; #define PG8_STAGE(bufoff, gbase, voff) do { _Pragma("unroll") for (int _i = 0; _i < 2; ++_i) \
;         __builtin_amdgcn_global_load_lds((const unsigned*)((const char*)(gbase) + (voff)[_i]), (LAS unsigned*)(lds + (bufoff) + ldsw + _i * 8192), 16, 0, 0); } while (0)
; #define PG8_LDA(dst, b, h) do { _Pragma("unroll") for (int m = 0; m < 4; ++m) _Pragma("unroll") for (int k = 0; k < 2; ++k) dst[m][k] = *(const LAS bf16x8*)(lds + PG8_SA(b, h) + aoff + m * 2048 + k * 1024); } while (0)
; #define PG8_MMA(ai, bj, At, Bt) do { __builtin_amdgcn_s_setprio(1); _Pragma("unroll") for (int m = 0; m < 4; ++m) _Pragma("unroll") for (int n = 0; n < 2; ++n) _Pragma("unroll") for (int k = 0; k < 2; ++k) \
;         acc[ai][bj][m][n] = __builtin_amdgcn_mfma_f32_16x16x32_bf16(Bt[n][k], At[m][k], acc[ai][bj][m][n], 0, 0, 0); __builtin_amdgcn_s_setprio(0); } while (0)
; #define PG8_WAIT_V(n) asm volatile("s_waitcnt vmcnt(" #n ")" ::: "memory")
; #define PG8_WAIT_L(n) asm volatile("s_waitcnt lgkmcnt(" #n ")" ::: "memory")
; #define PG8_BAR __builtin_amdgcn_s_barrier()
; #define PG8_SCHED __builtin_amdgcn_sched_barrier(0)
; template <class Epi, class Sched>
; DI void gemm_phase(LAS unsigned char* lds, const Gemm g, const Sched& S, const Epi& E) {
;     ...
;             PG8_LDA(At, 1, 1); PG8_STAGE(PG8_SA(1, 0), a3, voffA);
;             PG8_BAR; PG8_WAIT_L(0); PG8_MMA(1, 0, At, B0); PG8_BAR; PG8_SCHED;
;             PG8_STAGE(PG8_SB(1, 1), b3 + hstep, voffB);
;             PG8_WAIT_V(6); PG8_BAR; PG8_MMA(1, 1, At, B1); PG8_BAR;
	s_waitcnt lgkmcnt(0)
	s_setprio 1
	v_mfma_f32_16x16x32_bf16 v[108:111], v[210:213], v[170:173], v[108:111]
	v_mfma_f32_16x16x32_bf16 v[100:103], v[218:221], v[170:173], v[100:103]
	v_mfma_f32_16x16x32_bf16 v[92:95], v[210:213], v[178:181], v[92:95]
	v_mfma_f32_16x16x32_bf16 v[84:87], v[218:221], v[178:181], v[84:87]
	v_mfma_f32_16x16x32_bf16 v[76:79], v[210:213], v[194:197], v[76:79]
	v_mfma_f32_16x16x32_bf16 v[72:75], v[218:221], v[194:197], v[72:75]
	v_mfma_f32_16x16x32_bf16 v[68:71], v[210:213], v[202:205], v[68:71]
	v_mfma_f32_16x16x32_bf16 v[64:67], v[218:221], v[202:205], v[64:67]
	v_mfma_f32_16x16x32_bf16 v[108:111], v[214:217], v[174:177], v[108:111]
	v_mfma_f32_16x16x32_bf16 v[100:103], v[222:225], v[174:177], v[100:103]
	v_mfma_f32_16x16x32_bf16 v[92:95], v[214:217], v[188:191], v[92:95]
	v_mfma_f32_16x16x32_bf16 v[84:87], v[222:225], v[188:191], v[84:87]
	v_mfma_f32_16x16x32_bf16 v[76:79], v[214:217], v[198:201], v[76:79]
	v_mfma_f32_16x16x32_bf16 v[72:75], v[222:225], v[198:201], v[72:75]
	v_mfma_f32_16x16x32_bf16 v[68:71], v[214:217], v[206:209], v[68:71]
	v_mfma_f32_16x16x32_bf16 v[64:67], v[222:225], v[206:209], v[64:67]
	s_setprio 0
	s_add_i32 m0, s56, 0xffffff80
	s_barrier
	ds_read_b128 v[170:173], v142 offset:49152
	ds_read_b128 v[174:177], v142 offset:50176
	ds_read_b128 v[178:181], v142 offset:51200
	ds_read_b128 v[188:191], v142 offset:52224
	ds_read_b128 v[194:197], v142 offset:53248
	ds_read_b128 v[198:201], v142 offset:54272
	ds_read_b128 v[202:205], v142 offset:55296
	global_load_lds_dwordx4 v130, s[38:39] offset:128
	s_add_i32 m0, s57, 0xffffff80
	ds_read_b128 v[206:209], v142 offset:56320
	global_load_lds_dwordx4 v128, s[38:39] offset:128
	s_barrier
	s_waitcnt lgkmcnt(0)
	s_setprio 1
	v_mfma_f32_16x16x32_bf16 v[60:63], v[150:153], v[170:173], v[60:63]
	v_mfma_f32_16x16x32_bf16 v[56:59], v[162:165], v[170:173], v[56:59]
	v_mfma_f32_16x16x32_bf16 v[52:55], v[150:153], v[178:181], v[52:55]
	v_mfma_f32_16x16x32_bf16 v[48:51], v[162:165], v[178:181], v[48:51]
	v_mfma_f32_16x16x32_bf16 v[40:43], v[150:153], v[194:197], v[40:43]
	v_mfma_f32_16x16x32_bf16 v[32:35], v[162:165], v[194:197], v[32:35]
	v_mfma_f32_16x16x32_bf16 v[24:27], v[150:153], v[202:205], v[24:27]
	v_mfma_f32_16x16x32_bf16 v[16:19], v[162:165], v[202:205], v[16:19]
	v_mfma_f32_16x16x32_bf16 v[60:63], v[154:157], v[174:177], v[60:63]
	v_mfma_f32_16x16x32_bf16 v[56:59], v[166:169], v[174:177], v[56:59]
	v_mfma_f32_16x16x32_bf16 v[52:55], v[154:157], v[188:191], v[52:55]
	v_mfma_f32_16x16x32_bf16 v[48:51], v[166:169], v[188:191], v[48:51]
	v_mfma_f32_16x16x32_bf16 v[40:43], v[154:157], v[198:201], v[40:43]
	v_mfma_f32_16x16x32_bf16 v[32:35], v[166:169], v[198:201], v[32:35]
	v_mfma_f32_16x16x32_bf16 v[24:27], v[154:157], v[206:209], v[24:27]
	v_mfma_f32_16x16x32_bf16 v[16:19], v[166:169], v[206:209], v[16:19]
	s_setprio 0
	s_barrier
	s_add_i32 s4, s4, s35
	s_mov_b32 m0, s4
	s_add_u32 s0, s36, 0x160080
	s_addc_u32 s1, s37, 0
	global_load_lds_dwordx4 v130, s[0:1]
	s_add_i32 m0, s4, 0x2000
	s_nop 0
	global_load_lds_dwordx4 v128, s[0:1]
	s_add_i32 s68, s68, 2
	s_add_u32 s8, s8, 0x100
	s_addc_u32 s9, s9, 0
	s_add_u32 s66, s66, 0x100
	s_addc_u32 s67, s67, 0
	s_cmp_gt_u32 s68, 5
	s_waitcnt vmcnt(6)
	s_barrier
	s_setprio 1
	v_mfma_f32_16x16x32_bf16 v[44:47], v[210:213], v[170:173], v[44:47]
	v_mfma_f32_16x16x32_bf16 v[36:39], v[218:221], v[170:173], v[36:39]
	v_mfma_f32_16x16x32_bf16 v[28:31], v[210:213], v[178:181], v[28:31]
	v_mfma_f32_16x16x32_bf16 v[20:23], v[218:221], v[178:181], v[20:23]
	v_mfma_f32_16x16x32_bf16 v[12:15], v[210:213], v[194:197], v[12:15]
	v_mfma_f32_16x16x32_bf16 v[8:11], v[218:221], v[194:197], v[8:11]
	v_mfma_f32_16x16x32_bf16 v[4:7], v[210:213], v[202:205], v[4:7]
	v_mfma_f32_16x16x32_bf16 v[0:3], v[218:221], v[202:205], v[0:3]
	v_mfma_f32_16x16x32_bf16 v[44:47], v[214:217], v[174:177], v[44:47]
	v_mfma_f32_16x16x32_bf16 v[36:39], v[222:225], v[174:177], v[36:39]
	v_mfma_f32_16x16x32_bf16 v[28:31], v[214:217], v[188:191], v[28:31]
	v_mfma_f32_16x16x32_bf16 v[20:23], v[222:225], v[188:191], v[20:23]
	v_mfma_f32_16x16x32_bf16 v[12:15], v[214:217], v[198:201], v[12:15]
	v_mfma_f32_16x16x32_bf16 v[8:11], v[222:225], v[198:201], v[8:11]
	v_mfma_f32_16x16x32_bf16 v[4:7], v[214:217], v[206:209], v[4:7]
	v_mfma_f32_16x16x32_bf16 v[0:3], v[222:225], v[206:209], v[0:3]
	s_setprio 0
	s_cbranch_scc0 .Lrot_326
	s_barrier
	s_branch .Lpeel_done_326

; #define PG8_STAGE(bufoff, gbase, voff) do { _Pragma("unroll") for (int _i = 0; _i < 2; ++_i) \
;         __builtin_amdgcn_global_load_lds((const unsigned*)((const char*)(gbase) + (voff)[_i]), (LAS unsigned*)(lds + (bufoff) + ldsw + _i * 8192), 16, 0, 0); } while (0)
; #define PG8_LDA(dst, b, h) do { _Pragma("unroll") for (int m = 0; m < 4; ++m) _Pragma("unroll") for (int k = 0; k < 2; ++k) dst[m][k] = *(const LAS bf16x8*)(lds + PG8_SA(b, h) + aoff + m * 2048 + k * 1024); } while (0)
; #define PG8_LDB(dst, b, h) do { _Pragma("unroll") for (int n = 0; n < 2; ++n) _Pragma("unroll") for (int k = 0; k < 2; ++k) dst[n][k] = *(const LAS bf16x8*)(lds + PG8_SB(b, h) + boff + n * 2048 + k * 1024); } while (0)
; #define PG8_MMA(ai, bj, At, Bt) do { __builtin_amdgcn_s_setprio(1); _Pragma("unroll") for (int m = 0; m < 4; ++m) _Pragma("unroll") for (int n = 0; n < 2; ++n) _Pragma("unroll") for (int k = 0; k < 2; ++k) \
;         acc[ai][bj][m][n] = __builtin_amdgcn_mfma_f32_16x16x32_bf16(Bt[n][k], At[m][k], acc[ai][bj][m][n], 0, 0, 0); __builtin_amdgcn_s_setprio(0); } while (0)
; #define PG8_WAIT_V(n) asm volatile("s_waitcnt vmcnt(" #n ")" ::: "memory")
; #define PG8_WAIT_L(n) asm volatile("s_waitcnt lgkmcnt(" #n ")" ::: "memory")
; #define PG8_BAR __builtin_amdgcn_s_barrier()
; #define PG8_SCHED __builtin_amdgcn_sched_barrier(0)
; template <class Epi, class Sched>
; DI void gemm_phase(LAS unsigned char* lds, const Gemm g, const Sched& S, const Epi& E) {
;     ...
;             const char* a2 = last ? nA : cA + (size_t)(t + 2) * kstep; const char* b2 = last ? nB : cB + (size_t)(t + 2) * kstep;
;             const char* a3 = a2 + kstep; const char* b3 = b2 + kstep;
;             PG8_LDB(B0, 0, 0); PG8_SCHED; PG8_LDA(At, 0, 0); PG8_STAGE(PG8_SA(1, 1), a1 + hstep, voffA);
;             PG8_WAIT_L(8); PG8_BAR; PG8_WAIT_L(0); PG8_MMA(0, 0, At, B0); PG8_BAR; PG8_SCHED;
;             PG8_LDB(B1, 0, 1); PG8_STAGE(PG8_SB(0, 0), b2, voffB);
;             PG8_BAR; PG8_WAIT_L(0); PG8_MMA(0, 1, At, B1); PG8_BAR;
;             PG8_LDA(At, 0, 1); PG8_STAGE(PG8_SA(0, 0), a2, voffA);
;             PG8_BAR; PG8_WAIT_L(0); PG8_MMA(1, 0, At, B0); PG8_BAR; PG8_SCHED;
;             PG8_STAGE(PG8_SB(0, 1), b2 + hstep, voffB);
;             PG8_WAIT_V(6); PG8_BAR; PG8_MMA(1, 1, At, B1); PG8_BAR;
.LBB0_326:
	ds_read_b128 v[150:153], v141
	ds_read_b128 v[154:157], v141 offset:1024
	ds_read_b128 v[162:165], v141 offset:2048
	ds_read_b128 v[166:169], v141 offset:3072
	s_mov_b32 m0, s58
	ds_read_b128 v[170:173], v142
	ds_read_b128 v[174:177], v142 offset:1024
	ds_read_b128 v[178:181], v142 offset:2048
	ds_read_b128 v[188:191], v142 offset:3072
	ds_read_b128 v[194:197], v142 offset:4096
	ds_read_b128 v[198:201], v142 offset:5120
	ds_read_b128 v[202:205], v142 offset:6144
	global_load_lds_dwordx4 v132, s[8:9]
	s_mov_b32 m0, s59
	ds_read_b128 v[206:209], v142 offset:7168
	global_load_lds_dwordx4 v134, s[8:9]
	s_add_u32 s0, s8, 0xffea0080
	s_addc_u32 s1, s9, -1
	s_cmp_eq_u32 s68, 4
	s_cselect_b32 s39, s15, s1
	s_cselect_b32 s38, s17, s0
	s_cselect_b32 s37, s19, s67
	s_cselect_b32 s36, s18, s66
	s_waitcnt lgkmcnt(8)
	s_barrier
	s_waitcnt lgkmcnt(0)
	s_setprio 1
	v_mfma_f32_16x16x32_bf16 v[124:127], v[150:153], v[170:173], v[124:127]
	v_mfma_f32_16x16x32_bf16 v[120:123], v[162:165], v[170:173], v[120:123]
	v_mfma_f32_16x16x32_bf16 v[116:119], v[150:153], v[178:181], v[116:119]
	v_mfma_f32_16x16x32_bf16 v[112:115], v[162:165], v[178:181], v[112:115]
	v_mfma_f32_16x16x32_bf16 v[104:107], v[150:153], v[194:197], v[104:107]
	v_mfma_f32_16x16x32_bf16 v[96:99], v[162:165], v[194:197], v[96:99]
	v_mfma_f32_16x16x32_bf16 v[88:91], v[150:153], v[202:205], v[88:91]
	v_mfma_f32_16x16x32_bf16 v[80:83], v[162:165], v[202:205], v[80:83]
	v_mfma_f32_16x16x32_bf16 v[124:127], v[154:157], v[174:177], v[124:127]
	v_mfma_f32_16x16x32_bf16 v[120:123], v[166:169], v[174:177], v[120:123]
	v_mfma_f32_16x16x32_bf16 v[116:119], v[154:157], v[188:191], v[116:119]
	v_mfma_f32_16x16x32_bf16 v[112:115], v[166:169], v[188:191], v[112:115]
	v_mfma_f32_16x16x32_bf16 v[104:107], v[154:157], v[198:201], v[104:107]
	v_mfma_f32_16x16x32_bf16 v[96:99], v[166:169], v[198:201], v[96:99]
	v_mfma_f32_16x16x32_bf16 v[88:91], v[154:157], v[206:209], v[88:91]
	v_mfma_f32_16x16x32_bf16 v[80:83], v[166:169], v[206:209], v[80:83]
	s_setprio 0
	s_barrier
	s_mov_b32 m0, s60
	ds_read_b128 v[210:213], v143
	ds_read_b128 v[214:217], v143 offset:1024
	ds_read_b128 v[218:221], v143 offset:2048
	global_load_lds_dwordx4 v130, s[36:37]
	s_mov_b32 m0, s61
	ds_read_b128 v[222:225], v143 offset:3072
	global_load_lds_dwordx4 v128, s[36:37]
	s_barrier
	s_waitcnt lgkmcnt(0)
	s_setprio 1
	v_mfma_f32_16x16x32_bf16 v[108:111], v[210:213], v[170:173], v[108:111]
	v_mfma_f32_16x16x32_bf16 v[100:103], v[218:221], v[170:173], v[100:103]
	v_mfma_f32_16x16x32_bf16 v[92:95], v[210:213], v[178:181], v[92:95]
	v_mfma_f32_16x16x32_bf16 v[84:87], v[218:221], v[178:181], v[84:87]
	v_mfma_f32_16x16x32_bf16 v[76:79], v[210:213], v[194:197], v[76:79]
	v_mfma_f32_16x16x32_bf16 v[72:75], v[218:221], v[194:197], v[72:75]
	v_mfma_f32_16x16x32_bf16 v[68:71], v[210:213], v[202:205], v[68:71]
	v_mfma_f32_16x16x32_bf16 v[64:67], v[218:221], v[202:205], v[64:67]
	v_mfma_f32_16x16x32_bf16 v[108:111], v[214:217], v[174:177], v[108:111]
	v_mfma_f32_16x16x32_bf16 v[100:103], v[222:225], v[174:177], v[100:103]
	v_mfma_f32_16x16x32_bf16 v[92:95], v[214:217], v[188:191], v[92:95]
	v_mfma_f32_16x16x32_bf16 v[84:87], v[222:225], v[188:191], v[84:87]
	v_mfma_f32_16x16x32_bf16 v[76:79], v[214:217], v[198:201], v[76:79]
	v_mfma_f32_16x16x32_bf16 v[72:75], v[222:225], v[198:201], v[72:75]
	v_mfma_f32_16x16x32_bf16 v[68:71], v[214:217], v[206:209], v[68:71]
	v_mfma_f32_16x16x32_bf16 v[64:67], v[222:225], v[206:209], v[64:67]
	s_setprio 0
	s_mov_b32 m0, s42
	s_barrier
	ds_read_b128 v[170:173], v142 offset:16384
	ds_read_b128 v[174:177], v142 offset:17408
	ds_read_b128 v[178:181], v142 offset:18432
	ds_read_b128 v[188:191], v142 offset:19456
	ds_read_b128 v[194:197], v142 offset:20480
	ds_read_b128 v[198:201], v142 offset:21504
	ds_read_b128 v[202:205], v142 offset:22528
	global_load_lds_dwordx4 v130, s[38:39]
	s_mov_b32 m0, s43
	ds_read_b128 v[206:209], v142 offset:23552
	global_load_lds_dwordx4 v128, s[38:39]
	s_barrier
	s_waitcnt lgkmcnt(0)
	s_setprio 1
	v_mfma_f32_16x16x32_bf16 v[60:63], v[150:153], v[170:173], v[60:63]
	v_mfma_f32_16x16x32_bf16 v[56:59], v[162:165], v[170:173], v[56:59]
	v_mfma_f32_16x16x32_bf16 v[52:55], v[150:153], v[178:181], v[52:55]
	v_mfma_f32_16x16x32_bf16 v[48:51], v[162:165], v[178:181], v[48:51]
	v_mfma_f32_16x16x32_bf16 v[40:43], v[150:153], v[194:197], v[40:43]
	v_mfma_f32_16x16x32_bf16 v[32:35], v[162:165], v[194:197], v[32:35]
	v_mfma_f32_16x16x32_bf16 v[24:27], v[150:153], v[202:205], v[24:27]
	v_mfma_f32_16x16x32_bf16 v[16:19], v[162:165], v[202:205], v[16:19]
	v_mfma_f32_16x16x32_bf16 v[60:63], v[154:157], v[174:177], v[60:63]
	v_mfma_f32_16x16x32_bf16 v[56:59], v[166:169], v[174:177], v[56:59]
	v_mfma_f32_16x16x32_bf16 v[52:55], v[154:157], v[188:191], v[52:55]
	v_mfma_f32_16x16x32_bf16 v[48:51], v[166:169], v[188:191], v[48:51]
	v_mfma_f32_16x16x32_bf16 v[40:43], v[154:157], v[198:201], v[40:43]
	v_mfma_f32_16x16x32_bf16 v[32:35], v[166:169], v[198:201], v[32:35]
	v_mfma_f32_16x16x32_bf16 v[24:27], v[154:157], v[206:209], v[24:27]
	v_mfma_f32_16x16x32_bf16 v[16:19], v[166:169], v[206:209], v[16:19]
	s_setprio 0
	s_barrier
	s_add_u32 s0, s36, 0x160000
	s_addc_u32 s1, s37, 0
	s_mov_b32 m0, s62
	s_nop 0
	global_load_lds_dwordx4 v130, s[0:1]
	s_mov_b32 m0, s63
	s_nop 0
	global_load_lds_dwordx4 v128, s[0:1]
	s_waitcnt vmcnt(6)
	s_barrier
; #define PG8_STAGE(bufoff, gbase, voff) do { _Pragma("unroll") for (int _i = 0; _i < 2; ++_i) \
;         __builtin_amdgcn_global_load_lds((const unsigned*)((const char*)(gbase) + (voff)[_i]), (LAS unsigned*)(lds + (bufoff) + ldsw + _i * 8192), 16, 0, 0); } while (0)
; #define PG8_LDA(dst, b, h) do { _Pragma("unroll") for (int m = 0; m < 4; ++m) _Pragma("unroll") for (int k = 0; k < 2; ++k) dst[m][k] = *(const LAS bf16x8*)(lds + PG8_SA(b, h) + aoff + m * 2048 + k * 1024); } while (0)
; #define PG8_LDB(dst, b, h) do { _Pragma("unroll") for (int n = 0; n < 2; ++n) _Pragma("unroll") for (int k = 0; k < 2; ++k) dst[n][k] = *(const LAS bf16x8*)(lds + PG8_SB(b, h) + boff + n * 2048 + k * 1024); } while (0)
; #define PG8_MMA(ai, bj, At, Bt) do { __builtin_amdgcn_s_setprio(1); _Pragma("unroll") for (int m = 0; m < 4; ++m) _Pragma("unroll") for (int n = 0; n < 2; ++n) _Pragma("unroll") for (int k = 0; k < 2; ++k) \
;         acc[ai][bj][m][n] = __builtin_amdgcn_mfma_f32_16x16x32_bf16(Bt[n][k], At[m][k], acc[ai][bj][m][n], 0, 0, 0); __builtin_amdgcn_s_setprio(0); } while (0)
; #define PG8_WAIT_V(n) asm volatile("s_waitcnt vmcnt(" #n ")" ::: "memory")
; #define PG8_WAIT_L(n) asm volatile("s_waitcnt lgkmcnt(" #n ")" ::: "memory")
; #define PG8_BAR __builtin_amdgcn_s_barrier()
; #define PG8_SCHED __builtin_amdgcn_sched_barrier(0)
; template <class Epi, class Sched>
; DI void gemm_phase(LAS unsigned char* lds, const Gemm g, const Sched& S, const Epi& E) {
;     ...
;             PG8_WAIT_V(6); PG8_BAR; PG8_MMA(1, 1, At, B1); PG8_BAR;
;             PG8_LDB(B0, 1, 0); PG8_SCHED; PG8_LDA(At, 1, 0); PG8_STAGE(PG8_SA(0, 1), a2 + hstep, voffA);
;             PG8_WAIT_L(8); PG8_BAR; PG8_WAIT_L(0); PG8_MMA(0, 0, At, B0); PG8_BAR; PG8_SCHED;
;             PG8_LDB(B1, 1, 1); PG8_STAGE(PG8_SB(1, 0), b3, voffB);
;             PG8_BAR; PG8_WAIT_L(0); PG8_MMA(0, 1, At, B1); PG8_BAR;
	s_setprio 1
	v_mfma_f32_16x16x32_bf16 v[44:47], v[210:213], v[170:173], v[44:47]
	v_mfma_f32_16x16x32_bf16 v[36:39], v[218:221], v[170:173], v[36:39]
	v_mfma_f32_16x16x32_bf16 v[28:31], v[210:213], v[178:181], v[28:31]
	v_mfma_f32_16x16x32_bf16 v[20:23], v[218:221], v[178:181], v[20:23]
	v_mfma_f32_16x16x32_bf16 v[12:15], v[210:213], v[194:197], v[12:15]
	v_mfma_f32_16x16x32_bf16 v[8:11], v[218:221], v[194:197], v[8:11]
	v_mfma_f32_16x16x32_bf16 v[4:7], v[210:213], v[202:205], v[4:7]
	v_mfma_f32_16x16x32_bf16 v[0:3], v[218:221], v[202:205], v[0:3]
	v_mfma_f32_16x16x32_bf16 v[44:47], v[214:217], v[174:177], v[44:47]
	v_mfma_f32_16x16x32_bf16 v[36:39], v[222:225], v[174:177], v[36:39]
	v_mfma_f32_16x16x32_bf16 v[28:31], v[214:217], v[188:191], v[28:31]
	v_mfma_f32_16x16x32_bf16 v[20:23], v[222:225], v[188:191], v[20:23]
	v_mfma_f32_16x16x32_bf16 v[12:15], v[214:217], v[198:201], v[12:15]
	v_mfma_f32_16x16x32_bf16 v[8:11], v[222:225], v[198:201], v[8:11]
	v_mfma_f32_16x16x32_bf16 v[4:7], v[214:217], v[206:209], v[4:7]
	v_mfma_f32_16x16x32_bf16 v[0:3], v[222:225], v[206:209], v[0:3]
	s_setprio 0
	s_barrier
	ds_read_b128 v[150:153], v144
	ds_read_b128 v[154:157], v144 offset:1024
	ds_read_b128 v[162:165], v144 offset:2048
	ds_read_b128 v[166:169], v144 offset:3072
	s_add_u32 s0, s38, 0x160000
	s_addc_u32 s1, s39, 0
	s_mov_b32 m0, s44
	ds_read_b128 v[170:173], v142 offset:32768
	ds_read_b128 v[174:177], v142 offset:33792
	ds_read_b128 v[178:181], v142 offset:34816
	ds_read_b128 v[188:191], v142 offset:35840
	ds_read_b128 v[194:197], v142 offset:36864
	ds_read_b128 v[198:201], v142 offset:37888
	ds_read_b128 v[202:205], v142 offset:38912
	global_load_lds_dwordx4 v130, s[0:1]
	s_mov_b32 m0, s45
	ds_read_b128 v[206:209], v142 offset:39936
	global_load_lds_dwordx4 v128, s[0:1]
	s_waitcnt lgkmcnt(8)
	s_barrier
	s_waitcnt lgkmcnt(0)
	s_setprio 1
	v_mfma_f32_16x16x32_bf16 v[124:127], v[150:153], v[170:173], v[124:127]
	v_mfma_f32_16x16x32_bf16 v[120:123], v[162:165], v[170:173], v[120:123]
	v_mfma_f32_16x16x32_bf16 v[116:119], v[150:153], v[178:181], v[116:119]
	v_mfma_f32_16x16x32_bf16 v[112:115], v[162:165], v[178:181], v[112:115]
	v_mfma_f32_16x16x32_bf16 v[104:107], v[150:153], v[194:197], v[104:107]
	v_mfma_f32_16x16x32_bf16 v[96:99], v[162:165], v[194:197], v[96:99]
	v_mfma_f32_16x16x32_bf16 v[88:91], v[150:153], v[202:205], v[88:91]
	v_mfma_f32_16x16x32_bf16 v[80:83], v[162:165], v[202:205], v[80:83]
	v_mfma_f32_16x16x32_bf16 v[124:127], v[154:157], v[174:177], v[124:127]
	v_mfma_f32_16x16x32_bf16 v[120:123], v[166:169], v[174:177], v[120:123]
	v_mfma_f32_16x16x32_bf16 v[116:119], v[154:157], v[188:191], v[116:119]
	v_mfma_f32_16x16x32_bf16 v[112:115], v[166:169], v[188:191], v[112:115]
	v_mfma_f32_16x16x32_bf16 v[104:107], v[154:157], v[198:201], v[104:107]
	v_mfma_f32_16x16x32_bf16 v[96:99], v[166:169], v[198:201], v[96:99]
	v_mfma_f32_16x16x32_bf16 v[88:91], v[154:157], v[206:209], v[88:91]
	v_mfma_f32_16x16x32_bf16 v[80:83], v[166:169], v[206:209], v[80:83]
	s_setprio 0
	s_barrier
	s_add_i32 s4, 0, 0x1c000
	s_add_i32 s0, s64, s35
	v_add_u32_e32 v145, s4, v140
	s_add_i32 m0, s0, 0xffffff80
	ds_read_b128 v[210:213], v145
	ds_read_b128 v[214:217], v145 offset:1024
	ds_read_b128 v[218:221], v145 offset:2048
	global_load_lds_dwordx4 v130, s[36:37] offset:128
	s_add_i32 m0, s0, 0x1f80
	ds_read_b128 v[222:225], v145 offset:3072
	global_load_lds_dwordx4 v128, s[36:37] offset:128
	s_barrier
; #define PG8_STAGE(bufoff, gbase, voff) do { _Pragma("unroll") for (int _i = 0; _i < 2; ++_i) \
;         __builtin_amdgcn_global_load_lds((const unsigned*)((const char*)(gbase) + (voff)[_i]), (LAS unsigned*)(lds + (bufoff) + ldsw + _i * 8192), 16, 0, 0); } while (0)
; #define PG8_LDA(dst, b, h) do { _Pragma("unroll") for (int m = 0; m < 4; ++m) _Pragma("unroll") for (int k = 0; k < 2; ++k) dst[m][k] = *(const LAS bf16x8*)(lds + PG8_SA(b, h) + aoff + m * 2048 + k * 1024); } while (0)
; #define PG8_MMA(ai, bj, At, Bt) do { __builtin_amdgcn_s_setprio(1); _Pragma("unroll") for (int m = 0; m < 4; ++m) _Pragma("unroll") for (int n = 0; n < 2; ++n) _Pragma("unroll") for (int k = 0; k < 2; ++k) \
;         acc[ai][bj][m][n] = __builtin_amdgcn_mfma_f32_16x16x32_bf16(Bt[n][k], At[m][k], acc[ai][bj][m][n], 0, 0, 0); __builtin_amdgcn_s_setprio(0); } while (0)
; #define PG8_WAIT_V(n) asm volatile("s_waitcnt vmcnt(" #n ")" ::: "memory")
; #define PG8_WAIT_L(n) asm volatile("s_waitcnt lgkmcnt(" #n ")" ::: "memory")
; #define PG8_BAR __builtin_amdgcn_s_barrier()
; #define PG8_SCHED __builtin_amdgcn_sched_barrier(0)
; template <class Epi, class Sched>
; DI void gemm_phase(LAS unsigned char* lds, const Gemm g, const Sched& S, const Epi& E) {
;     ...
;             PG8_LDA(At, 1, 1); PG8_STAGE(PG8_SA(1, 0), a3, voffA);
;             PG8_BAR; PG8_WAIT_L(0); PG8_MMA(1, 0, At, B0); PG8_BAR; PG8_SCHED;
;             PG8_STAGE(PG8_SB(1, 1), b3 + hstep, voffB);
;             PG8_WAIT_V(6); PG8_BAR; PG8_MMA(1, 1, At, B1); PG8_BAR;
	s_waitcnt lgkmcnt(0)
	s_setprio 1
	v_mfma_f32_16x16x32_bf16 v[108:111], v[210:213], v[170:173], v[108:111]
	v_mfma_f32_16x16x32_bf16 v[100:103], v[218:221], v[170:173], v[100:103]
	v_mfma_f32_16x16x32_bf16 v[92:95], v[210:213], v[178:181], v[92:95]
	v_mfma_f32_16x16x32_bf16 v[84:87], v[218:221], v[178:181], v[84:87]
	v_mfma_f32_16x16x32_bf16 v[76:79], v[210:213], v[194:197], v[76:79]
	v_mfma_f32_16x16x32_bf16 v[72:75], v[218:221], v[194:197], v[72:75]
	v_mfma_f32_16x16x32_bf16 v[68:71], v[210:213], v[202:205], v[68:71]
	v_mfma_f32_16x16x32_bf16 v[64:67], v[218:221], v[202:205], v[64:67]
	v_mfma_f32_16x16x32_bf16 v[108:111], v[214:217], v[174:177], v[108:111]
	v_mfma_f32_16x16x32_bf16 v[100:103], v[222:225], v[174:177], v[100:103]
	v_mfma_f32_16x16x32_bf16 v[92:95], v[214:217], v[188:191], v[92:95]
	v_mfma_f32_16x16x32_bf16 v[84:87], v[222:225], v[188:191], v[84:87]
	v_mfma_f32_16x16x32_bf16 v[76:79], v[214:217], v[198:201], v[76:79]
	v_mfma_f32_16x16x32_bf16 v[72:75], v[222:225], v[198:201], v[72:75]
	v_mfma_f32_16x16x32_bf16 v[68:71], v[214:217], v[206:209], v[68:71]
	v_mfma_f32_16x16x32_bf16 v[64:67], v[222:225], v[206:209], v[64:67]
	s_setprio 0
	s_add_i32 m0, s56, 0xffffff80
	s_barrier
	ds_read_b128 v[170:173], v142 offset:49152
	ds_read_b128 v[174:177], v142 offset:50176
	ds_read_b128 v[178:181], v142 offset:51200
	ds_read_b128 v[188:191], v142 offset:52224
	ds_read_b128 v[194:197], v142 offset:53248
	ds_read_b128 v[198:201], v142 offset:54272
	ds_read_b128 v[202:205], v142 offset:55296
	global_load_lds_dwordx4 v130, s[38:39] offset:128
	s_add_i32 m0, s57, 0xffffff80
	ds_read_b128 v[206:209], v142 offset:56320
	global_load_lds_dwordx4 v128, s[38:39] offset:128
	s_barrier
	s_waitcnt lgkmcnt(0)
	s_setprio 1
	v_mfma_f32_16x16x32_bf16 v[60:63], v[150:153], v[170:173], v[60:63]
	v_mfma_f32_16x16x32_bf16 v[56:59], v[162:165], v[170:173], v[56:59]
	v_mfma_f32_16x16x32_bf16 v[52:55], v[150:153], v[178:181], v[52:55]
	v_mfma_f32_16x16x32_bf16 v[48:51], v[162:165], v[178:181], v[48:51]
	v_mfma_f32_16x16x32_bf16 v[40:43], v[150:153], v[194:197], v[40:43]
	v_mfma_f32_16x16x32_bf16 v[32:35], v[162:165], v[194:197], v[32:35]
	v_mfma_f32_16x16x32_bf16 v[24:27], v[150:153], v[202:205], v[24:27]
	v_mfma_f32_16x16x32_bf16 v[16:19], v[162:165], v[202:205], v[16:19]
	v_mfma_f32_16x16x32_bf16 v[60:63], v[154:157], v[174:177], v[60:63]
	v_mfma_f32_16x16x32_bf16 v[56:59], v[166:169], v[174:177], v[56:59]
	v_mfma_f32_16x16x32_bf16 v[52:55], v[154:157], v[188:191], v[52:55]
	v_mfma_f32_16x16x32_bf16 v[48:51], v[166:169], v[188:191], v[48:51]
	v_mfma_f32_16x16x32_bf16 v[40:43], v[154:157], v[198:201], v[40:43]
	v_mfma_f32_16x16x32_bf16 v[32:35], v[166:169], v[198:201], v[32:35]
	v_mfma_f32_16x16x32_bf16 v[24:27], v[154:157], v[206:209], v[24:27]
	v_mfma_f32_16x16x32_bf16 v[16:19], v[166:169], v[206:209], v[16:19]
	s_setprio 0
	s_barrier
	s_add_i32 s4, s4, s35
	s_mov_b32 m0, s4
	s_add_u32 s0, s36, 0x160080
	s_addc_u32 s1, s37, 0
	global_load_lds_dwordx4 v130, s[0:1]
	s_add_i32 m0, s4, 0x2000
	s_nop 0
	global_load_lds_dwordx4 v128, s[0:1]
	s_add_i32 s68, s68, 2
	s_add_u32 s8, s8, 0x100
	s_addc_u32 s9, s9, 0
	s_add_u32 s66, s66, 0x100
	s_addc_u32 s67, s67, 0
	s_cmp_gt_u32 s68, 5
	s_waitcnt vmcnt(6)
	s_barrier
	s_setprio 1
	v_mfma_f32_16x16x32_bf16 v[44:47], v[210:213], v[170:173], v[44:47]
	v_mfma_f32_16x16x32_bf16 v[36:39], v[218:221], v[170:173], v[36:39]
	v_mfma_f32_16x16x32_bf16 v[28:31], v[210:213], v[178:181], v[28:31]
	v_mfma_f32_16x16x32_bf16 v[20:23], v[218:221], v[178:181], v[20:23]
	v_mfma_f32_16x16x32_bf16 v[12:15], v[210:213], v[194:197], v[12:15]
	v_mfma_f32_16x16x32_bf16 v[8:11], v[218:221], v[194:197], v[8:11]
	v_mfma_f32_16x16x32_bf16 v[4:7], v[210:213], v[202:205], v[4:7]
	v_mfma_f32_16x16x32_bf16 v[0:3], v[218:221], v[202:205], v[0:3]
	v_mfma_f32_16x16x32_bf16 v[44:47], v[214:217], v[174:177], v[44:47]
	v_mfma_f32_16x16x32_bf16 v[36:39], v[222:225], v[174:177], v[36:39]
	v_mfma_f32_16x16x32_bf16 v[28:31], v[214:217], v[188:191], v[28:31]
	v_mfma_f32_16x16x32_bf16 v[20:23], v[222:225], v[188:191], v[20:23]
	v_mfma_f32_16x16x32_bf16 v[12:15], v[214:217], v[198:201], v[12:15]
	v_mfma_f32_16x16x32_bf16 v[8:11], v[222:225], v[198:201], v[8:11]
	v_mfma_f32_16x16x32_bf16 v[4:7], v[214:217], v[206:209], v[4:7]
	v_mfma_f32_16x16x32_bf16 v[0:3], v[222:225], v[206:209], v[0:3]
	s_setprio 0
	s_cbranch_scc0 .Lrot_326
	s_barrier

;     DI size_t aoff(const Unit& u, size_t tstep) const { return (size_t)u.pm * tstep; }
;     DI size_t boff(const Unit& u, size_t tstep) const { return (size_t)u.pn * tstep; }
;     DI bool next(int i, Unit& u) const { const long L = (long)i * G + c; if (L >= np) return false; u.pm = pmv; u.pn = (int)(L % nN); u.ks = (int)(L / nN); return true; }
;     DI size_t aoff(const Unit& u, size_t) const { return (size_t)u.ks * kbytes; }
;     DI size_t boff(const Unit& u, size_t tstep) const { return (size_t)u.pn * tstep + (size_t)u.ks * kbytes; }
;     DI bool next(int i, Unit& u) const { Unit t; if (!S.next(i / 3, t)) return false; u.pm = t.pm; u.pn = t.pn; u.ks = i % 3; return true; }
;     DI size_t aoff(const Unit& u, size_t tstep) const { return (u.ks < 2 ? offU : offOA) + (size_t)u.pm * tstep; }
; #define PG8_LDA(dst, b, h) do { _Pragma("unroll") for (int m = 0; m < 4; ++m) _Pragma("unroll") for (int k = 0; k < 2; ++k) dst[m][k] = *(const LAS bf16x8*)(lds + PG8_SA(b, h) + aoff + m * 2048 + k * 1024); } while (0)
; template <class Epi, class Sched>
; DI void gemm_phase(LAS unsigned char* lds, const Gemm g, const Sched& S, const Epi& E) {
;     ...
;         const bool has_next = S.next(ui + 1, nxt);
;         const char* nA = has_next ? (const char*)g.A + S.aoff(nxt, tstep) : cA; const char* nB = has_next ? (const char*)g.Bt + S.boff(nxt, tstep) : cB;
;         for (int t = 0; t < nt; t += 2) {
;             if constexpr (Epi::HAS_MID) { if (t == E.mid_t(nt)) { int fr3 = fr, fq3 = fq; asm volatile("" : "+v"(fr3), "+v"(fq3)); E.mid(acc, cur, wr, wc, fr3, fq3); } }
;             const bool last = (t == nt - 2);
;             const char* a1 = cA + (size_t)(t + 1) * kstep;
;             const char* a2 = last ? nA : cA + (size_t)(t + 2) * kstep; const char* b2 = last ? nB : cB + (size_t)(t + 2) * kstep;
;             const char* a3 = a2 + kstep; const char* b3 = b2 + kstep;
;             PG8_LDB(B0, 0, 0); PG8_SCHED; PG8_LDA(At, 0, 0); PG8_STAGE(PG8_SA(1, 1), a1 + hstep, voffA);
;             PG8_WAIT_L(8); PG8_BAR; PG8_WAIT_L(0); PG8_MMA(0, 0, At, B0); PG8_BAR; PG8_SCHED;
;             PG8_LDB(B1, 0, 1); PG8_STAGE(PG8_SB(0, 0), b2, voffB);
;             PG8_BAR; PG8_WAIT_L(0); PG8_MMA(0, 1, At, B1); PG8_BAR;
;             PG8_LDA(At, 0, 1); PG8_STAGE(PG8_SA(0, 0), a2, voffA);
;             PG8_BAR; PG8_WAIT_L(0); PG8_MMA(1, 0, At, B0); PG8_BAR; PG8_SCHED;
.LBB0_526:
	s_ashr_i32 s51, s50, 31
	s_lshl_b64 s[0:1], s[50:51], 20
	s_add_u32 s52, s70, s0
	v_cmp_lt_i64_e32 vcc, s[12:13], v[142:143]
	s_addc_u32 s53, s71, s1
	s_and_b64 s[0:1], vcc, exec
	s_cselect_b32 s14, s53, s9
	s_cselect_b32 s15, s52, s8
	s_ashr_i32 s49, s48, 31
	s_lshl_b64 s[0:1], s[48:49], 20
	s_add_u32 s54, s72, s0
	s_addc_u32 s55, s73, s1
	s_and_b64 s[0:1], vcc, exec
	s_cselect_b32 s16, s55, s11
	s_cselect_b32 s17, s54, s10
	s_add_u32 s8, s8, 0x80080
	s_addc_u32 s9, s9, 0
	s_add_u32 s28, s10, 0x100
	v_mov_b32_e32 v0, 0
	s_addc_u32 s34, s11, 0
	s_mov_b32 s35, -2
	ds_read_b128 v[146:149], v164
	ds_read_b128 v[150:153], v164 offset:1024
	ds_read_b128 v[154:157], v164 offset:2048
	ds_read_b128 v[170:173], v164 offset:3072
	s_add_i32 m0, s59, 0xc000
	ds_read_b128 v[174:177], v165
	ds_read_b128 v[178:181], v165 offset:1024
	ds_read_b128 v[188:191], v165 offset:2048
	ds_read_b128 v[194:197], v165 offset:3072
	ds_read_b128 v[198:201], v165 offset:4096
	ds_read_b128 v[202:205], v165 offset:5120
	ds_read_b128 v[206:209], v165 offset:6144
	global_load_lds_dwordx4 v138, s[8:9]
	s_add_i32 m0, s59, 0xe000
	ds_read_b128 v[210:213], v165 offset:7168
	global_load_lds_dwordx4 v140, s[8:9]
	s_add_u32 s0, s8, 0xfff80080
	s_addc_u32 s1, s9, -1
	s_cmp_eq_u32 s35, 28
	s_cselect_b32 s13, s14, s1
	s_cselect_b32 s12, s15, s0
	s_cselect_b32 s11, s16, s34
	s_cselect_b32 s10, s17, s28
	s_waitcnt lgkmcnt(8)
	s_barrier
	s_waitcnt lgkmcnt(0)
	s_setprio 1
	v_mfma_f32_16x16x32_bf16 v[124:127], v[146:149], v[174:177], 0
	v_mfma_f32_16x16x32_bf16 v[120:123], v[154:157], v[174:177], 0
	v_mfma_f32_16x16x32_bf16 v[108:111], v[146:149], v[188:191], 0
	v_mfma_f32_16x16x32_bf16 v[104:107], v[154:157], v[188:191], 0
	v_mfma_f32_16x16x32_bf16 v[92:95], v[146:149], v[198:201], 0
	v_mfma_f32_16x16x32_bf16 v[88:91], v[154:157], v[198:201], 0
	v_mfma_f32_16x16x32_bf16 v[76:79], v[146:149], v[206:209], 0
	v_mfma_f32_16x16x32_bf16 v[72:75], v[154:157], v[206:209], 0
	v_mfma_f32_16x16x32_bf16 v[124:127], v[150:153], v[178:181], v[124:127]
	v_mfma_f32_16x16x32_bf16 v[120:123], v[170:173], v[178:181], v[120:123]
	v_mfma_f32_16x16x32_bf16 v[108:111], v[150:153], v[194:197], v[108:111]
	v_mfma_f32_16x16x32_bf16 v[104:107], v[170:173], v[194:197], v[104:107]
	v_mfma_f32_16x16x32_bf16 v[92:95], v[150:153], v[202:205], v[92:95]
	v_mfma_f32_16x16x32_bf16 v[88:91], v[170:173], v[202:205], v[88:91]
	v_mfma_f32_16x16x32_bf16 v[76:79], v[150:153], v[210:213], v[76:79]
	v_mfma_f32_16x16x32_bf16 v[72:75], v[170:173], v[210:213], v[72:75]
	s_setprio 0
	s_barrier
	s_add_i32 s0, s47, s74
	s_mov_b32 m0, s0
	ds_read_b128 v[214:217], v166
	ds_read_b128 v[218:221], v166 offset:1024
	ds_read_b128 v[222:225], v166 offset:2048
	global_load_lds_dwordx4 v130, s[10:11]
	s_add_i32 m0, s0, 0x2000
	ds_read_b128 v[226:229], v166 offset:3072
	global_load_lds_dwordx4 v134, s[10:11]
	s_barrier
	s_waitcnt lgkmcnt(0)
	s_setprio 1
	v_mfma_f32_16x16x32_bf16 v[116:119], v[214:217], v[174:177], 0
	v_mfma_f32_16x16x32_bf16 v[112:115], v[222:225], v[174:177], 0
	v_mfma_f32_16x16x32_bf16 v[100:103], v[214:217], v[188:191], 0
	v_mfma_f32_16x16x32_bf16 v[96:99], v[222:225], v[188:191], 0
	v_mfma_f32_16x16x32_bf16 v[84:87], v[214:217], v[198:201], 0
	v_mfma_f32_16x16x32_bf16 v[80:83], v[222:225], v[198:201], 0
	v_mfma_f32_16x16x32_bf16 v[68:71], v[214:217], v[206:209], 0
	v_mfma_f32_16x16x32_bf16 v[64:67], v[222:225], v[206:209], 0
	v_mfma_f32_16x16x32_bf16 v[116:119], v[218:221], v[178:181], v[116:119]
	v_mfma_f32_16x16x32_bf16 v[112:115], v[226:229], v[178:181], v[112:115]
	v_mfma_f32_16x16x32_bf16 v[100:103], v[218:221], v[194:197], v[100:103]
	v_mfma_f32_16x16x32_bf16 v[96:99], v[226:229], v[194:197], v[96:99]
	v_mfma_f32_16x16x32_bf16 v[84:87], v[218:221], v[202:205], v[84:87]
	v_mfma_f32_16x16x32_bf16 v[80:83], v[226:229], v[202:205], v[80:83]
	v_mfma_f32_16x16x32_bf16 v[68:71], v[218:221], v[210:213], v[68:71]
	v_mfma_f32_16x16x32_bf16 v[64:67], v[226:229], v[210:213], v[64:67]
	s_setprio 0
	s_mov_b32 m0, s59
	s_barrier
	ds_read_b128 v[174:177], v165 offset:16384
	ds_read_b128 v[178:181], v165 offset:17408
	ds_read_b128 v[188:191], v165 offset:18432
	ds_read_b128 v[194:197], v165 offset:19456
	ds_read_b128 v[198:201], v165 offset:20480
	ds_read_b128 v[202:205], v165 offset:21504
	ds_read_b128 v[206:209], v165 offset:22528
	global_load_lds_dwordx4 v128, s[12:13]
	s_mov_b32 m0, s75
	ds_read_b128 v[210:213], v165 offset:23552
	global_load_lds_dwordx4 v132, s[12:13]
	s_barrier
	s_waitcnt lgkmcnt(0)
	s_setprio 1
	v_mfma_f32_16x16x32_bf16 v[60:63], v[146:149], v[174:177], 0
	v_mfma_f32_16x16x32_bf16 v[56:59], v[154:157], v[174:177], 0
	v_mfma_f32_16x16x32_bf16 v[44:47], v[146:149], v[188:191], 0
	v_mfma_f32_16x16x32_bf16 v[40:43], v[154:157], v[188:191], 0
	v_mfma_f32_16x16x32_bf16 v[28:31], v[146:149], v[198:201], 0
	v_mfma_f32_16x16x32_bf16 v[24:27], v[154:157], v[198:201], 0
	v_mfma_f32_16x16x32_bf16 v[12:15], v[146:149], v[206:209], 0
	v_mfma_f32_16x16x32_bf16 v[8:11], v[154:157], v[206:209], 0
	v_mfma_f32_16x16x32_bf16 v[60:63], v[150:153], v[178:181], v[60:63]
	v_mfma_f32_16x16x32_bf16 v[56:59], v[170:173], v[178:181], v[56:59]
	v_mfma_f32_16x16x32_bf16 v[44:47], v[150:153], v[194:197], v[44:47]
	v_mfma_f32_16x16x32_bf16 v[40:43], v[170:173], v[194:197], v[40:43]
	v_mfma_f32_16x16x32_bf16 v[28:31], v[150:153], v[202:205], v[28:31]
	v_mfma_f32_16x16x32_bf16 v[24:27], v[170:173], v[202:205], v[24:27]
	v_mfma_f32_16x16x32_bf16 v[12:15], v[150:153], v[210:213], v[12:15]
	v_mfma_f32_16x16x32_bf16 v[8:11], v[170:173], v[210:213], v[8:11]
	s_setprio 0
	s_barrier
; #define PG8_STAGE(bufoff, gbase, voff) do { _Pragma("unroll") for (int _i = 0; _i < 2; ++_i) \
;         __builtin_amdgcn_global_load_lds((const unsigned*)((const char*)(gbase) + (voff)[_i]), (LAS unsigned*)(lds + (bufoff) + ldsw + _i * 8192), 16, 0, 0); } while (0)
; #define PG8_LDA(dst, b, h) do { _Pragma("unroll") for (int m = 0; m < 4; ++m) _Pragma("unroll") for (int k = 0; k < 2; ++k) dst[m][k] = *(const LAS bf16x8*)(lds + PG8_SA(b, h) + aoff + m * 2048 + k * 1024); } while (0)
; #define PG8_LDB(dst, b, h) do { _Pragma("unroll") for (int n = 0; n < 2; ++n) _Pragma("unroll") for (int k = 0; k < 2; ++k) dst[n][k] = *(const LAS bf16x8*)(lds + PG8_SB(b, h) + boff + n * 2048 + k * 1024); } while (0)
; #define PG8_MMA(ai, bj, At, Bt) do { __builtin_amdgcn_s_setprio(1); _Pragma("unroll") for (int m = 0; m < 4; ++m) _Pragma("unroll") for (int n = 0; n < 2; ++n) _Pragma("unroll") for (int k = 0; k < 2; ++k) \
;         acc[ai][bj][m][n] = __builtin_amdgcn_mfma_f32_16x16x32_bf16(Bt[n][k], At[m][k], acc[ai][bj][m][n], 0, 0, 0); __builtin_amdgcn_s_setprio(0); } while (0)
; #define PG8_WAIT_V(n) asm volatile("s_waitcnt vmcnt(" #n ")" ::: "memory")
; #define PG8_WAIT_L(n) asm volatile("s_waitcnt lgkmcnt(" #n ")" ::: "memory")
; #define PG8_BAR __builtin_amdgcn_s_barrier()
; #define PG8_SCHED __builtin_amdgcn_sched_barrier(0)
; template <class Epi, class Sched>
; DI void gemm_phase(LAS unsigned char* lds, const Gemm g, const Sched& S, const Epi& E) {
;     ...
;             PG8_STAGE(PG8_SB(0, 1), b2 + hstep, voffB);
;             PG8_WAIT_V(6); PG8_BAR; PG8_MMA(1, 1, At, B1); PG8_BAR;
;             PG8_LDB(B0, 1, 0); PG8_SCHED; PG8_LDA(At, 1, 0); PG8_STAGE(PG8_SA(0, 1), a2 + hstep, voffA);
;             PG8_WAIT_L(8); PG8_BAR; PG8_WAIT_L(0); PG8_MMA(0, 0, At, B0); PG8_BAR; PG8_SCHED;
;             PG8_LDB(B1, 1, 1); PG8_STAGE(PG8_SB(1, 0), b3, voffB);
;             PG8_BAR; PG8_WAIT_L(0); PG8_MMA(0, 1, At, B1); PG8_BAR;
	s_add_i32 s4, s87, s74
	s_mov_b32 m0, s4
	s_add_u32 s0, s10, 0x80000
	s_addc_u32 s1, s11, 0
	global_load_lds_dwordx4 v130, s[0:1]
	s_add_i32 m0, s4, 0x2000
	s_nop 0
	global_load_lds_dwordx4 v134, s[0:1]
	s_waitcnt vmcnt(6)
	s_barrier
	s_setprio 1
	v_mfma_f32_16x16x32_bf16 v[52:55], v[214:217], v[174:177], 0
	v_mfma_f32_16x16x32_bf16 v[48:51], v[222:225], v[174:177], 0
	v_mfma_f32_16x16x32_bf16 v[36:39], v[214:217], v[188:191], 0
	v_mfma_f32_16x16x32_bf16 v[32:35], v[222:225], v[188:191], 0
	v_mfma_f32_16x16x32_bf16 v[20:23], v[214:217], v[198:201], 0
	v_mfma_f32_16x16x32_bf16 v[16:19], v[222:225], v[198:201], 0
	v_mfma_f32_16x16x32_bf16 v[4:7], v[214:217], v[206:209], 0
	v_mfma_f32_16x16x32_bf16 v[0:3], v[222:225], v[206:209], 0
	v_mfma_f32_16x16x32_bf16 v[52:55], v[218:221], v[178:181], v[52:55]
	v_mfma_f32_16x16x32_bf16 v[48:51], v[226:229], v[178:181], v[48:51]
	v_mfma_f32_16x16x32_bf16 v[36:39], v[218:221], v[194:197], v[36:39]
	v_mfma_f32_16x16x32_bf16 v[32:35], v[226:229], v[194:197], v[32:35]
	v_mfma_f32_16x16x32_bf16 v[20:23], v[218:221], v[202:205], v[20:23]
	v_mfma_f32_16x16x32_bf16 v[16:19], v[226:229], v[202:205], v[16:19]
	v_mfma_f32_16x16x32_bf16 v[4:7], v[218:221], v[210:213], v[4:7]
	v_mfma_f32_16x16x32_bf16 v[0:3], v[226:229], v[210:213], v[0:3]
	s_setprio 0
	s_add_i32 s4, 0, 0x18000
	v_add_u32_e32 v158, s4, v163
	s_barrier
	ds_read_b128 v[146:149], v158
	ds_read_b128 v[150:153], v158 offset:1024
	ds_read_b128 v[154:157], v158 offset:2048
	ds_read_b128 v[170:173], v158 offset:3072
	s_add_u32 s0, s12, 0x80000
	s_addc_u32 s1, s13, 0
	s_mov_b32 m0, s76
	ds_read_b128 v[174:177], v165 offset:32768
	ds_read_b128 v[178:181], v165 offset:33792
	ds_read_b128 v[188:191], v165 offset:34816
	ds_read_b128 v[194:197], v165 offset:35840
	ds_read_b128 v[198:201], v165 offset:36864
	ds_read_b128 v[202:205], v165 offset:37888
	ds_read_b128 v[206:209], v165 offset:38912
	global_load_lds_dwordx4 v128, s[0:1]
	s_mov_b32 m0, s77
	ds_read_b128 v[210:213], v165 offset:39936
	global_load_lds_dwordx4 v132, s[0:1]
	s_waitcnt lgkmcnt(8)
	s_barrier
	s_waitcnt lgkmcnt(0)
	s_setprio 1
	v_mfma_f32_16x16x32_bf16 v[124:127], v[146:149], v[174:177], v[124:127]
	v_mfma_f32_16x16x32_bf16 v[120:123], v[154:157], v[174:177], v[120:123]
	v_mfma_f32_16x16x32_bf16 v[108:111], v[146:149], v[188:191], v[108:111]
	v_mfma_f32_16x16x32_bf16 v[104:107], v[154:157], v[188:191], v[104:107]
	v_mfma_f32_16x16x32_bf16 v[92:95], v[146:149], v[198:201], v[92:95]
	v_mfma_f32_16x16x32_bf16 v[88:91], v[154:157], v[198:201], v[88:91]
	v_mfma_f32_16x16x32_bf16 v[76:79], v[146:149], v[206:209], v[76:79]
	v_mfma_f32_16x16x32_bf16 v[72:75], v[154:157], v[206:209], v[72:75]
	v_mfma_f32_16x16x32_bf16 v[124:127], v[150:153], v[178:181], v[124:127]
	v_mfma_f32_16x16x32_bf16 v[120:123], v[170:173], v[178:181], v[120:123]
	v_mfma_f32_16x16x32_bf16 v[108:111], v[150:153], v[194:197], v[108:111]
	v_mfma_f32_16x16x32_bf16 v[104:107], v[170:173], v[194:197], v[104:107]
	v_mfma_f32_16x16x32_bf16 v[92:95], v[150:153], v[202:205], v[92:95]
	v_mfma_f32_16x16x32_bf16 v[88:91], v[170:173], v[202:205], v[88:91]
	v_mfma_f32_16x16x32_bf16 v[76:79], v[150:153], v[210:213], v[76:79]
	v_mfma_f32_16x16x32_bf16 v[72:75], v[170:173], v[210:213], v[72:75]
	s_setprio 0
	s_barrier
	s_add_i32 s5, 0, 0x1c000
	s_add_i32 s0, s4, s74
	v_add_u32_e32 v159, s5, v163
	s_add_i32 m0, s0, 0xffffff80
	ds_read_b128 v[214:217], v159
	ds_read_b128 v[218:221], v159 offset:1024
	ds_read_b128 v[222:225], v159 offset:2048
	global_load_lds_dwordx4 v130, s[10:11] offset:128
	s_add_i32 m0, s0, 0x1f80
	ds_read_b128 v[226:229], v159 offset:3072
	global_load_lds_dwordx4 v134, s[10:11] offset:128
	s_barrier
; #define PG8_STAGE(bufoff, gbase, voff) do { _Pragma("unroll") for (int _i = 0; _i < 2; ++_i) \
;         __builtin_amdgcn_global_load_lds((const unsigned*)((const char*)(gbase) + (voff)[_i]), (LAS unsigned*)(lds + (bufoff) + ldsw + _i * 8192), 16, 0, 0); } while (0)
; #define PG8_LDA(dst, b, h) do { _Pragma("unroll") for (int m = 0; m < 4; ++m) _Pragma("unroll") for (int k = 0; k < 2; ++k) dst[m][k] = *(const LAS bf16x8*)(lds + PG8_SA(b, h) + aoff + m * 2048 + k * 1024); } while (0)
; #define PG8_MMA(ai, bj, At, Bt) do { __builtin_amdgcn_s_setprio(1); _Pragma("unroll") for (int m = 0; m < 4; ++m) _Pragma("unroll") for (int n = 0; n < 2; ++n) _Pragma("unroll") for (int k = 0; k < 2; ++k) \
;         acc[ai][bj][m][n] = __builtin_amdgcn_mfma_f32_16x16x32_bf16(Bt[n][k], At[m][k], acc[ai][bj][m][n], 0, 0, 0); __builtin_amdgcn_s_setprio(0); } while (0)
; #define PG8_WAIT_V(n) asm volatile("s_waitcnt vmcnt(" #n ")" ::: "memory")
; #define PG8_WAIT_L(n) asm volatile("s_waitcnt lgkmcnt(" #n ")" ::: "memory")
; #define PG8_BAR __builtin_amdgcn_s_barrier()
; #define PG8_SCHED __builtin_amdgcn_sched_barrier(0)
; template <class Epi, class Sched>
; DI void gemm_phase(LAS unsigned char* lds, const Gemm g, const Sched& S, const Epi& E) {
;     ...
;             PG8_LDA(At, 1, 1); PG8_STAGE(PG8_SA(1, 0), a3, voffA);
;             PG8_BAR; PG8_WAIT_L(0); PG8_MMA(1, 0, At, B0); PG8_BAR; PG8_SCHED;
;             PG8_STAGE(PG8_SB(1, 1), b3 + hstep, voffB);
;             PG8_WAIT_V(6); PG8_BAR; PG8_MMA(1, 1, At, B1); PG8_BAR;
	s_waitcnt lgkmcnt(0)
	s_setprio 1
	v_mfma_f32_16x16x32_bf16 v[116:119], v[214:217], v[174:177], v[116:119]
	v_mfma_f32_16x16x32_bf16 v[112:115], v[222:225], v[174:177], v[112:115]
	v_mfma_f32_16x16x32_bf16 v[100:103], v[214:217], v[188:191], v[100:103]
	v_mfma_f32_16x16x32_bf16 v[96:99], v[222:225], v[188:191], v[96:99]
	v_mfma_f32_16x16x32_bf16 v[84:87], v[214:217], v[198:201], v[84:87]
	v_mfma_f32_16x16x32_bf16 v[80:83], v[222:225], v[198:201], v[80:83]
	v_mfma_f32_16x16x32_bf16 v[68:71], v[214:217], v[206:209], v[68:71]
	v_mfma_f32_16x16x32_bf16 v[64:67], v[222:225], v[206:209], v[64:67]
	v_mfma_f32_16x16x32_bf16 v[116:119], v[218:221], v[178:181], v[116:119]
	v_mfma_f32_16x16x32_bf16 v[112:115], v[226:229], v[178:181], v[112:115]
	v_mfma_f32_16x16x32_bf16 v[100:103], v[218:221], v[194:197], v[100:103]
	v_mfma_f32_16x16x32_bf16 v[96:99], v[226:229], v[194:197], v[96:99]
	v_mfma_f32_16x16x32_bf16 v[84:87], v[218:221], v[202:205], v[84:87]
	v_mfma_f32_16x16x32_bf16 v[80:83], v[226:229], v[202:205], v[80:83]
	v_mfma_f32_16x16x32_bf16 v[68:71], v[218:221], v[210:213], v[68:71]
	v_mfma_f32_16x16x32_bf16 v[64:67], v[226:229], v[210:213], v[64:67]
	s_setprio 0
	s_add_i32 m0, s97, 0xffffff80
	s_barrier
	ds_read_b128 v[174:177], v165 offset:49152
	ds_read_b128 v[178:181], v165 offset:50176
	ds_read_b128 v[188:191], v165 offset:51200
	ds_read_b128 v[194:197], v165 offset:52224
	ds_read_b128 v[198:201], v165 offset:53248
	ds_read_b128 v[202:205], v165 offset:54272
	ds_read_b128 v[206:209], v165 offset:55296
	global_load_lds_dwordx4 v128, s[12:13] offset:128
	s_add_i32 m0, s84, 0xffffff80
	ds_read_b128 v[210:213], v165 offset:56320
	global_load_lds_dwordx4 v132, s[12:13] offset:128
	s_barrier
	s_waitcnt lgkmcnt(0)
	s_setprio 1
	v_mfma_f32_16x16x32_bf16 v[60:63], v[146:149], v[174:177], v[60:63]
	v_mfma_f32_16x16x32_bf16 v[56:59], v[154:157], v[174:177], v[56:59]
	v_mfma_f32_16x16x32_bf16 v[44:47], v[146:149], v[188:191], v[44:47]
	v_mfma_f32_16x16x32_bf16 v[40:43], v[154:157], v[188:191], v[40:43]
	v_mfma_f32_16x16x32_bf16 v[28:31], v[146:149], v[198:201], v[28:31]
	v_mfma_f32_16x16x32_bf16 v[24:27], v[154:157], v[198:201], v[24:27]
	v_mfma_f32_16x16x32_bf16 v[12:15], v[146:149], v[206:209], v[12:15]
	v_mfma_f32_16x16x32_bf16 v[8:11], v[154:157], v[206:209], v[8:11]
	v_mfma_f32_16x16x32_bf16 v[60:63], v[150:153], v[178:181], v[60:63]
	v_mfma_f32_16x16x32_bf16 v[56:59], v[170:173], v[178:181], v[56:59]
	v_mfma_f32_16x16x32_bf16 v[44:47], v[150:153], v[194:197], v[44:47]
	v_mfma_f32_16x16x32_bf16 v[40:43], v[170:173], v[194:197], v[40:43]
	v_mfma_f32_16x16x32_bf16 v[28:31], v[150:153], v[202:205], v[28:31]
	v_mfma_f32_16x16x32_bf16 v[24:27], v[170:173], v[202:205], v[24:27]
	v_mfma_f32_16x16x32_bf16 v[12:15], v[150:153], v[210:213], v[12:15]
	v_mfma_f32_16x16x32_bf16 v[8:11], v[170:173], v[210:213], v[8:11]
	s_setprio 0
	s_barrier
	s_add_i32 s4, s5, s74
	s_mov_b32 m0, s4
	s_add_u32 s0, s10, 0x80080
	s_addc_u32 s1, s11, 0
	global_load_lds_dwordx4 v130, s[0:1]
	v_lshl_add_u64 v[146:147], s[0:1], 0, v[134:135]
	s_add_i32 m0, s4, 0x2000
	s_nop 0
	global_load_lds_dwordx4 v134, s[0:1]
	s_add_i32 s35, s35, 2
	s_add_u32 s8, s8, 0x100
	s_addc_u32 s9, s9, 0
	s_add_u32 s28, s28, 0x100
	s_addc_u32 s34, s34, 0
	s_cmp_gt_u32 s35, 29
	s_waitcnt vmcnt(6)
	s_barrier
	s_setprio 1
	v_mfma_f32_16x16x32_bf16 v[52:55], v[214:217], v[174:177], v[52:55]
	v_mfma_f32_16x16x32_bf16 v[48:51], v[222:225], v[174:177], v[48:51]
	v_mfma_f32_16x16x32_bf16 v[36:39], v[214:217], v[188:191], v[36:39]
	v_mfma_f32_16x16x32_bf16 v[32:35], v[222:225], v[188:191], v[32:35]
	v_mfma_f32_16x16x32_bf16 v[20:23], v[214:217], v[198:201], v[20:23]
	v_mfma_f32_16x16x32_bf16 v[16:19], v[222:225], v[198:201], v[16:19]
	v_mfma_f32_16x16x32_bf16 v[4:7], v[214:217], v[206:209], v[4:7]
	v_mfma_f32_16x16x32_bf16 v[0:3], v[222:225], v[206:209], v[0:3]
	v_mfma_f32_16x16x32_bf16 v[52:55], v[218:221], v[178:181], v[52:55]
	v_mfma_f32_16x16x32_bf16 v[48:51], v[226:229], v[178:181], v[48:51]
	v_mfma_f32_16x16x32_bf16 v[36:39], v[218:221], v[194:197], v[36:39]
	v_mfma_f32_16x16x32_bf16 v[32:35], v[226:229], v[194:197], v[32:35]
	v_mfma_f32_16x16x32_bf16 v[20:23], v[218:221], v[202:205], v[20:23]
	v_mfma_f32_16x16x32_bf16 v[16:19], v[226:229], v[202:205], v[16:19]
	v_mfma_f32_16x16x32_bf16 v[4:7], v[218:221], v[210:213], v[4:7]
	v_mfma_f32_16x16x32_bf16 v[0:3], v[226:229], v[210:213], v[0:3]
	s_setprio 0
	s_cbranch_scc0 .Lrot_527
	s_barrier
	s_branch .Lpeel_done_527

; #define PG8_STAGE(bufoff, gbase, voff) do { _Pragma("unroll") for (int _i = 0; _i < 2; ++_i) \
;         __builtin_amdgcn_global_load_lds((const unsigned*)((const char*)(gbase) + (voff)[_i]), (LAS unsigned*)(lds + (bufoff) + ldsw + _i * 8192), 16, 0, 0); } while (0)
; #define PG8_LDA(dst, b, h) do { _Pragma("unroll") for (int m = 0; m < 4; ++m) _Pragma("unroll") for (int k = 0; k < 2; ++k) dst[m][k] = *(const LAS bf16x8*)(lds + PG8_SA(b, h) + aoff + m * 2048 + k * 1024); } while (0)
; #define PG8_LDB(dst, b, h) do { _Pragma("unroll") for (int n = 0; n < 2; ++n) _Pragma("unroll") for (int k = 0; k < 2; ++k) dst[n][k] = *(const LAS bf16x8*)(lds + PG8_SB(b, h) + boff + n * 2048 + k * 1024); } while (0)
; #define PG8_MMA(ai, bj, At, Bt) do { __builtin_amdgcn_s_setprio(1); _Pragma("unroll") for (int m = 0; m < 4; ++m) _Pragma("unroll") for (int n = 0; n < 2; ++n) _Pragma("unroll") for (int k = 0; k < 2; ++k) \
;         acc[ai][bj][m][n] = __builtin_amdgcn_mfma_f32_16x16x32_bf16(Bt[n][k], At[m][k], acc[ai][bj][m][n], 0, 0, 0); __builtin_amdgcn_s_setprio(0); } while (0)
; #define PG8_WAIT_V(n) asm volatile("s_waitcnt vmcnt(" #n ")" ::: "memory")
; #define PG8_WAIT_L(n) asm volatile("s_waitcnt lgkmcnt(" #n ")" ::: "memory")
; #define PG8_BAR __builtin_amdgcn_s_barrier()
; #define PG8_SCHED __builtin_amdgcn_sched_barrier(0)
; template <class Epi, class Sched>
; DI void gemm_phase(LAS unsigned char* lds, const Gemm g, const Sched& S, const Epi& E) {
;     ...
;             const char* a2 = last ? nA : cA + (size_t)(t + 2) * kstep; const char* b2 = last ? nB : cB + (size_t)(t + 2) * kstep;
;             const char* a3 = a2 + kstep; const char* b3 = b2 + kstep;
;             PG8_LDB(B0, 0, 0); PG8_SCHED; PG8_LDA(At, 0, 0); PG8_STAGE(PG8_SA(1, 1), a1 + hstep, voffA);
;             PG8_WAIT_L(8); PG8_BAR; PG8_WAIT_L(0); PG8_MMA(0, 0, At, B0); PG8_BAR; PG8_SCHED;
;             PG8_LDB(B1, 0, 1); PG8_STAGE(PG8_SB(0, 0), b2, voffB);
;             PG8_BAR; PG8_WAIT_L(0); PG8_MMA(0, 1, At, B1); PG8_BAR;
;             PG8_LDA(At, 0, 1); PG8_STAGE(PG8_SA(0, 0), a2, voffA);
;             PG8_BAR; PG8_WAIT_L(0); PG8_MMA(1, 0, At, B0); PG8_BAR; PG8_SCHED;
;             PG8_STAGE(PG8_SB(0, 1), b2 + hstep, voffB);
;             PG8_WAIT_V(6); PG8_BAR; PG8_MMA(1, 1, At, B1); PG8_BAR;
.LBB0_527:
	ds_read_b128 v[146:149], v164
	ds_read_b128 v[150:153], v164 offset:1024
	ds_read_b128 v[154:157], v164 offset:2048
	ds_read_b128 v[170:173], v164 offset:3072
	s_add_i32 m0, s59, 0xc000
	ds_read_b128 v[174:177], v165
	ds_read_b128 v[178:181], v165 offset:1024
	ds_read_b128 v[188:191], v165 offset:2048
	ds_read_b128 v[194:197], v165 offset:3072
	ds_read_b128 v[198:201], v165 offset:4096
	ds_read_b128 v[202:205], v165 offset:5120
	ds_read_b128 v[206:209], v165 offset:6144
	global_load_lds_dwordx4 v138, s[8:9]
	s_add_i32 m0, s59, 0xe000
	ds_read_b128 v[210:213], v165 offset:7168
	global_load_lds_dwordx4 v140, s[8:9]
	s_add_u32 s0, s8, 0xfff80080
	s_addc_u32 s1, s9, -1
	s_cmp_eq_u32 s35, 28
	s_cselect_b32 s13, s14, s1
	s_cselect_b32 s12, s15, s0
	s_cselect_b32 s11, s16, s34
	s_cselect_b32 s10, s17, s28
	s_waitcnt lgkmcnt(8)
	s_barrier
	s_waitcnt lgkmcnt(0)
	s_setprio 1
	v_mfma_f32_16x16x32_bf16 v[124:127], v[146:149], v[174:177], v[124:127]
	v_mfma_f32_16x16x32_bf16 v[120:123], v[154:157], v[174:177], v[120:123]
	v_mfma_f32_16x16x32_bf16 v[108:111], v[146:149], v[188:191], v[108:111]
	v_mfma_f32_16x16x32_bf16 v[104:107], v[154:157], v[188:191], v[104:107]
	v_mfma_f32_16x16x32_bf16 v[92:95], v[146:149], v[198:201], v[92:95]
	v_mfma_f32_16x16x32_bf16 v[88:91], v[154:157], v[198:201], v[88:91]
	v_mfma_f32_16x16x32_bf16 v[76:79], v[146:149], v[206:209], v[76:79]
	v_mfma_f32_16x16x32_bf16 v[72:75], v[154:157], v[206:209], v[72:75]
	v_mfma_f32_16x16x32_bf16 v[124:127], v[150:153], v[178:181], v[124:127]
	v_mfma_f32_16x16x32_bf16 v[120:123], v[170:173], v[178:181], v[120:123]
	v_mfma_f32_16x16x32_bf16 v[108:111], v[150:153], v[194:197], v[108:111]
	v_mfma_f32_16x16x32_bf16 v[104:107], v[170:173], v[194:197], v[104:107]
	v_mfma_f32_16x16x32_bf16 v[92:95], v[150:153], v[202:205], v[92:95]
	v_mfma_f32_16x16x32_bf16 v[88:91], v[170:173], v[202:205], v[88:91]
	v_mfma_f32_16x16x32_bf16 v[76:79], v[150:153], v[210:213], v[76:79]
	v_mfma_f32_16x16x32_bf16 v[72:75], v[170:173], v[210:213], v[72:75]
	s_setprio 0
	s_barrier
	s_add_i32 s0, s47, s74
	s_mov_b32 m0, s0
	ds_read_b128 v[214:217], v166
	ds_read_b128 v[218:221], v166 offset:1024
	ds_read_b128 v[222:225], v166 offset:2048
	global_load_lds_dwordx4 v130, s[10:11]
	s_add_i32 m0, s0, 0x2000
	ds_read_b128 v[226:229], v166 offset:3072
	global_load_lds_dwordx4 v134, s[10:11]
	s_barrier
	s_waitcnt lgkmcnt(0)
	s_setprio 1
	v_mfma_f32_16x16x32_bf16 v[116:119], v[214:217], v[174:177], v[116:119]
	v_mfma_f32_16x16x32_bf16 v[112:115], v[222:225], v[174:177], v[112:115]
	v_mfma_f32_16x16x32_bf16 v[100:103], v[214:217], v[188:191], v[100:103]
	v_mfma_f32_16x16x32_bf16 v[96:99], v[222:225], v[188:191], v[96:99]
	v_mfma_f32_16x16x32_bf16 v[84:87], v[214:217], v[198:201], v[84:87]
	v_mfma_f32_16x16x32_bf16 v[80:83], v[222:225], v[198:201], v[80:83]
	v_mfma_f32_16x16x32_bf16 v[68:71], v[214:217], v[206:209], v[68:71]
	v_mfma_f32_16x16x32_bf16 v[64:67], v[222:225], v[206:209], v[64:67]
	v_mfma_f32_16x16x32_bf16 v[116:119], v[218:221], v[178:181], v[116:119]
	v_mfma_f32_16x16x32_bf16 v[112:115], v[226:229], v[178:181], v[112:115]
	v_mfma_f32_16x16x32_bf16 v[100:103], v[218:221], v[194:197], v[100:103]
	v_mfma_f32_16x16x32_bf16 v[96:99], v[226:229], v[194:197], v[96:99]
	v_mfma_f32_16x16x32_bf16 v[84:87], v[218:221], v[202:205], v[84:87]
	v_mfma_f32_16x16x32_bf16 v[80:83], v[226:229], v[202:205], v[80:83]
	v_mfma_f32_16x16x32_bf16 v[68:71], v[218:221], v[210:213], v[68:71]
	v_mfma_f32_16x16x32_bf16 v[64:67], v[226:229], v[210:213], v[64:67]
	s_setprio 0
	s_mov_b32 m0, s59
	s_barrier
	ds_read_b128 v[174:177], v165 offset:16384
	ds_read_b128 v[178:181], v165 offset:17408
	ds_read_b128 v[188:191], v165 offset:18432
	ds_read_b128 v[194:197], v165 offset:19456
	ds_read_b128 v[198:201], v165 offset:20480
	ds_read_b128 v[202:205], v165 offset:21504
	ds_read_b128 v[206:209], v165 offset:22528
	global_load_lds_dwordx4 v128, s[12:13]
	s_mov_b32 m0, s75
	ds_read_b128 v[210:213], v165 offset:23552
	global_load_lds_dwordx4 v132, s[12:13]
	s_barrier
	s_waitcnt lgkmcnt(0)
	s_setprio 1
	v_mfma_f32_16x16x32_bf16 v[60:63], v[146:149], v[174:177], v[60:63]
	v_mfma_f32_16x16x32_bf16 v[56:59], v[154:157], v[174:177], v[56:59]
	v_mfma_f32_16x16x32_bf16 v[44:47], v[146:149], v[188:191], v[44:47]
	v_mfma_f32_16x16x32_bf16 v[40:43], v[154:157], v[188:191], v[40:43]
	v_mfma_f32_16x16x32_bf16 v[28:31], v[146:149], v[198:201], v[28:31]
	v_mfma_f32_16x16x32_bf16 v[24:27], v[154:157], v[198:201], v[24:27]
	v_mfma_f32_16x16x32_bf16 v[12:15], v[146:149], v[206:209], v[12:15]
	v_mfma_f32_16x16x32_bf16 v[8:11], v[154:157], v[206:209], v[8:11]
	v_mfma_f32_16x16x32_bf16 v[60:63], v[150:153], v[178:181], v[60:63]
	v_mfma_f32_16x16x32_bf16 v[56:59], v[170:173], v[178:181], v[56:59]
	v_mfma_f32_16x16x32_bf16 v[44:47], v[150:153], v[194:197], v[44:47]
	v_mfma_f32_16x16x32_bf16 v[40:43], v[170:173], v[194:197], v[40:43]
	v_mfma_f32_16x16x32_bf16 v[28:31], v[150:153], v[202:205], v[28:31]
	v_mfma_f32_16x16x32_bf16 v[24:27], v[170:173], v[202:205], v[24:27]
	v_mfma_f32_16x16x32_bf16 v[12:15], v[150:153], v[210:213], v[12:15]
	v_mfma_f32_16x16x32_bf16 v[8:11], v[170:173], v[210:213], v[8:11]
	s_setprio 0
	s_barrier
	s_add_i32 s4, s87, s74
	s_mov_b32 m0, s4
	s_add_u32 s0, s10, 0x80000
	s_addc_u32 s1, s11, 0
	global_load_lds_dwordx4 v130, s[0:1]
	s_add_i32 m0, s4, 0x2000
	s_nop 0
	global_load_lds_dwordx4 v134, s[0:1]
	s_waitcnt vmcnt(6)
	s_barrier
; #define PG8_STAGE(bufoff, gbase, voff) do { _Pragma("unroll") for (int _i = 0; _i < 2; ++_i) \
;         __builtin_amdgcn_global_load_lds((const unsigned*)((const char*)(gbase) + (voff)[_i]), (LAS unsigned*)(lds + (bufoff) + ldsw + _i * 8192), 16, 0, 0); } while (0)
; #define PG8_LDA(dst, b, h) do { _Pragma("unroll") for (int m = 0; m < 4; ++m) _Pragma("unroll") for (int k = 0; k < 2; ++k) dst[m][k] = *(const LAS bf16x8*)(lds + PG8_SA(b, h) + aoff + m * 2048 + k * 1024); } while (0)
; #define PG8_LDB(dst, b, h) do { _Pragma("unroll") for (int n = 0; n < 2; ++n) _Pragma("unroll") for (int k = 0; k < 2; ++k) dst[n][k] = *(const LAS bf16x8*)(lds + PG8_SB(b, h) + boff + n * 2048 + k * 1024); } while (0)
; #define PG8_MMA(ai, bj, At, Bt) do { __builtin_amdgcn_s_setprio(1); _Pragma("unroll") for (int m = 0; m < 4; ++m) _Pragma("unroll") for (int n = 0; n < 2; ++n) _Pragma("unroll") for (int k = 0; k < 2; ++k) \
;         acc[ai][bj][m][n] = __builtin_amdgcn_mfma_f32_16x16x32_bf16(Bt[n][k], At[m][k], acc[ai][bj][m][n], 0, 0, 0); __builtin_amdgcn_s_setprio(0); } while (0)
; #define PG8_WAIT_V(n) asm volatile("s_waitcnt vmcnt(" #n ")" ::: "memory")
; #define PG8_WAIT_L(n) asm volatile("s_waitcnt lgkmcnt(" #n ")" ::: "memory")
; #define PG8_BAR __builtin_amdgcn_s_barrier()
; #define PG8_SCHED __builtin_amdgcn_sched_barrier(0)
; template <class Epi, class Sched>
; DI void gemm_phase(LAS unsigned char* lds, const Gemm g, const Sched& S, const Epi& E) {
;     ...
;             PG8_WAIT_V(6); PG8_BAR; PG8_MMA(1, 1, At, B1); PG8_BAR;
;             PG8_LDB(B0, 1, 0); PG8_SCHED; PG8_LDA(At, 1, 0); PG8_STAGE(PG8_SA(0, 1), a2 + hstep, voffA);
;             PG8_WAIT_L(8); PG8_BAR; PG8_WAIT_L(0); PG8_MMA(0, 0, At, B0); PG8_BAR; PG8_SCHED;
;             PG8_LDB(B1, 1, 1); PG8_STAGE(PG8_SB(1, 0), b3, voffB);
;             PG8_BAR; PG8_WAIT_L(0); PG8_MMA(0, 1, At, B1); PG8_BAR;
	s_setprio 1
	v_mfma_f32_16x16x32_bf16 v[52:55], v[214:217], v[174:177], v[52:55]
	v_mfma_f32_16x16x32_bf16 v[48:51], v[222:225], v[174:177], v[48:51]
	v_mfma_f32_16x16x32_bf16 v[36:39], v[214:217], v[188:191], v[36:39]
	v_mfma_f32_16x16x32_bf16 v[32:35], v[222:225], v[188:191], v[32:35]
	v_mfma_f32_16x16x32_bf16 v[20:23], v[214:217], v[198:201], v[20:23]
	v_mfma_f32_16x16x32_bf16 v[16:19], v[222:225], v[198:201], v[16:19]
	v_mfma_f32_16x16x32_bf16 v[4:7], v[214:217], v[206:209], v[4:7]
	v_mfma_f32_16x16x32_bf16 v[0:3], v[222:225], v[206:209], v[0:3]
	v_mfma_f32_16x16x32_bf16 v[52:55], v[218:221], v[178:181], v[52:55]
	v_mfma_f32_16x16x32_bf16 v[48:51], v[226:229], v[178:181], v[48:51]
	v_mfma_f32_16x16x32_bf16 v[36:39], v[218:221], v[194:197], v[36:39]
	v_mfma_f32_16x16x32_bf16 v[32:35], v[226:229], v[194:197], v[32:35]
	v_mfma_f32_16x16x32_bf16 v[20:23], v[218:221], v[202:205], v[20:23]
	v_mfma_f32_16x16x32_bf16 v[16:19], v[226:229], v[202:205], v[16:19]
	v_mfma_f32_16x16x32_bf16 v[4:7], v[218:221], v[210:213], v[4:7]
	v_mfma_f32_16x16x32_bf16 v[0:3], v[226:229], v[210:213], v[0:3]
	s_setprio 0
	s_add_i32 s4, 0, 0x18000
	s_barrier
	ds_read_b128 v[146:149], v158
	ds_read_b128 v[150:153], v158 offset:1024
	ds_read_b128 v[154:157], v158 offset:2048
	ds_read_b128 v[170:173], v158 offset:3072
	s_add_u32 s0, s12, 0x80000
	s_addc_u32 s1, s13, 0
	s_mov_b32 m0, s76
	ds_read_b128 v[174:177], v165 offset:32768
	ds_read_b128 v[178:181], v165 offset:33792
	ds_read_b128 v[188:191], v165 offset:34816
	ds_read_b128 v[194:197], v165 offset:35840
	ds_read_b128 v[198:201], v165 offset:36864
	ds_read_b128 v[202:205], v165 offset:37888
	ds_read_b128 v[206:209], v165 offset:38912
	global_load_lds_dwordx4 v128, s[0:1]
	s_mov_b32 m0, s77
	ds_read_b128 v[210:213], v165 offset:39936
	global_load_lds_dwordx4 v132, s[0:1]
	s_waitcnt lgkmcnt(8)
	s_barrier
	s_waitcnt lgkmcnt(0)
	s_setprio 1
	v_mfma_f32_16x16x32_bf16 v[124:127], v[146:149], v[174:177], v[124:127]
	v_mfma_f32_16x16x32_bf16 v[120:123], v[154:157], v[174:177], v[120:123]
	v_mfma_f32_16x16x32_bf16 v[108:111], v[146:149], v[188:191], v[108:111]
	v_mfma_f32_16x16x32_bf16 v[104:107], v[154:157], v[188:191], v[104:107]
	v_mfma_f32_16x16x32_bf16 v[92:95], v[146:149], v[198:201], v[92:95]
	v_mfma_f32_16x16x32_bf16 v[88:91], v[154:157], v[198:201], v[88:91]
	v_mfma_f32_16x16x32_bf16 v[76:79], v[146:149], v[206:209], v[76:79]
	v_mfma_f32_16x16x32_bf16 v[72:75], v[154:157], v[206:209], v[72:75]
	v_mfma_f32_16x16x32_bf16 v[124:127], v[150:153], v[178:181], v[124:127]
	v_mfma_f32_16x16x32_bf16 v[120:123], v[170:173], v[178:181], v[120:123]
	v_mfma_f32_16x16x32_bf16 v[108:111], v[150:153], v[194:197], v[108:111]
	v_mfma_f32_16x16x32_bf16 v[104:107], v[170:173], v[194:197], v[104:107]
	v_mfma_f32_16x16x32_bf16 v[92:95], v[150:153], v[202:205], v[92:95]
	v_mfma_f32_16x16x32_bf16 v[88:91], v[170:173], v[202:205], v[88:91]
	v_mfma_f32_16x16x32_bf16 v[76:79], v[150:153], v[210:213], v[76:79]
	v_mfma_f32_16x16x32_bf16 v[72:75], v[170:173], v[210:213], v[72:75]
	s_setprio 0
	s_barrier
	s_add_i32 s5, 0, 0x1c000
	s_add_i32 s0, s4, s74
	s_add_i32 m0, s0, 0xffffff80
	ds_read_b128 v[214:217], v159
	ds_read_b128 v[218:221], v159 offset:1024
	ds_read_b128 v[222:225], v159 offset:2048
	global_load_lds_dwordx4 v130, s[10:11] offset:128
	s_add_i32 m0, s0, 0x1f80
	ds_read_b128 v[226:229], v159 offset:3072
	global_load_lds_dwordx4 v134, s[10:11] offset:128
	s_barrier
; #define PG8_STAGE(bufoff, gbase, voff) do { _Pragma("unroll") for (int _i = 0; _i < 2; ++_i) \
;         __builtin_amdgcn_global_load_lds((const unsigned*)((const char*)(gbase) + (voff)[_i]), (LAS unsigned*)(lds + (bufoff) + ldsw + _i * 8192), 16, 0, 0); } while (0)
; #define PG8_LDA(dst, b, h) do { _Pragma("unroll") for (int m = 0; m < 4; ++m) _Pragma("unroll") for (int k = 0; k < 2; ++k) dst[m][k] = *(const LAS bf16x8*)(lds + PG8_SA(b, h) + aoff + m * 2048 + k * 1024); } while (0)
; #define PG8_MMA(ai, bj, At, Bt) do { __builtin_amdgcn_s_setprio(1); _Pragma("unroll") for (int m = 0; m < 4; ++m) _Pragma("unroll") for (int n = 0; n < 2; ++n) _Pragma("unroll") for (int k = 0; k < 2; ++k) \
;         acc[ai][bj][m][n] = __builtin_amdgcn_mfma_f32_16x16x32_bf16(Bt[n][k], At[m][k], acc[ai][bj][m][n], 0, 0, 0); __builtin_amdgcn_s_setprio(0); } while (0)
; #define PG8_WAIT_V(n) asm volatile("s_waitcnt vmcnt(" #n ")" ::: "memory")
; #define PG8_WAIT_L(n) asm volatile("s_waitcnt lgkmcnt(" #n ")" ::: "memory")
; #define PG8_BAR __builtin_amdgcn_s_barrier()
; #define PG8_SCHED __builtin_amdgcn_sched_barrier(0)
; template <class Epi, class Sched>
; DI void gemm_phase(LAS unsigned char* lds, const Gemm g, const Sched& S, const Epi& E) {
;     ...
;             PG8_LDA(At, 1, 1); PG8_STAGE(PG8_SA(1, 0), a3, voffA);
;             PG8_BAR; PG8_WAIT_L(0); PG8_MMA(1, 0, At, B0); PG8_BAR; PG8_SCHED;
;             PG8_STAGE(PG8_SB(1, 1), b3 + hstep, voffB);
;             PG8_WAIT_V(6); PG8_BAR; PG8_MMA(1, 1, At, B1); PG8_BAR;
	s_waitcnt lgkmcnt(0)
	s_setprio 1
	v_mfma_f32_16x16x32_bf16 v[116:119], v[214:217], v[174:177], v[116:119]
	v_mfma_f32_16x16x32_bf16 v[112:115], v[222:225], v[174:177], v[112:115]
	v_mfma_f32_16x16x32_bf16 v[100:103], v[214:217], v[188:191], v[100:103]
	v_mfma_f32_16x16x32_bf16 v[96:99], v[222:225], v[188:191], v[96:99]
	v_mfma_f32_16x16x32_bf16 v[84:87], v[214:217], v[198:201], v[84:87]
	v_mfma_f32_16x16x32_bf16 v[80:83], v[222:225], v[198:201], v[80:83]
	v_mfma_f32_16x16x32_bf16 v[68:71], v[214:217], v[206:209], v[68:71]
	v_mfma_f32_16x16x32_bf16 v[64:67], v[222:225], v[206:209], v[64:67]
	v_mfma_f32_16x16x32_bf16 v[116:119], v[218:221], v[178:181], v[116:119]
	v_mfma_f32_16x16x32_bf16 v[112:115], v[226:229], v[178:181], v[112:115]
	v_mfma_f32_16x16x32_bf16 v[100:103], v[218:221], v[194:197], v[100:103]
	v_mfma_f32_16x16x32_bf16 v[96:99], v[226:229], v[194:197], v[96:99]
	v_mfma_f32_16x16x32_bf16 v[84:87], v[218:221], v[202:205], v[84:87]
	v_mfma_f32_16x16x32_bf16 v[80:83], v[226:229], v[202:205], v[80:83]
	v_mfma_f32_16x16x32_bf16 v[68:71], v[218:221], v[210:213], v[68:71]
	v_mfma_f32_16x16x32_bf16 v[64:67], v[226:229], v[210:213], v[64:67]
	s_setprio 0
	s_add_i32 m0, s97, 0xffffff80
	s_barrier
	ds_read_b128 v[174:177], v165 offset:49152
	ds_read_b128 v[178:181], v165 offset:50176
	ds_read_b128 v[188:191], v165 offset:51200
	ds_read_b128 v[194:197], v165 offset:52224
	ds_read_b128 v[198:201], v165 offset:53248
	ds_read_b128 v[202:205], v165 offset:54272
	ds_read_b128 v[206:209], v165 offset:55296
	global_load_lds_dwordx4 v128, s[12:13] offset:128
	s_add_i32 m0, s84, 0xffffff80
	ds_read_b128 v[210:213], v165 offset:56320
	global_load_lds_dwordx4 v132, s[12:13] offset:128
	s_barrier
	s_waitcnt lgkmcnt(0)
	s_setprio 1
	v_mfma_f32_16x16x32_bf16 v[60:63], v[146:149], v[174:177], v[60:63]
	v_mfma_f32_16x16x32_bf16 v[56:59], v[154:157], v[174:177], v[56:59]
	v_mfma_f32_16x16x32_bf16 v[44:47], v[146:149], v[188:191], v[44:47]
	v_mfma_f32_16x16x32_bf16 v[40:43], v[154:157], v[188:191], v[40:43]
	v_mfma_f32_16x16x32_bf16 v[28:31], v[146:149], v[198:201], v[28:31]
	v_mfma_f32_16x16x32_bf16 v[24:27], v[154:157], v[198:201], v[24:27]
	v_mfma_f32_16x16x32_bf16 v[12:15], v[146:149], v[206:209], v[12:15]
	v_mfma_f32_16x16x32_bf16 v[8:11], v[154:157], v[206:209], v[8:11]
	v_mfma_f32_16x16x32_bf16 v[60:63], v[150:153], v[178:181], v[60:63]
	v_mfma_f32_16x16x32_bf16 v[56:59], v[170:173], v[178:181], v[56:59]
	v_mfma_f32_16x16x32_bf16 v[44:47], v[150:153], v[194:197], v[44:47]
	v_mfma_f32_16x16x32_bf16 v[40:43], v[170:173], v[194:197], v[40:43]
	v_mfma_f32_16x16x32_bf16 v[28:31], v[150:153], v[202:205], v[28:31]
	v_mfma_f32_16x16x32_bf16 v[24:27], v[170:173], v[202:205], v[24:27]
	v_mfma_f32_16x16x32_bf16 v[12:15], v[150:153], v[210:213], v[12:15]
	v_mfma_f32_16x16x32_bf16 v[8:11], v[170:173], v[210:213], v[8:11]
	s_setprio 0
	s_barrier
	s_add_i32 s4, s5, s74
	s_mov_b32 m0, s4
	s_add_u32 s0, s10, 0x80080
	s_addc_u32 s1, s11, 0
	global_load_lds_dwordx4 v130, s[0:1]
	v_lshl_add_u64 v[146:147], s[0:1], 0, v[134:135]
	s_add_i32 m0, s4, 0x2000
	s_nop 0
	global_load_lds_dwordx4 v134, s[0:1]
	s_add_i32 s35, s35, 2
	s_add_u32 s8, s8, 0x100
	s_addc_u32 s9, s9, 0
	s_add_u32 s28, s28, 0x100
	s_addc_u32 s34, s34, 0
	s_cmp_gt_u32 s35, 29
	s_waitcnt vmcnt(6)
	s_barrier
	s_setprio 1
	v_mfma_f32_16x16x32_bf16 v[52:55], v[214:217], v[174:177], v[52:55]
	v_mfma_f32_16x16x32_bf16 v[48:51], v[222:225], v[174:177], v[48:51]
	v_mfma_f32_16x16x32_bf16 v[36:39], v[214:217], v[188:191], v[36:39]
	v_mfma_f32_16x16x32_bf16 v[32:35], v[222:225], v[188:191], v[32:35]
	v_mfma_f32_16x16x32_bf16 v[20:23], v[214:217], v[198:201], v[20:23]
	v_mfma_f32_16x16x32_bf16 v[16:19], v[222:225], v[198:201], v[16:19]
	v_mfma_f32_16x16x32_bf16 v[4:7], v[214:217], v[206:209], v[4:7]
	v_mfma_f32_16x16x32_bf16 v[0:3], v[222:225], v[206:209], v[0:3]
	v_mfma_f32_16x16x32_bf16 v[52:55], v[218:221], v[178:181], v[52:55]
	v_mfma_f32_16x16x32_bf16 v[48:51], v[226:229], v[178:181], v[48:51]
	v_mfma_f32_16x16x32_bf16 v[36:39], v[218:221], v[194:197], v[36:39]
	v_mfma_f32_16x16x32_bf16 v[32:35], v[226:229], v[194:197], v[32:35]
	v_mfma_f32_16x16x32_bf16 v[20:23], v[218:221], v[202:205], v[20:23]
	v_mfma_f32_16x16x32_bf16 v[16:19], v[226:229], v[202:205], v[16:19]
	v_mfma_f32_16x16x32_bf16 v[4:7], v[218:221], v[210:213], v[4:7]
	v_mfma_f32_16x16x32_bf16 v[0:3], v[226:229], v[210:213], v[0:3]
	s_setprio 0
	s_cbranch_scc0 .Lrot_527
	s_barrier

;     DI size_t aoff(const Unit& u, size_t tstep) const { return (size_t)u.pm * tstep; }
;     DI size_t boff(const Unit& u, size_t tstep) const { return (size_t)u.pn * tstep; }
;     DI bool next(int i, Unit& u) const { const long L = (long)i * G + c; if (L >= np) return false; u.pm = pmv; u.pn = (int)(L % nN); u.ks = (int)(L / nN); return true; }
;     DI size_t aoff(const Unit& u, size_t) const { return (size_t)u.ks * kbytes; }
;     DI size_t boff(const Unit& u, size_t tstep) const { return (size_t)u.pn * tstep + (size_t)u.ks * kbytes; }
;     DI bool next(int i, Unit& u) const { Unit t; if (!S.next(i / 3, t)) return false; u.pm = t.pm; u.pn = t.pn; u.ks = i % 3; return true; }
;     DI size_t aoff(const Unit& u, size_t tstep) const { return (u.ks < 2 ? offU : offOA) + (size_t)u.pm * tstep; }
; #define PG8_WAIT_V(n) asm volatile("s_waitcnt vmcnt(" #n ")" ::: "memory")
; template <class Epi, class Sched>
; DI void gemm_phase(LAS unsigned char* lds, const Gemm g, const Sched& S, const Epi& E) {
;     ...
;         const bool has_next = S.next(ui + 1, nxt);
;         const char* nA = has_next ? (const char*)g.A + S.aoff(nxt, tstep) : cA; const char* nB = has_next ? (const char*)g.Bt + S.boff(nxt, tstep) : cB;
;         for (int t = 0; t < nt; t += 2) {
;             if constexpr (Epi::HAS_MID) { if (t == E.mid_t(nt)) { int fr3 = fr, fq3 = fq; asm volatile("" : "+v"(fr3), "+v"(fq3)); E.mid(acc, cur, wr, wc, fr3, fq3); } }
;             const bool last = (t == nt - 2);
;             const char* a1 = cA + (size_t)(t + 1) * kstep;
;             const char* a2 = last ? nA : cA + (size_t)(t + 2) * kstep; const char* b2 = last ? nB : cB + (size_t)(t + 2) * kstep;
;             const char* a3 = a2 + kstep; const char* b3 = b2 + kstep;
;             PG8_LDB(B0, 0, 0); PG8_SCHED; PG8_LDA(At, 0, 0); PG8_STAGE(PG8_SA(1, 1), a1 + hstep, voffA);
;             PG8_WAIT_L(8); PG8_BAR; PG8_WAIT_L(0); PG8_MMA(0, 0, At, B0); PG8_BAR; PG8_SCHED;
;             PG8_LDB(B1, 0, 1); PG8_STAGE(PG8_SB(0, 0), b2, voffB);
;             PG8_BAR; PG8_WAIT_L(0); PG8_MMA(0, 1, At, B1); PG8_BAR;
;             PG8_LDA(At, 0, 1); PG8_STAGE(PG8_SA(0, 0), a2, voffA);
;             PG8_BAR; PG8_WAIT_L(0); PG8_MMA(1, 0, At, B0); PG8_BAR; PG8_SCHED;
;             PG8_STAGE(PG8_SB(0, 1), b2 + hstep, voffB);
;             PG8_WAIT_V(6); PG8_BAR; PG8_MMA(1, 1, At, B1); PG8_BAR;
.LBB0_937:
	s_add_u32 s8, s38, 0x30080
	s_addc_u32 s9, s39, 0
	s_add_u32 s35, s36, 0x100
	v_mov_b32_e32 v0, 0
	s_addc_u32 s40, s37, 0
	s_mov_b32 s41, -2
	ds_read_b128 v[144:147], v165
	ds_read_b128 v[168:171], v165 offset:1024
	ds_read_b128 v[172:175], v165 offset:2048
	ds_read_b128 v[176:179], v165 offset:3072
	s_add_i32 m0, s51, 0xc000
	ds_read_b128 v[180:183], v166
	ds_read_b128 v[188:191], v166 offset:1024
	ds_read_b128 v[194:197], v166 offset:2048
	ds_read_b128 v[198:201], v166 offset:3072
	ds_read_b128 v[202:205], v166 offset:4096
	ds_read_b128 v[206:209], v166 offset:5120
	ds_read_b128 v[210:213], v166 offset:6144
	global_load_lds_dwordx4 v136, s[8:9]
	s_add_i32 m0, s51, 0xe000
	ds_read_b128 v[214:217], v166 offset:7168
	global_load_lds_dwordx4 v138, s[8:9]
	s_add_u32 s0, s8, 0xfffd0080
	s_addc_u32 s1, s9, -1
	s_cmp_eq_u32 s41, 8
	s_cselect_b32 s39, s31, s1
	s_cselect_b32 s38, s30, s0
	s_cselect_b32 s37, s11, s40
	s_cselect_b32 s36, s10, s35
	s_waitcnt lgkmcnt(8)
	s_barrier
	s_waitcnt lgkmcnt(0)
	s_setprio 1
	v_mfma_f32_16x16x32_bf16 v[124:127], v[144:147], v[180:183], 0
	v_mfma_f32_16x16x32_bf16 v[120:123], v[172:175], v[180:183], 0
	v_mfma_f32_16x16x32_bf16 v[108:111], v[144:147], v[194:197], 0
	v_mfma_f32_16x16x32_bf16 v[104:107], v[172:175], v[194:197], 0
	v_mfma_f32_16x16x32_bf16 v[92:95], v[144:147], v[202:205], 0
	v_mfma_f32_16x16x32_bf16 v[88:91], v[172:175], v[202:205], 0
	v_mfma_f32_16x16x32_bf16 v[76:79], v[144:147], v[210:213], 0
	v_mfma_f32_16x16x32_bf16 v[72:75], v[172:175], v[210:213], 0
	v_mfma_f32_16x16x32_bf16 v[124:127], v[168:171], v[188:191], v[124:127]
	v_mfma_f32_16x16x32_bf16 v[120:123], v[176:179], v[188:191], v[120:123]
	v_mfma_f32_16x16x32_bf16 v[108:111], v[168:171], v[198:201], v[108:111]
	v_mfma_f32_16x16x32_bf16 v[104:107], v[176:179], v[198:201], v[104:107]
	v_mfma_f32_16x16x32_bf16 v[92:95], v[168:171], v[206:209], v[92:95]
	v_mfma_f32_16x16x32_bf16 v[88:91], v[176:179], v[206:209], v[88:91]
	v_mfma_f32_16x16x32_bf16 v[76:79], v[168:171], v[214:217], v[76:79]
	v_mfma_f32_16x16x32_bf16 v[72:75], v[176:179], v[214:217], v[72:75]
	s_setprio 0
	s_barrier
	s_add_i32 s0, s61, s50
	s_mov_b32 m0, s0
	ds_read_b128 v[218:221], v167
	ds_read_b128 v[222:225], v167 offset:1024
	ds_read_b128 v[226:229], v167 offset:2048
	global_load_lds_dwordx4 v130, s[36:37]
	s_add_i32 m0, s0, 0x2000
	ds_read_b128 v[230:233], v167 offset:3072
	global_load_lds_dwordx4 v134, s[36:37]
	s_barrier
	s_waitcnt lgkmcnt(0)
	s_setprio 1
	v_mfma_f32_16x16x32_bf16 v[116:119], v[218:221], v[180:183], 0
	v_mfma_f32_16x16x32_bf16 v[112:115], v[226:229], v[180:183], 0
	v_mfma_f32_16x16x32_bf16 v[100:103], v[218:221], v[194:197], 0
	v_mfma_f32_16x16x32_bf16 v[96:99], v[226:229], v[194:197], 0
	v_mfma_f32_16x16x32_bf16 v[84:87], v[218:221], v[202:205], 0
	v_mfma_f32_16x16x32_bf16 v[80:83], v[226:229], v[202:205], 0
	v_mfma_f32_16x16x32_bf16 v[68:71], v[218:221], v[210:213], 0
	v_mfma_f32_16x16x32_bf16 v[64:67], v[226:229], v[210:213], 0
	v_mfma_f32_16x16x32_bf16 v[116:119], v[222:225], v[188:191], v[116:119]
	v_mfma_f32_16x16x32_bf16 v[112:115], v[230:233], v[188:191], v[112:115]
	v_mfma_f32_16x16x32_bf16 v[100:103], v[222:225], v[198:201], v[100:103]
	v_mfma_f32_16x16x32_bf16 v[96:99], v[230:233], v[198:201], v[96:99]
	v_mfma_f32_16x16x32_bf16 v[84:87], v[222:225], v[206:209], v[84:87]
	v_mfma_f32_16x16x32_bf16 v[80:83], v[230:233], v[206:209], v[80:83]
	v_mfma_f32_16x16x32_bf16 v[68:71], v[222:225], v[214:217], v[68:71]
	v_mfma_f32_16x16x32_bf16 v[64:67], v[230:233], v[214:217], v[64:67]
	s_setprio 0
	s_mov_b32 m0, s51
	s_barrier
	ds_read_b128 v[180:183], v166 offset:16384
	ds_read_b128 v[188:191], v166 offset:17408
	ds_read_b128 v[194:197], v166 offset:18432
	ds_read_b128 v[198:201], v166 offset:19456
	ds_read_b128 v[202:205], v166 offset:20480
	ds_read_b128 v[206:209], v166 offset:21504
	ds_read_b128 v[210:213], v166 offset:22528
	global_load_lds_dwordx4 v128, s[38:39]
	s_mov_b32 m0, s52
	ds_read_b128 v[214:217], v166 offset:23552
	global_load_lds_dwordx4 v132, s[38:39]
	s_barrier
	s_waitcnt lgkmcnt(0)
	s_setprio 1
	v_mfma_f32_16x16x32_bf16 v[60:63], v[144:147], v[180:183], 0
	v_mfma_f32_16x16x32_bf16 v[56:59], v[172:175], v[180:183], 0
	v_mfma_f32_16x16x32_bf16 v[44:47], v[144:147], v[194:197], 0
	v_mfma_f32_16x16x32_bf16 v[40:43], v[172:175], v[194:197], 0
	v_mfma_f32_16x16x32_bf16 v[28:31], v[144:147], v[202:205], 0
	v_mfma_f32_16x16x32_bf16 v[24:27], v[172:175], v[202:205], 0
	v_mfma_f32_16x16x32_bf16 v[12:15], v[144:147], v[210:213], 0
	v_mfma_f32_16x16x32_bf16 v[8:11], v[172:175], v[210:213], 0
	v_mfma_f32_16x16x32_bf16 v[60:63], v[168:171], v[188:191], v[60:63]
	v_mfma_f32_16x16x32_bf16 v[56:59], v[176:179], v[188:191], v[56:59]
	v_mfma_f32_16x16x32_bf16 v[44:47], v[168:171], v[198:201], v[44:47]
	v_mfma_f32_16x16x32_bf16 v[40:43], v[176:179], v[198:201], v[40:43]
	v_mfma_f32_16x16x32_bf16 v[28:31], v[168:171], v[206:209], v[28:31]
	v_mfma_f32_16x16x32_bf16 v[24:27], v[176:179], v[206:209], v[24:27]
	v_mfma_f32_16x16x32_bf16 v[12:15], v[168:171], v[214:217], v[12:15]
	v_mfma_f32_16x16x32_bf16 v[8:11], v[176:179], v[214:217], v[8:11]
	s_setprio 0
	s_barrier
	s_add_i32 s4, s62, s50
	s_mov_b32 m0, s4
	s_add_u32 s0, s36, 0x30000
	s_addc_u32 s1, s37, 0
	global_load_lds_dwordx4 v130, s[0:1]
	s_add_i32 m0, s4, 0x2000
	s_nop 0
	global_load_lds_dwordx4 v134, s[0:1]
	s_waitcnt vmcnt(6)
	s_barrier
; #define PG8_STAGE(bufoff, gbase, voff) do { _Pragma("unroll") for (int _i = 0; _i < 2; ++_i) \
;         __builtin_amdgcn_global_load_lds((const unsigned*)((const char*)(gbase) + (voff)[_i]), (LAS unsigned*)(lds + (bufoff) + ldsw + _i * 8192), 16, 0, 0); } while (0)
; #define PG8_LDA(dst, b, h) do { _Pragma("unroll") for (int m = 0; m < 4; ++m) _Pragma("unroll") for (int k = 0; k < 2; ++k) dst[m][k] = *(const LAS bf16x8*)(lds + PG8_SA(b, h) + aoff + m * 2048 + k * 1024); } while (0)
; #define PG8_LDB(dst, b, h) do { _Pragma("unroll") for (int n = 0; n < 2; ++n) _Pragma("unroll") for (int k = 0; k < 2; ++k) dst[n][k] = *(const LAS bf16x8*)(lds + PG8_SB(b, h) + boff + n * 2048 + k * 1024); } while (0)
; #define PG8_MMA(ai, bj, At, Bt) do { __builtin_amdgcn_s_setprio(1); _Pragma("unroll") for (int m = 0; m < 4; ++m) _Pragma("unroll") for (int n = 0; n < 2; ++n) _Pragma("unroll") for (int k = 0; k < 2; ++k) \
;         acc[ai][bj][m][n] = __builtin_amdgcn_mfma_f32_16x16x32_bf16(Bt[n][k], At[m][k], acc[ai][bj][m][n], 0, 0, 0); __builtin_amdgcn_s_setprio(0); } while (0)
; #define PG8_WAIT_V(n) asm volatile("s_waitcnt vmcnt(" #n ")" ::: "memory")
; #define PG8_WAIT_L(n) asm volatile("s_waitcnt lgkmcnt(" #n ")" ::: "memory")
; #define PG8_BAR __builtin_amdgcn_s_barrier()
; #define PG8_SCHED __builtin_amdgcn_sched_barrier(0)
; template <class Epi, class Sched>
; DI void gemm_phase(LAS unsigned char* lds, const Gemm g, const Sched& S, const Epi& E) {
;     ...
;             PG8_WAIT_V(6); PG8_BAR; PG8_MMA(1, 1, At, B1); PG8_BAR;
;             PG8_LDB(B0, 1, 0); PG8_SCHED; PG8_LDA(At, 1, 0); PG8_STAGE(PG8_SA(0, 1), a2 + hstep, voffA);
;             PG8_WAIT_L(8); PG8_BAR; PG8_WAIT_L(0); PG8_MMA(0, 0, At, B0); PG8_BAR; PG8_SCHED;
;             PG8_LDB(B1, 1, 1); PG8_STAGE(PG8_SB(1, 0), b3, voffB);
;             PG8_BAR; PG8_WAIT_L(0); PG8_MMA(0, 1, At, B1); PG8_BAR;
	s_setprio 1
	v_mfma_f32_16x16x32_bf16 v[52:55], v[218:221], v[180:183], 0
	v_mfma_f32_16x16x32_bf16 v[48:51], v[226:229], v[180:183], 0
	v_mfma_f32_16x16x32_bf16 v[36:39], v[218:221], v[194:197], 0
	v_mfma_f32_16x16x32_bf16 v[32:35], v[226:229], v[194:197], 0
	v_mfma_f32_16x16x32_bf16 v[20:23], v[218:221], v[202:205], 0
	v_mfma_f32_16x16x32_bf16 v[16:19], v[226:229], v[202:205], 0
	v_mfma_f32_16x16x32_bf16 v[4:7], v[218:221], v[210:213], 0
	v_mfma_f32_16x16x32_bf16 v[0:3], v[226:229], v[210:213], 0
	v_mfma_f32_16x16x32_bf16 v[52:55], v[222:225], v[188:191], v[52:55]
	v_mfma_f32_16x16x32_bf16 v[48:51], v[230:233], v[188:191], v[48:51]
	v_mfma_f32_16x16x32_bf16 v[36:39], v[222:225], v[198:201], v[36:39]
	v_mfma_f32_16x16x32_bf16 v[32:35], v[230:233], v[198:201], v[32:35]
	v_mfma_f32_16x16x32_bf16 v[20:23], v[222:225], v[206:209], v[20:23]
	v_mfma_f32_16x16x32_bf16 v[16:19], v[230:233], v[206:209], v[16:19]
	v_mfma_f32_16x16x32_bf16 v[4:7], v[222:225], v[214:217], v[4:7]
	v_mfma_f32_16x16x32_bf16 v[0:3], v[230:233], v[214:217], v[0:3]
	s_setprio 0
	s_add_i32 s4, 0, 0x18000
	v_add_u32_e32 v148, s4, v164
	s_barrier
	ds_read_b128 v[144:147], v148
	ds_read_b128 v[168:171], v148 offset:1024
	ds_read_b128 v[172:175], v148 offset:2048
	ds_read_b128 v[176:179], v148 offset:3072
	s_add_u32 s0, s38, 0x30000
	s_addc_u32 s1, s39, 0
	s_mov_b32 m0, s53
	ds_read_b128 v[180:183], v166 offset:32768
	ds_read_b128 v[188:191], v166 offset:33792
	ds_read_b128 v[194:197], v166 offset:34816
	ds_read_b128 v[198:201], v166 offset:35840
	ds_read_b128 v[202:205], v166 offset:36864
	ds_read_b128 v[206:209], v166 offset:37888
	ds_read_b128 v[210:213], v166 offset:38912
	global_load_lds_dwordx4 v128, s[0:1]
	s_mov_b32 m0, s54
	ds_read_b128 v[214:217], v166 offset:39936
	global_load_lds_dwordx4 v132, s[0:1]
	s_waitcnt lgkmcnt(8)
	s_barrier
	s_waitcnt lgkmcnt(0)
	s_setprio 1
	v_mfma_f32_16x16x32_bf16 v[124:127], v[144:147], v[180:183], v[124:127]
	v_mfma_f32_16x16x32_bf16 v[120:123], v[172:175], v[180:183], v[120:123]
	v_mfma_f32_16x16x32_bf16 v[108:111], v[144:147], v[194:197], v[108:111]
	v_mfma_f32_16x16x32_bf16 v[104:107], v[172:175], v[194:197], v[104:107]
	v_mfma_f32_16x16x32_bf16 v[92:95], v[144:147], v[202:205], v[92:95]
	v_mfma_f32_16x16x32_bf16 v[88:91], v[172:175], v[202:205], v[88:91]
	v_mfma_f32_16x16x32_bf16 v[76:79], v[144:147], v[210:213], v[76:79]
	v_mfma_f32_16x16x32_bf16 v[72:75], v[172:175], v[210:213], v[72:75]
	v_mfma_f32_16x16x32_bf16 v[124:127], v[168:171], v[188:191], v[124:127]
	v_mfma_f32_16x16x32_bf16 v[120:123], v[176:179], v[188:191], v[120:123]
	v_mfma_f32_16x16x32_bf16 v[108:111], v[168:171], v[198:201], v[108:111]
	v_mfma_f32_16x16x32_bf16 v[104:107], v[176:179], v[198:201], v[104:107]
	v_mfma_f32_16x16x32_bf16 v[92:95], v[168:171], v[206:209], v[92:95]
	v_mfma_f32_16x16x32_bf16 v[88:91], v[176:179], v[206:209], v[88:91]
	v_mfma_f32_16x16x32_bf16 v[76:79], v[168:171], v[214:217], v[76:79]
	v_mfma_f32_16x16x32_bf16 v[72:75], v[176:179], v[214:217], v[72:75]
	s_setprio 0
	s_barrier
	s_add_i32 s5, 0, 0x1c000
	s_add_i32 s0, s4, s50
	v_add_u32_e32 v149, s5, v164
	s_add_i32 m0, s0, 0xffffff80
	ds_read_b128 v[218:221], v149
	ds_read_b128 v[222:225], v149 offset:1024
	ds_read_b128 v[226:229], v149 offset:2048
	global_load_lds_dwordx4 v130, s[36:37] offset:128
	s_add_i32 m0, s0, 0x1f80
	ds_read_b128 v[230:233], v149 offset:3072
	global_load_lds_dwordx4 v134, s[36:37] offset:128
	s_barrier
; #define PG8_STAGE(bufoff, gbase, voff) do { _Pragma("unroll") for (int _i = 0; _i < 2; ++_i) \
;         __builtin_amdgcn_global_load_lds((const unsigned*)((const char*)(gbase) + (voff)[_i]), (LAS unsigned*)(lds + (bufoff) + ldsw + _i * 8192), 16, 0, 0); } while (0)
; #define PG8_LDA(dst, b, h) do { _Pragma("unroll") for (int m = 0; m < 4; ++m) _Pragma("unroll") for (int k = 0; k < 2; ++k) dst[m][k] = *(const LAS bf16x8*)(lds + PG8_SA(b, h) + aoff + m * 2048 + k * 1024); } while (0)
; #define PG8_MMA(ai, bj, At, Bt) do { __builtin_amdgcn_s_setprio(1); _Pragma("unroll") for (int m = 0; m < 4; ++m) _Pragma("unroll") for (int n = 0; n < 2; ++n) _Pragma("unroll") for (int k = 0; k < 2; ++k) \
;         acc[ai][bj][m][n] = __builtin_amdgcn_mfma_f32_16x16x32_bf16(Bt[n][k], At[m][k], acc[ai][bj][m][n], 0, 0, 0); __builtin_amdgcn_s_setprio(0); } while (0)
; #define PG8_WAIT_V(n) asm volatile("s_waitcnt vmcnt(" #n ")" ::: "memory")
; #define PG8_WAIT_L(n) asm volatile("s_waitcnt lgkmcnt(" #n ")" ::: "memory")
; #define PG8_BAR __builtin_amdgcn_s_barrier()
; #define PG8_SCHED __builtin_amdgcn_sched_barrier(0)
; template <class Epi, class Sched>
; DI void gemm_phase(LAS unsigned char* lds, const Gemm g, const Sched& S, const Epi& E) {
;     ...
;             PG8_LDA(At, 1, 1); PG8_STAGE(PG8_SA(1, 0), a3, voffA);
;             PG8_BAR; PG8_WAIT_L(0); PG8_MMA(1, 0, At, B0); PG8_BAR; PG8_SCHED;
;             PG8_STAGE(PG8_SB(1, 1), b3 + hstep, voffB);
;             PG8_WAIT_V(6); PG8_BAR; PG8_MMA(1, 1, At, B1); PG8_BAR;
	s_waitcnt lgkmcnt(0)
	s_setprio 1
	v_mfma_f32_16x16x32_bf16 v[116:119], v[218:221], v[180:183], v[116:119]
	v_mfma_f32_16x16x32_bf16 v[112:115], v[226:229], v[180:183], v[112:115]
	v_mfma_f32_16x16x32_bf16 v[100:103], v[218:221], v[194:197], v[100:103]
	v_mfma_f32_16x16x32_bf16 v[96:99], v[226:229], v[194:197], v[96:99]
	v_mfma_f32_16x16x32_bf16 v[84:87], v[218:221], v[202:205], v[84:87]
	v_mfma_f32_16x16x32_bf16 v[80:83], v[226:229], v[202:205], v[80:83]
	v_mfma_f32_16x16x32_bf16 v[68:71], v[218:221], v[210:213], v[68:71]
	v_mfma_f32_16x16x32_bf16 v[64:67], v[226:229], v[210:213], v[64:67]
	v_mfma_f32_16x16x32_bf16 v[116:119], v[222:225], v[188:191], v[116:119]
	v_mfma_f32_16x16x32_bf16 v[112:115], v[230:233], v[188:191], v[112:115]
	v_mfma_f32_16x16x32_bf16 v[100:103], v[222:225], v[198:201], v[100:103]
	v_mfma_f32_16x16x32_bf16 v[96:99], v[230:233], v[198:201], v[96:99]
	v_mfma_f32_16x16x32_bf16 v[84:87], v[222:225], v[206:209], v[84:87]
	v_mfma_f32_16x16x32_bf16 v[80:83], v[230:233], v[206:209], v[80:83]
	v_mfma_f32_16x16x32_bf16 v[68:71], v[222:225], v[214:217], v[68:71]
	v_mfma_f32_16x16x32_bf16 v[64:67], v[230:233], v[214:217], v[64:67]
	s_setprio 0
	s_add_i32 m0, s57, 0xffffff80
	s_barrier
	ds_read_b128 v[180:183], v166 offset:49152
	ds_read_b128 v[188:191], v166 offset:50176
	ds_read_b128 v[194:197], v166 offset:51200
	ds_read_b128 v[198:201], v166 offset:52224
	ds_read_b128 v[202:205], v166 offset:53248
	ds_read_b128 v[206:209], v166 offset:54272
	ds_read_b128 v[210:213], v166 offset:55296
	global_load_lds_dwordx4 v128, s[38:39] offset:128
	s_add_i32 m0, s58, 0xffffff80
	ds_read_b128 v[214:217], v166 offset:56320
	global_load_lds_dwordx4 v132, s[38:39] offset:128
	s_barrier
	s_waitcnt lgkmcnt(0)
	s_setprio 1
	v_mfma_f32_16x16x32_bf16 v[60:63], v[144:147], v[180:183], v[60:63]
	v_mfma_f32_16x16x32_bf16 v[56:59], v[172:175], v[180:183], v[56:59]
	v_mfma_f32_16x16x32_bf16 v[44:47], v[144:147], v[194:197], v[44:47]
	v_mfma_f32_16x16x32_bf16 v[40:43], v[172:175], v[194:197], v[40:43]
	v_mfma_f32_16x16x32_bf16 v[28:31], v[144:147], v[202:205], v[28:31]
	v_mfma_f32_16x16x32_bf16 v[24:27], v[172:175], v[202:205], v[24:27]
	v_mfma_f32_16x16x32_bf16 v[12:15], v[144:147], v[210:213], v[12:15]
	v_mfma_f32_16x16x32_bf16 v[8:11], v[172:175], v[210:213], v[8:11]
	v_mfma_f32_16x16x32_bf16 v[60:63], v[168:171], v[188:191], v[60:63]
	v_mfma_f32_16x16x32_bf16 v[56:59], v[176:179], v[188:191], v[56:59]
	v_mfma_f32_16x16x32_bf16 v[44:47], v[168:171], v[198:201], v[44:47]
	v_mfma_f32_16x16x32_bf16 v[40:43], v[176:179], v[198:201], v[40:43]
	v_mfma_f32_16x16x32_bf16 v[28:31], v[168:171], v[206:209], v[28:31]
	v_mfma_f32_16x16x32_bf16 v[24:27], v[176:179], v[206:209], v[24:27]
	v_mfma_f32_16x16x32_bf16 v[12:15], v[168:171], v[214:217], v[12:15]
	v_mfma_f32_16x16x32_bf16 v[8:11], v[176:179], v[214:217], v[8:11]
	s_setprio 0
	s_barrier
	s_add_i32 s4, s5, s50
	s_mov_b32 m0, s4
	s_add_u32 s0, s36, 0x30080
	s_addc_u32 s1, s37, 0
	global_load_lds_dwordx4 v130, s[0:1]
	s_add_i32 m0, s4, 0x2000
	s_nop 0
	global_load_lds_dwordx4 v134, s[0:1]
	s_add_i32 s41, s41, 2
	s_add_u32 s8, s8, 0x100
	s_addc_u32 s9, s9, 0
	s_add_u32 s35, s35, 0x100
	s_addc_u32 s40, s40, 0
	s_cmp_gt_u32 s41, 9
	s_waitcnt vmcnt(6)
	s_barrier
	s_setprio 1
	v_mfma_f32_16x16x32_bf16 v[52:55], v[218:221], v[180:183], v[52:55]
	v_mfma_f32_16x16x32_bf16 v[48:51], v[226:229], v[180:183], v[48:51]
	v_mfma_f32_16x16x32_bf16 v[36:39], v[218:221], v[194:197], v[36:39]
	v_mfma_f32_16x16x32_bf16 v[32:35], v[226:229], v[194:197], v[32:35]
	v_mfma_f32_16x16x32_bf16 v[20:23], v[218:221], v[202:205], v[20:23]
	v_mfma_f32_16x16x32_bf16 v[16:19], v[226:229], v[202:205], v[16:19]
	v_mfma_f32_16x16x32_bf16 v[4:7], v[218:221], v[210:213], v[4:7]
	v_mfma_f32_16x16x32_bf16 v[0:3], v[226:229], v[210:213], v[0:3]
	v_mfma_f32_16x16x32_bf16 v[52:55], v[222:225], v[188:191], v[52:55]
	v_mfma_f32_16x16x32_bf16 v[48:51], v[230:233], v[188:191], v[48:51]
	v_mfma_f32_16x16x32_bf16 v[36:39], v[222:225], v[198:201], v[36:39]
	v_mfma_f32_16x16x32_bf16 v[32:35], v[230:233], v[198:201], v[32:35]
	v_mfma_f32_16x16x32_bf16 v[20:23], v[222:225], v[206:209], v[20:23]
	v_mfma_f32_16x16x32_bf16 v[16:19], v[230:233], v[206:209], v[16:19]
	v_mfma_f32_16x16x32_bf16 v[4:7], v[222:225], v[214:217], v[4:7]
	v_mfma_f32_16x16x32_bf16 v[0:3], v[230:233], v[214:217], v[0:3]
	s_setprio 0
	s_cbranch_scc0 .Lrot_938
	s_barrier
	s_branch .Lpeel_done_938

; #define PG8_STAGE(bufoff, gbase, voff) do { _Pragma("unroll") for (int _i = 0; _i < 2; ++_i) \
;         __builtin_amdgcn_global_load_lds((const unsigned*)((const char*)(gbase) + (voff)[_i]), (LAS unsigned*)(lds + (bufoff) + ldsw + _i * 8192), 16, 0, 0); } while (0)
; #define PG8_LDA(dst, b, h) do { _Pragma("unroll") for (int m = 0; m < 4; ++m) _Pragma("unroll") for (int k = 0; k < 2; ++k) dst[m][k] = *(const LAS bf16x8*)(lds + PG8_SA(b, h) + aoff + m * 2048 + k * 1024); } while (0)
; #define PG8_LDB(dst, b, h) do { _Pragma("unroll") for (int n = 0; n < 2; ++n) _Pragma("unroll") for (int k = 0; k < 2; ++k) dst[n][k] = *(const LAS bf16x8*)(lds + PG8_SB(b, h) + boff + n * 2048 + k * 1024); } while (0)
; #define PG8_MMA(ai, bj, At, Bt) do { __builtin_amdgcn_s_setprio(1); _Pragma("unroll") for (int m = 0; m < 4; ++m) _Pragma("unroll") for (int n = 0; n < 2; ++n) _Pragma("unroll") for (int k = 0; k < 2; ++k) \
;         acc[ai][bj][m][n] = __builtin_amdgcn_mfma_f32_16x16x32_bf16(Bt[n][k], At[m][k], acc[ai][bj][m][n], 0, 0, 0); __builtin_amdgcn_s_setprio(0); } while (0)
; #define PG8_WAIT_V(n) asm volatile("s_waitcnt vmcnt(" #n ")" ::: "memory")
; #define PG8_WAIT_L(n) asm volatile("s_waitcnt lgkmcnt(" #n ")" ::: "memory")
; #define PG8_BAR __builtin_amdgcn_s_barrier()
; #define PG8_SCHED __builtin_amdgcn_sched_barrier(0)
; template <class Epi, class Sched>
; DI void gemm_phase(LAS unsigned char* lds, const Gemm g, const Sched& S, const Epi& E) {
;     ...
;             const char* a2 = last ? nA : cA + (size_t)(t + 2) * kstep; const char* b2 = last ? nB : cB + (size_t)(t + 2) * kstep;
;             const char* a3 = a2 + kstep; const char* b3 = b2 + kstep;
;             PG8_LDB(B0, 0, 0); PG8_SCHED; PG8_LDA(At, 0, 0); PG8_STAGE(PG8_SA(1, 1), a1 + hstep, voffA);
;             PG8_WAIT_L(8); PG8_BAR; PG8_WAIT_L(0); PG8_MMA(0, 0, At, B0); PG8_BAR; PG8_SCHED;
;             PG8_LDB(B1, 0, 1); PG8_STAGE(PG8_SB(0, 0), b2, voffB);
;             PG8_BAR; PG8_WAIT_L(0); PG8_MMA(0, 1, At, B1); PG8_BAR;
;             PG8_LDA(At, 0, 1); PG8_STAGE(PG8_SA(0, 0), a2, voffA);
;             PG8_BAR; PG8_WAIT_L(0); PG8_MMA(1, 0, At, B0); PG8_BAR; PG8_SCHED;
;             PG8_STAGE(PG8_SB(0, 1), b2 + hstep, voffB);
;             PG8_WAIT_V(6); PG8_BAR; PG8_MMA(1, 1, At, B1); PG8_BAR;
.LBB0_938:
	ds_read_b128 v[144:147], v165
	ds_read_b128 v[168:171], v165 offset:1024
	ds_read_b128 v[172:175], v165 offset:2048
	ds_read_b128 v[176:179], v165 offset:3072
	s_add_i32 m0, s51, 0xc000
	ds_read_b128 v[180:183], v166
	ds_read_b128 v[188:191], v166 offset:1024
	ds_read_b128 v[194:197], v166 offset:2048
	ds_read_b128 v[198:201], v166 offset:3072
	ds_read_b128 v[202:205], v166 offset:4096
	ds_read_b128 v[206:209], v166 offset:5120
	ds_read_b128 v[210:213], v166 offset:6144
	global_load_lds_dwordx4 v136, s[8:9]
	s_add_i32 m0, s51, 0xe000
	ds_read_b128 v[214:217], v166 offset:7168
	global_load_lds_dwordx4 v138, s[8:9]
	s_add_u32 s0, s8, 0xfffd0080
	s_addc_u32 s1, s9, -1
	s_cmp_eq_u32 s41, 8
	s_cselect_b32 s39, s31, s1
	s_cselect_b32 s38, s30, s0
	s_cselect_b32 s37, s11, s40
	s_cselect_b32 s36, s10, s35
	s_waitcnt lgkmcnt(8)
	s_barrier
	s_waitcnt lgkmcnt(0)
	s_setprio 1
	v_mfma_f32_16x16x32_bf16 v[124:127], v[144:147], v[180:183], v[124:127]
	v_mfma_f32_16x16x32_bf16 v[120:123], v[172:175], v[180:183], v[120:123]
	v_mfma_f32_16x16x32_bf16 v[108:111], v[144:147], v[194:197], v[108:111]
	v_mfma_f32_16x16x32_bf16 v[104:107], v[172:175], v[194:197], v[104:107]
	v_mfma_f32_16x16x32_bf16 v[92:95], v[144:147], v[202:205], v[92:95]
	v_mfma_f32_16x16x32_bf16 v[88:91], v[172:175], v[202:205], v[88:91]
	v_mfma_f32_16x16x32_bf16 v[76:79], v[144:147], v[210:213], v[76:79]
	v_mfma_f32_16x16x32_bf16 v[72:75], v[172:175], v[210:213], v[72:75]
	v_mfma_f32_16x16x32_bf16 v[124:127], v[168:171], v[188:191], v[124:127]
	v_mfma_f32_16x16x32_bf16 v[120:123], v[176:179], v[188:191], v[120:123]
	v_mfma_f32_16x16x32_bf16 v[108:111], v[168:171], v[198:201], v[108:111]
	v_mfma_f32_16x16x32_bf16 v[104:107], v[176:179], v[198:201], v[104:107]
	v_mfma_f32_16x16x32_bf16 v[92:95], v[168:171], v[206:209], v[92:95]
	v_mfma_f32_16x16x32_bf16 v[88:91], v[176:179], v[206:209], v[88:91]
	v_mfma_f32_16x16x32_bf16 v[76:79], v[168:171], v[214:217], v[76:79]
	v_mfma_f32_16x16x32_bf16 v[72:75], v[176:179], v[214:217], v[72:75]
	s_setprio 0
	s_barrier
	s_add_i32 s0, s61, s50
	s_mov_b32 m0, s0
	ds_read_b128 v[218:221], v167
	ds_read_b128 v[222:225], v167 offset:1024
	ds_read_b128 v[226:229], v167 offset:2048
	global_load_lds_dwordx4 v130, s[36:37]
	s_add_i32 m0, s0, 0x2000
	ds_read_b128 v[230:233], v167 offset:3072
	global_load_lds_dwordx4 v134, s[36:37]
	s_barrier
	s_waitcnt lgkmcnt(0)
	s_setprio 1
	v_mfma_f32_16x16x32_bf16 v[116:119], v[218:221], v[180:183], v[116:119]
	v_mfma_f32_16x16x32_bf16 v[112:115], v[226:229], v[180:183], v[112:115]
	v_mfma_f32_16x16x32_bf16 v[100:103], v[218:221], v[194:197], v[100:103]
	v_mfma_f32_16x16x32_bf16 v[96:99], v[226:229], v[194:197], v[96:99]
	v_mfma_f32_16x16x32_bf16 v[84:87], v[218:221], v[202:205], v[84:87]
	v_mfma_f32_16x16x32_bf16 v[80:83], v[226:229], v[202:205], v[80:83]
	v_mfma_f32_16x16x32_bf16 v[68:71], v[218:221], v[210:213], v[68:71]
	v_mfma_f32_16x16x32_bf16 v[64:67], v[226:229], v[210:213], v[64:67]
	v_mfma_f32_16x16x32_bf16 v[116:119], v[222:225], v[188:191], v[116:119]
	v_mfma_f32_16x16x32_bf16 v[112:115], v[230:233], v[188:191], v[112:115]
	v_mfma_f32_16x16x32_bf16 v[100:103], v[222:225], v[198:201], v[100:103]
	v_mfma_f32_16x16x32_bf16 v[96:99], v[230:233], v[198:201], v[96:99]
	v_mfma_f32_16x16x32_bf16 v[84:87], v[222:225], v[206:209], v[84:87]
	v_mfma_f32_16x16x32_bf16 v[80:83], v[230:233], v[206:209], v[80:83]
	v_mfma_f32_16x16x32_bf16 v[68:71], v[222:225], v[214:217], v[68:71]
	v_mfma_f32_16x16x32_bf16 v[64:67], v[230:233], v[214:217], v[64:67]
	s_setprio 0
	s_mov_b32 m0, s51
	s_barrier
	ds_read_b128 v[180:183], v166 offset:16384
	ds_read_b128 v[188:191], v166 offset:17408
	ds_read_b128 v[194:197], v166 offset:18432
	ds_read_b128 v[198:201], v166 offset:19456
	ds_read_b128 v[202:205], v166 offset:20480
	ds_read_b128 v[206:209], v166 offset:21504
	ds_read_b128 v[210:213], v166 offset:22528
	global_load_lds_dwordx4 v128, s[38:39]
	s_mov_b32 m0, s52
	ds_read_b128 v[214:217], v166 offset:23552
	global_load_lds_dwordx4 v132, s[38:39]
	s_barrier
	s_waitcnt lgkmcnt(0)
	s_setprio 1
	v_mfma_f32_16x16x32_bf16 v[60:63], v[144:147], v[180:183], v[60:63]
	v_mfma_f32_16x16x32_bf16 v[56:59], v[172:175], v[180:183], v[56:59]
	v_mfma_f32_16x16x32_bf16 v[44:47], v[144:147], v[194:197], v[44:47]
	v_mfma_f32_16x16x32_bf16 v[40:43], v[172:175], v[194:197], v[40:43]
	v_mfma_f32_16x16x32_bf16 v[28:31], v[144:147], v[202:205], v[28:31]
	v_mfma_f32_16x16x32_bf16 v[24:27], v[172:175], v[202:205], v[24:27]
	v_mfma_f32_16x16x32_bf16 v[12:15], v[144:147], v[210:213], v[12:15]
	v_mfma_f32_16x16x32_bf16 v[8:11], v[172:175], v[210:213], v[8:11]
	v_mfma_f32_16x16x32_bf16 v[60:63], v[168:171], v[188:191], v[60:63]
	v_mfma_f32_16x16x32_bf16 v[56:59], v[176:179], v[188:191], v[56:59]
	v_mfma_f32_16x16x32_bf16 v[44:47], v[168:171], v[198:201], v[44:47]
	v_mfma_f32_16x16x32_bf16 v[40:43], v[176:179], v[198:201], v[40:43]
	v_mfma_f32_16x16x32_bf16 v[28:31], v[168:171], v[206:209], v[28:31]
	v_mfma_f32_16x16x32_bf16 v[24:27], v[176:179], v[206:209], v[24:27]
	v_mfma_f32_16x16x32_bf16 v[12:15], v[168:171], v[214:217], v[12:15]
	v_mfma_f32_16x16x32_bf16 v[8:11], v[176:179], v[214:217], v[8:11]
	s_setprio 0
	s_barrier
	s_add_i32 s4, s62, s50
	s_mov_b32 m0, s4
	s_add_u32 s0, s36, 0x30000
	s_addc_u32 s1, s37, 0
	global_load_lds_dwordx4 v130, s[0:1]
	s_add_i32 m0, s4, 0x2000
	s_nop 0
	global_load_lds_dwordx4 v134, s[0:1]
	s_waitcnt vmcnt(6)
	s_barrier
; #define PG8_STAGE(bufoff, gbase, voff) do { _Pragma("unroll") for (int _i = 0; _i < 2; ++_i) \
;         __builtin_amdgcn_global_load_lds((const unsigned*)((const char*)(gbase) + (voff)[_i]), (LAS unsigned*)(lds + (bufoff) + ldsw + _i * 8192), 16, 0, 0); } while (0)
; #define PG8_LDA(dst, b, h) do { _Pragma("unroll") for (int m = 0; m < 4; ++m) _Pragma("unroll") for (int k = 0; k < 2; ++k) dst[m][k] = *(const LAS bf16x8*)(lds + PG8_SA(b, h) + aoff + m * 2048 + k * 1024); } while (0)
; #define PG8_LDB(dst, b, h) do { _Pragma("unroll") for (int n = 0; n < 2; ++n) _Pragma("unroll") for (int k = 0; k < 2; ++k) dst[n][k] = *(const LAS bf16x8*)(lds + PG8_SB(b, h) + boff + n * 2048 + k * 1024); } while (0)
; #define PG8_MMA(ai, bj, At, Bt) do { __builtin_amdgcn_s_setprio(1); _Pragma("unroll") for (int m = 0; m < 4; ++m) _Pragma("unroll") for (int n = 0; n < 2; ++n) _Pragma("unroll") for (int k = 0; k < 2; ++k) \
;         acc[ai][bj][m][n] = __builtin_amdgcn_mfma_f32_16x16x32_bf16(Bt[n][k], At[m][k], acc[ai][bj][m][n], 0, 0, 0); __builtin_amdgcn_s_setprio(0); } while (0)
; #define PG8_WAIT_V(n) asm volatile("s_waitcnt vmcnt(" #n ")" ::: "memory")
; #define PG8_WAIT_L(n) asm volatile("s_waitcnt lgkmcnt(" #n ")" ::: "memory")
; #define PG8_BAR __builtin_amdgcn_s_barrier()
; #define PG8_SCHED __builtin_amdgcn_sched_barrier(0)
; template <class Epi, class Sched>
; DI void gemm_phase(LAS unsigned char* lds, const Gemm g, const Sched& S, const Epi& E) {
;     ...
;             PG8_WAIT_V(6); PG8_BAR; PG8_MMA(1, 1, At, B1); PG8_BAR;
;             PG8_LDB(B0, 1, 0); PG8_SCHED; PG8_LDA(At, 1, 0); PG8_STAGE(PG8_SA(0, 1), a2 + hstep, voffA);
;             PG8_WAIT_L(8); PG8_BAR; PG8_WAIT_L(0); PG8_MMA(0, 0, At, B0); PG8_BAR; PG8_SCHED;
;             PG8_LDB(B1, 1, 1); PG8_STAGE(PG8_SB(1, 0), b3, voffB);
;             PG8_BAR; PG8_WAIT_L(0); PG8_MMA(0, 1, At, B1); PG8_BAR;
	s_setprio 1
	v_mfma_f32_16x16x32_bf16 v[52:55], v[218:221], v[180:183], v[52:55]
	v_mfma_f32_16x16x32_bf16 v[48:51], v[226:229], v[180:183], v[48:51]
	v_mfma_f32_16x16x32_bf16 v[36:39], v[218:221], v[194:197], v[36:39]
	v_mfma_f32_16x16x32_bf16 v[32:35], v[226:229], v[194:197], v[32:35]
	v_mfma_f32_16x16x32_bf16 v[20:23], v[218:221], v[202:205], v[20:23]
	v_mfma_f32_16x16x32_bf16 v[16:19], v[226:229], v[202:205], v[16:19]
	v_mfma_f32_16x16x32_bf16 v[4:7], v[218:221], v[210:213], v[4:7]
	v_mfma_f32_16x16x32_bf16 v[0:3], v[226:229], v[210:213], v[0:3]
	v_mfma_f32_16x16x32_bf16 v[52:55], v[222:225], v[188:191], v[52:55]
	v_mfma_f32_16x16x32_bf16 v[48:51], v[230:233], v[188:191], v[48:51]
	v_mfma_f32_16x16x32_bf16 v[36:39], v[222:225], v[198:201], v[36:39]
	v_mfma_f32_16x16x32_bf16 v[32:35], v[230:233], v[198:201], v[32:35]
	v_mfma_f32_16x16x32_bf16 v[20:23], v[222:225], v[206:209], v[20:23]
	v_mfma_f32_16x16x32_bf16 v[16:19], v[230:233], v[206:209], v[16:19]
	v_mfma_f32_16x16x32_bf16 v[4:7], v[222:225], v[214:217], v[4:7]
	v_mfma_f32_16x16x32_bf16 v[0:3], v[230:233], v[214:217], v[0:3]
	s_setprio 0
	s_add_i32 s4, 0, 0x18000
	s_barrier
	ds_read_b128 v[144:147], v148
	ds_read_b128 v[168:171], v148 offset:1024
	ds_read_b128 v[172:175], v148 offset:2048
	ds_read_b128 v[176:179], v148 offset:3072
	s_add_u32 s0, s38, 0x30000
	s_addc_u32 s1, s39, 0
	s_mov_b32 m0, s53
	ds_read_b128 v[180:183], v166 offset:32768
	ds_read_b128 v[188:191], v166 offset:33792
	ds_read_b128 v[194:197], v166 offset:34816
	ds_read_b128 v[198:201], v166 offset:35840
	ds_read_b128 v[202:205], v166 offset:36864
	ds_read_b128 v[206:209], v166 offset:37888
	ds_read_b128 v[210:213], v166 offset:38912
	global_load_lds_dwordx4 v128, s[0:1]
	s_mov_b32 m0, s54
	ds_read_b128 v[214:217], v166 offset:39936
	global_load_lds_dwordx4 v132, s[0:1]
	s_waitcnt lgkmcnt(8)
	s_barrier
	s_waitcnt lgkmcnt(0)
	s_setprio 1
	v_mfma_f32_16x16x32_bf16 v[124:127], v[144:147], v[180:183], v[124:127]
	v_mfma_f32_16x16x32_bf16 v[120:123], v[172:175], v[180:183], v[120:123]
	v_mfma_f32_16x16x32_bf16 v[108:111], v[144:147], v[194:197], v[108:111]
	v_mfma_f32_16x16x32_bf16 v[104:107], v[172:175], v[194:197], v[104:107]
	v_mfma_f32_16x16x32_bf16 v[92:95], v[144:147], v[202:205], v[92:95]
	v_mfma_f32_16x16x32_bf16 v[88:91], v[172:175], v[202:205], v[88:91]
	v_mfma_f32_16x16x32_bf16 v[76:79], v[144:147], v[210:213], v[76:79]
	v_mfma_f32_16x16x32_bf16 v[72:75], v[172:175], v[210:213], v[72:75]
	v_mfma_f32_16x16x32_bf16 v[124:127], v[168:171], v[188:191], v[124:127]
	v_mfma_f32_16x16x32_bf16 v[120:123], v[176:179], v[188:191], v[120:123]
	v_mfma_f32_16x16x32_bf16 v[108:111], v[168:171], v[198:201], v[108:111]
	v_mfma_f32_16x16x32_bf16 v[104:107], v[176:179], v[198:201], v[104:107]
	v_mfma_f32_16x16x32_bf16 v[92:95], v[168:171], v[206:209], v[92:95]
	v_mfma_f32_16x16x32_bf16 v[88:91], v[176:179], v[206:209], v[88:91]
	v_mfma_f32_16x16x32_bf16 v[76:79], v[168:171], v[214:217], v[76:79]
	v_mfma_f32_16x16x32_bf16 v[72:75], v[176:179], v[214:217], v[72:75]
	s_setprio 0
	s_barrier
	s_add_i32 s5, 0, 0x1c000
	s_add_i32 s0, s4, s50
	s_add_i32 m0, s0, 0xffffff80
	ds_read_b128 v[218:221], v149
	ds_read_b128 v[222:225], v149 offset:1024
	ds_read_b128 v[226:229], v149 offset:2048
	global_load_lds_dwordx4 v130, s[36:37] offset:128
	s_add_i32 m0, s0, 0x1f80
	ds_read_b128 v[230:233], v149 offset:3072
	global_load_lds_dwordx4 v134, s[36:37] offset:128
	s_barrier
; #define PG8_STAGE(bufoff, gbase, voff) do { _Pragma("unroll") for (int _i = 0; _i < 2; ++_i) \
;         __builtin_amdgcn_global_load_lds((const unsigned*)((const char*)(gbase) + (voff)[_i]), (LAS unsigned*)(lds + (bufoff) + ldsw + _i * 8192), 16, 0, 0); } while (0)
; #define PG8_LDA(dst, b, h) do { _Pragma("unroll") for (int m = 0; m < 4; ++m) _Pragma("unroll") for (int k = 0; k < 2; ++k) dst[m][k] = *(const LAS bf16x8*)(lds + PG8_SA(b, h) + aoff + m * 2048 + k * 1024); } while (0)
; #define PG8_MMA(ai, bj, At, Bt) do { __builtin_amdgcn_s_setprio(1); _Pragma("unroll") for (int m = 0; m < 4; ++m) _Pragma("unroll") for (int n = 0; n < 2; ++n) _Pragma("unroll") for (int k = 0; k < 2; ++k) \
;         acc[ai][bj][m][n] = __builtin_amdgcn_mfma_f32_16x16x32_bf16(Bt[n][k], At[m][k], acc[ai][bj][m][n], 0, 0, 0); __builtin_amdgcn_s_setprio(0); } while (0)
; #define PG8_WAIT_V(n) asm volatile("s_waitcnt vmcnt(" #n ")" ::: "memory")
; #define PG8_WAIT_L(n) asm volatile("s_waitcnt lgkmcnt(" #n ")" ::: "memory")
; #define PG8_BAR __builtin_amdgcn_s_barrier()
; #define PG8_SCHED __builtin_amdgcn_sched_barrier(0)
; template <class Epi, class Sched>
; DI void gemm_phase(LAS unsigned char* lds, const Gemm g, const Sched& S, const Epi& E) {
;     ...
;             PG8_LDA(At, 1, 1); PG8_STAGE(PG8_SA(1, 0), a3, voffA);
;             PG8_BAR; PG8_WAIT_L(0); PG8_MMA(1, 0, At, B0); PG8_BAR; PG8_SCHED;
;             PG8_STAGE(PG8_SB(1, 1), b3 + hstep, voffB);
;             PG8_WAIT_V(6); PG8_BAR; PG8_MMA(1, 1, At, B1); PG8_BAR;
	s_waitcnt lgkmcnt(0)
	s_setprio 1
	v_mfma_f32_16x16x32_bf16 v[116:119], v[218:221], v[180:183], v[116:119]
	v_mfma_f32_16x16x32_bf16 v[112:115], v[226:229], v[180:183], v[112:115]
	v_mfma_f32_16x16x32_bf16 v[100:103], v[218:221], v[194:197], v[100:103]
	v_mfma_f32_16x16x32_bf16 v[96:99], v[226:229], v[194:197], v[96:99]
	v_mfma_f32_16x16x32_bf16 v[84:87], v[218:221], v[202:205], v[84:87]
	v_mfma_f32_16x16x32_bf16 v[80:83], v[226:229], v[202:205], v[80:83]
	v_mfma_f32_16x16x32_bf16 v[68:71], v[218:221], v[210:213], v[68:71]
	v_mfma_f32_16x16x32_bf16 v[64:67], v[226:229], v[210:213], v[64:67]
	v_mfma_f32_16x16x32_bf16 v[116:119], v[222:225], v[188:191], v[116:119]
	v_mfma_f32_16x16x32_bf16 v[112:115], v[230:233], v[188:191], v[112:115]
	v_mfma_f32_16x16x32_bf16 v[100:103], v[222:225], v[198:201], v[100:103]
	v_mfma_f32_16x16x32_bf16 v[96:99], v[230:233], v[198:201], v[96:99]
	v_mfma_f32_16x16x32_bf16 v[84:87], v[222:225], v[206:209], v[84:87]
	v_mfma_f32_16x16x32_bf16 v[80:83], v[230:233], v[206:209], v[80:83]
	v_mfma_f32_16x16x32_bf16 v[68:71], v[222:225], v[214:217], v[68:71]
	v_mfma_f32_16x16x32_bf16 v[64:67], v[230:233], v[214:217], v[64:67]
	s_setprio 0
	s_add_i32 m0, s57, 0xffffff80
	s_barrier
	ds_read_b128 v[180:183], v166 offset:49152
	ds_read_b128 v[188:191], v166 offset:50176
	ds_read_b128 v[194:197], v166 offset:51200
	ds_read_b128 v[198:201], v166 offset:52224
	ds_read_b128 v[202:205], v166 offset:53248
	ds_read_b128 v[206:209], v166 offset:54272
	ds_read_b128 v[210:213], v166 offset:55296
	global_load_lds_dwordx4 v128, s[38:39] offset:128
	s_add_i32 m0, s58, 0xffffff80
	ds_read_b128 v[214:217], v166 offset:56320
	global_load_lds_dwordx4 v132, s[38:39] offset:128
	s_barrier
	s_waitcnt lgkmcnt(0)
	s_setprio 1
	v_mfma_f32_16x16x32_bf16 v[60:63], v[144:147], v[180:183], v[60:63]
	v_mfma_f32_16x16x32_bf16 v[56:59], v[172:175], v[180:183], v[56:59]
	v_mfma_f32_16x16x32_bf16 v[44:47], v[144:147], v[194:197], v[44:47]
	v_mfma_f32_16x16x32_bf16 v[40:43], v[172:175], v[194:197], v[40:43]
	v_mfma_f32_16x16x32_bf16 v[28:31], v[144:147], v[202:205], v[28:31]
	v_mfma_f32_16x16x32_bf16 v[24:27], v[172:175], v[202:205], v[24:27]
	v_mfma_f32_16x16x32_bf16 v[12:15], v[144:147], v[210:213], v[12:15]
	v_mfma_f32_16x16x32_bf16 v[8:11], v[172:175], v[210:213], v[8:11]
	v_mfma_f32_16x16x32_bf16 v[60:63], v[168:171], v[188:191], v[60:63]
	v_mfma_f32_16x16x32_bf16 v[56:59], v[176:179], v[188:191], v[56:59]
	v_mfma_f32_16x16x32_bf16 v[44:47], v[168:171], v[198:201], v[44:47]
	v_mfma_f32_16x16x32_bf16 v[40:43], v[176:179], v[198:201], v[40:43]
	v_mfma_f32_16x16x32_bf16 v[28:31], v[168:171], v[206:209], v[28:31]
	v_mfma_f32_16x16x32_bf16 v[24:27], v[176:179], v[206:209], v[24:27]
	v_mfma_f32_16x16x32_bf16 v[12:15], v[168:171], v[214:217], v[12:15]
	v_mfma_f32_16x16x32_bf16 v[8:11], v[176:179], v[214:217], v[8:11]
	s_setprio 0
	s_barrier
	s_add_i32 s4, s5, s50
	s_mov_b32 m0, s4
	s_add_u32 s0, s36, 0x30080
	s_addc_u32 s1, s37, 0
	global_load_lds_dwordx4 v130, s[0:1]
	s_add_i32 m0, s4, 0x2000
	s_nop 0
	global_load_lds_dwordx4 v134, s[0:1]
	s_add_i32 s41, s41, 2
	s_add_u32 s8, s8, 0x100
	s_addc_u32 s9, s9, 0
	s_add_u32 s35, s35, 0x100
	s_addc_u32 s40, s40, 0
	s_cmp_gt_u32 s41, 9
	s_waitcnt vmcnt(6)
	s_barrier
	s_setprio 1
	v_mfma_f32_16x16x32_bf16 v[52:55], v[218:221], v[180:183], v[52:55]
	v_mfma_f32_16x16x32_bf16 v[48:51], v[226:229], v[180:183], v[48:51]
	v_mfma_f32_16x16x32_bf16 v[36:39], v[218:221], v[194:197], v[36:39]
	v_mfma_f32_16x16x32_bf16 v[32:35], v[226:229], v[194:197], v[32:35]
	v_mfma_f32_16x16x32_bf16 v[20:23], v[218:221], v[202:205], v[20:23]
	v_mfma_f32_16x16x32_bf16 v[16:19], v[226:229], v[202:205], v[16:19]
	v_mfma_f32_16x16x32_bf16 v[4:7], v[218:221], v[210:213], v[4:7]
	v_mfma_f32_16x16x32_bf16 v[0:3], v[226:229], v[210:213], v[0:3]
	v_mfma_f32_16x16x32_bf16 v[52:55], v[222:225], v[188:191], v[52:55]
	v_mfma_f32_16x16x32_bf16 v[48:51], v[230:233], v[188:191], v[48:51]
	v_mfma_f32_16x16x32_bf16 v[36:39], v[222:225], v[198:201], v[36:39]
	v_mfma_f32_16x16x32_bf16 v[32:35], v[230:233], v[198:201], v[32:35]
	v_mfma_f32_16x16x32_bf16 v[20:23], v[222:225], v[206:209], v[20:23]
	v_mfma_f32_16x16x32_bf16 v[16:19], v[230:233], v[206:209], v[16:19]
	v_mfma_f32_16x16x32_bf16 v[4:7], v[222:225], v[214:217], v[4:7]
	v_mfma_f32_16x16x32_bf16 v[0:3], v[230:233], v[214:217], v[0:3]
	s_setprio 0
	s_cbranch_scc0 .Lrot_938
	s_barrier

;     DI size_t aoff(const Unit& u, size_t tstep) const { return (size_t)u.pm * tstep; }
;     DI size_t boff(const Unit& u, size_t tstep) const { return (size_t)u.pn * tstep; }
;     DI bool next(int i, Unit& u) const { const long L = (long)i * G + c; if (L >= np) return false; u.pm = pmv; u.pn = (int)(L % nN); u.ks = (int)(L / nN); return true; }
;     DI size_t aoff(const Unit& u, size_t) const { return (size_t)u.ks * kbytes; }
;     DI size_t boff(const Unit& u, size_t tstep) const { return (size_t)u.pn * tstep + (size_t)u.ks * kbytes; }
;     DI bool next(int i, Unit& u) const { Unit t; if (!S.next(i / 3, t)) return false; u.pm = t.pm; u.pn = t.pn; u.ks = i % 3; return true; }
;     DI size_t aoff(const Unit& u, size_t tstep) const { return (u.ks < 2 ? offU : offOA) + (size_t)u.pm * tstep; }
; #define PG8_WAIT_V(n) asm volatile("s_waitcnt vmcnt(" #n ")" ::: "memory")
; template <class Epi, class Sched>
; DI void gemm_phase(LAS unsigned char* lds, const Gemm g, const Sched& S, const Epi& E) {
;     ...
;         const bool has_next = S.next(ui + 1, nxt);
;         const char* nA = has_next ? (const char*)g.A + S.aoff(nxt, tstep) : cA; const char* nB = has_next ? (const char*)g.Bt + S.boff(nxt, tstep) : cB;
;         for (int t = 0; t < nt; t += 2) {
;             if constexpr (Epi::HAS_MID) { if (t == E.mid_t(nt)) { int fr3 = fr, fq3 = fq; asm volatile("" : "+v"(fr3), "+v"(fq3)); E.mid(acc, cur, wr, wc, fr3, fq3); } }
;             const bool last = (t == nt - 2);
;             const char* a1 = cA + (size_t)(t + 1) * kstep;
;             const char* a2 = last ? nA : cA + (size_t)(t + 2) * kstep; const char* b2 = last ? nB : cB + (size_t)(t + 2) * kstep;
;             const char* a3 = a2 + kstep; const char* b3 = b2 + kstep;
;             PG8_LDB(B0, 0, 0); PG8_SCHED; PG8_LDA(At, 0, 0); PG8_STAGE(PG8_SA(1, 1), a1 + hstep, voffA);
;             PG8_WAIT_L(8); PG8_BAR; PG8_WAIT_L(0); PG8_MMA(0, 0, At, B0); PG8_BAR; PG8_SCHED;
;             PG8_LDB(B1, 0, 1); PG8_STAGE(PG8_SB(0, 0), b2, voffB);
;             PG8_BAR; PG8_WAIT_L(0); PG8_MMA(0, 1, At, B1); PG8_BAR;
;             PG8_LDA(At, 0, 1); PG8_STAGE(PG8_SA(0, 0), a2, voffA);
;             PG8_BAR; PG8_WAIT_L(0); PG8_MMA(1, 0, At, B0); PG8_BAR; PG8_SCHED;
;             PG8_STAGE(PG8_SB(0, 1), b2 + hstep, voffB);
;             PG8_WAIT_V(6); PG8_BAR; PG8_MMA(1, 1, At, B1); PG8_BAR;
.LBB0_983:
	s_ashr_i32 s31, s30, 31
	s_lshl_b64 s[0:1], s[30:31], 18
	v_cmp_lt_i64_e32 vcc, s[36:37], v[142:143]
	s_add_u32 s36, s51, s0
	s_addc_u32 s37, s52, s1
	s_and_b64 s[0:1], vcc, exec
	s_cselect_b32 s9, s37, s43
	s_cselect_b32 s31, s36, s42
	s_ashr_i32 s29, s28, 31
	s_lshl_b64 s[0:1], s[28:29], 18
	s_add_u32 s38, s53, s0
	s_addc_u32 s39, s54, s1
	s_and_b64 s[0:1], vcc, exec
	s_cselect_b32 s29, s39, s45
	s_cselect_b32 s34, s38, s44
	s_add_u32 s42, s42, 0x20080
	s_addc_u32 s43, s43, 0
	s_add_u32 s35, s44, 0x100
	v_mov_b32_e32 v0, 0
	s_addc_u32 s41, s45, 0
	s_mov_b32 s79, -2
	ds_read_b128 v[146:149], v156
	ds_read_b128 v[150:153], v156 offset:1024
	ds_read_b128 v[160:163], v156 offset:2048
	ds_read_b128 v[164:167], v156 offset:3072
	s_add_i32 m0, s55, 0xc000
	ds_read_b128 v[168:171], v158
	ds_read_b128 v[172:175], v158 offset:1024
	ds_read_b128 v[176:179], v158 offset:2048
	ds_read_b128 v[180:183], v158 offset:3072
	ds_read_b128 v[188:191], v158 offset:4096
	ds_read_b128 v[194:197], v158 offset:5120
	ds_read_b128 v[198:201], v158 offset:6144
	global_load_lds_dwordx4 v138, s[42:43]
	s_add_i32 m0, s55, 0xe000
	ds_read_b128 v[202:205], v158 offset:7168
	global_load_lds_dwordx4 v140, s[42:43]
	s_add_u32 s0, s42, 0xfffe0080
	s_addc_u32 s1, s43, -1
	s_cmp_eq_u32 s79, 4
	s_cselect_b32 s47, s9, s1
	s_cselect_b32 s46, s31, s0
	s_cselect_b32 s45, s29, s41
	s_cselect_b32 s44, s34, s35
	s_waitcnt lgkmcnt(8)
	s_barrier
	s_waitcnt lgkmcnt(0)
	s_setprio 1
	v_mfma_f32_16x16x32_bf16 v[124:127], v[146:149], v[168:171], 0
	v_mfma_f32_16x16x32_bf16 v[120:123], v[160:163], v[168:171], 0
	v_mfma_f32_16x16x32_bf16 v[108:111], v[146:149], v[176:179], 0
	v_mfma_f32_16x16x32_bf16 v[104:107], v[160:163], v[176:179], 0
	v_mfma_f32_16x16x32_bf16 v[92:95], v[146:149], v[188:191], 0
	v_mfma_f32_16x16x32_bf16 v[88:91], v[160:163], v[188:191], 0
	v_mfma_f32_16x16x32_bf16 v[76:79], v[146:149], v[198:201], 0
	v_mfma_f32_16x16x32_bf16 v[72:75], v[160:163], v[198:201], 0
	v_mfma_f32_16x16x32_bf16 v[124:127], v[150:153], v[172:175], v[124:127]
	v_mfma_f32_16x16x32_bf16 v[120:123], v[164:167], v[172:175], v[120:123]
	v_mfma_f32_16x16x32_bf16 v[108:111], v[150:153], v[180:183], v[108:111]
	v_mfma_f32_16x16x32_bf16 v[104:107], v[164:167], v[180:183], v[104:107]
	v_mfma_f32_16x16x32_bf16 v[92:95], v[150:153], v[194:197], v[92:95]
	v_mfma_f32_16x16x32_bf16 v[88:91], v[164:167], v[194:197], v[88:91]
	v_mfma_f32_16x16x32_bf16 v[76:79], v[150:153], v[202:205], v[76:79]
	v_mfma_f32_16x16x32_bf16 v[72:75], v[164:167], v[202:205], v[72:75]
	s_setprio 0
	s_barrier
	s_add_i32 s0, s66, s50
	s_mov_b32 m0, s0
	ds_read_b128 v[206:209], v159
	ds_read_b128 v[210:213], v159 offset:1024
	ds_read_b128 v[214:217], v159 offset:2048
	global_load_lds_dwordx4 v130, s[44:45]
	s_add_i32 m0, s0, 0x2000
	ds_read_b128 v[218:221], v159 offset:3072
	global_load_lds_dwordx4 v134, s[44:45]
	s_barrier
	s_waitcnt lgkmcnt(0)
	s_setprio 1
	v_mfma_f32_16x16x32_bf16 v[116:119], v[206:209], v[168:171], 0
	v_mfma_f32_16x16x32_bf16 v[112:115], v[214:217], v[168:171], 0
	v_mfma_f32_16x16x32_bf16 v[100:103], v[206:209], v[176:179], 0
	v_mfma_f32_16x16x32_bf16 v[96:99], v[214:217], v[176:179], 0
	v_mfma_f32_16x16x32_bf16 v[84:87], v[206:209], v[188:191], 0
	v_mfma_f32_16x16x32_bf16 v[80:83], v[214:217], v[188:191], 0
	v_mfma_f32_16x16x32_bf16 v[68:71], v[206:209], v[198:201], 0
	v_mfma_f32_16x16x32_bf16 v[64:67], v[214:217], v[198:201], 0
	v_mfma_f32_16x16x32_bf16 v[116:119], v[210:213], v[172:175], v[116:119]
	v_mfma_f32_16x16x32_bf16 v[112:115], v[218:221], v[172:175], v[112:115]
	v_mfma_f32_16x16x32_bf16 v[100:103], v[210:213], v[180:183], v[100:103]
	v_mfma_f32_16x16x32_bf16 v[96:99], v[218:221], v[180:183], v[96:99]
	v_mfma_f32_16x16x32_bf16 v[84:87], v[210:213], v[194:197], v[84:87]
	v_mfma_f32_16x16x32_bf16 v[80:83], v[218:221], v[194:197], v[80:83]
	v_mfma_f32_16x16x32_bf16 v[68:71], v[210:213], v[202:205], v[68:71]
	v_mfma_f32_16x16x32_bf16 v[64:67], v[218:221], v[202:205], v[64:67]
	s_setprio 0
	s_mov_b32 m0, s55
	s_barrier
	ds_read_b128 v[168:171], v158 offset:16384
	ds_read_b128 v[172:175], v158 offset:17408
	ds_read_b128 v[176:179], v158 offset:18432
	ds_read_b128 v[180:183], v158 offset:19456
	ds_read_b128 v[188:191], v158 offset:20480
	ds_read_b128 v[194:197], v158 offset:21504
	ds_read_b128 v[198:201], v158 offset:22528
	global_load_lds_dwordx4 v128, s[46:47]
	s_mov_b32 m0, s56
	ds_read_b128 v[202:205], v158 offset:23552
	global_load_lds_dwordx4 v132, s[46:47]
	s_barrier
	s_waitcnt lgkmcnt(0)
	s_setprio 1
	v_mfma_f32_16x16x32_bf16 v[60:63], v[146:149], v[168:171], 0
	v_mfma_f32_16x16x32_bf16 v[56:59], v[160:163], v[168:171], 0
	v_mfma_f32_16x16x32_bf16 v[44:47], v[146:149], v[176:179], 0
	v_mfma_f32_16x16x32_bf16 v[40:43], v[160:163], v[176:179], 0
	v_mfma_f32_16x16x32_bf16 v[28:31], v[146:149], v[188:191], 0
	v_mfma_f32_16x16x32_bf16 v[24:27], v[160:163], v[188:191], 0
	v_mfma_f32_16x16x32_bf16 v[12:15], v[146:149], v[198:201], 0
	v_mfma_f32_16x16x32_bf16 v[8:11], v[160:163], v[198:201], 0
	v_mfma_f32_16x16x32_bf16 v[60:63], v[150:153], v[172:175], v[60:63]
	v_mfma_f32_16x16x32_bf16 v[56:59], v[164:167], v[172:175], v[56:59]
	v_mfma_f32_16x16x32_bf16 v[44:47], v[150:153], v[180:183], v[44:47]
	v_mfma_f32_16x16x32_bf16 v[40:43], v[164:167], v[180:183], v[40:43]
	v_mfma_f32_16x16x32_bf16 v[28:31], v[150:153], v[194:197], v[28:31]
	v_mfma_f32_16x16x32_bf16 v[24:27], v[164:167], v[194:197], v[24:27]
	v_mfma_f32_16x16x32_bf16 v[12:15], v[150:153], v[202:205], v[12:15]
	v_mfma_f32_16x16x32_bf16 v[8:11], v[164:167], v[202:205], v[8:11]
	s_setprio 0
	s_barrier
; #define PG8_STAGE(bufoff, gbase, voff) do { _Pragma("unroll") for (int _i = 0; _i < 2; ++_i) \
;         __builtin_amdgcn_global_load_lds((const unsigned*)((const char*)(gbase) + (voff)[_i]), (LAS unsigned*)(lds + (bufoff) + ldsw + _i * 8192), 16, 0, 0); } while (0)
; #define PG8_LDA(dst, b, h) do { _Pragma("unroll") for (int m = 0; m < 4; ++m) _Pragma("unroll") for (int k = 0; k < 2; ++k) dst[m][k] = *(const LAS bf16x8*)(lds + PG8_SA(b, h) + aoff + m * 2048 + k * 1024); } while (0)
; #define PG8_LDB(dst, b, h) do { _Pragma("unroll") for (int n = 0; n < 2; ++n) _Pragma("unroll") for (int k = 0; k < 2; ++k) dst[n][k] = *(const LAS bf16x8*)(lds + PG8_SB(b, h) + boff + n * 2048 + k * 1024); } while (0)
; #define PG8_MMA(ai, bj, At, Bt) do { __builtin_amdgcn_s_setprio(1); _Pragma("unroll") for (int m = 0; m < 4; ++m) _Pragma("unroll") for (int n = 0; n < 2; ++n) _Pragma("unroll") for (int k = 0; k < 2; ++k) \
;         acc[ai][bj][m][n] = __builtin_amdgcn_mfma_f32_16x16x32_bf16(Bt[n][k], At[m][k], acc[ai][bj][m][n], 0, 0, 0); __builtin_amdgcn_s_setprio(0); } while (0)
; #define PG8_WAIT_V(n) asm volatile("s_waitcnt vmcnt(" #n ")" ::: "memory")
; #define PG8_WAIT_L(n) asm volatile("s_waitcnt lgkmcnt(" #n ")" ::: "memory")
; #define PG8_BAR __builtin_amdgcn_s_barrier()
; #define PG8_SCHED __builtin_amdgcn_sched_barrier(0)
; template <class Epi, class Sched>
; DI void gemm_phase(LAS unsigned char* lds, const Gemm g, const Sched& S, const Epi& E) {
;     ...
;             PG8_WAIT_V(6); PG8_BAR; PG8_MMA(1, 1, At, B1); PG8_BAR;
;             PG8_LDB(B0, 1, 0); PG8_SCHED; PG8_LDA(At, 1, 0); PG8_STAGE(PG8_SA(0, 1), a2 + hstep, voffA);
;             PG8_WAIT_L(8); PG8_BAR; PG8_WAIT_L(0); PG8_MMA(0, 0, At, B0); PG8_BAR; PG8_SCHED;
;             PG8_LDB(B1, 1, 1); PG8_STAGE(PG8_SB(1, 0), b3, voffB);
;             PG8_BAR; PG8_WAIT_L(0); PG8_MMA(0, 1, At, B1); PG8_BAR;
	s_add_i32 s4, s67, s50
	s_mov_b32 m0, s4
	s_add_u32 s0, s44, 0x20000
	s_addc_u32 s1, s45, 0
	global_load_lds_dwordx4 v130, s[0:1]
	s_add_i32 m0, s4, 0x2000
	s_nop 0
	global_load_lds_dwordx4 v134, s[0:1]
	s_waitcnt vmcnt(6)
	s_barrier
	s_setprio 1
	v_mfma_f32_16x16x32_bf16 v[52:55], v[206:209], v[168:171], 0
	v_mfma_f32_16x16x32_bf16 v[48:51], v[214:217], v[168:171], 0
	v_mfma_f32_16x16x32_bf16 v[36:39], v[206:209], v[176:179], 0
	v_mfma_f32_16x16x32_bf16 v[32:35], v[214:217], v[176:179], 0
	v_mfma_f32_16x16x32_bf16 v[20:23], v[206:209], v[188:191], 0
	v_mfma_f32_16x16x32_bf16 v[16:19], v[214:217], v[188:191], 0
	v_mfma_f32_16x16x32_bf16 v[4:7], v[206:209], v[198:201], 0
	v_mfma_f32_16x16x32_bf16 v[0:3], v[214:217], v[198:201], 0
	v_mfma_f32_16x16x32_bf16 v[52:55], v[210:213], v[172:175], v[52:55]
	v_mfma_f32_16x16x32_bf16 v[48:51], v[218:221], v[172:175], v[48:51]
	v_mfma_f32_16x16x32_bf16 v[36:39], v[210:213], v[180:183], v[36:39]
	v_mfma_f32_16x16x32_bf16 v[32:35], v[218:221], v[180:183], v[32:35]
	v_mfma_f32_16x16x32_bf16 v[20:23], v[210:213], v[194:197], v[20:23]
	v_mfma_f32_16x16x32_bf16 v[16:19], v[218:221], v[194:197], v[16:19]
	v_mfma_f32_16x16x32_bf16 v[4:7], v[210:213], v[202:205], v[4:7]
	v_mfma_f32_16x16x32_bf16 v[0:3], v[218:221], v[202:205], v[0:3]
	s_setprio 0
	s_add_i32 s4, 0, 0x18000
	v_add_u32_e32 v222, s4, v157
	s_barrier
	ds_read_b128 v[146:149], v222
	ds_read_b128 v[150:153], v222 offset:1024
	ds_read_b128 v[160:163], v222 offset:2048
	ds_read_b128 v[164:167], v222 offset:3072
	s_add_u32 s0, s46, 0x20000
	s_addc_u32 s1, s47, 0
	s_mov_b32 m0, s57
	ds_read_b128 v[168:171], v158 offset:32768
	ds_read_b128 v[172:175], v158 offset:33792
	ds_read_b128 v[176:179], v158 offset:34816
	ds_read_b128 v[180:183], v158 offset:35840
	ds_read_b128 v[188:191], v158 offset:36864
	ds_read_b128 v[194:197], v158 offset:37888
	ds_read_b128 v[198:201], v158 offset:38912
	global_load_lds_dwordx4 v128, s[0:1]
	s_mov_b32 m0, s58
	ds_read_b128 v[202:205], v158 offset:39936
	global_load_lds_dwordx4 v132, s[0:1]
	s_waitcnt lgkmcnt(8)
	s_barrier
	s_waitcnt lgkmcnt(0)
	s_setprio 1
	v_mfma_f32_16x16x32_bf16 v[124:127], v[146:149], v[168:171], v[124:127]
	v_mfma_f32_16x16x32_bf16 v[120:123], v[160:163], v[168:171], v[120:123]
	v_mfma_f32_16x16x32_bf16 v[108:111], v[146:149], v[176:179], v[108:111]
	v_mfma_f32_16x16x32_bf16 v[104:107], v[160:163], v[176:179], v[104:107]
	v_mfma_f32_16x16x32_bf16 v[92:95], v[146:149], v[188:191], v[92:95]
	v_mfma_f32_16x16x32_bf16 v[88:91], v[160:163], v[188:191], v[88:91]
	v_mfma_f32_16x16x32_bf16 v[76:79], v[146:149], v[198:201], v[76:79]
	v_mfma_f32_16x16x32_bf16 v[72:75], v[160:163], v[198:201], v[72:75]
	v_mfma_f32_16x16x32_bf16 v[124:127], v[150:153], v[172:175], v[124:127]
	v_mfma_f32_16x16x32_bf16 v[120:123], v[164:167], v[172:175], v[120:123]
	v_mfma_f32_16x16x32_bf16 v[108:111], v[150:153], v[180:183], v[108:111]
	v_mfma_f32_16x16x32_bf16 v[104:107], v[164:167], v[180:183], v[104:107]
	v_mfma_f32_16x16x32_bf16 v[92:95], v[150:153], v[194:197], v[92:95]
	v_mfma_f32_16x16x32_bf16 v[88:91], v[164:167], v[194:197], v[88:91]
	v_mfma_f32_16x16x32_bf16 v[76:79], v[150:153], v[202:205], v[76:79]
	v_mfma_f32_16x16x32_bf16 v[72:75], v[164:167], v[202:205], v[72:75]
	s_setprio 0
	s_barrier
	s_add_i32 s5, 0, 0x1c000
	s_add_i32 s0, s4, s50
	v_add_u32_e32 v223, s5, v157
	s_add_i32 m0, s0, 0xffffff80
	ds_read_b128 v[206:209], v223
	ds_read_b128 v[210:213], v223 offset:1024
	ds_read_b128 v[214:217], v223 offset:2048
	global_load_lds_dwordx4 v130, s[44:45] offset:128
	s_add_i32 m0, s0, 0x1f80
	ds_read_b128 v[218:221], v223 offset:3072
	global_load_lds_dwordx4 v134, s[44:45] offset:128
	s_barrier
; #define PG8_STAGE(bufoff, gbase, voff) do { _Pragma("unroll") for (int _i = 0; _i < 2; ++_i) \
;         __builtin_amdgcn_global_load_lds((const unsigned*)((const char*)(gbase) + (voff)[_i]), (LAS unsigned*)(lds + (bufoff) + ldsw + _i * 8192), 16, 0, 0); } while (0)
; #define PG8_LDA(dst, b, h) do { _Pragma("unroll") for (int m = 0; m < 4; ++m) _Pragma("unroll") for (int k = 0; k < 2; ++k) dst[m][k] = *(const LAS bf16x8*)(lds + PG8_SA(b, h) + aoff + m * 2048 + k * 1024); } while (0)
; #define PG8_MMA(ai, bj, At, Bt) do { __builtin_amdgcn_s_setprio(1); _Pragma("unroll") for (int m = 0; m < 4; ++m) _Pragma("unroll") for (int n = 0; n < 2; ++n) _Pragma("unroll") for (int k = 0; k < 2; ++k) \
;         acc[ai][bj][m][n] = __builtin_amdgcn_mfma_f32_16x16x32_bf16(Bt[n][k], At[m][k], acc[ai][bj][m][n], 0, 0, 0); __builtin_amdgcn_s_setprio(0); } while (0)
; #define PG8_WAIT_V(n) asm volatile("s_waitcnt vmcnt(" #n ")" ::: "memory")
; #define PG8_WAIT_L(n) asm volatile("s_waitcnt lgkmcnt(" #n ")" ::: "memory")
; #define PG8_BAR __builtin_amdgcn_s_barrier()
; #define PG8_SCHED __builtin_amdgcn_sched_barrier(0)
; template <class Epi, class Sched>
; DI void gemm_phase(LAS unsigned char* lds, const Gemm g, const Sched& S, const Epi& E) {
;     ...
;             PG8_LDA(At, 1, 1); PG8_STAGE(PG8_SA(1, 0), a3, voffA);
;             PG8_BAR; PG8_WAIT_L(0); PG8_MMA(1, 0, At, B0); PG8_BAR; PG8_SCHED;
;             PG8_STAGE(PG8_SB(1, 1), b3 + hstep, voffB);
;             PG8_WAIT_V(6); PG8_BAR; PG8_MMA(1, 1, At, B1); PG8_BAR;
	s_waitcnt lgkmcnt(0)
	s_setprio 1
	v_mfma_f32_16x16x32_bf16 v[116:119], v[206:209], v[168:171], v[116:119]
	v_mfma_f32_16x16x32_bf16 v[112:115], v[214:217], v[168:171], v[112:115]
	v_mfma_f32_16x16x32_bf16 v[100:103], v[206:209], v[176:179], v[100:103]
	v_mfma_f32_16x16x32_bf16 v[96:99], v[214:217], v[176:179], v[96:99]
	v_mfma_f32_16x16x32_bf16 v[84:87], v[206:209], v[188:191], v[84:87]
	v_mfma_f32_16x16x32_bf16 v[80:83], v[214:217], v[188:191], v[80:83]
	v_mfma_f32_16x16x32_bf16 v[68:71], v[206:209], v[198:201], v[68:71]
	v_mfma_f32_16x16x32_bf16 v[64:67], v[214:217], v[198:201], v[64:67]
	v_mfma_f32_16x16x32_bf16 v[116:119], v[210:213], v[172:175], v[116:119]
	v_mfma_f32_16x16x32_bf16 v[112:115], v[218:221], v[172:175], v[112:115]
	v_mfma_f32_16x16x32_bf16 v[100:103], v[210:213], v[180:183], v[100:103]
	v_mfma_f32_16x16x32_bf16 v[96:99], v[218:221], v[180:183], v[96:99]
	v_mfma_f32_16x16x32_bf16 v[84:87], v[210:213], v[194:197], v[84:87]
	v_mfma_f32_16x16x32_bf16 v[80:83], v[218:221], v[194:197], v[80:83]
	v_mfma_f32_16x16x32_bf16 v[68:71], v[210:213], v[202:205], v[68:71]
	v_mfma_f32_16x16x32_bf16 v[64:67], v[218:221], v[202:205], v[64:67]
	s_setprio 0
	s_add_i32 m0, s62, 0xffffff80
	s_barrier
	ds_read_b128 v[168:171], v158 offset:49152
	ds_read_b128 v[172:175], v158 offset:50176
	ds_read_b128 v[176:179], v158 offset:51200
	ds_read_b128 v[180:183], v158 offset:52224
	ds_read_b128 v[188:191], v158 offset:53248
	ds_read_b128 v[194:197], v158 offset:54272
	ds_read_b128 v[198:201], v158 offset:55296
	global_load_lds_dwordx4 v128, s[46:47] offset:128
	s_add_i32 m0, s63, 0xffffff80
	ds_read_b128 v[202:205], v158 offset:56320
	global_load_lds_dwordx4 v132, s[46:47] offset:128
	s_barrier
	s_waitcnt lgkmcnt(0)
	s_setprio 1
	v_mfma_f32_16x16x32_bf16 v[60:63], v[146:149], v[168:171], v[60:63]
	v_mfma_f32_16x16x32_bf16 v[56:59], v[160:163], v[168:171], v[56:59]
	v_mfma_f32_16x16x32_bf16 v[44:47], v[146:149], v[176:179], v[44:47]
	v_mfma_f32_16x16x32_bf16 v[40:43], v[160:163], v[176:179], v[40:43]
	v_mfma_f32_16x16x32_bf16 v[28:31], v[146:149], v[188:191], v[28:31]
	v_mfma_f32_16x16x32_bf16 v[24:27], v[160:163], v[188:191], v[24:27]
	v_mfma_f32_16x16x32_bf16 v[12:15], v[146:149], v[198:201], v[12:15]
	v_mfma_f32_16x16x32_bf16 v[8:11], v[160:163], v[198:201], v[8:11]
	v_mfma_f32_16x16x32_bf16 v[60:63], v[150:153], v[172:175], v[60:63]
	v_mfma_f32_16x16x32_bf16 v[56:59], v[164:167], v[172:175], v[56:59]
	v_mfma_f32_16x16x32_bf16 v[44:47], v[150:153], v[180:183], v[44:47]
	v_mfma_f32_16x16x32_bf16 v[40:43], v[164:167], v[180:183], v[40:43]
	v_mfma_f32_16x16x32_bf16 v[28:31], v[150:153], v[194:197], v[28:31]
	v_mfma_f32_16x16x32_bf16 v[24:27], v[164:167], v[194:197], v[24:27]
	v_mfma_f32_16x16x32_bf16 v[12:15], v[150:153], v[202:205], v[12:15]
	v_mfma_f32_16x16x32_bf16 v[8:11], v[164:167], v[202:205], v[8:11]
	s_setprio 0
	s_barrier
	s_add_i32 s4, s5, s50
	s_mov_b32 m0, s4
	s_add_u32 s0, s44, 0x20080
	s_addc_u32 s1, s45, 0
	global_load_lds_dwordx4 v130, s[0:1]
	v_lshl_add_u64 v[146:147], s[0:1], 0, v[134:135]
	s_add_i32 m0, s4, 0x2000
	s_nop 0
	global_load_lds_dwordx4 v134, s[0:1]
	s_add_i32 s79, s79, 2
	s_add_u32 s42, s42, 0x100
	s_addc_u32 s43, s43, 0
	s_add_u32 s35, s35, 0x100
	s_addc_u32 s41, s41, 0
	s_cmp_gt_u32 s79, 5
	s_waitcnt vmcnt(6)
	s_barrier
	s_setprio 1
	v_mfma_f32_16x16x32_bf16 v[52:55], v[206:209], v[168:171], v[52:55]
	v_mfma_f32_16x16x32_bf16 v[48:51], v[214:217], v[168:171], v[48:51]
	v_mfma_f32_16x16x32_bf16 v[36:39], v[206:209], v[176:179], v[36:39]
	v_mfma_f32_16x16x32_bf16 v[32:35], v[214:217], v[176:179], v[32:35]
	v_mfma_f32_16x16x32_bf16 v[20:23], v[206:209], v[188:191], v[20:23]
	v_mfma_f32_16x16x32_bf16 v[16:19], v[214:217], v[188:191], v[16:19]
	v_mfma_f32_16x16x32_bf16 v[4:7], v[206:209], v[198:201], v[4:7]
	v_mfma_f32_16x16x32_bf16 v[0:3], v[214:217], v[198:201], v[0:3]
	v_mfma_f32_16x16x32_bf16 v[52:55], v[210:213], v[172:175], v[52:55]
	v_mfma_f32_16x16x32_bf16 v[48:51], v[218:221], v[172:175], v[48:51]
	v_mfma_f32_16x16x32_bf16 v[36:39], v[210:213], v[180:183], v[36:39]
	v_mfma_f32_16x16x32_bf16 v[32:35], v[218:221], v[180:183], v[32:35]
	v_mfma_f32_16x16x32_bf16 v[20:23], v[210:213], v[194:197], v[20:23]
	v_mfma_f32_16x16x32_bf16 v[16:19], v[218:221], v[194:197], v[16:19]
	v_mfma_f32_16x16x32_bf16 v[4:7], v[210:213], v[202:205], v[4:7]
	v_mfma_f32_16x16x32_bf16 v[0:3], v[218:221], v[202:205], v[0:3]
	s_setprio 0
	s_cbranch_scc0 .Lrot_984
	s_barrier
	s_branch .Lpeel_done_984

; #define PG8_STAGE(bufoff, gbase, voff) do { _Pragma("unroll") for (int _i = 0; _i < 2; ++_i) \
;         __builtin_amdgcn_global_load_lds((const unsigned*)((const char*)(gbase) + (voff)[_i]), (LAS unsigned*)(lds + (bufoff) + ldsw + _i * 8192), 16, 0, 0); } while (0)
; #define PG8_LDA(dst, b, h) do { _Pragma("unroll") for (int m = 0; m < 4; ++m) _Pragma("unroll") for (int k = 0; k < 2; ++k) dst[m][k] = *(const LAS bf16x8*)(lds + PG8_SA(b, h) + aoff + m * 2048 + k * 1024); } while (0)
; #define PG8_LDB(dst, b, h) do { _Pragma("unroll") for (int n = 0; n < 2; ++n) _Pragma("unroll") for (int k = 0; k < 2; ++k) dst[n][k] = *(const LAS bf16x8*)(lds + PG8_SB(b, h) + boff + n * 2048 + k * 1024); } while (0)
; #define PG8_MMA(ai, bj, At, Bt) do { __builtin_amdgcn_s_setprio(1); _Pragma("unroll") for (int m = 0; m < 4; ++m) _Pragma("unroll") for (int n = 0; n < 2; ++n) _Pragma("unroll") for (int k = 0; k < 2; ++k) \
;         acc[ai][bj][m][n] = __builtin_amdgcn_mfma_f32_16x16x32_bf16(Bt[n][k], At[m][k], acc[ai][bj][m][n], 0, 0, 0); __builtin_amdgcn_s_setprio(0); } while (0)
; #define PG8_WAIT_V(n) asm volatile("s_waitcnt vmcnt(" #n ")" ::: "memory")
; #define PG8_WAIT_L(n) asm volatile("s_waitcnt lgkmcnt(" #n ")" ::: "memory")
; #define PG8_BAR __builtin_amdgcn_s_barrier()
; #define PG8_SCHED __builtin_amdgcn_sched_barrier(0)
; template <class Epi, class Sched>
; DI void gemm_phase(LAS unsigned char* lds, const Gemm g, const Sched& S, const Epi& E) {
;     ...
;             const char* a2 = last ? nA : cA + (size_t)(t + 2) * kstep; const char* b2 = last ? nB : cB + (size_t)(t + 2) * kstep;
;             const char* a3 = a2 + kstep; const char* b3 = b2 + kstep;
;             PG8_LDB(B0, 0, 0); PG8_SCHED; PG8_LDA(At, 0, 0); PG8_STAGE(PG8_SA(1, 1), a1 + hstep, voffA);
;             PG8_WAIT_L(8); PG8_BAR; PG8_WAIT_L(0); PG8_MMA(0, 0, At, B0); PG8_BAR; PG8_SCHED;
;             PG8_LDB(B1, 0, 1); PG8_STAGE(PG8_SB(0, 0), b2, voffB);
;             PG8_BAR; PG8_WAIT_L(0); PG8_MMA(0, 1, At, B1); PG8_BAR;
;             PG8_LDA(At, 0, 1); PG8_STAGE(PG8_SA(0, 0), a2, voffA);
;             PG8_BAR; PG8_WAIT_L(0); PG8_MMA(1, 0, At, B0); PG8_BAR; PG8_SCHED;
;             PG8_STAGE(PG8_SB(0, 1), b2 + hstep, voffB);
;             PG8_WAIT_V(6); PG8_BAR; PG8_MMA(1, 1, At, B1); PG8_BAR;
.LBB0_984:
	ds_read_b128 v[146:149], v156
	ds_read_b128 v[150:153], v156 offset:1024
	ds_read_b128 v[160:163], v156 offset:2048
	ds_read_b128 v[164:167], v156 offset:3072
	s_add_i32 m0, s55, 0xc000
	ds_read_b128 v[168:171], v158
	ds_read_b128 v[172:175], v158 offset:1024
	ds_read_b128 v[176:179], v158 offset:2048
	ds_read_b128 v[180:183], v158 offset:3072
	ds_read_b128 v[188:191], v158 offset:4096
	ds_read_b128 v[194:197], v158 offset:5120
	ds_read_b128 v[198:201], v158 offset:6144
	global_load_lds_dwordx4 v138, s[42:43]
	s_add_i32 m0, s55, 0xe000
	ds_read_b128 v[202:205], v158 offset:7168
	global_load_lds_dwordx4 v140, s[42:43]
	s_add_u32 s0, s42, 0xfffe0080
	s_addc_u32 s1, s43, -1
	s_cmp_eq_u32 s79, 4
	s_cselect_b32 s47, s9, s1
	s_cselect_b32 s46, s31, s0
	s_cselect_b32 s45, s29, s41
	s_cselect_b32 s44, s34, s35
	s_waitcnt lgkmcnt(8)
	s_barrier
	s_waitcnt lgkmcnt(0)
	s_setprio 1
	v_mfma_f32_16x16x32_bf16 v[124:127], v[146:149], v[168:171], v[124:127]
	v_mfma_f32_16x16x32_bf16 v[120:123], v[160:163], v[168:171], v[120:123]
	v_mfma_f32_16x16x32_bf16 v[108:111], v[146:149], v[176:179], v[108:111]
	v_mfma_f32_16x16x32_bf16 v[104:107], v[160:163], v[176:179], v[104:107]
	v_mfma_f32_16x16x32_bf16 v[92:95], v[146:149], v[188:191], v[92:95]
	v_mfma_f32_16x16x32_bf16 v[88:91], v[160:163], v[188:191], v[88:91]
	v_mfma_f32_16x16x32_bf16 v[76:79], v[146:149], v[198:201], v[76:79]
	v_mfma_f32_16x16x32_bf16 v[72:75], v[160:163], v[198:201], v[72:75]
	v_mfma_f32_16x16x32_bf16 v[124:127], v[150:153], v[172:175], v[124:127]
	v_mfma_f32_16x16x32_bf16 v[120:123], v[164:167], v[172:175], v[120:123]
	v_mfma_f32_16x16x32_bf16 v[108:111], v[150:153], v[180:183], v[108:111]
	v_mfma_f32_16x16x32_bf16 v[104:107], v[164:167], v[180:183], v[104:107]
	v_mfma_f32_16x16x32_bf16 v[92:95], v[150:153], v[194:197], v[92:95]
	v_mfma_f32_16x16x32_bf16 v[88:91], v[164:167], v[194:197], v[88:91]
	v_mfma_f32_16x16x32_bf16 v[76:79], v[150:153], v[202:205], v[76:79]
	v_mfma_f32_16x16x32_bf16 v[72:75], v[164:167], v[202:205], v[72:75]
	s_setprio 0
	s_barrier
	s_add_i32 s0, s66, s50
	s_mov_b32 m0, s0
	ds_read_b128 v[206:209], v159
	ds_read_b128 v[210:213], v159 offset:1024
	ds_read_b128 v[214:217], v159 offset:2048
	global_load_lds_dwordx4 v130, s[44:45]
	s_add_i32 m0, s0, 0x2000
	ds_read_b128 v[218:221], v159 offset:3072
	global_load_lds_dwordx4 v134, s[44:45]
	s_barrier
	s_waitcnt lgkmcnt(0)
	s_setprio 1
	v_mfma_f32_16x16x32_bf16 v[116:119], v[206:209], v[168:171], v[116:119]
	v_mfma_f32_16x16x32_bf16 v[112:115], v[214:217], v[168:171], v[112:115]
	v_mfma_f32_16x16x32_bf16 v[100:103], v[206:209], v[176:179], v[100:103]
	v_mfma_f32_16x16x32_bf16 v[96:99], v[214:217], v[176:179], v[96:99]
	v_mfma_f32_16x16x32_bf16 v[84:87], v[206:209], v[188:191], v[84:87]
	v_mfma_f32_16x16x32_bf16 v[80:83], v[214:217], v[188:191], v[80:83]
	v_mfma_f32_16x16x32_bf16 v[68:71], v[206:209], v[198:201], v[68:71]
	v_mfma_f32_16x16x32_bf16 v[64:67], v[214:217], v[198:201], v[64:67]
	v_mfma_f32_16x16x32_bf16 v[116:119], v[210:213], v[172:175], v[116:119]
	v_mfma_f32_16x16x32_bf16 v[112:115], v[218:221], v[172:175], v[112:115]
	v_mfma_f32_16x16x32_bf16 v[100:103], v[210:213], v[180:183], v[100:103]
	v_mfma_f32_16x16x32_bf16 v[96:99], v[218:221], v[180:183], v[96:99]
	v_mfma_f32_16x16x32_bf16 v[84:87], v[210:213], v[194:197], v[84:87]
	v_mfma_f32_16x16x32_bf16 v[80:83], v[218:221], v[194:197], v[80:83]
	v_mfma_f32_16x16x32_bf16 v[68:71], v[210:213], v[202:205], v[68:71]
	v_mfma_f32_16x16x32_bf16 v[64:67], v[218:221], v[202:205], v[64:67]
	s_setprio 0
	s_mov_b32 m0, s55
	s_barrier
	ds_read_b128 v[168:171], v158 offset:16384
	ds_read_b128 v[172:175], v158 offset:17408
	ds_read_b128 v[176:179], v158 offset:18432
	ds_read_b128 v[180:183], v158 offset:19456
	ds_read_b128 v[188:191], v158 offset:20480
	ds_read_b128 v[194:197], v158 offset:21504
	ds_read_b128 v[198:201], v158 offset:22528
	global_load_lds_dwordx4 v128, s[46:47]
	s_mov_b32 m0, s56
	ds_read_b128 v[202:205], v158 offset:23552
	global_load_lds_dwordx4 v132, s[46:47]
	s_barrier
	s_waitcnt lgkmcnt(0)
	s_setprio 1
	v_mfma_f32_16x16x32_bf16 v[60:63], v[146:149], v[168:171], v[60:63]
	v_mfma_f32_16x16x32_bf16 v[56:59], v[160:163], v[168:171], v[56:59]
	v_mfma_f32_16x16x32_bf16 v[44:47], v[146:149], v[176:179], v[44:47]
	v_mfma_f32_16x16x32_bf16 v[40:43], v[160:163], v[176:179], v[40:43]
	v_mfma_f32_16x16x32_bf16 v[28:31], v[146:149], v[188:191], v[28:31]
	v_mfma_f32_16x16x32_bf16 v[24:27], v[160:163], v[188:191], v[24:27]
	v_mfma_f32_16x16x32_bf16 v[12:15], v[146:149], v[198:201], v[12:15]
	v_mfma_f32_16x16x32_bf16 v[8:11], v[160:163], v[198:201], v[8:11]
	v_mfma_f32_16x16x32_bf16 v[60:63], v[150:153], v[172:175], v[60:63]
	v_mfma_f32_16x16x32_bf16 v[56:59], v[164:167], v[172:175], v[56:59]
	v_mfma_f32_16x16x32_bf16 v[44:47], v[150:153], v[180:183], v[44:47]
	v_mfma_f32_16x16x32_bf16 v[40:43], v[164:167], v[180:183], v[40:43]
	v_mfma_f32_16x16x32_bf16 v[28:31], v[150:153], v[194:197], v[28:31]
	v_mfma_f32_16x16x32_bf16 v[24:27], v[164:167], v[194:197], v[24:27]
	v_mfma_f32_16x16x32_bf16 v[12:15], v[150:153], v[202:205], v[12:15]
	v_mfma_f32_16x16x32_bf16 v[8:11], v[164:167], v[202:205], v[8:11]
	s_setprio 0
	s_barrier
	s_add_i32 s4, s67, s50
	s_mov_b32 m0, s4
	s_add_u32 s0, s44, 0x20000
	s_addc_u32 s1, s45, 0
	global_load_lds_dwordx4 v130, s[0:1]
	s_add_i32 m0, s4, 0x2000
	s_nop 0
	global_load_lds_dwordx4 v134, s[0:1]
	s_waitcnt vmcnt(6)
	s_barrier
; #define PG8_STAGE(bufoff, gbase, voff) do { _Pragma("unroll") for (int _i = 0; _i < 2; ++_i) \
;         __builtin_amdgcn_global_load_lds((const unsigned*)((const char*)(gbase) + (voff)[_i]), (LAS unsigned*)(lds + (bufoff) + ldsw + _i * 8192), 16, 0, 0); } while (0)
; #define PG8_LDA(dst, b, h) do { _Pragma("unroll") for (int m = 0; m < 4; ++m) _Pragma("unroll") for (int k = 0; k < 2; ++k) dst[m][k] = *(const LAS bf16x8*)(lds + PG8_SA(b, h) + aoff + m * 2048 + k * 1024); } while (0)
; #define PG8_LDB(dst, b, h) do { _Pragma("unroll") for (int n = 0; n < 2; ++n) _Pragma("unroll") for (int k = 0; k < 2; ++k) dst[n][k] = *(const LAS bf16x8*)(lds + PG8_SB(b, h) + boff + n * 2048 + k * 1024); } while (0)
; #define PG8_MMA(ai, bj, At, Bt) do { __builtin_amdgcn_s_setprio(1); _Pragma("unroll") for (int m = 0; m < 4; ++m) _Pragma("unroll") for (int n = 0; n < 2; ++n) _Pragma("unroll") for (int k = 0; k < 2; ++k) \
;         acc[ai][bj][m][n] = __builtin_amdgcn_mfma_f32_16x16x32_bf16(Bt[n][k], At[m][k], acc[ai][bj][m][n], 0, 0, 0); __builtin_amdgcn_s_setprio(0); } while (0)
; #define PG8_WAIT_V(n) asm volatile("s_waitcnt vmcnt(" #n ")" ::: "memory")
; #define PG8_WAIT_L(n) asm volatile("s_waitcnt lgkmcnt(" #n ")" ::: "memory")
; #define PG8_BAR __builtin_amdgcn_s_barrier()
; #define PG8_SCHED __builtin_amdgcn_sched_barrier(0)
; template <class Epi, class Sched>
; DI void gemm_phase(LAS unsigned char* lds, const Gemm g, const Sched& S, const Epi& E) {
;     ...
;             PG8_WAIT_V(6); PG8_BAR; PG8_MMA(1, 1, At, B1); PG8_BAR;
;             PG8_LDB(B0, 1, 0); PG8_SCHED; PG8_LDA(At, 1, 0); PG8_STAGE(PG8_SA(0, 1), a2 + hstep, voffA);
;             PG8_WAIT_L(8); PG8_BAR; PG8_WAIT_L(0); PG8_MMA(0, 0, At, B0); PG8_BAR; PG8_SCHED;
;             PG8_LDB(B1, 1, 1); PG8_STAGE(PG8_SB(1, 0), b3, voffB);
;             PG8_BAR; PG8_WAIT_L(0); PG8_MMA(0, 1, At, B1); PG8_BAR;
	s_setprio 1
	v_mfma_f32_16x16x32_bf16 v[52:55], v[206:209], v[168:171], v[52:55]
	v_mfma_f32_16x16x32_bf16 v[48:51], v[214:217], v[168:171], v[48:51]
	v_mfma_f32_16x16x32_bf16 v[36:39], v[206:209], v[176:179], v[36:39]
	v_mfma_f32_16x16x32_bf16 v[32:35], v[214:217], v[176:179], v[32:35]
	v_mfma_f32_16x16x32_bf16 v[20:23], v[206:209], v[188:191], v[20:23]
	v_mfma_f32_16x16x32_bf16 v[16:19], v[214:217], v[188:191], v[16:19]
	v_mfma_f32_16x16x32_bf16 v[4:7], v[206:209], v[198:201], v[4:7]
	v_mfma_f32_16x16x32_bf16 v[0:3], v[214:217], v[198:201], v[0:3]
	v_mfma_f32_16x16x32_bf16 v[52:55], v[210:213], v[172:175], v[52:55]
	v_mfma_f32_16x16x32_bf16 v[48:51], v[218:221], v[172:175], v[48:51]
	v_mfma_f32_16x16x32_bf16 v[36:39], v[210:213], v[180:183], v[36:39]
	v_mfma_f32_16x16x32_bf16 v[32:35], v[218:221], v[180:183], v[32:35]
	v_mfma_f32_16x16x32_bf16 v[20:23], v[210:213], v[194:197], v[20:23]
	v_mfma_f32_16x16x32_bf16 v[16:19], v[218:221], v[194:197], v[16:19]
	v_mfma_f32_16x16x32_bf16 v[4:7], v[210:213], v[202:205], v[4:7]
	v_mfma_f32_16x16x32_bf16 v[0:3], v[218:221], v[202:205], v[0:3]
	s_setprio 0
	s_add_i32 s4, 0, 0x18000
	s_barrier
	ds_read_b128 v[146:149], v222
	ds_read_b128 v[150:153], v222 offset:1024
	ds_read_b128 v[160:163], v222 offset:2048
	ds_read_b128 v[164:167], v222 offset:3072
	s_add_u32 s0, s46, 0x20000
	s_addc_u32 s1, s47, 0
	s_mov_b32 m0, s57
	ds_read_b128 v[168:171], v158 offset:32768
	ds_read_b128 v[172:175], v158 offset:33792
	ds_read_b128 v[176:179], v158 offset:34816
	ds_read_b128 v[180:183], v158 offset:35840
	ds_read_b128 v[188:191], v158 offset:36864
	ds_read_b128 v[194:197], v158 offset:37888
	ds_read_b128 v[198:201], v158 offset:38912
	global_load_lds_dwordx4 v128, s[0:1]
	s_mov_b32 m0, s58
	ds_read_b128 v[202:205], v158 offset:39936
	global_load_lds_dwordx4 v132, s[0:1]
	s_waitcnt lgkmcnt(8)
	s_barrier
	s_waitcnt lgkmcnt(0)
	s_setprio 1
	v_mfma_f32_16x16x32_bf16 v[124:127], v[146:149], v[168:171], v[124:127]
	v_mfma_f32_16x16x32_bf16 v[120:123], v[160:163], v[168:171], v[120:123]
	v_mfma_f32_16x16x32_bf16 v[108:111], v[146:149], v[176:179], v[108:111]
	v_mfma_f32_16x16x32_bf16 v[104:107], v[160:163], v[176:179], v[104:107]
	v_mfma_f32_16x16x32_bf16 v[92:95], v[146:149], v[188:191], v[92:95]
	v_mfma_f32_16x16x32_bf16 v[88:91], v[160:163], v[188:191], v[88:91]
	v_mfma_f32_16x16x32_bf16 v[76:79], v[146:149], v[198:201], v[76:79]
	v_mfma_f32_16x16x32_bf16 v[72:75], v[160:163], v[198:201], v[72:75]
	v_mfma_f32_16x16x32_bf16 v[124:127], v[150:153], v[172:175], v[124:127]
	v_mfma_f32_16x16x32_bf16 v[120:123], v[164:167], v[172:175], v[120:123]
	v_mfma_f32_16x16x32_bf16 v[108:111], v[150:153], v[180:183], v[108:111]
	v_mfma_f32_16x16x32_bf16 v[104:107], v[164:167], v[180:183], v[104:107]
	v_mfma_f32_16x16x32_bf16 v[92:95], v[150:153], v[194:197], v[92:95]
	v_mfma_f32_16x16x32_bf16 v[88:91], v[164:167], v[194:197], v[88:91]
	v_mfma_f32_16x16x32_bf16 v[76:79], v[150:153], v[202:205], v[76:79]
	v_mfma_f32_16x16x32_bf16 v[72:75], v[164:167], v[202:205], v[72:75]
	s_setprio 0
	s_barrier
	s_add_i32 s5, 0, 0x1c000
	s_add_i32 s0, s4, s50
	s_add_i32 m0, s0, 0xffffff80
	ds_read_b128 v[206:209], v223
	ds_read_b128 v[210:213], v223 offset:1024
	ds_read_b128 v[214:217], v223 offset:2048
	global_load_lds_dwordx4 v130, s[44:45] offset:128
	s_add_i32 m0, s0, 0x1f80
	ds_read_b128 v[218:221], v223 offset:3072
	global_load_lds_dwordx4 v134, s[44:45] offset:128
	s_barrier
; #define PG8_STAGE(bufoff, gbase, voff) do { _Pragma("unroll") for (int _i = 0; _i < 2; ++_i) \
;         __builtin_amdgcn_global_load_lds((const unsigned*)((const char*)(gbase) + (voff)[_i]), (LAS unsigned*)(lds + (bufoff) + ldsw + _i * 8192), 16, 0, 0); } while (0)
; #define PG8_LDA(dst, b, h) do { _Pragma("unroll") for (int m = 0; m < 4; ++m) _Pragma("unroll") for (int k = 0; k < 2; ++k) dst[m][k] = *(const LAS bf16x8*)(lds + PG8_SA(b, h) + aoff + m * 2048 + k * 1024); } while (0)
; #define PG8_MMA(ai, bj, At, Bt) do { __builtin_amdgcn_s_setprio(1); _Pragma("unroll") for (int m = 0; m < 4; ++m) _Pragma("unroll") for (int n = 0; n < 2; ++n) _Pragma("unroll") for (int k = 0; k < 2; ++k) \
;         acc[ai][bj][m][n] = __builtin_amdgcn_mfma_f32_16x16x32_bf16(Bt[n][k], At[m][k], acc[ai][bj][m][n], 0, 0, 0); __builtin_amdgcn_s_setprio(0); } while (0)
; #define PG8_WAIT_V(n) asm volatile("s_waitcnt vmcnt(" #n ")" ::: "memory")
; #define PG8_WAIT_L(n) asm volatile("s_waitcnt lgkmcnt(" #n ")" ::: "memory")
; #define PG8_BAR __builtin_amdgcn_s_barrier()
; #define PG8_SCHED __builtin_amdgcn_sched_barrier(0)
; template <class Epi, class Sched>
; DI void gemm_phase(LAS unsigned char* lds, const Gemm g, const Sched& S, const Epi& E) {
;     ...
;             PG8_LDA(At, 1, 1); PG8_STAGE(PG8_SA(1, 0), a3, voffA);
;             PG8_BAR; PG8_WAIT_L(0); PG8_MMA(1, 0, At, B0); PG8_BAR; PG8_SCHED;
;             PG8_STAGE(PG8_SB(1, 1), b3 + hstep, voffB);
;             PG8_WAIT_V(6); PG8_BAR; PG8_MMA(1, 1, At, B1); PG8_BAR;
	s_waitcnt lgkmcnt(0)
	s_setprio 1
	v_mfma_f32_16x16x32_bf16 v[116:119], v[206:209], v[168:171], v[116:119]
	v_mfma_f32_16x16x32_bf16 v[112:115], v[214:217], v[168:171], v[112:115]
	v_mfma_f32_16x16x32_bf16 v[100:103], v[206:209], v[176:179], v[100:103]
	v_mfma_f32_16x16x32_bf16 v[96:99], v[214:217], v[176:179], v[96:99]
	v_mfma_f32_16x16x32_bf16 v[84:87], v[206:209], v[188:191], v[84:87]
	v_mfma_f32_16x16x32_bf16 v[80:83], v[214:217], v[188:191], v[80:83]
	v_mfma_f32_16x16x32_bf16 v[68:71], v[206:209], v[198:201], v[68:71]
	v_mfma_f32_16x16x32_bf16 v[64:67], v[214:217], v[198:201], v[64:67]
	v_mfma_f32_16x16x32_bf16 v[116:119], v[210:213], v[172:175], v[116:119]
	v_mfma_f32_16x16x32_bf16 v[112:115], v[218:221], v[172:175], v[112:115]
	v_mfma_f32_16x16x32_bf16 v[100:103], v[210:213], v[180:183], v[100:103]
	v_mfma_f32_16x16x32_bf16 v[96:99], v[218:221], v[180:183], v[96:99]
	v_mfma_f32_16x16x32_bf16 v[84:87], v[210:213], v[194:197], v[84:87]
	v_mfma_f32_16x16x32_bf16 v[80:83], v[218:221], v[194:197], v[80:83]
	v_mfma_f32_16x16x32_bf16 v[68:71], v[210:213], v[202:205], v[68:71]
	v_mfma_f32_16x16x32_bf16 v[64:67], v[218:221], v[202:205], v[64:67]
	s_setprio 0
	s_add_i32 m0, s62, 0xffffff80
	s_barrier
	ds_read_b128 v[168:171], v158 offset:49152
	ds_read_b128 v[172:175], v158 offset:50176
	ds_read_b128 v[176:179], v158 offset:51200
	ds_read_b128 v[180:183], v158 offset:52224
	ds_read_b128 v[188:191], v158 offset:53248
	ds_read_b128 v[194:197], v158 offset:54272
	ds_read_b128 v[198:201], v158 offset:55296
	global_load_lds_dwordx4 v128, s[46:47] offset:128
	s_add_i32 m0, s63, 0xffffff80
	ds_read_b128 v[202:205], v158 offset:56320
	global_load_lds_dwordx4 v132, s[46:47] offset:128
	s_barrier
	s_waitcnt lgkmcnt(0)
	s_setprio 1
	v_mfma_f32_16x16x32_bf16 v[60:63], v[146:149], v[168:171], v[60:63]
	v_mfma_f32_16x16x32_bf16 v[56:59], v[160:163], v[168:171], v[56:59]
	v_mfma_f32_16x16x32_bf16 v[44:47], v[146:149], v[176:179], v[44:47]
	v_mfma_f32_16x16x32_bf16 v[40:43], v[160:163], v[176:179], v[40:43]
	v_mfma_f32_16x16x32_bf16 v[28:31], v[146:149], v[188:191], v[28:31]
	v_mfma_f32_16x16x32_bf16 v[24:27], v[160:163], v[188:191], v[24:27]
	v_mfma_f32_16x16x32_bf16 v[12:15], v[146:149], v[198:201], v[12:15]
	v_mfma_f32_16x16x32_bf16 v[8:11], v[160:163], v[198:201], v[8:11]
	v_mfma_f32_16x16x32_bf16 v[60:63], v[150:153], v[172:175], v[60:63]
	v_mfma_f32_16x16x32_bf16 v[56:59], v[164:167], v[172:175], v[56:59]
	v_mfma_f32_16x16x32_bf16 v[44:47], v[150:153], v[180:183], v[44:47]
	v_mfma_f32_16x16x32_bf16 v[40:43], v[164:167], v[180:183], v[40:43]
	v_mfma_f32_16x16x32_bf16 v[28:31], v[150:153], v[194:197], v[28:31]
	v_mfma_f32_16x16x32_bf16 v[24:27], v[164:167], v[194:197], v[24:27]
	v_mfma_f32_16x16x32_bf16 v[12:15], v[150:153], v[202:205], v[12:15]
	v_mfma_f32_16x16x32_bf16 v[8:11], v[164:167], v[202:205], v[8:11]
	s_setprio 0
	s_barrier
	s_add_i32 s4, s5, s50
	s_mov_b32 m0, s4
	s_add_u32 s0, s44, 0x20080
	s_addc_u32 s1, s45, 0
	global_load_lds_dwordx4 v130, s[0:1]
	v_lshl_add_u64 v[146:147], s[0:1], 0, v[134:135]
	s_add_i32 m0, s4, 0x2000
	s_nop 0
	global_load_lds_dwordx4 v134, s[0:1]
	s_add_i32 s79, s79, 2
	s_add_u32 s42, s42, 0x100
	s_addc_u32 s43, s43, 0
	s_add_u32 s35, s35, 0x100
	s_addc_u32 s41, s41, 0
	s_cmp_gt_u32 s79, 5
	s_waitcnt vmcnt(6)
	s_barrier
	s_setprio 1
	v_mfma_f32_16x16x32_bf16 v[52:55], v[206:209], v[168:171], v[52:55]
	v_mfma_f32_16x16x32_bf16 v[48:51], v[214:217], v[168:171], v[48:51]
	v_mfma_f32_16x16x32_bf16 v[36:39], v[206:209], v[176:179], v[36:39]
	v_mfma_f32_16x16x32_bf16 v[32:35], v[214:217], v[176:179], v[32:35]
	v_mfma_f32_16x16x32_bf16 v[20:23], v[206:209], v[188:191], v[20:23]
	v_mfma_f32_16x16x32_bf16 v[16:19], v[214:217], v[188:191], v[16:19]
	v_mfma_f32_16x16x32_bf16 v[4:7], v[206:209], v[198:201], v[4:7]
	v_mfma_f32_16x16x32_bf16 v[0:3], v[214:217], v[198:201], v[0:3]
	v_mfma_f32_16x16x32_bf16 v[52:55], v[210:213], v[172:175], v[52:55]
	v_mfma_f32_16x16x32_bf16 v[48:51], v[218:221], v[172:175], v[48:51]
	v_mfma_f32_16x16x32_bf16 v[36:39], v[210:213], v[180:183], v[36:39]
	v_mfma_f32_16x16x32_bf16 v[32:35], v[218:221], v[180:183], v[32:35]
	v_mfma_f32_16x16x32_bf16 v[20:23], v[210:213], v[194:197], v[20:23]
	v_mfma_f32_16x16x32_bf16 v[16:19], v[218:221], v[194:197], v[16:19]
	v_mfma_f32_16x16x32_bf16 v[4:7], v[210:213], v[202:205], v[4:7]
	v_mfma_f32_16x16x32_bf16 v[0:3], v[218:221], v[202:205], v[0:3]
	s_setprio 0
	s_cbranch_scc0 .Lrot_984
	s_barrier

;     DI size_t aoff(const Unit& u, size_t tstep) const { return (size_t)u.pm * tstep; }
;     DI size_t boff(const Unit& u, size_t tstep) const { return (size_t)u.pn * tstep; }
;     DI bool next(int i, Unit& u) const { const long L = (long)i * G + c; if (L >= np) return false; u.pm = pmv; u.pn = (int)(L % nN); u.ks = (int)(L / nN); return true; }
;     DI size_t aoff(const Unit& u, size_t) const { return (size_t)u.ks * kbytes; }
;     DI size_t boff(const Unit& u, size_t tstep) const { return (size_t)u.pn * tstep + (size_t)u.ks * kbytes; }
;     DI bool next(int i, Unit& u) const { Unit t; if (!S.next(i / 3, t)) return false; u.pm = t.pm; u.pn = t.pn; u.ks = i % 3; return true; }
;     DI size_t aoff(const Unit& u, size_t tstep) const { return (u.ks < 2 ? offU : offOA) + (size_t)u.pm * tstep; }
; #define PG8_WAIT_V(n) asm volatile("s_waitcnt vmcnt(" #n ")" ::: "memory")
; template <class Epi, class Sched>
; DI void gemm_phase(LAS unsigned char* lds, const Gemm g, const Sched& S, const Epi& E) {
;     ...
;         const bool has_next = S.next(ui + 1, nxt);
;         const char* nA = has_next ? (const char*)g.A + S.aoff(nxt, tstep) : cA; const char* nB = has_next ? (const char*)g.Bt + S.boff(nxt, tstep) : cB;
;         for (int t = 0; t < nt; t += 2) {
;             if constexpr (Epi::HAS_MID) { if (t == E.mid_t(nt)) { int fr3 = fr, fq3 = fq; asm volatile("" : "+v"(fr3), "+v"(fq3)); E.mid(acc, cur, wr, wc, fr3, fq3); } }
;             const bool last = (t == nt - 2);
;             const char* a1 = cA + (size_t)(t + 1) * kstep;
;             const char* a2 = last ? nA : cA + (size_t)(t + 2) * kstep; const char* b2 = last ? nB : cB + (size_t)(t + 2) * kstep;
;             const char* a3 = a2 + kstep; const char* b3 = b2 + kstep;
;             PG8_LDB(B0, 0, 0); PG8_SCHED; PG8_LDA(At, 0, 0); PG8_STAGE(PG8_SA(1, 1), a1 + hstep, voffA);
;             PG8_WAIT_L(8); PG8_BAR; PG8_WAIT_L(0); PG8_MMA(0, 0, At, B0); PG8_BAR; PG8_SCHED;
;             PG8_LDB(B1, 0, 1); PG8_STAGE(PG8_SB(0, 0), b2, voffB);
;             PG8_BAR; PG8_WAIT_L(0); PG8_MMA(0, 1, At, B1); PG8_BAR;
;             PG8_LDA(At, 0, 1); PG8_STAGE(PG8_SA(0, 0), a2, voffA);
;             PG8_BAR; PG8_WAIT_L(0); PG8_MMA(1, 0, At, B0); PG8_BAR; PG8_SCHED;
;             PG8_STAGE(PG8_SB(0, 1), b2 + hstep, voffB);
;             PG8_WAIT_V(6); PG8_BAR; PG8_MMA(1, 1, At, B1); PG8_BAR;
.LBB0_1507:
	s_ashr_i32 s37, s36, 31
	s_lshl_b64 s[0:1], s[36:37], 20
	v_cmp_lt_i64_e32 vcc, s[38:39], v[140:141]
	s_add_u32 s38, s13, s0
	s_addc_u32 s39, s50, s1
	s_and_b64 s[0:1], vcc, exec
	s_cselect_b32 s34, s39, s45
	s_cselect_b32 s35, s38, s44
	s_ashr_i32 s31, s30, 31
	s_lshl_b64 s[0:1], s[30:31], 20
	s_add_u32 s40, s55, s0
	s_addc_u32 s41, s56, s1
	s_and_b64 s[0:1], vcc, exec
	s_cselect_b32 s31, s41, s47
	s_cselect_b32 s37, s40, s46
	s_add_u32 s44, s44, 0x80080
	s_addc_u32 s45, s45, 0
	s_add_u32 s43, s46, 0x100
	v_mov_b32_e32 v0, 0
	s_addc_u32 s68, s47, 0
	s_mov_b32 s69, -2
	s_waitcnt lgkmcnt(0)
	ds_read_b128 v[144:147], v150
	ds_read_b128 v[154:157], v150 offset:1024
	ds_read_b128 v[158:161], v150 offset:2048
	ds_read_b128 v[162:165], v150 offset:3072
	s_add_i32 m0, s52, 0xc000
	ds_read_b128 v[166:169], v151
	ds_read_b128 v[170:173], v151 offset:1024
	ds_read_b128 v[174:177], v151 offset:2048
	ds_read_b128 v[178:181], v151 offset:3072
	ds_read_b128 v[188:191], v151 offset:4096
	ds_read_b128 v[206:209], v151 offset:5120
	ds_read_b128 v[210:213], v151 offset:6144
	global_load_lds_dwordx4 v136, s[44:45]
	s_add_i32 m0, s52, 0xe000
	ds_read_b128 v[214:217], v151 offset:7168
	global_load_lds_dwordx4 v138, s[44:45]
	s_add_u32 s0, s44, 0xfff80080
	s_addc_u32 s1, s45, -1
	s_cmp_eq_u32 s69, 28
	s_cselect_b32 s49, s34, s1
	s_cselect_b32 s48, s35, s0
	s_cselect_b32 s47, s31, s68
	s_cselect_b32 s46, s37, s43
	s_waitcnt lgkmcnt(8)
	s_barrier
	s_waitcnt lgkmcnt(0)
	s_setprio 1
	v_mfma_f32_16x16x32_bf16 v[124:127], v[144:147], v[166:169], 0
	v_mfma_f32_16x16x32_bf16 v[120:123], v[158:161], v[166:169], 0
	v_mfma_f32_16x16x32_bf16 v[108:111], v[144:147], v[174:177], 0
	v_mfma_f32_16x16x32_bf16 v[104:107], v[158:161], v[174:177], 0
	v_mfma_f32_16x16x32_bf16 v[92:95], v[144:147], v[188:191], 0
	v_mfma_f32_16x16x32_bf16 v[88:91], v[158:161], v[188:191], 0
	v_mfma_f32_16x16x32_bf16 v[76:79], v[144:147], v[210:213], 0
	v_mfma_f32_16x16x32_bf16 v[72:75], v[158:161], v[210:213], 0
	v_mfma_f32_16x16x32_bf16 v[124:127], v[154:157], v[170:173], v[124:127]
	v_mfma_f32_16x16x32_bf16 v[120:123], v[162:165], v[170:173], v[120:123]
	v_mfma_f32_16x16x32_bf16 v[108:111], v[154:157], v[178:181], v[108:111]
	v_mfma_f32_16x16x32_bf16 v[104:107], v[162:165], v[178:181], v[104:107]
	v_mfma_f32_16x16x32_bf16 v[92:95], v[154:157], v[206:209], v[92:95]
	v_mfma_f32_16x16x32_bf16 v[88:91], v[162:165], v[206:209], v[88:91]
	v_mfma_f32_16x16x32_bf16 v[76:79], v[154:157], v[214:217], v[76:79]
	v_mfma_f32_16x16x32_bf16 v[72:75], v[162:165], v[214:217], v[72:75]
	s_setprio 0
	s_barrier
	s_add_i32 s0, s65, s51
	s_mov_b32 m0, s0
	ds_read_b128 v[218:221], v152
	ds_read_b128 v[222:225], v152 offset:1024
	ds_read_b128 v[226:229], v152 offset:2048
	global_load_lds_dwordx4 v132, s[46:47]
	s_add_i32 m0, s0, 0x2000
	ds_read_b128 v[230:233], v152 offset:3072
	global_load_lds_dwordx4 v134, s[46:47]
	s_barrier
	s_waitcnt lgkmcnt(0)
	s_setprio 1
	v_mfma_f32_16x16x32_bf16 v[116:119], v[218:221], v[166:169], 0
	v_mfma_f32_16x16x32_bf16 v[112:115], v[226:229], v[166:169], 0
	v_mfma_f32_16x16x32_bf16 v[100:103], v[218:221], v[174:177], 0
	v_mfma_f32_16x16x32_bf16 v[96:99], v[226:229], v[174:177], 0
	v_mfma_f32_16x16x32_bf16 v[84:87], v[218:221], v[188:191], 0
	v_mfma_f32_16x16x32_bf16 v[80:83], v[226:229], v[188:191], 0
	v_mfma_f32_16x16x32_bf16 v[68:71], v[218:221], v[210:213], 0
	v_mfma_f32_16x16x32_bf16 v[64:67], v[226:229], v[210:213], 0
	v_mfma_f32_16x16x32_bf16 v[116:119], v[222:225], v[170:173], v[116:119]
	v_mfma_f32_16x16x32_bf16 v[112:115], v[230:233], v[170:173], v[112:115]
	v_mfma_f32_16x16x32_bf16 v[100:103], v[222:225], v[178:181], v[100:103]
	v_mfma_f32_16x16x32_bf16 v[96:99], v[230:233], v[178:181], v[96:99]
	v_mfma_f32_16x16x32_bf16 v[84:87], v[222:225], v[206:209], v[84:87]
	v_mfma_f32_16x16x32_bf16 v[80:83], v[230:233], v[206:209], v[80:83]
	v_mfma_f32_16x16x32_bf16 v[68:71], v[222:225], v[214:217], v[68:71]
	v_mfma_f32_16x16x32_bf16 v[64:67], v[230:233], v[214:217], v[64:67]
	s_setprio 0
	s_mov_b32 m0, s52
	s_barrier
	ds_read_b128 v[166:169], v151 offset:16384
	ds_read_b128 v[170:173], v151 offset:17408
	ds_read_b128 v[174:177], v151 offset:18432
	ds_read_b128 v[178:181], v151 offset:19456
	ds_read_b128 v[188:191], v151 offset:20480
	ds_read_b128 v[206:209], v151 offset:21504
	ds_read_b128 v[210:213], v151 offset:22528
	global_load_lds_dwordx4 v128, s[48:49]
	s_mov_b32 m0, s53
	ds_read_b128 v[214:217], v151 offset:23552
	global_load_lds_dwordx4 v130, s[48:49]
	s_barrier
	s_waitcnt lgkmcnt(0)
	s_setprio 1
	v_mfma_f32_16x16x32_bf16 v[60:63], v[144:147], v[166:169], 0
	v_mfma_f32_16x16x32_bf16 v[56:59], v[158:161], v[166:169], 0
	v_mfma_f32_16x16x32_bf16 v[44:47], v[144:147], v[174:177], 0
	v_mfma_f32_16x16x32_bf16 v[40:43], v[158:161], v[174:177], 0
	v_mfma_f32_16x16x32_bf16 v[28:31], v[144:147], v[188:191], 0
	v_mfma_f32_16x16x32_bf16 v[24:27], v[158:161], v[188:191], 0
	v_mfma_f32_16x16x32_bf16 v[12:15], v[144:147], v[210:213], 0
	v_mfma_f32_16x16x32_bf16 v[8:11], v[158:161], v[210:213], 0
	v_mfma_f32_16x16x32_bf16 v[60:63], v[154:157], v[170:173], v[60:63]
	v_mfma_f32_16x16x32_bf16 v[56:59], v[162:165], v[170:173], v[56:59]
	v_mfma_f32_16x16x32_bf16 v[44:47], v[154:157], v[178:181], v[44:47]
	v_mfma_f32_16x16x32_bf16 v[40:43], v[162:165], v[178:181], v[40:43]
	v_mfma_f32_16x16x32_bf16 v[28:31], v[154:157], v[206:209], v[28:31]
	v_mfma_f32_16x16x32_bf16 v[24:27], v[162:165], v[206:209], v[24:27]
	v_mfma_f32_16x16x32_bf16 v[12:15], v[154:157], v[214:217], v[12:15]
	v_mfma_f32_16x16x32_bf16 v[8:11], v[162:165], v[214:217], v[8:11]
	s_setprio 0
	s_barrier
; #define PG8_STAGE(bufoff, gbase, voff) do { _Pragma("unroll") for (int _i = 0; _i < 2; ++_i) \
;         __builtin_amdgcn_global_load_lds((const unsigned*)((const char*)(gbase) + (voff)[_i]), (LAS unsigned*)(lds + (bufoff) + ldsw + _i * 8192), 16, 0, 0); } while (0)
; #define PG8_LDA(dst, b, h) do { _Pragma("unroll") for (int m = 0; m < 4; ++m) _Pragma("unroll") for (int k = 0; k < 2; ++k) dst[m][k] = *(const LAS bf16x8*)(lds + PG8_SA(b, h) + aoff + m * 2048 + k * 1024); } while (0)
; #define PG8_LDB(dst, b, h) do { _Pragma("unroll") for (int n = 0; n < 2; ++n) _Pragma("unroll") for (int k = 0; k < 2; ++k) dst[n][k] = *(const LAS bf16x8*)(lds + PG8_SB(b, h) + boff + n * 2048 + k * 1024); } while (0)
; #define PG8_MMA(ai, bj, At, Bt) do { __builtin_amdgcn_s_setprio(1); _Pragma("unroll") for (int m = 0; m < 4; ++m) _Pragma("unroll") for (int n = 0; n < 2; ++n) _Pragma("unroll") for (int k = 0; k < 2; ++k) \
;         acc[ai][bj][m][n] = __builtin_amdgcn_mfma_f32_16x16x32_bf16(Bt[n][k], At[m][k], acc[ai][bj][m][n], 0, 0, 0); __builtin_amdgcn_s_setprio(0); } while (0)
; #define PG8_WAIT_V(n) asm volatile("s_waitcnt vmcnt(" #n ")" ::: "memory")
; #define PG8_WAIT_L(n) asm volatile("s_waitcnt lgkmcnt(" #n ")" ::: "memory")
; #define PG8_BAR __builtin_amdgcn_s_barrier()
; #define PG8_SCHED __builtin_amdgcn_sched_barrier(0)
; template <class Epi, class Sched>
; DI void gemm_phase(LAS unsigned char* lds, const Gemm g, const Sched& S, const Epi& E) {
;     ...
;             PG8_WAIT_V(6); PG8_BAR; PG8_MMA(1, 1, At, B1); PG8_BAR;
;             PG8_LDB(B0, 1, 0); PG8_SCHED; PG8_LDA(At, 1, 0); PG8_STAGE(PG8_SA(0, 1), a2 + hstep, voffA);
;             PG8_WAIT_L(8); PG8_BAR; PG8_WAIT_L(0); PG8_MMA(0, 0, At, B0); PG8_BAR; PG8_SCHED;
;             PG8_LDB(B1, 1, 1); PG8_STAGE(PG8_SB(1, 0), b3, voffB);
;             PG8_BAR; PG8_WAIT_L(0); PG8_MMA(0, 1, At, B1); PG8_BAR;
	s_add_i32 s4, s66, s51
	s_mov_b32 m0, s4
	s_add_u32 s0, s46, 0x80000
	s_addc_u32 s1, s47, 0
	global_load_lds_dwordx4 v132, s[0:1]
	s_add_i32 m0, s4, 0x2000
	s_nop 0
	global_load_lds_dwordx4 v134, s[0:1]
	s_waitcnt vmcnt(6)
	s_barrier
	s_setprio 1
	v_mfma_f32_16x16x32_bf16 v[52:55], v[218:221], v[166:169], 0
	v_mfma_f32_16x16x32_bf16 v[48:51], v[226:229], v[166:169], 0
	v_mfma_f32_16x16x32_bf16 v[36:39], v[218:221], v[174:177], 0
	v_mfma_f32_16x16x32_bf16 v[32:35], v[226:229], v[174:177], 0
	v_mfma_f32_16x16x32_bf16 v[20:23], v[218:221], v[188:191], 0
	v_mfma_f32_16x16x32_bf16 v[16:19], v[226:229], v[188:191], 0
	v_mfma_f32_16x16x32_bf16 v[4:7], v[218:221], v[210:213], 0
	v_mfma_f32_16x16x32_bf16 v[0:3], v[226:229], v[210:213], 0
	v_mfma_f32_16x16x32_bf16 v[52:55], v[222:225], v[170:173], v[52:55]
	v_mfma_f32_16x16x32_bf16 v[48:51], v[230:233], v[170:173], v[48:51]
	v_mfma_f32_16x16x32_bf16 v[36:39], v[222:225], v[178:181], v[36:39]
	v_mfma_f32_16x16x32_bf16 v[32:35], v[230:233], v[178:181], v[32:35]
	v_mfma_f32_16x16x32_bf16 v[20:23], v[222:225], v[206:209], v[20:23]
	v_mfma_f32_16x16x32_bf16 v[16:19], v[230:233], v[206:209], v[16:19]
	v_mfma_f32_16x16x32_bf16 v[4:7], v[222:225], v[214:217], v[4:7]
	v_mfma_f32_16x16x32_bf16 v[0:3], v[230:233], v[214:217], v[0:3]
	s_setprio 0
	s_add_i32 s4, 0, 0x18000
	v_add_u32_e32 v162, s4, v149
	s_barrier
	ds_read_b128 v[144:147], v162
	ds_read_b128 v[154:157], v162 offset:1024
	ds_read_b128 v[158:161], v162 offset:2048
	ds_read_b128 v[162:165], v162 offset:3072
	s_add_u32 s0, s48, 0x80000
	s_addc_u32 s1, s49, 0
	s_mov_b32 m0, s58
	ds_read_b128 v[166:169], v151 offset:32768
	ds_read_b128 v[170:173], v151 offset:33792
	ds_read_b128 v[174:177], v151 offset:34816
	ds_read_b128 v[178:181], v151 offset:35840
	ds_read_b128 v[188:191], v151 offset:36864
	ds_read_b128 v[206:209], v151 offset:37888
	ds_read_b128 v[210:213], v151 offset:38912
	global_load_lds_dwordx4 v128, s[0:1]
	s_mov_b32 m0, s59
	ds_read_b128 v[214:217], v151 offset:39936
	global_load_lds_dwordx4 v130, s[0:1]
	s_waitcnt lgkmcnt(8)
	s_barrier
	s_waitcnt lgkmcnt(0)
	s_setprio 1
	v_mfma_f32_16x16x32_bf16 v[124:127], v[144:147], v[166:169], v[124:127]
	v_mfma_f32_16x16x32_bf16 v[120:123], v[158:161], v[166:169], v[120:123]
	v_mfma_f32_16x16x32_bf16 v[108:111], v[144:147], v[174:177], v[108:111]
	v_mfma_f32_16x16x32_bf16 v[104:107], v[158:161], v[174:177], v[104:107]
	v_mfma_f32_16x16x32_bf16 v[92:95], v[144:147], v[188:191], v[92:95]
	v_mfma_f32_16x16x32_bf16 v[88:91], v[158:161], v[188:191], v[88:91]
	v_mfma_f32_16x16x32_bf16 v[76:79], v[144:147], v[210:213], v[76:79]
	v_mfma_f32_16x16x32_bf16 v[72:75], v[158:161], v[210:213], v[72:75]
	v_mfma_f32_16x16x32_bf16 v[124:127], v[154:157], v[170:173], v[124:127]
	v_mfma_f32_16x16x32_bf16 v[120:123], v[162:165], v[170:173], v[120:123]
	v_mfma_f32_16x16x32_bf16 v[108:111], v[154:157], v[178:181], v[108:111]
	v_mfma_f32_16x16x32_bf16 v[104:107], v[162:165], v[178:181], v[104:107]
	v_mfma_f32_16x16x32_bf16 v[92:95], v[154:157], v[206:209], v[92:95]
	v_mfma_f32_16x16x32_bf16 v[88:91], v[162:165], v[206:209], v[88:91]
	v_mfma_f32_16x16x32_bf16 v[76:79], v[154:157], v[214:217], v[76:79]
	v_mfma_f32_16x16x32_bf16 v[72:75], v[162:165], v[214:217], v[72:75]
	s_setprio 0
	s_barrier
	s_add_i32 s5, 0, 0x1c000
	s_add_i32 s0, s4, s51
	v_add_u32_e32 v201, s5, v149
	s_add_i32 m0, s0, 0xffffff80
	ds_read_b128 v[218:221], v201
	ds_read_b128 v[222:225], v201 offset:1024
	ds_read_b128 v[226:229], v201 offset:2048
	global_load_lds_dwordx4 v132, s[46:47] offset:128
	s_add_i32 m0, s0, 0x1f80
	ds_read_b128 v[230:233], v201 offset:3072
	global_load_lds_dwordx4 v134, s[46:47] offset:128
	s_barrier
; #define PG8_STAGE(bufoff, gbase, voff) do { _Pragma("unroll") for (int _i = 0; _i < 2; ++_i) \
;         __builtin_amdgcn_global_load_lds((const unsigned*)((const char*)(gbase) + (voff)[_i]), (LAS unsigned*)(lds + (bufoff) + ldsw + _i * 8192), 16, 0, 0); } while (0)
; #define PG8_LDA(dst, b, h) do { _Pragma("unroll") for (int m = 0; m < 4; ++m) _Pragma("unroll") for (int k = 0; k < 2; ++k) dst[m][k] = *(const LAS bf16x8*)(lds + PG8_SA(b, h) + aoff + m * 2048 + k * 1024); } while (0)
; #define PG8_MMA(ai, bj, At, Bt) do { __builtin_amdgcn_s_setprio(1); _Pragma("unroll") for (int m = 0; m < 4; ++m) _Pragma("unroll") for (int n = 0; n < 2; ++n) _Pragma("unroll") for (int k = 0; k < 2; ++k) \
;         acc[ai][bj][m][n] = __builtin_amdgcn_mfma_f32_16x16x32_bf16(Bt[n][k], At[m][k], acc[ai][bj][m][n], 0, 0, 0); __builtin_amdgcn_s_setprio(0); } while (0)
; #define PG8_WAIT_V(n) asm volatile("s_waitcnt vmcnt(" #n ")" ::: "memory")
; #define PG8_WAIT_L(n) asm volatile("s_waitcnt lgkmcnt(" #n ")" ::: "memory")
; #define PG8_BAR __builtin_amdgcn_s_barrier()
; #define PG8_SCHED __builtin_amdgcn_sched_barrier(0)
; template <class Epi, class Sched>
; DI void gemm_phase(LAS unsigned char* lds, const Gemm g, const Sched& S, const Epi& E) {
;     ...
;             PG8_LDA(At, 1, 1); PG8_STAGE(PG8_SA(1, 0), a3, voffA);
;             PG8_BAR; PG8_WAIT_L(0); PG8_MMA(1, 0, At, B0); PG8_BAR; PG8_SCHED;
;             PG8_STAGE(PG8_SB(1, 1), b3 + hstep, voffB);
;             PG8_WAIT_V(6); PG8_BAR; PG8_MMA(1, 1, At, B1); PG8_BAR;
	s_waitcnt lgkmcnt(0)
	s_setprio 1
	v_mfma_f32_16x16x32_bf16 v[116:119], v[218:221], v[166:169], v[116:119]
	v_mfma_f32_16x16x32_bf16 v[112:115], v[226:229], v[166:169], v[112:115]
	v_mfma_f32_16x16x32_bf16 v[100:103], v[218:221], v[174:177], v[100:103]
	v_mfma_f32_16x16x32_bf16 v[96:99], v[226:229], v[174:177], v[96:99]
	v_mfma_f32_16x16x32_bf16 v[84:87], v[218:221], v[188:191], v[84:87]
	v_mfma_f32_16x16x32_bf16 v[80:83], v[226:229], v[188:191], v[80:83]
	v_mfma_f32_16x16x32_bf16 v[68:71], v[218:221], v[210:213], v[68:71]
	v_mfma_f32_16x16x32_bf16 v[64:67], v[226:229], v[210:213], v[64:67]
	v_mfma_f32_16x16x32_bf16 v[116:119], v[222:225], v[170:173], v[116:119]
	v_mfma_f32_16x16x32_bf16 v[112:115], v[230:233], v[170:173], v[112:115]
	v_mfma_f32_16x16x32_bf16 v[100:103], v[222:225], v[178:181], v[100:103]
	v_mfma_f32_16x16x32_bf16 v[96:99], v[230:233], v[178:181], v[96:99]
	v_mfma_f32_16x16x32_bf16 v[84:87], v[222:225], v[206:209], v[84:87]
	v_mfma_f32_16x16x32_bf16 v[80:83], v[230:233], v[206:209], v[80:83]
	v_mfma_f32_16x16x32_bf16 v[68:71], v[222:225], v[214:217], v[68:71]
	v_mfma_f32_16x16x32_bf16 v[64:67], v[230:233], v[214:217], v[64:67]
	s_setprio 0
	s_add_i32 m0, s63, 0xffffff80
	s_barrier
	ds_read_b128 v[166:169], v151 offset:49152
	ds_read_b128 v[170:173], v151 offset:50176
	ds_read_b128 v[174:177], v151 offset:51200
	ds_read_b128 v[178:181], v151 offset:52224
	ds_read_b128 v[188:191], v151 offset:53248
	ds_read_b128 v[206:209], v151 offset:54272
	ds_read_b128 v[210:213], v151 offset:55296
	global_load_lds_dwordx4 v128, s[48:49] offset:128
	s_add_i32 m0, s64, 0xffffff80
	ds_read_b128 v[214:217], v151 offset:56320
	global_load_lds_dwordx4 v130, s[48:49] offset:128
	s_barrier
	s_waitcnt lgkmcnt(0)
	s_setprio 1
	v_mfma_f32_16x16x32_bf16 v[60:63], v[144:147], v[166:169], v[60:63]
	v_mfma_f32_16x16x32_bf16 v[56:59], v[158:161], v[166:169], v[56:59]
	v_mfma_f32_16x16x32_bf16 v[44:47], v[144:147], v[174:177], v[44:47]
	v_mfma_f32_16x16x32_bf16 v[40:43], v[158:161], v[174:177], v[40:43]
	v_mfma_f32_16x16x32_bf16 v[28:31], v[144:147], v[188:191], v[28:31]
	v_mfma_f32_16x16x32_bf16 v[24:27], v[158:161], v[188:191], v[24:27]
	v_mfma_f32_16x16x32_bf16 v[12:15], v[144:147], v[210:213], v[12:15]
	v_mfma_f32_16x16x32_bf16 v[8:11], v[158:161], v[210:213], v[8:11]
	v_mfma_f32_16x16x32_bf16 v[60:63], v[154:157], v[170:173], v[60:63]
	v_mfma_f32_16x16x32_bf16 v[56:59], v[162:165], v[170:173], v[56:59]
	v_mfma_f32_16x16x32_bf16 v[44:47], v[154:157], v[178:181], v[44:47]
	v_mfma_f32_16x16x32_bf16 v[40:43], v[162:165], v[178:181], v[40:43]
	v_mfma_f32_16x16x32_bf16 v[28:31], v[154:157], v[206:209], v[28:31]
	v_mfma_f32_16x16x32_bf16 v[24:27], v[162:165], v[206:209], v[24:27]
	v_mfma_f32_16x16x32_bf16 v[12:15], v[154:157], v[214:217], v[12:15]
	v_mfma_f32_16x16x32_bf16 v[8:11], v[162:165], v[214:217], v[8:11]
	s_setprio 0
	s_barrier
	s_add_i32 s4, s5, s51
	s_mov_b32 m0, s4
	s_add_u32 s0, s46, 0x80080
	s_addc_u32 s1, s47, 0
	global_load_lds_dwordx4 v132, s[0:1]
	s_add_i32 m0, s4, 0x2000
	s_nop 0
	global_load_lds_dwordx4 v134, s[0:1]
	s_add_i32 s69, s69, 2
	s_add_u32 s44, s44, 0x100
	s_addc_u32 s45, s45, 0
	s_add_u32 s43, s43, 0x100
	s_addc_u32 s68, s68, 0
	s_cmp_gt_u32 s69, 29
	s_waitcnt vmcnt(6)
	s_barrier
	s_setprio 1
	v_mfma_f32_16x16x32_bf16 v[52:55], v[218:221], v[166:169], v[52:55]
	v_mfma_f32_16x16x32_bf16 v[48:51], v[226:229], v[166:169], v[48:51]
	v_mfma_f32_16x16x32_bf16 v[36:39], v[218:221], v[174:177], v[36:39]
	v_mfma_f32_16x16x32_bf16 v[32:35], v[226:229], v[174:177], v[32:35]
	v_mfma_f32_16x16x32_bf16 v[20:23], v[218:221], v[188:191], v[20:23]
	v_mfma_f32_16x16x32_bf16 v[16:19], v[226:229], v[188:191], v[16:19]
	v_mfma_f32_16x16x32_bf16 v[4:7], v[218:221], v[210:213], v[4:7]
	v_mfma_f32_16x16x32_bf16 v[0:3], v[226:229], v[210:213], v[0:3]
	v_mfma_f32_16x16x32_bf16 v[52:55], v[222:225], v[170:173], v[52:55]
	v_mfma_f32_16x16x32_bf16 v[48:51], v[230:233], v[170:173], v[48:51]
	v_mfma_f32_16x16x32_bf16 v[36:39], v[222:225], v[178:181], v[36:39]
	v_mfma_f32_16x16x32_bf16 v[32:35], v[230:233], v[178:181], v[32:35]
	v_mfma_f32_16x16x32_bf16 v[20:23], v[222:225], v[206:209], v[20:23]
	v_mfma_f32_16x16x32_bf16 v[16:19], v[230:233], v[206:209], v[16:19]
	v_mfma_f32_16x16x32_bf16 v[4:7], v[222:225], v[214:217], v[4:7]
	v_mfma_f32_16x16x32_bf16 v[0:3], v[230:233], v[214:217], v[0:3]
	s_setprio 0
	s_cbranch_scc0 .Lrot_1508
	s_barrier
	s_branch .Lpeel_done_1508

; #define PG8_STAGE(bufoff, gbase, voff) do { _Pragma("unroll") for (int _i = 0; _i < 2; ++_i) \
;         __builtin_amdgcn_global_load_lds((const unsigned*)((const char*)(gbase) + (voff)[_i]), (LAS unsigned*)(lds + (bufoff) + ldsw + _i * 8192), 16, 0, 0); } while (0)
; #define PG8_LDA(dst, b, h) do { _Pragma("unroll") for (int m = 0; m < 4; ++m) _Pragma("unroll") for (int k = 0; k < 2; ++k) dst[m][k] = *(const LAS bf16x8*)(lds + PG8_SA(b, h) + aoff + m * 2048 + k * 1024); } while (0)
; #define PG8_LDB(dst, b, h) do { _Pragma("unroll") for (int n = 0; n < 2; ++n) _Pragma("unroll") for (int k = 0; k < 2; ++k) dst[n][k] = *(const LAS bf16x8*)(lds + PG8_SB(b, h) + boff + n * 2048 + k * 1024); } while (0)
; #define PG8_MMA(ai, bj, At, Bt) do { __builtin_amdgcn_s_setprio(1); _Pragma("unroll") for (int m = 0; m < 4; ++m) _Pragma("unroll") for (int n = 0; n < 2; ++n) _Pragma("unroll") for (int k = 0; k < 2; ++k) \
;         acc[ai][bj][m][n] = __builtin_amdgcn_mfma_f32_16x16x32_bf16(Bt[n][k], At[m][k], acc[ai][bj][m][n], 0, 0, 0); __builtin_amdgcn_s_setprio(0); } while (0)
; #define PG8_WAIT_V(n) asm volatile("s_waitcnt vmcnt(" #n ")" ::: "memory")
; #define PG8_WAIT_L(n) asm volatile("s_waitcnt lgkmcnt(" #n ")" ::: "memory")
; #define PG8_BAR __builtin_amdgcn_s_barrier()
; #define PG8_SCHED __builtin_amdgcn_sched_barrier(0)
; template <class Epi, class Sched>
; DI void gemm_phase(LAS unsigned char* lds, const Gemm g, const Sched& S, const Epi& E) {
;     ...
;             const char* a2 = last ? nA : cA + (size_t)(t + 2) * kstep; const char* b2 = last ? nB : cB + (size_t)(t + 2) * kstep;
;             const char* a3 = a2 + kstep; const char* b3 = b2 + kstep;
;             PG8_LDB(B0, 0, 0); PG8_SCHED; PG8_LDA(At, 0, 0); PG8_STAGE(PG8_SA(1, 1), a1 + hstep, voffA);
;             PG8_WAIT_L(8); PG8_BAR; PG8_WAIT_L(0); PG8_MMA(0, 0, At, B0); PG8_BAR; PG8_SCHED;
;             PG8_LDB(B1, 0, 1); PG8_STAGE(PG8_SB(0, 0), b2, voffB);
;             PG8_BAR; PG8_WAIT_L(0); PG8_MMA(0, 1, At, B1); PG8_BAR;
;             PG8_LDA(At, 0, 1); PG8_STAGE(PG8_SA(0, 0), a2, voffA);
;             PG8_BAR; PG8_WAIT_L(0); PG8_MMA(1, 0, At, B0); PG8_BAR; PG8_SCHED;
;             PG8_STAGE(PG8_SB(0, 1), b2 + hstep, voffB);
;             PG8_WAIT_V(6); PG8_BAR; PG8_MMA(1, 1, At, B1); PG8_BAR;
.LBB0_1508:
	ds_read_b128 v[144:147], v150
	ds_read_b128 v[154:157], v150 offset:1024
	ds_read_b128 v[158:161], v150 offset:2048
	ds_read_b128 v[162:165], v150 offset:3072
	s_add_i32 m0, s52, 0xc000
	ds_read_b128 v[166:169], v151
	ds_read_b128 v[170:173], v151 offset:1024
	ds_read_b128 v[174:177], v151 offset:2048
	ds_read_b128 v[178:181], v151 offset:3072
	ds_read_b128 v[188:191], v151 offset:4096
	ds_read_b128 v[206:209], v151 offset:5120
	ds_read_b128 v[210:213], v151 offset:6144
	global_load_lds_dwordx4 v136, s[44:45]
	s_add_i32 m0, s52, 0xe000
	ds_read_b128 v[214:217], v151 offset:7168
	global_load_lds_dwordx4 v138, s[44:45]
	s_add_u32 s0, s44, 0xfff80080
	s_addc_u32 s1, s45, -1
	s_cmp_eq_u32 s69, 28
	s_cselect_b32 s49, s34, s1
	s_cselect_b32 s48, s35, s0
	s_cselect_b32 s47, s31, s68
	s_cselect_b32 s46, s37, s43
	s_waitcnt lgkmcnt(8)
	s_barrier
	s_waitcnt lgkmcnt(0)
	s_setprio 1
	v_mfma_f32_16x16x32_bf16 v[124:127], v[144:147], v[166:169], v[124:127]
	v_mfma_f32_16x16x32_bf16 v[120:123], v[158:161], v[166:169], v[120:123]
	v_mfma_f32_16x16x32_bf16 v[108:111], v[144:147], v[174:177], v[108:111]
	v_mfma_f32_16x16x32_bf16 v[104:107], v[158:161], v[174:177], v[104:107]
	v_mfma_f32_16x16x32_bf16 v[92:95], v[144:147], v[188:191], v[92:95]
	v_mfma_f32_16x16x32_bf16 v[88:91], v[158:161], v[188:191], v[88:91]
	v_mfma_f32_16x16x32_bf16 v[76:79], v[144:147], v[210:213], v[76:79]
	v_mfma_f32_16x16x32_bf16 v[72:75], v[158:161], v[210:213], v[72:75]
	v_mfma_f32_16x16x32_bf16 v[124:127], v[154:157], v[170:173], v[124:127]
	v_mfma_f32_16x16x32_bf16 v[120:123], v[162:165], v[170:173], v[120:123]
	v_mfma_f32_16x16x32_bf16 v[108:111], v[154:157], v[178:181], v[108:111]
	v_mfma_f32_16x16x32_bf16 v[104:107], v[162:165], v[178:181], v[104:107]
	v_mfma_f32_16x16x32_bf16 v[92:95], v[154:157], v[206:209], v[92:95]
	v_mfma_f32_16x16x32_bf16 v[88:91], v[162:165], v[206:209], v[88:91]
	v_mfma_f32_16x16x32_bf16 v[76:79], v[154:157], v[214:217], v[76:79]
	v_mfma_f32_16x16x32_bf16 v[72:75], v[162:165], v[214:217], v[72:75]
	s_setprio 0
	s_barrier
	s_add_i32 s0, s65, s51
	s_mov_b32 m0, s0
	ds_read_b128 v[218:221], v152
	ds_read_b128 v[222:225], v152 offset:1024
	ds_read_b128 v[226:229], v152 offset:2048
	global_load_lds_dwordx4 v132, s[46:47]
	s_add_i32 m0, s0, 0x2000
	ds_read_b128 v[230:233], v152 offset:3072
	global_load_lds_dwordx4 v134, s[46:47]
	s_barrier
	s_waitcnt lgkmcnt(0)
	s_setprio 1
	v_mfma_f32_16x16x32_bf16 v[116:119], v[218:221], v[166:169], v[116:119]
	v_mfma_f32_16x16x32_bf16 v[112:115], v[226:229], v[166:169], v[112:115]
	v_mfma_f32_16x16x32_bf16 v[100:103], v[218:221], v[174:177], v[100:103]
	v_mfma_f32_16x16x32_bf16 v[96:99], v[226:229], v[174:177], v[96:99]
	v_mfma_f32_16x16x32_bf16 v[84:87], v[218:221], v[188:191], v[84:87]
	v_mfma_f32_16x16x32_bf16 v[80:83], v[226:229], v[188:191], v[80:83]
	v_mfma_f32_16x16x32_bf16 v[68:71], v[218:221], v[210:213], v[68:71]
	v_mfma_f32_16x16x32_bf16 v[64:67], v[226:229], v[210:213], v[64:67]
	v_mfma_f32_16x16x32_bf16 v[116:119], v[222:225], v[170:173], v[116:119]
	v_mfma_f32_16x16x32_bf16 v[112:115], v[230:233], v[170:173], v[112:115]
	v_mfma_f32_16x16x32_bf16 v[100:103], v[222:225], v[178:181], v[100:103]
	v_mfma_f32_16x16x32_bf16 v[96:99], v[230:233], v[178:181], v[96:99]
	v_mfma_f32_16x16x32_bf16 v[84:87], v[222:225], v[206:209], v[84:87]
	v_mfma_f32_16x16x32_bf16 v[80:83], v[230:233], v[206:209], v[80:83]
	v_mfma_f32_16x16x32_bf16 v[68:71], v[222:225], v[214:217], v[68:71]
	v_mfma_f32_16x16x32_bf16 v[64:67], v[230:233], v[214:217], v[64:67]
	s_setprio 0
	s_mov_b32 m0, s52
	s_barrier
	ds_read_b128 v[166:169], v151 offset:16384
	ds_read_b128 v[170:173], v151 offset:17408
	ds_read_b128 v[174:177], v151 offset:18432
	ds_read_b128 v[178:181], v151 offset:19456
	ds_read_b128 v[188:191], v151 offset:20480
	ds_read_b128 v[206:209], v151 offset:21504
	ds_read_b128 v[210:213], v151 offset:22528
	global_load_lds_dwordx4 v128, s[48:49]
	s_mov_b32 m0, s53
	ds_read_b128 v[214:217], v151 offset:23552
	global_load_lds_dwordx4 v130, s[48:49]
	s_barrier
	s_waitcnt lgkmcnt(0)
	s_setprio 1
	v_mfma_f32_16x16x32_bf16 v[60:63], v[144:147], v[166:169], v[60:63]
	v_mfma_f32_16x16x32_bf16 v[56:59], v[158:161], v[166:169], v[56:59]
	v_mfma_f32_16x16x32_bf16 v[44:47], v[144:147], v[174:177], v[44:47]
	v_mfma_f32_16x16x32_bf16 v[40:43], v[158:161], v[174:177], v[40:43]
	v_mfma_f32_16x16x32_bf16 v[28:31], v[144:147], v[188:191], v[28:31]
	v_mfma_f32_16x16x32_bf16 v[24:27], v[158:161], v[188:191], v[24:27]
	v_mfma_f32_16x16x32_bf16 v[12:15], v[144:147], v[210:213], v[12:15]
	v_mfma_f32_16x16x32_bf16 v[8:11], v[158:161], v[210:213], v[8:11]
	v_mfma_f32_16x16x32_bf16 v[60:63], v[154:157], v[170:173], v[60:63]
	v_mfma_f32_16x16x32_bf16 v[56:59], v[162:165], v[170:173], v[56:59]
	v_mfma_f32_16x16x32_bf16 v[44:47], v[154:157], v[178:181], v[44:47]
	v_mfma_f32_16x16x32_bf16 v[40:43], v[162:165], v[178:181], v[40:43]
	v_mfma_f32_16x16x32_bf16 v[28:31], v[154:157], v[206:209], v[28:31]
	v_mfma_f32_16x16x32_bf16 v[24:27], v[162:165], v[206:209], v[24:27]
	v_mfma_f32_16x16x32_bf16 v[12:15], v[154:157], v[214:217], v[12:15]
	v_mfma_f32_16x16x32_bf16 v[8:11], v[162:165], v[214:217], v[8:11]
	s_setprio 0
	s_barrier
	s_add_i32 s4, s66, s51
	s_mov_b32 m0, s4
	s_add_u32 s0, s46, 0x80000
	s_addc_u32 s1, s47, 0
	global_load_lds_dwordx4 v132, s[0:1]
	s_add_i32 m0, s4, 0x2000
	s_nop 0
	global_load_lds_dwordx4 v134, s[0:1]
	s_waitcnt vmcnt(6)
	s_barrier
; #define PG8_STAGE(bufoff, gbase, voff) do { _Pragma("unroll") for (int _i = 0; _i < 2; ++_i) \
;         __builtin_amdgcn_global_load_lds((const unsigned*)((const char*)(gbase) + (voff)[_i]), (LAS unsigned*)(lds + (bufoff) + ldsw + _i * 8192), 16, 0, 0); } while (0)
; #define PG8_LDA(dst, b, h) do { _Pragma("unroll") for (int m = 0; m < 4; ++m) _Pragma("unroll") for (int k = 0; k < 2; ++k) dst[m][k] = *(const LAS bf16x8*)(lds + PG8_SA(b, h) + aoff + m * 2048 + k * 1024); } while (0)
; #define PG8_LDB(dst, b, h) do { _Pragma("unroll") for (int n = 0; n < 2; ++n) _Pragma("unroll") for (int k = 0; k < 2; ++k) dst[n][k] = *(const LAS bf16x8*)(lds + PG8_SB(b, h) + boff + n * 2048 + k * 1024); } while (0)
; #define PG8_MMA(ai, bj, At, Bt) do { __builtin_amdgcn_s_setprio(1); _Pragma("unroll") for (int m = 0; m < 4; ++m) _Pragma("unroll") for (int n = 0; n < 2; ++n) _Pragma("unroll") for (int k = 0; k < 2; ++k) \
;         acc[ai][bj][m][n] = __builtin_amdgcn_mfma_f32_16x16x32_bf16(Bt[n][k], At[m][k], acc[ai][bj][m][n], 0, 0, 0); __builtin_amdgcn_s_setprio(0); } while (0)
; #define PG8_WAIT_V(n) asm volatile("s_waitcnt vmcnt(" #n ")" ::: "memory")
; #define PG8_WAIT_L(n) asm volatile("s_waitcnt lgkmcnt(" #n ")" ::: "memory")
; #define PG8_BAR __builtin_amdgcn_s_barrier()
; #define PG8_SCHED __builtin_amdgcn_sched_barrier(0)
; template <class Epi, class Sched>
; DI void gemm_phase(LAS unsigned char* lds, const Gemm g, const Sched& S, const Epi& E) {
;     ...
;             PG8_WAIT_V(6); PG8_BAR; PG8_MMA(1, 1, At, B1); PG8_BAR;
;             PG8_LDB(B0, 1, 0); PG8_SCHED; PG8_LDA(At, 1, 0); PG8_STAGE(PG8_SA(0, 1), a2 + hstep, voffA);
;             PG8_WAIT_L(8); PG8_BAR; PG8_WAIT_L(0); PG8_MMA(0, 0, At, B0); PG8_BAR; PG8_SCHED;
;             PG8_LDB(B1, 1, 1); PG8_STAGE(PG8_SB(1, 0), b3, voffB);
;             PG8_BAR; PG8_WAIT_L(0); PG8_MMA(0, 1, At, B1); PG8_BAR;
	s_setprio 1
	v_mfma_f32_16x16x32_bf16 v[52:55], v[218:221], v[166:169], v[52:55]
	v_mfma_f32_16x16x32_bf16 v[48:51], v[226:229], v[166:169], v[48:51]
	v_mfma_f32_16x16x32_bf16 v[36:39], v[218:221], v[174:177], v[36:39]
	v_mfma_f32_16x16x32_bf16 v[32:35], v[226:229], v[174:177], v[32:35]
	v_mfma_f32_16x16x32_bf16 v[20:23], v[218:221], v[188:191], v[20:23]
	v_mfma_f32_16x16x32_bf16 v[16:19], v[226:229], v[188:191], v[16:19]
	v_mfma_f32_16x16x32_bf16 v[4:7], v[218:221], v[210:213], v[4:7]
	v_mfma_f32_16x16x32_bf16 v[0:3], v[226:229], v[210:213], v[0:3]
	v_mfma_f32_16x16x32_bf16 v[52:55], v[222:225], v[170:173], v[52:55]
	v_mfma_f32_16x16x32_bf16 v[48:51], v[230:233], v[170:173], v[48:51]
	v_mfma_f32_16x16x32_bf16 v[36:39], v[222:225], v[178:181], v[36:39]
	v_mfma_f32_16x16x32_bf16 v[32:35], v[230:233], v[178:181], v[32:35]
	v_mfma_f32_16x16x32_bf16 v[20:23], v[222:225], v[206:209], v[20:23]
	v_mfma_f32_16x16x32_bf16 v[16:19], v[230:233], v[206:209], v[16:19]
	v_mfma_f32_16x16x32_bf16 v[4:7], v[222:225], v[214:217], v[4:7]
	v_mfma_f32_16x16x32_bf16 v[0:3], v[230:233], v[214:217], v[0:3]
	s_setprio 0
	s_add_i32 s4, 0, 0x18000
	v_add_u32_e32 v162, s4, v149
	s_barrier
	ds_read_b128 v[144:147], v162
	ds_read_b128 v[154:157], v162 offset:1024
	ds_read_b128 v[158:161], v162 offset:2048
	ds_read_b128 v[162:165], v162 offset:3072
	s_add_u32 s0, s48, 0x80000
	s_addc_u32 s1, s49, 0
	s_mov_b32 m0, s58
	ds_read_b128 v[166:169], v151 offset:32768
	ds_read_b128 v[170:173], v151 offset:33792
	ds_read_b128 v[174:177], v151 offset:34816
	ds_read_b128 v[178:181], v151 offset:35840
	ds_read_b128 v[188:191], v151 offset:36864
	ds_read_b128 v[206:209], v151 offset:37888
	ds_read_b128 v[210:213], v151 offset:38912
	global_load_lds_dwordx4 v128, s[0:1]
	s_mov_b32 m0, s59
	ds_read_b128 v[214:217], v151 offset:39936
	global_load_lds_dwordx4 v130, s[0:1]
	s_waitcnt lgkmcnt(8)
	s_barrier
	s_waitcnt lgkmcnt(0)
	s_setprio 1
	v_mfma_f32_16x16x32_bf16 v[124:127], v[144:147], v[166:169], v[124:127]
	v_mfma_f32_16x16x32_bf16 v[120:123], v[158:161], v[166:169], v[120:123]
	v_mfma_f32_16x16x32_bf16 v[108:111], v[144:147], v[174:177], v[108:111]
	v_mfma_f32_16x16x32_bf16 v[104:107], v[158:161], v[174:177], v[104:107]
	v_mfma_f32_16x16x32_bf16 v[92:95], v[144:147], v[188:191], v[92:95]
	v_mfma_f32_16x16x32_bf16 v[88:91], v[158:161], v[188:191], v[88:91]
	v_mfma_f32_16x16x32_bf16 v[76:79], v[144:147], v[210:213], v[76:79]
	v_mfma_f32_16x16x32_bf16 v[72:75], v[158:161], v[210:213], v[72:75]
	v_mfma_f32_16x16x32_bf16 v[124:127], v[154:157], v[170:173], v[124:127]
	v_mfma_f32_16x16x32_bf16 v[120:123], v[162:165], v[170:173], v[120:123]
	v_mfma_f32_16x16x32_bf16 v[108:111], v[154:157], v[178:181], v[108:111]
	v_mfma_f32_16x16x32_bf16 v[104:107], v[162:165], v[178:181], v[104:107]
	v_mfma_f32_16x16x32_bf16 v[92:95], v[154:157], v[206:209], v[92:95]
	v_mfma_f32_16x16x32_bf16 v[88:91], v[162:165], v[206:209], v[88:91]
	v_mfma_f32_16x16x32_bf16 v[76:79], v[154:157], v[214:217], v[76:79]
	v_mfma_f32_16x16x32_bf16 v[72:75], v[162:165], v[214:217], v[72:75]
	s_setprio 0
	s_barrier
	s_add_i32 s5, 0, 0x1c000
	s_add_i32 s0, s4, s51
	v_add_u32_e32 v201, s5, v149
	s_add_i32 m0, s0, 0xffffff80
	ds_read_b128 v[218:221], v201
	ds_read_b128 v[222:225], v201 offset:1024
	ds_read_b128 v[226:229], v201 offset:2048
	global_load_lds_dwordx4 v132, s[46:47] offset:128
	s_add_i32 m0, s0, 0x1f80
	ds_read_b128 v[230:233], v201 offset:3072
	global_load_lds_dwordx4 v134, s[46:47] offset:128
	s_barrier
; #define PG8_STAGE(bufoff, gbase, voff) do { _Pragma("unroll") for (int _i = 0; _i < 2; ++_i) \
;         __builtin_amdgcn_global_load_lds((const unsigned*)((const char*)(gbase) + (voff)[_i]), (LAS unsigned*)(lds + (bufoff) + ldsw + _i * 8192), 16, 0, 0); } while (0)
; #define PG8_LDA(dst, b, h) do { _Pragma("unroll") for (int m = 0; m < 4; ++m) _Pragma("unroll") for (int k = 0; k < 2; ++k) dst[m][k] = *(const LAS bf16x8*)(lds + PG8_SA(b, h) + aoff + m * 2048 + k * 1024); } while (0)
; #define PG8_MMA(ai, bj, At, Bt) do { __builtin_amdgcn_s_setprio(1); _Pragma("unroll") for (int m = 0; m < 4; ++m) _Pragma("unroll") for (int n = 0; n < 2; ++n) _Pragma("unroll") for (int k = 0; k < 2; ++k) \
;         acc[ai][bj][m][n] = __builtin_amdgcn_mfma_f32_16x16x32_bf16(Bt[n][k], At[m][k], acc[ai][bj][m][n], 0, 0, 0); __builtin_amdgcn_s_setprio(0); } while (0)
; #define PG8_WAIT_V(n) asm volatile("s_waitcnt vmcnt(" #n ")" ::: "memory")
; #define PG8_WAIT_L(n) asm volatile("s_waitcnt lgkmcnt(" #n ")" ::: "memory")
; #define PG8_BAR __builtin_amdgcn_s_barrier()
; #define PG8_SCHED __builtin_amdgcn_sched_barrier(0)
; template <class Epi, class Sched>
; DI void gemm_phase(LAS unsigned char* lds, const Gemm g, const Sched& S, const Epi& E) {
;     ...
;             PG8_BAR; PG8_WAIT_L(0); PG8_MMA(0, 1, At, B1); PG8_BAR;
;             PG8_LDA(At, 1, 1); PG8_STAGE(PG8_SA(1, 0), a3, voffA);
;             PG8_BAR; PG8_WAIT_L(0); PG8_MMA(1, 0, At, B0); PG8_BAR; PG8_SCHED;
;             PG8_STAGE(PG8_SB(1, 1), b3 + hstep, voffB);
;             PG8_WAIT_V(6); PG8_BAR; PG8_MMA(1, 1, At, B1); PG8_BAR;
;         }
	s_waitcnt lgkmcnt(0)
	s_setprio 1
	v_mfma_f32_16x16x32_bf16 v[116:119], v[218:221], v[166:169], v[116:119]
	v_mfma_f32_16x16x32_bf16 v[112:115], v[226:229], v[166:169], v[112:115]
	v_mfma_f32_16x16x32_bf16 v[100:103], v[218:221], v[174:177], v[100:103]
	v_mfma_f32_16x16x32_bf16 v[96:99], v[226:229], v[174:177], v[96:99]
	v_mfma_f32_16x16x32_bf16 v[84:87], v[218:221], v[188:191], v[84:87]
	v_mfma_f32_16x16x32_bf16 v[80:83], v[226:229], v[188:191], v[80:83]
	v_mfma_f32_16x16x32_bf16 v[68:71], v[218:221], v[210:213], v[68:71]
	v_mfma_f32_16x16x32_bf16 v[64:67], v[226:229], v[210:213], v[64:67]
	v_mfma_f32_16x16x32_bf16 v[116:119], v[222:225], v[170:173], v[116:119]
	v_mfma_f32_16x16x32_bf16 v[112:115], v[230:233], v[170:173], v[112:115]
	v_mfma_f32_16x16x32_bf16 v[100:103], v[222:225], v[178:181], v[100:103]
	v_mfma_f32_16x16x32_bf16 v[96:99], v[230:233], v[178:181], v[96:99]
	v_mfma_f32_16x16x32_bf16 v[84:87], v[222:225], v[206:209], v[84:87]
	v_mfma_f32_16x16x32_bf16 v[80:83], v[230:233], v[206:209], v[80:83]
	v_mfma_f32_16x16x32_bf16 v[68:71], v[222:225], v[214:217], v[68:71]
	v_mfma_f32_16x16x32_bf16 v[64:67], v[230:233], v[214:217], v[64:67]
	s_setprio 0
	s_add_i32 m0, s63, 0xffffff80
	s_barrier
	ds_read_b128 v[166:169], v151 offset:49152
	ds_read_b128 v[170:173], v151 offset:50176
	ds_read_b128 v[174:177], v151 offset:51200
	ds_read_b128 v[178:181], v151 offset:52224
	ds_read_b128 v[188:191], v151 offset:53248
	ds_read_b128 v[206:209], v151 offset:54272
	ds_read_b128 v[210:213], v151 offset:55296
	global_load_lds_dwordx4 v128, s[48:49] offset:128
	s_add_i32 m0, s64, 0xffffff80
	ds_read_b128 v[214:217], v151 offset:56320
	global_load_lds_dwordx4 v130, s[48:49] offset:128
	s_barrier
	s_waitcnt lgkmcnt(0)
	s_setprio 1
	v_mfma_f32_16x16x32_bf16 v[60:63], v[144:147], v[166:169], v[60:63]
	v_mfma_f32_16x16x32_bf16 v[56:59], v[158:161], v[166:169], v[56:59]
	v_mfma_f32_16x16x32_bf16 v[44:47], v[144:147], v[174:177], v[44:47]
	v_mfma_f32_16x16x32_bf16 v[40:43], v[158:161], v[174:177], v[40:43]
	v_mfma_f32_16x16x32_bf16 v[28:31], v[144:147], v[188:191], v[28:31]
	v_mfma_f32_16x16x32_bf16 v[24:27], v[158:161], v[188:191], v[24:27]
	v_mfma_f32_16x16x32_bf16 v[12:15], v[144:147], v[210:213], v[12:15]
	v_mfma_f32_16x16x32_bf16 v[8:11], v[158:161], v[210:213], v[8:11]
	v_mfma_f32_16x16x32_bf16 v[60:63], v[154:157], v[170:173], v[60:63]
	v_mfma_f32_16x16x32_bf16 v[56:59], v[162:165], v[170:173], v[56:59]
	v_mfma_f32_16x16x32_bf16 v[44:47], v[154:157], v[178:181], v[44:47]
	v_mfma_f32_16x16x32_bf16 v[40:43], v[162:165], v[178:181], v[40:43]
	v_mfma_f32_16x16x32_bf16 v[28:31], v[154:157], v[206:209], v[28:31]
	v_mfma_f32_16x16x32_bf16 v[24:27], v[162:165], v[206:209], v[24:27]
	v_mfma_f32_16x16x32_bf16 v[12:15], v[154:157], v[214:217], v[12:15]
	v_mfma_f32_16x16x32_bf16 v[8:11], v[162:165], v[214:217], v[8:11]
	s_setprio 0
	s_barrier
	s_add_i32 s4, s5, s51
	s_mov_b32 m0, s4
	s_add_u32 s0, s46, 0x80080
	s_addc_u32 s1, s47, 0
	global_load_lds_dwordx4 v132, s[0:1]
	s_add_i32 m0, s4, 0x2000
	s_nop 0
	global_load_lds_dwordx4 v134, s[0:1]
	s_add_i32 s69, s69, 2
	s_add_u32 s44, s44, 0x100
	s_addc_u32 s45, s45, 0
	s_add_u32 s43, s43, 0x100
	s_addc_u32 s68, s68, 0
	s_cmp_gt_u32 s69, 29
	s_waitcnt vmcnt(6)
	s_barrier
	s_setprio 1
	v_mfma_f32_16x16x32_bf16 v[52:55], v[218:221], v[166:169], v[52:55]
	v_mfma_f32_16x16x32_bf16 v[48:51], v[226:229], v[166:169], v[48:51]
	v_mfma_f32_16x16x32_bf16 v[36:39], v[218:221], v[174:177], v[36:39]
	v_mfma_f32_16x16x32_bf16 v[32:35], v[226:229], v[174:177], v[32:35]
	v_mfma_f32_16x16x32_bf16 v[20:23], v[218:221], v[188:191], v[20:23]
	v_mfma_f32_16x16x32_bf16 v[16:19], v[226:229], v[188:191], v[16:19]
	v_mfma_f32_16x16x32_bf16 v[4:7], v[218:221], v[210:213], v[4:7]
	v_mfma_f32_16x16x32_bf16 v[0:3], v[226:229], v[210:213], v[0:3]
	v_mfma_f32_16x16x32_bf16 v[52:55], v[222:225], v[170:173], v[52:55]
	v_mfma_f32_16x16x32_bf16 v[48:51], v[230:233], v[170:173], v[48:51]
	v_mfma_f32_16x16x32_bf16 v[36:39], v[222:225], v[178:181], v[36:39]
	v_mfma_f32_16x16x32_bf16 v[32:35], v[230:233], v[178:181], v[32:35]
	v_mfma_f32_16x16x32_bf16 v[20:23], v[222:225], v[206:209], v[20:23]
	v_mfma_f32_16x16x32_bf16 v[16:19], v[230:233], v[206:209], v[16:19]
	v_mfma_f32_16x16x32_bf16 v[4:7], v[222:225], v[214:217], v[4:7]
	v_mfma_f32_16x16x32_bf16 v[0:3], v[230:233], v[214:217], v[0:3]
	s_setprio 0
	s_cbranch_scc0 .Lrot_1508
	s_barrier

;     DI size_t aoff(const Unit& u, size_t tstep) const { return (size_t)u.pm * tstep; }
;     DI size_t boff(const Unit& u, size_t tstep) const { return (size_t)u.pn * tstep; }
;     DI bool next(int i, Unit& u) const { const long L = (long)i * G + c; if (L >= np) return false; u.pm = pmv; u.pn = (int)(L % nN); u.ks = (int)(L / nN); return true; }
;     DI size_t aoff(const Unit& u, size_t) const { return (size_t)u.ks * kbytes; }
;     DI size_t boff(const Unit& u, size_t tstep) const { return (size_t)u.pn * tstep + (size_t)u.ks * kbytes; }
;     DI bool next(int i, Unit& u) const { Unit t; if (!S.next(i / 3, t)) return false; u.pm = t.pm; u.pn = t.pn; u.ks = i % 3; return true; }
;     DI size_t aoff(const Unit& u, size_t tstep) const { return (u.ks < 2 ? offU : offOA) + (size_t)u.pm * tstep; }
; #define PG8_LDA(dst, b, h) do { _Pragma("unroll") for (int m = 0; m < 4; ++m) _Pragma("unroll") for (int k = 0; k < 2; ++k) dst[m][k] = *(const LAS bf16x8*)(lds + PG8_SA(b, h) + aoff + m * 2048 + k * 1024); } while (0)
; template <class Epi, class Sched>
; DI void gemm_phase(LAS unsigned char* lds, const Gemm g, const Sched& S, const Epi& E) {
;     ...
;         const bool has_next = S.next(ui + 1, nxt);
;         const char* nA = has_next ? (const char*)g.A + S.aoff(nxt, tstep) : cA; const char* nB = has_next ? (const char*)g.Bt + S.boff(nxt, tstep) : cB;
;         for (int t = 0; t < nt; t += 2) {
;             if constexpr (Epi::HAS_MID) { if (t == E.mid_t(nt)) { int fr3 = fr, fq3 = fq; asm volatile("" : "+v"(fr3), "+v"(fq3)); E.mid(acc, cur, wr, wc, fr3, fq3); } }
;             const bool last = (t == nt - 2);
;             const char* a1 = cA + (size_t)(t + 1) * kstep;
;             const char* a2 = last ? nA : cA + (size_t)(t + 2) * kstep; const char* b2 = last ? nB : cB + (size_t)(t + 2) * kstep;
;             const char* a3 = a2 + kstep; const char* b3 = b2 + kstep;
;             PG8_LDB(B0, 0, 0); PG8_SCHED; PG8_LDA(At, 0, 0); PG8_STAGE(PG8_SA(1, 1), a1 + hstep, voffA);
;             PG8_WAIT_L(8); PG8_BAR; PG8_WAIT_L(0); PG8_MMA(0, 0, At, B0); PG8_BAR; PG8_SCHED;
;             PG8_LDB(B1, 0, 1); PG8_STAGE(PG8_SB(0, 0), b2, voffB);
;             PG8_BAR; PG8_WAIT_L(0); PG8_MMA(0, 1, At, B1); PG8_BAR;
;             PG8_LDA(At, 0, 1); PG8_STAGE(PG8_SA(0, 0), a2, voffA);
;             PG8_BAR; PG8_WAIT_L(0); PG8_MMA(1, 0, At, B0); PG8_BAR; PG8_SCHED;
.LBB0_1667:
	s_ashr_i32 s29, s28, 31
	s_lshl_b64 s[0:1], s[28:29], 20
	s_add_u32 s30, s45, s0
	v_cmp_lt_i64_e32 vcc, s[8:9], v[140:141]
	s_addc_u32 s31, s46, s1
	s_and_b64 s[0:1], vcc, exec
	s_cselect_b32 s29, s31, s43
	s_cselect_b32 s35, s30, s42
	s_ashr_i32 s19, s18, 31
	s_lshl_b64 s[0:1], s[18:19], 20
	s_add_u32 s36, s47, s0
	s_addc_u32 s37, s48, s1
	s_and_b64 s[0:1], vcc, exec
	s_cselect_b32 s19, s37, s41
	s_cselect_b32 s65, s36, s40
	s_add_u32 s8, s42, 0x80080
	s_addc_u32 s9, s43, 0
	s_add_u32 s66, s40, 0x100
	v_mov_b32_e32 v8, 0
	s_addc_u32 s67, s41, 0
	s_mov_b32 s68, -2
	ds_read_b128 v[144:147], v149
	ds_read_b128 v[156:159], v149 offset:1024
	ds_read_b128 v[160:163], v149 offset:2048
	ds_read_b128 v[164:167], v149 offset:3072
	s_add_i32 m0, s39, 0xc000
	ds_read_b128 v[168:171], v150
	ds_read_b128 v[172:175], v150 offset:1024
	ds_read_b128 v[176:179], v150 offset:2048
	ds_read_b128 v[180:183], v150 offset:3072
	ds_read_b128 v[188:191], v150 offset:4096
	ds_read_b128 v[206:209], v150 offset:5120
	ds_read_b128 v[210:213], v150 offset:6144
	global_load_lds_dwordx4 v136, s[8:9]
	s_add_i32 m0, s39, 0xe000
	ds_read_b128 v[214:217], v150 offset:7168
	global_load_lds_dwordx4 v138, s[8:9]
	s_add_u32 s0, s8, 0xfff80080
	s_addc_u32 s1, s9, -1
	s_cmp_eq_u32 s68, 28
	s_cselect_b32 s43, s29, s1
	s_cselect_b32 s42, s35, s0
	s_cselect_b32 s41, s19, s67
	s_cselect_b32 s40, s65, s66
	s_waitcnt lgkmcnt(8)
	s_barrier
	s_waitcnt lgkmcnt(0)
	s_setprio 1
	v_mfma_f32_16x16x32_bf16 v[116:119], v[144:147], v[168:171], 0
	v_mfma_f32_16x16x32_bf16 v[112:115], v[160:163], v[168:171], 0
	v_mfma_f32_16x16x32_bf16 v[100:103], v[144:147], v[176:179], 0
	v_mfma_f32_16x16x32_bf16 v[96:99], v[160:163], v[176:179], 0
	v_mfma_f32_16x16x32_bf16 v[84:87], v[144:147], v[188:191], 0
	v_mfma_f32_16x16x32_bf16 v[80:83], v[160:163], v[188:191], 0
	v_mfma_f32_16x16x32_bf16 v[68:71], v[144:147], v[210:213], 0
	v_mfma_f32_16x16x32_bf16 v[64:67], v[160:163], v[210:213], 0
	v_mfma_f32_16x16x32_bf16 v[116:119], v[156:159], v[172:175], v[116:119]
	v_mfma_f32_16x16x32_bf16 v[112:115], v[164:167], v[172:175], v[112:115]
	v_mfma_f32_16x16x32_bf16 v[100:103], v[156:159], v[180:183], v[100:103]
	v_mfma_f32_16x16x32_bf16 v[96:99], v[164:167], v[180:183], v[96:99]
	v_mfma_f32_16x16x32_bf16 v[84:87], v[156:159], v[206:209], v[84:87]
	v_mfma_f32_16x16x32_bf16 v[80:83], v[164:167], v[206:209], v[80:83]
	v_mfma_f32_16x16x32_bf16 v[68:71], v[156:159], v[214:217], v[68:71]
	v_mfma_f32_16x16x32_bf16 v[64:67], v[164:167], v[214:217], v[64:67]
	s_setprio 0
	s_barrier
	s_add_i32 s0, s61, s50
	s_mov_b32 m0, s0
	ds_read_b128 v[218:221], v151
	ds_read_b128 v[222:225], v151 offset:1024
	ds_read_b128 v[226:229], v151 offset:2048
	global_load_lds_dwordx4 v130, s[40:41]
	s_add_i32 m0, s0, 0x2000
	ds_read_b128 v[230:233], v151 offset:3072
	global_load_lds_dwordx4 v134, s[40:41]
	s_barrier
	s_waitcnt lgkmcnt(0)
	s_setprio 1
	v_mfma_f32_16x16x32_bf16 v[124:127], v[218:221], v[168:171], 0
	v_mfma_f32_16x16x32_bf16 v[120:123], v[226:229], v[168:171], 0
	v_mfma_f32_16x16x32_bf16 v[108:111], v[218:221], v[176:179], 0
	v_mfma_f32_16x16x32_bf16 v[104:107], v[226:229], v[176:179], 0
	v_mfma_f32_16x16x32_bf16 v[92:95], v[218:221], v[188:191], 0
	v_mfma_f32_16x16x32_bf16 v[88:91], v[226:229], v[188:191], 0
	v_mfma_f32_16x16x32_bf16 v[76:79], v[218:221], v[210:213], 0
	v_mfma_f32_16x16x32_bf16 v[72:75], v[226:229], v[210:213], 0
	v_mfma_f32_16x16x32_bf16 v[124:127], v[222:225], v[172:175], v[124:127]
	v_mfma_f32_16x16x32_bf16 v[120:123], v[230:233], v[172:175], v[120:123]
	v_mfma_f32_16x16x32_bf16 v[108:111], v[222:225], v[180:183], v[108:111]
	v_mfma_f32_16x16x32_bf16 v[104:107], v[230:233], v[180:183], v[104:107]
	v_mfma_f32_16x16x32_bf16 v[92:95], v[222:225], v[206:209], v[92:95]
	v_mfma_f32_16x16x32_bf16 v[88:91], v[230:233], v[206:209], v[88:91]
	v_mfma_f32_16x16x32_bf16 v[76:79], v[222:225], v[214:217], v[76:79]
	v_mfma_f32_16x16x32_bf16 v[72:75], v[230:233], v[214:217], v[72:75]
	s_setprio 0
	s_mov_b32 m0, s39
	s_barrier
	ds_read_b128 v[168:171], v150 offset:16384
	ds_read_b128 v[172:175], v150 offset:17408
	ds_read_b128 v[176:179], v150 offset:18432
	ds_read_b128 v[180:183], v150 offset:19456
	ds_read_b128 v[188:191], v150 offset:20480
	ds_read_b128 v[206:209], v150 offset:21504
	ds_read_b128 v[210:213], v150 offset:22528
	global_load_lds_dwordx4 v128, s[42:43]
	s_mov_b32 m0, s51
	ds_read_b128 v[214:217], v150 offset:23552
	global_load_lds_dwordx4 v132, s[42:43]
	s_barrier
	s_waitcnt lgkmcnt(0)
	s_setprio 1
	v_mfma_f32_16x16x32_bf16 v[52:55], v[144:147], v[168:171], 0
	v_mfma_f32_16x16x32_bf16 v[48:51], v[160:163], v[168:171], 0
	v_mfma_f32_16x16x32_bf16 v[36:39], v[144:147], v[176:179], 0
	v_mfma_f32_16x16x32_bf16 v[32:35], v[160:163], v[176:179], 0
	v_mfma_f32_16x16x32_bf16 v[20:23], v[144:147], v[188:191], 0
	v_mfma_f32_16x16x32_bf16 v[16:19], v[160:163], v[188:191], 0
	v_mfma_f32_16x16x32_bf16 v[4:7], v[144:147], v[210:213], 0
	v_mfma_f32_16x16x32_bf16 v[0:3], v[160:163], v[210:213], 0
	v_mfma_f32_16x16x32_bf16 v[52:55], v[156:159], v[172:175], v[52:55]
	v_mfma_f32_16x16x32_bf16 v[48:51], v[164:167], v[172:175], v[48:51]
	v_mfma_f32_16x16x32_bf16 v[36:39], v[156:159], v[180:183], v[36:39]
	v_mfma_f32_16x16x32_bf16 v[32:35], v[164:167], v[180:183], v[32:35]
	v_mfma_f32_16x16x32_bf16 v[20:23], v[156:159], v[206:209], v[20:23]
	v_mfma_f32_16x16x32_bf16 v[16:19], v[164:167], v[206:209], v[16:19]
	v_mfma_f32_16x16x32_bf16 v[4:7], v[156:159], v[214:217], v[4:7]
	v_mfma_f32_16x16x32_bf16 v[0:3], v[164:167], v[214:217], v[0:3]
	s_setprio 0
	s_barrier
; #define PG8_STAGE(bufoff, gbase, voff) do { _Pragma("unroll") for (int _i = 0; _i < 2; ++_i) \
;         __builtin_amdgcn_global_load_lds((const unsigned*)((const char*)(gbase) + (voff)[_i]), (LAS unsigned*)(lds + (bufoff) + ldsw + _i * 8192), 16, 0, 0); } while (0)
; #define PG8_LDA(dst, b, h) do { _Pragma("unroll") for (int m = 0; m < 4; ++m) _Pragma("unroll") for (int k = 0; k < 2; ++k) dst[m][k] = *(const LAS bf16x8*)(lds + PG8_SA(b, h) + aoff + m * 2048 + k * 1024); } while (0)
; #define PG8_LDB(dst, b, h) do { _Pragma("unroll") for (int n = 0; n < 2; ++n) _Pragma("unroll") for (int k = 0; k < 2; ++k) dst[n][k] = *(const LAS bf16x8*)(lds + PG8_SB(b, h) + boff + n * 2048 + k * 1024); } while (0)
; #define PG8_MMA(ai, bj, At, Bt) do { __builtin_amdgcn_s_setprio(1); _Pragma("unroll") for (int m = 0; m < 4; ++m) _Pragma("unroll") for (int n = 0; n < 2; ++n) _Pragma("unroll") for (int k = 0; k < 2; ++k) \
;         acc[ai][bj][m][n] = __builtin_amdgcn_mfma_f32_16x16x32_bf16(Bt[n][k], At[m][k], acc[ai][bj][m][n], 0, 0, 0); __builtin_amdgcn_s_setprio(0); } while (0)
; #define PG8_WAIT_V(n) asm volatile("s_waitcnt vmcnt(" #n ")" ::: "memory")
; #define PG8_WAIT_L(n) asm volatile("s_waitcnt lgkmcnt(" #n ")" ::: "memory")
; #define PG8_BAR __builtin_amdgcn_s_barrier()
; #define PG8_SCHED __builtin_amdgcn_sched_barrier(0)
; template <class Epi, class Sched>
; DI void gemm_phase(LAS unsigned char* lds, const Gemm g, const Sched& S, const Epi& E) {
;     ...
;             PG8_STAGE(PG8_SB(0, 1), b2 + hstep, voffB);
;             PG8_WAIT_V(6); PG8_BAR; PG8_MMA(1, 1, At, B1); PG8_BAR;
;             PG8_LDB(B0, 1, 0); PG8_SCHED; PG8_LDA(At, 1, 0); PG8_STAGE(PG8_SA(0, 1), a2 + hstep, voffA);
;             PG8_WAIT_L(8); PG8_BAR; PG8_WAIT_L(0); PG8_MMA(0, 0, At, B0); PG8_BAR; PG8_SCHED;
;             PG8_LDB(B1, 1, 1); PG8_STAGE(PG8_SB(1, 0), b3, voffB);
	s_add_i32 s4, s62, s50
	s_mov_b32 m0, s4
	s_add_u32 s0, s40, 0x80000
	s_addc_u32 s1, s41, 0
	global_load_lds_dwordx4 v130, s[0:1]
	s_add_i32 m0, s4, 0x2000
	s_nop 0
	global_load_lds_dwordx4 v134, s[0:1]
	s_waitcnt vmcnt(6)
	s_barrier
	s_setprio 1
	v_mfma_f32_16x16x32_bf16 v[60:63], v[218:221], v[168:171], 0
	v_mfma_f32_16x16x32_bf16 v[56:59], v[226:229], v[168:171], 0
	v_mfma_f32_16x16x32_bf16 v[44:47], v[218:221], v[176:179], 0
	v_mfma_f32_16x16x32_bf16 v[40:43], v[226:229], v[176:179], 0
	v_mfma_f32_16x16x32_bf16 v[28:31], v[218:221], v[188:191], 0
	v_mfma_f32_16x16x32_bf16 v[24:27], v[226:229], v[188:191], 0
	v_mfma_f32_16x16x32_bf16 v[12:15], v[218:221], v[210:213], 0
	v_mfma_f32_16x16x32_bf16 v[8:11], v[226:229], v[210:213], 0
	v_mfma_f32_16x16x32_bf16 v[60:63], v[222:225], v[172:175], v[60:63]
	v_mfma_f32_16x16x32_bf16 v[56:59], v[230:233], v[172:175], v[56:59]
	v_mfma_f32_16x16x32_bf16 v[44:47], v[222:225], v[180:183], v[44:47]
	v_mfma_f32_16x16x32_bf16 v[40:43], v[230:233], v[180:183], v[40:43]
	v_mfma_f32_16x16x32_bf16 v[28:31], v[222:225], v[206:209], v[28:31]
	v_mfma_f32_16x16x32_bf16 v[24:27], v[230:233], v[206:209], v[24:27]
	v_mfma_f32_16x16x32_bf16 v[12:15], v[222:225], v[214:217], v[12:15]
	v_mfma_f32_16x16x32_bf16 v[8:11], v[230:233], v[214:217], v[8:11]
	s_setprio 0
	s_add_i32 s4, 0, 0x18000
	v_add_u32_e32 v202, s4, v148
	s_barrier
	ds_read_b128 v[144:147], v202
	ds_read_b128 v[156:159], v202 offset:1024
	ds_read_b128 v[160:163], v202 offset:2048
	ds_read_b128 v[164:167], v202 offset:3072
	s_add_u32 s0, s42, 0x80000
	s_addc_u32 s1, s43, 0
	s_mov_b32 m0, s52
	ds_read_b128 v[168:171], v150 offset:32768
	ds_read_b128 v[172:175], v150 offset:33792
	ds_read_b128 v[176:179], v150 offset:34816
	ds_read_b128 v[180:183], v150 offset:35840
	ds_read_b128 v[188:191], v150 offset:36864
	ds_read_b128 v[206:209], v150 offset:37888
	ds_read_b128 v[210:213], v150 offset:38912
	global_load_lds_dwordx4 v128, s[0:1]
	s_mov_b32 m0, s53
	ds_read_b128 v[214:217], v150 offset:39936
	global_load_lds_dwordx4 v132, s[0:1]
	s_waitcnt lgkmcnt(8)
	s_barrier
	s_waitcnt lgkmcnt(0)
	s_setprio 1
	v_mfma_f32_16x16x32_bf16 v[116:119], v[144:147], v[168:171], v[116:119]
	v_mfma_f32_16x16x32_bf16 v[112:115], v[160:163], v[168:171], v[112:115]
	v_mfma_f32_16x16x32_bf16 v[100:103], v[144:147], v[176:179], v[100:103]
	v_mfma_f32_16x16x32_bf16 v[96:99], v[160:163], v[176:179], v[96:99]
	v_mfma_f32_16x16x32_bf16 v[84:87], v[144:147], v[188:191], v[84:87]
	v_mfma_f32_16x16x32_bf16 v[80:83], v[160:163], v[188:191], v[80:83]
	v_mfma_f32_16x16x32_bf16 v[68:71], v[144:147], v[210:213], v[68:71]
	v_mfma_f32_16x16x32_bf16 v[64:67], v[160:163], v[210:213], v[64:67]
	v_mfma_f32_16x16x32_bf16 v[116:119], v[156:159], v[172:175], v[116:119]
	v_mfma_f32_16x16x32_bf16 v[112:115], v[164:167], v[172:175], v[112:115]
	v_mfma_f32_16x16x32_bf16 v[100:103], v[156:159], v[180:183], v[100:103]
	v_mfma_f32_16x16x32_bf16 v[96:99], v[164:167], v[180:183], v[96:99]
	v_mfma_f32_16x16x32_bf16 v[84:87], v[156:159], v[206:209], v[84:87]
	v_mfma_f32_16x16x32_bf16 v[80:83], v[164:167], v[206:209], v[80:83]
	v_mfma_f32_16x16x32_bf16 v[68:71], v[156:159], v[214:217], v[68:71]
	v_mfma_f32_16x16x32_bf16 v[64:67], v[164:167], v[214:217], v[64:67]
	s_setprio 0
	s_barrier
	s_add_i32 s5, 0, 0x1c000
	s_add_i32 s0, s4, s50
	v_add_u32_e32 v203, s5, v148
	s_add_i32 m0, s0, 0xffffff80
	ds_read_b128 v[218:221], v203
	ds_read_b128 v[222:225], v203 offset:1024
	ds_read_b128 v[226:229], v203 offset:2048
	global_load_lds_dwordx4 v130, s[40:41] offset:128
	s_add_i32 m0, s0, 0x1f80
	ds_read_b128 v[230:233], v203 offset:3072
	global_load_lds_dwordx4 v134, s[40:41] offset:128
	s_barrier
; #define PG8_STAGE(bufoff, gbase, voff) do { _Pragma("unroll") for (int _i = 0; _i < 2; ++_i) \
;         __builtin_amdgcn_global_load_lds((const unsigned*)((const char*)(gbase) + (voff)[_i]), (LAS unsigned*)(lds + (bufoff) + ldsw + _i * 8192), 16, 0, 0); } while (0)
; #define PG8_LDA(dst, b, h) do { _Pragma("unroll") for (int m = 0; m < 4; ++m) _Pragma("unroll") for (int k = 0; k < 2; ++k) dst[m][k] = *(const LAS bf16x8*)(lds + PG8_SA(b, h) + aoff + m * 2048 + k * 1024); } while (0)
; #define PG8_MMA(ai, bj, At, Bt) do { __builtin_amdgcn_s_setprio(1); _Pragma("unroll") for (int m = 0; m < 4; ++m) _Pragma("unroll") for (int n = 0; n < 2; ++n) _Pragma("unroll") for (int k = 0; k < 2; ++k) \
;         acc[ai][bj][m][n] = __builtin_amdgcn_mfma_f32_16x16x32_bf16(Bt[n][k], At[m][k], acc[ai][bj][m][n], 0, 0, 0); __builtin_amdgcn_s_setprio(0); } while (0)
; #define PG8_WAIT_V(n) asm volatile("s_waitcnt vmcnt(" #n ")" ::: "memory")
; #define PG8_WAIT_L(n) asm volatile("s_waitcnt lgkmcnt(" #n ")" ::: "memory")
; #define PG8_BAR __builtin_amdgcn_s_barrier()
; #define PG8_SCHED __builtin_amdgcn_sched_barrier(0)
; template <class Epi, class Sched>
; DI void gemm_phase(LAS unsigned char* lds, const Gemm g, const Sched& S, const Epi& E) {
;     ...
;             PG8_BAR; PG8_WAIT_L(0); PG8_MMA(0, 1, At, B1); PG8_BAR;
;             PG8_LDA(At, 1, 1); PG8_STAGE(PG8_SA(1, 0), a3, voffA);
;             PG8_BAR; PG8_WAIT_L(0); PG8_MMA(1, 0, At, B0); PG8_BAR; PG8_SCHED;
;             PG8_STAGE(PG8_SB(1, 1), b3 + hstep, voffB);
;             PG8_WAIT_V(6); PG8_BAR; PG8_MMA(1, 1, At, B1); PG8_BAR;
;         }
	s_waitcnt lgkmcnt(0)
	s_setprio 1
	v_mfma_f32_16x16x32_bf16 v[124:127], v[218:221], v[168:171], v[124:127]
	v_mfma_f32_16x16x32_bf16 v[120:123], v[226:229], v[168:171], v[120:123]
	v_mfma_f32_16x16x32_bf16 v[108:111], v[218:221], v[176:179], v[108:111]
	v_mfma_f32_16x16x32_bf16 v[104:107], v[226:229], v[176:179], v[104:107]
	v_mfma_f32_16x16x32_bf16 v[92:95], v[218:221], v[188:191], v[92:95]
	v_mfma_f32_16x16x32_bf16 v[88:91], v[226:229], v[188:191], v[88:91]
	v_mfma_f32_16x16x32_bf16 v[76:79], v[218:221], v[210:213], v[76:79]
	v_mfma_f32_16x16x32_bf16 v[72:75], v[226:229], v[210:213], v[72:75]
	v_mfma_f32_16x16x32_bf16 v[124:127], v[222:225], v[172:175], v[124:127]
	v_mfma_f32_16x16x32_bf16 v[120:123], v[230:233], v[172:175], v[120:123]
	v_mfma_f32_16x16x32_bf16 v[108:111], v[222:225], v[180:183], v[108:111]
	v_mfma_f32_16x16x32_bf16 v[104:107], v[230:233], v[180:183], v[104:107]
	v_mfma_f32_16x16x32_bf16 v[92:95], v[222:225], v[206:209], v[92:95]
	v_mfma_f32_16x16x32_bf16 v[88:91], v[230:233], v[206:209], v[88:91]
	v_mfma_f32_16x16x32_bf16 v[76:79], v[222:225], v[214:217], v[76:79]
	v_mfma_f32_16x16x32_bf16 v[72:75], v[230:233], v[214:217], v[72:75]
	s_setprio 0
	s_add_i32 m0, s57, 0xffffff80
	s_barrier
	ds_read_b128 v[168:171], v150 offset:49152
	ds_read_b128 v[172:175], v150 offset:50176
	ds_read_b128 v[176:179], v150 offset:51200
	ds_read_b128 v[180:183], v150 offset:52224
	ds_read_b128 v[188:191], v150 offset:53248
	ds_read_b128 v[206:209], v150 offset:54272
	ds_read_b128 v[210:213], v150 offset:55296
	global_load_lds_dwordx4 v128, s[42:43] offset:128
	s_add_i32 m0, s58, 0xffffff80
	ds_read_b128 v[214:217], v150 offset:56320
	global_load_lds_dwordx4 v132, s[42:43] offset:128
	s_barrier
	s_waitcnt lgkmcnt(0)
	s_setprio 1
	v_mfma_f32_16x16x32_bf16 v[52:55], v[144:147], v[168:171], v[52:55]
	v_mfma_f32_16x16x32_bf16 v[48:51], v[160:163], v[168:171], v[48:51]
	v_mfma_f32_16x16x32_bf16 v[36:39], v[144:147], v[176:179], v[36:39]
	v_mfma_f32_16x16x32_bf16 v[32:35], v[160:163], v[176:179], v[32:35]
	v_mfma_f32_16x16x32_bf16 v[20:23], v[144:147], v[188:191], v[20:23]
	v_mfma_f32_16x16x32_bf16 v[16:19], v[160:163], v[188:191], v[16:19]
	v_mfma_f32_16x16x32_bf16 v[4:7], v[144:147], v[210:213], v[4:7]
	v_mfma_f32_16x16x32_bf16 v[0:3], v[160:163], v[210:213], v[0:3]
	v_mfma_f32_16x16x32_bf16 v[52:55], v[156:159], v[172:175], v[52:55]
	v_mfma_f32_16x16x32_bf16 v[48:51], v[164:167], v[172:175], v[48:51]
	v_mfma_f32_16x16x32_bf16 v[36:39], v[156:159], v[180:183], v[36:39]
	v_mfma_f32_16x16x32_bf16 v[32:35], v[164:167], v[180:183], v[32:35]
	v_mfma_f32_16x16x32_bf16 v[20:23], v[156:159], v[206:209], v[20:23]
	v_mfma_f32_16x16x32_bf16 v[16:19], v[164:167], v[206:209], v[16:19]
	v_mfma_f32_16x16x32_bf16 v[4:7], v[156:159], v[214:217], v[4:7]
	v_mfma_f32_16x16x32_bf16 v[0:3], v[164:167], v[214:217], v[0:3]
	s_setprio 0
	s_barrier
	s_add_i32 s4, s5, s50
	s_mov_b32 m0, s4
	s_add_u32 s0, s40, 0x80080
	s_addc_u32 s1, s41, 0
	global_load_lds_dwordx4 v130, s[0:1]
	s_add_i32 m0, s4, 0x2000
	s_nop 0
	global_load_lds_dwordx4 v134, s[0:1]
	s_add_i32 s68, s68, 2
	s_add_u32 s8, s8, 0x100
	s_addc_u32 s9, s9, 0
	s_add_u32 s66, s66, 0x100
	s_addc_u32 s67, s67, 0
	s_cmp_gt_u32 s68, 29
	s_waitcnt vmcnt(6)
	s_barrier
	s_setprio 1
	v_mfma_f32_16x16x32_bf16 v[60:63], v[218:221], v[168:171], v[60:63]
	v_mfma_f32_16x16x32_bf16 v[56:59], v[226:229], v[168:171], v[56:59]
	v_mfma_f32_16x16x32_bf16 v[44:47], v[218:221], v[176:179], v[44:47]
	v_mfma_f32_16x16x32_bf16 v[40:43], v[226:229], v[176:179], v[40:43]
	v_mfma_f32_16x16x32_bf16 v[28:31], v[218:221], v[188:191], v[28:31]
	v_mfma_f32_16x16x32_bf16 v[24:27], v[226:229], v[188:191], v[24:27]
	v_mfma_f32_16x16x32_bf16 v[12:15], v[218:221], v[210:213], v[12:15]
	v_mfma_f32_16x16x32_bf16 v[8:11], v[226:229], v[210:213], v[8:11]
	v_mfma_f32_16x16x32_bf16 v[60:63], v[222:225], v[172:175], v[60:63]
	v_mfma_f32_16x16x32_bf16 v[56:59], v[230:233], v[172:175], v[56:59]
	v_mfma_f32_16x16x32_bf16 v[44:47], v[222:225], v[180:183], v[44:47]
	v_mfma_f32_16x16x32_bf16 v[40:43], v[230:233], v[180:183], v[40:43]
	v_mfma_f32_16x16x32_bf16 v[28:31], v[222:225], v[206:209], v[28:31]
	v_mfma_f32_16x16x32_bf16 v[24:27], v[230:233], v[206:209], v[24:27]
	v_mfma_f32_16x16x32_bf16 v[12:15], v[222:225], v[214:217], v[12:15]
	v_mfma_f32_16x16x32_bf16 v[8:11], v[230:233], v[214:217], v[8:11]
	s_setprio 0
	s_cbranch_scc0 .Lrot_1668
	s_barrier
	s_branch .Lpeel_done_1668

; #define PG8_STAGE(bufoff, gbase, voff) do { _Pragma("unroll") for (int _i = 0; _i < 2; ++_i) \
;         __builtin_amdgcn_global_load_lds((const unsigned*)((const char*)(gbase) + (voff)[_i]), (LAS unsigned*)(lds + (bufoff) + ldsw + _i * 8192), 16, 0, 0); } while (0)
; #define PG8_LDA(dst, b, h) do { _Pragma("unroll") for (int m = 0; m < 4; ++m) _Pragma("unroll") for (int k = 0; k < 2; ++k) dst[m][k] = *(const LAS bf16x8*)(lds + PG8_SA(b, h) + aoff + m * 2048 + k * 1024); } while (0)
; #define PG8_LDB(dst, b, h) do { _Pragma("unroll") for (int n = 0; n < 2; ++n) _Pragma("unroll") for (int k = 0; k < 2; ++k) dst[n][k] = *(const LAS bf16x8*)(lds + PG8_SB(b, h) + boff + n * 2048 + k * 1024); } while (0)
; #define PG8_MMA(ai, bj, At, Bt) do { __builtin_amdgcn_s_setprio(1); _Pragma("unroll") for (int m = 0; m < 4; ++m) _Pragma("unroll") for (int n = 0; n < 2; ++n) _Pragma("unroll") for (int k = 0; k < 2; ++k) \
;         acc[ai][bj][m][n] = __builtin_amdgcn_mfma_f32_16x16x32_bf16(Bt[n][k], At[m][k], acc[ai][bj][m][n], 0, 0, 0); __builtin_amdgcn_s_setprio(0); } while (0)
; #define PG8_WAIT_V(n) asm volatile("s_waitcnt vmcnt(" #n ")" ::: "memory")
; #define PG8_WAIT_L(n) asm volatile("s_waitcnt lgkmcnt(" #n ")" ::: "memory")
; #define PG8_BAR __builtin_amdgcn_s_barrier()
; #define PG8_SCHED __builtin_amdgcn_sched_barrier(0)
; template <class Epi, class Sched>
; DI void gemm_phase(LAS unsigned char* lds, const Gemm g, const Sched& S, const Epi& E) {
;     ...
;             PG8_LDB(B0, 0, 0); PG8_SCHED; PG8_LDA(At, 0, 0); PG8_STAGE(PG8_SA(1, 1), a1 + hstep, voffA);
;             PG8_WAIT_L(8); PG8_BAR; PG8_WAIT_L(0); PG8_MMA(0, 0, At, B0); PG8_BAR; PG8_SCHED;
;             PG8_LDB(B1, 0, 1); PG8_STAGE(PG8_SB(0, 0), b2, voffB);
;             PG8_BAR; PG8_WAIT_L(0); PG8_MMA(0, 1, At, B1); PG8_BAR;
;             PG8_LDA(At, 0, 1); PG8_STAGE(PG8_SA(0, 0), a2, voffA);
;             PG8_BAR; PG8_WAIT_L(0); PG8_MMA(1, 0, At, B0); PG8_BAR; PG8_SCHED;
;             PG8_STAGE(PG8_SB(0, 1), b2 + hstep, voffB);
;             PG8_WAIT_V(6); PG8_BAR; PG8_MMA(1, 1, At, B1); PG8_BAR;
.LBB0_1668:
	ds_read_b128 v[144:147], v149
	ds_read_b128 v[156:159], v149 offset:1024
	ds_read_b128 v[160:163], v149 offset:2048
	ds_read_b128 v[164:167], v149 offset:3072
	s_add_i32 m0, s39, 0xc000
	ds_read_b128 v[168:171], v150
	ds_read_b128 v[172:175], v150 offset:1024
	ds_read_b128 v[176:179], v150 offset:2048
	ds_read_b128 v[180:183], v150 offset:3072
	ds_read_b128 v[188:191], v150 offset:4096
	ds_read_b128 v[206:209], v150 offset:5120
	ds_read_b128 v[210:213], v150 offset:6144
	global_load_lds_dwordx4 v136, s[8:9]
	s_add_i32 m0, s39, 0xe000
	ds_read_b128 v[214:217], v150 offset:7168
	global_load_lds_dwordx4 v138, s[8:9]
	s_add_u32 s0, s8, 0xfff80080
	s_addc_u32 s1, s9, -1
	s_cmp_eq_u32 s68, 28
	s_cselect_b32 s43, s29, s1
	s_cselect_b32 s42, s35, s0
	s_cselect_b32 s41, s19, s67
	s_cselect_b32 s40, s65, s66
	s_waitcnt lgkmcnt(8)
	s_barrier
	s_waitcnt lgkmcnt(0)
	s_setprio 1
	v_mfma_f32_16x16x32_bf16 v[116:119], v[144:147], v[168:171], v[116:119]
	v_mfma_f32_16x16x32_bf16 v[112:115], v[160:163], v[168:171], v[112:115]
	v_mfma_f32_16x16x32_bf16 v[100:103], v[144:147], v[176:179], v[100:103]
	v_mfma_f32_16x16x32_bf16 v[96:99], v[160:163], v[176:179], v[96:99]
	v_mfma_f32_16x16x32_bf16 v[84:87], v[144:147], v[188:191], v[84:87]
	v_mfma_f32_16x16x32_bf16 v[80:83], v[160:163], v[188:191], v[80:83]
	v_mfma_f32_16x16x32_bf16 v[68:71], v[144:147], v[210:213], v[68:71]
	v_mfma_f32_16x16x32_bf16 v[64:67], v[160:163], v[210:213], v[64:67]
	v_mfma_f32_16x16x32_bf16 v[116:119], v[156:159], v[172:175], v[116:119]
	v_mfma_f32_16x16x32_bf16 v[112:115], v[164:167], v[172:175], v[112:115]
	v_mfma_f32_16x16x32_bf16 v[100:103], v[156:159], v[180:183], v[100:103]
	v_mfma_f32_16x16x32_bf16 v[96:99], v[164:167], v[180:183], v[96:99]
	v_mfma_f32_16x16x32_bf16 v[84:87], v[156:159], v[206:209], v[84:87]
	v_mfma_f32_16x16x32_bf16 v[80:83], v[164:167], v[206:209], v[80:83]
	v_mfma_f32_16x16x32_bf16 v[68:71], v[156:159], v[214:217], v[68:71]
	v_mfma_f32_16x16x32_bf16 v[64:67], v[164:167], v[214:217], v[64:67]
	s_setprio 0
	s_barrier
	s_add_i32 s0, s61, s50
	s_mov_b32 m0, s0
	ds_read_b128 v[218:221], v151
	ds_read_b128 v[222:225], v151 offset:1024
	ds_read_b128 v[226:229], v151 offset:2048
	global_load_lds_dwordx4 v130, s[40:41]
	s_add_i32 m0, s0, 0x2000
	ds_read_b128 v[230:233], v151 offset:3072
	global_load_lds_dwordx4 v134, s[40:41]
	s_barrier
	s_waitcnt lgkmcnt(0)
	s_setprio 1
	v_mfma_f32_16x16x32_bf16 v[124:127], v[218:221], v[168:171], v[124:127]
	v_mfma_f32_16x16x32_bf16 v[120:123], v[226:229], v[168:171], v[120:123]
	v_mfma_f32_16x16x32_bf16 v[108:111], v[218:221], v[176:179], v[108:111]
	v_mfma_f32_16x16x32_bf16 v[104:107], v[226:229], v[176:179], v[104:107]
	v_mfma_f32_16x16x32_bf16 v[92:95], v[218:221], v[188:191], v[92:95]
	v_mfma_f32_16x16x32_bf16 v[88:91], v[226:229], v[188:191], v[88:91]
	v_mfma_f32_16x16x32_bf16 v[76:79], v[218:221], v[210:213], v[76:79]
	v_mfma_f32_16x16x32_bf16 v[72:75], v[226:229], v[210:213], v[72:75]
	v_mfma_f32_16x16x32_bf16 v[124:127], v[222:225], v[172:175], v[124:127]
	v_mfma_f32_16x16x32_bf16 v[120:123], v[230:233], v[172:175], v[120:123]
	v_mfma_f32_16x16x32_bf16 v[108:111], v[222:225], v[180:183], v[108:111]
	v_mfma_f32_16x16x32_bf16 v[104:107], v[230:233], v[180:183], v[104:107]
	v_mfma_f32_16x16x32_bf16 v[92:95], v[222:225], v[206:209], v[92:95]
	v_mfma_f32_16x16x32_bf16 v[88:91], v[230:233], v[206:209], v[88:91]
	v_mfma_f32_16x16x32_bf16 v[76:79], v[222:225], v[214:217], v[76:79]
	v_mfma_f32_16x16x32_bf16 v[72:75], v[230:233], v[214:217], v[72:75]
	s_setprio 0
	s_mov_b32 m0, s39
	s_barrier
	ds_read_b128 v[168:171], v150 offset:16384
	ds_read_b128 v[172:175], v150 offset:17408
	ds_read_b128 v[176:179], v150 offset:18432
	ds_read_b128 v[180:183], v150 offset:19456
	ds_read_b128 v[188:191], v150 offset:20480
	ds_read_b128 v[206:209], v150 offset:21504
	ds_read_b128 v[210:213], v150 offset:22528
	global_load_lds_dwordx4 v128, s[42:43]
	s_mov_b32 m0, s51
	ds_read_b128 v[214:217], v150 offset:23552
	global_load_lds_dwordx4 v132, s[42:43]
	s_barrier
	s_waitcnt lgkmcnt(0)
	s_setprio 1
	v_mfma_f32_16x16x32_bf16 v[52:55], v[144:147], v[168:171], v[52:55]
	v_mfma_f32_16x16x32_bf16 v[48:51], v[160:163], v[168:171], v[48:51]
	v_mfma_f32_16x16x32_bf16 v[36:39], v[144:147], v[176:179], v[36:39]
	v_mfma_f32_16x16x32_bf16 v[32:35], v[160:163], v[176:179], v[32:35]
	v_mfma_f32_16x16x32_bf16 v[20:23], v[144:147], v[188:191], v[20:23]
	v_mfma_f32_16x16x32_bf16 v[16:19], v[160:163], v[188:191], v[16:19]
	v_mfma_f32_16x16x32_bf16 v[4:7], v[144:147], v[210:213], v[4:7]
	v_mfma_f32_16x16x32_bf16 v[0:3], v[160:163], v[210:213], v[0:3]
	v_mfma_f32_16x16x32_bf16 v[52:55], v[156:159], v[172:175], v[52:55]
	v_mfma_f32_16x16x32_bf16 v[48:51], v[164:167], v[172:175], v[48:51]
	v_mfma_f32_16x16x32_bf16 v[36:39], v[156:159], v[180:183], v[36:39]
	v_mfma_f32_16x16x32_bf16 v[32:35], v[164:167], v[180:183], v[32:35]
	v_mfma_f32_16x16x32_bf16 v[20:23], v[156:159], v[206:209], v[20:23]
	v_mfma_f32_16x16x32_bf16 v[16:19], v[164:167], v[206:209], v[16:19]
	v_mfma_f32_16x16x32_bf16 v[4:7], v[156:159], v[214:217], v[4:7]
	v_mfma_f32_16x16x32_bf16 v[0:3], v[164:167], v[214:217], v[0:3]
	s_setprio 0
	s_barrier
	s_add_i32 s4, s62, s50
	s_mov_b32 m0, s4
	s_add_u32 s0, s40, 0x80000
	s_addc_u32 s1, s41, 0
	global_load_lds_dwordx4 v130, s[0:1]
	s_add_i32 m0, s4, 0x2000
	s_nop 0
	global_load_lds_dwordx4 v134, s[0:1]
	s_waitcnt vmcnt(6)
	s_barrier
; #define PG8_STAGE(bufoff, gbase, voff) do { _Pragma("unroll") for (int _i = 0; _i < 2; ++_i) \
;         __builtin_amdgcn_global_load_lds((const unsigned*)((const char*)(gbase) + (voff)[_i]), (LAS unsigned*)(lds + (bufoff) + ldsw + _i * 8192), 16, 0, 0); } while (0)
; #define PG8_LDA(dst, b, h) do { _Pragma("unroll") for (int m = 0; m < 4; ++m) _Pragma("unroll") for (int k = 0; k < 2; ++k) dst[m][k] = *(const LAS bf16x8*)(lds + PG8_SA(b, h) + aoff + m * 2048 + k * 1024); } while (0)
; #define PG8_LDB(dst, b, h) do { _Pragma("unroll") for (int n = 0; n < 2; ++n) _Pragma("unroll") for (int k = 0; k < 2; ++k) dst[n][k] = *(const LAS bf16x8*)(lds + PG8_SB(b, h) + boff + n * 2048 + k * 1024); } while (0)
; #define PG8_MMA(ai, bj, At, Bt) do { __builtin_amdgcn_s_setprio(1); _Pragma("unroll") for (int m = 0; m < 4; ++m) _Pragma("unroll") for (int n = 0; n < 2; ++n) _Pragma("unroll") for (int k = 0; k < 2; ++k) \
;         acc[ai][bj][m][n] = __builtin_amdgcn_mfma_f32_16x16x32_bf16(Bt[n][k], At[m][k], acc[ai][bj][m][n], 0, 0, 0); __builtin_amdgcn_s_setprio(0); } while (0)
; #define PG8_WAIT_V(n) asm volatile("s_waitcnt vmcnt(" #n ")" ::: "memory")
; #define PG8_WAIT_L(n) asm volatile("s_waitcnt lgkmcnt(" #n ")" ::: "memory")
; #define PG8_BAR __builtin_amdgcn_s_barrier()
; #define PG8_SCHED __builtin_amdgcn_sched_barrier(0)
; template <class Epi, class Sched>
; DI void gemm_phase(LAS unsigned char* lds, const Gemm g, const Sched& S, const Epi& E) {
;     ...
;             PG8_WAIT_V(6); PG8_BAR; PG8_MMA(1, 1, At, B1); PG8_BAR;
;             PG8_LDB(B0, 1, 0); PG8_SCHED; PG8_LDA(At, 1, 0); PG8_STAGE(PG8_SA(0, 1), a2 + hstep, voffA);
;             PG8_WAIT_L(8); PG8_BAR; PG8_WAIT_L(0); PG8_MMA(0, 0, At, B0); PG8_BAR; PG8_SCHED;
;             PG8_LDB(B1, 1, 1); PG8_STAGE(PG8_SB(1, 0), b3, voffB);
	s_setprio 1
	v_mfma_f32_16x16x32_bf16 v[60:63], v[218:221], v[168:171], v[60:63]
	v_mfma_f32_16x16x32_bf16 v[56:59], v[226:229], v[168:171], v[56:59]
	v_mfma_f32_16x16x32_bf16 v[44:47], v[218:221], v[176:179], v[44:47]
	v_mfma_f32_16x16x32_bf16 v[40:43], v[226:229], v[176:179], v[40:43]
	v_mfma_f32_16x16x32_bf16 v[28:31], v[218:221], v[188:191], v[28:31]
	v_mfma_f32_16x16x32_bf16 v[24:27], v[226:229], v[188:191], v[24:27]
	v_mfma_f32_16x16x32_bf16 v[12:15], v[218:221], v[210:213], v[12:15]
	v_mfma_f32_16x16x32_bf16 v[8:11], v[226:229], v[210:213], v[8:11]
	v_mfma_f32_16x16x32_bf16 v[60:63], v[222:225], v[172:175], v[60:63]
	v_mfma_f32_16x16x32_bf16 v[56:59], v[230:233], v[172:175], v[56:59]
	v_mfma_f32_16x16x32_bf16 v[44:47], v[222:225], v[180:183], v[44:47]
	v_mfma_f32_16x16x32_bf16 v[40:43], v[230:233], v[180:183], v[40:43]
	v_mfma_f32_16x16x32_bf16 v[28:31], v[222:225], v[206:209], v[28:31]
	v_mfma_f32_16x16x32_bf16 v[24:27], v[230:233], v[206:209], v[24:27]
	v_mfma_f32_16x16x32_bf16 v[12:15], v[222:225], v[214:217], v[12:15]
	v_mfma_f32_16x16x32_bf16 v[8:11], v[230:233], v[214:217], v[8:11]
	s_setprio 0
	s_add_i32 s4, 0, 0x18000
	s_barrier
	ds_read_b128 v[144:147], v202
	ds_read_b128 v[156:159], v202 offset:1024
	ds_read_b128 v[160:163], v202 offset:2048
	ds_read_b128 v[164:167], v202 offset:3072
	s_add_u32 s0, s42, 0x80000
	s_addc_u32 s1, s43, 0
	s_mov_b32 m0, s52
	ds_read_b128 v[168:171], v150 offset:32768
	ds_read_b128 v[172:175], v150 offset:33792
	ds_read_b128 v[176:179], v150 offset:34816
	ds_read_b128 v[180:183], v150 offset:35840
	ds_read_b128 v[188:191], v150 offset:36864
	ds_read_b128 v[206:209], v150 offset:37888
	ds_read_b128 v[210:213], v150 offset:38912
	global_load_lds_dwordx4 v128, s[0:1]
	s_mov_b32 m0, s53
	ds_read_b128 v[214:217], v150 offset:39936
	global_load_lds_dwordx4 v132, s[0:1]
	s_waitcnt lgkmcnt(8)
	s_barrier
	s_waitcnt lgkmcnt(0)
	s_setprio 1
	v_mfma_f32_16x16x32_bf16 v[116:119], v[144:147], v[168:171], v[116:119]
	v_mfma_f32_16x16x32_bf16 v[112:115], v[160:163], v[168:171], v[112:115]
	v_mfma_f32_16x16x32_bf16 v[100:103], v[144:147], v[176:179], v[100:103]
	v_mfma_f32_16x16x32_bf16 v[96:99], v[160:163], v[176:179], v[96:99]
	v_mfma_f32_16x16x32_bf16 v[84:87], v[144:147], v[188:191], v[84:87]
	v_mfma_f32_16x16x32_bf16 v[80:83], v[160:163], v[188:191], v[80:83]
	v_mfma_f32_16x16x32_bf16 v[68:71], v[144:147], v[210:213], v[68:71]
	v_mfma_f32_16x16x32_bf16 v[64:67], v[160:163], v[210:213], v[64:67]
	v_mfma_f32_16x16x32_bf16 v[116:119], v[156:159], v[172:175], v[116:119]
	v_mfma_f32_16x16x32_bf16 v[112:115], v[164:167], v[172:175], v[112:115]
	v_mfma_f32_16x16x32_bf16 v[100:103], v[156:159], v[180:183], v[100:103]
	v_mfma_f32_16x16x32_bf16 v[96:99], v[164:167], v[180:183], v[96:99]
	v_mfma_f32_16x16x32_bf16 v[84:87], v[156:159], v[206:209], v[84:87]
	v_mfma_f32_16x16x32_bf16 v[80:83], v[164:167], v[206:209], v[80:83]
	v_mfma_f32_16x16x32_bf16 v[68:71], v[156:159], v[214:217], v[68:71]
	v_mfma_f32_16x16x32_bf16 v[64:67], v[164:167], v[214:217], v[64:67]
	s_setprio 0
	s_barrier
	s_add_i32 s5, 0, 0x1c000
	s_add_i32 s0, s4, s50
	s_add_i32 m0, s0, 0xffffff80
	ds_read_b128 v[218:221], v203
	ds_read_b128 v[222:225], v203 offset:1024
	ds_read_b128 v[226:229], v203 offset:2048
	global_load_lds_dwordx4 v130, s[40:41] offset:128
	s_add_i32 m0, s0, 0x1f80
	ds_read_b128 v[230:233], v203 offset:3072
	global_load_lds_dwordx4 v134, s[40:41] offset:128
	s_barrier
; #define PG8_STAGE(bufoff, gbase, voff) do { _Pragma("unroll") for (int _i = 0; _i < 2; ++_i) \
;         __builtin_amdgcn_global_load_lds((const unsigned*)((const char*)(gbase) + (voff)[_i]), (LAS unsigned*)(lds + (bufoff) + ldsw + _i * 8192), 16, 0, 0); } while (0)
; #define PG8_LDA(dst, b, h) do { _Pragma("unroll") for (int m = 0; m < 4; ++m) _Pragma("unroll") for (int k = 0; k < 2; ++k) dst[m][k] = *(const LAS bf16x8*)(lds + PG8_SA(b, h) + aoff + m * 2048 + k * 1024); } while (0)
; #define PG8_MMA(ai, bj, At, Bt) do { __builtin_amdgcn_s_setprio(1); _Pragma("unroll") for (int m = 0; m < 4; ++m) _Pragma("unroll") for (int n = 0; n < 2; ++n) _Pragma("unroll") for (int k = 0; k < 2; ++k) \
;         acc[ai][bj][m][n] = __builtin_amdgcn_mfma_f32_16x16x32_bf16(Bt[n][k], At[m][k], acc[ai][bj][m][n], 0, 0, 0); __builtin_amdgcn_s_setprio(0); } while (0)
; #define PG8_WAIT_V(n) asm volatile("s_waitcnt vmcnt(" #n ")" ::: "memory")
; #define PG8_WAIT_L(n) asm volatile("s_waitcnt lgkmcnt(" #n ")" ::: "memory")
; #define PG8_BAR __builtin_amdgcn_s_barrier()
; #define PG8_SCHED __builtin_amdgcn_sched_barrier(0)
; template <class Epi, class Sched>
; DI void gemm_phase(LAS unsigned char* lds, const Gemm g, const Sched& S, const Epi& E) {
;     ...
;             PG8_BAR; PG8_WAIT_L(0); PG8_MMA(0, 1, At, B1); PG8_BAR;
;             PG8_LDA(At, 1, 1); PG8_STAGE(PG8_SA(1, 0), a3, voffA);
;             PG8_BAR; PG8_WAIT_L(0); PG8_MMA(1, 0, At, B0); PG8_BAR; PG8_SCHED;
;             PG8_STAGE(PG8_SB(1, 1), b3 + hstep, voffB);
;             PG8_WAIT_V(6); PG8_BAR; PG8_MMA(1, 1, At, B1); PG8_BAR;
;         }
	s_waitcnt lgkmcnt(0)
	s_setprio 1
	v_mfma_f32_16x16x32_bf16 v[124:127], v[218:221], v[168:171], v[124:127]
	v_mfma_f32_16x16x32_bf16 v[120:123], v[226:229], v[168:171], v[120:123]
	v_mfma_f32_16x16x32_bf16 v[108:111], v[218:221], v[176:179], v[108:111]
	v_mfma_f32_16x16x32_bf16 v[104:107], v[226:229], v[176:179], v[104:107]
	v_mfma_f32_16x16x32_bf16 v[92:95], v[218:221], v[188:191], v[92:95]
	v_mfma_f32_16x16x32_bf16 v[88:91], v[226:229], v[188:191], v[88:91]
	v_mfma_f32_16x16x32_bf16 v[76:79], v[218:221], v[210:213], v[76:79]
	v_mfma_f32_16x16x32_bf16 v[72:75], v[226:229], v[210:213], v[72:75]
	v_mfma_f32_16x16x32_bf16 v[124:127], v[222:225], v[172:175], v[124:127]
	v_mfma_f32_16x16x32_bf16 v[120:123], v[230:233], v[172:175], v[120:123]
	v_mfma_f32_16x16x32_bf16 v[108:111], v[222:225], v[180:183], v[108:111]
	v_mfma_f32_16x16x32_bf16 v[104:107], v[230:233], v[180:183], v[104:107]
	v_mfma_f32_16x16x32_bf16 v[92:95], v[222:225], v[206:209], v[92:95]
	v_mfma_f32_16x16x32_bf16 v[88:91], v[230:233], v[206:209], v[88:91]
	v_mfma_f32_16x16x32_bf16 v[76:79], v[222:225], v[214:217], v[76:79]
	v_mfma_f32_16x16x32_bf16 v[72:75], v[230:233], v[214:217], v[72:75]
	s_setprio 0
	s_add_i32 m0, s57, 0xffffff80
	s_barrier
	ds_read_b128 v[168:171], v150 offset:49152
	ds_read_b128 v[172:175], v150 offset:50176
	ds_read_b128 v[176:179], v150 offset:51200
	ds_read_b128 v[180:183], v150 offset:52224
	ds_read_b128 v[188:191], v150 offset:53248
	ds_read_b128 v[206:209], v150 offset:54272
	ds_read_b128 v[210:213], v150 offset:55296
	global_load_lds_dwordx4 v128, s[42:43] offset:128
	s_add_i32 m0, s58, 0xffffff80
	ds_read_b128 v[214:217], v150 offset:56320
	global_load_lds_dwordx4 v132, s[42:43] offset:128
	s_barrier
	s_waitcnt lgkmcnt(0)
	s_setprio 1
	v_mfma_f32_16x16x32_bf16 v[52:55], v[144:147], v[168:171], v[52:55]
	v_mfma_f32_16x16x32_bf16 v[48:51], v[160:163], v[168:171], v[48:51]
	v_mfma_f32_16x16x32_bf16 v[36:39], v[144:147], v[176:179], v[36:39]
	v_mfma_f32_16x16x32_bf16 v[32:35], v[160:163], v[176:179], v[32:35]
	v_mfma_f32_16x16x32_bf16 v[20:23], v[144:147], v[188:191], v[20:23]
	v_mfma_f32_16x16x32_bf16 v[16:19], v[160:163], v[188:191], v[16:19]
	v_mfma_f32_16x16x32_bf16 v[4:7], v[144:147], v[210:213], v[4:7]
	v_mfma_f32_16x16x32_bf16 v[0:3], v[160:163], v[210:213], v[0:3]
	v_mfma_f32_16x16x32_bf16 v[52:55], v[156:159], v[172:175], v[52:55]
	v_mfma_f32_16x16x32_bf16 v[48:51], v[164:167], v[172:175], v[48:51]
	v_mfma_f32_16x16x32_bf16 v[36:39], v[156:159], v[180:183], v[36:39]
	v_mfma_f32_16x16x32_bf16 v[32:35], v[164:167], v[180:183], v[32:35]
	v_mfma_f32_16x16x32_bf16 v[20:23], v[156:159], v[206:209], v[20:23]
	v_mfma_f32_16x16x32_bf16 v[16:19], v[164:167], v[206:209], v[16:19]
	v_mfma_f32_16x16x32_bf16 v[4:7], v[156:159], v[214:217], v[4:7]
	v_mfma_f32_16x16x32_bf16 v[0:3], v[164:167], v[214:217], v[0:3]
	s_setprio 0
	s_barrier
	s_add_i32 s4, s5, s50
	s_mov_b32 m0, s4
	s_add_u32 s0, s40, 0x80080
	s_addc_u32 s1, s41, 0
	global_load_lds_dwordx4 v130, s[0:1]
	s_add_i32 m0, s4, 0x2000
	s_nop 0
	global_load_lds_dwordx4 v134, s[0:1]
	s_add_i32 s68, s68, 2
	s_add_u32 s8, s8, 0x100
	s_addc_u32 s9, s9, 0
	s_add_u32 s66, s66, 0x100
	s_addc_u32 s67, s67, 0
	s_cmp_gt_u32 s68, 29
	s_waitcnt vmcnt(6)
	s_barrier
	s_setprio 1
	v_mfma_f32_16x16x32_bf16 v[60:63], v[218:221], v[168:171], v[60:63]
	v_mfma_f32_16x16x32_bf16 v[56:59], v[226:229], v[168:171], v[56:59]
	v_mfma_f32_16x16x32_bf16 v[44:47], v[218:221], v[176:179], v[44:47]
	v_mfma_f32_16x16x32_bf16 v[40:43], v[226:229], v[176:179], v[40:43]
	v_mfma_f32_16x16x32_bf16 v[28:31], v[218:221], v[188:191], v[28:31]
	v_mfma_f32_16x16x32_bf16 v[24:27], v[226:229], v[188:191], v[24:27]
	v_mfma_f32_16x16x32_bf16 v[12:15], v[218:221], v[210:213], v[12:15]
	v_mfma_f32_16x16x32_bf16 v[8:11], v[226:229], v[210:213], v[8:11]
	v_mfma_f32_16x16x32_bf16 v[60:63], v[222:225], v[172:175], v[60:63]
	v_mfma_f32_16x16x32_bf16 v[56:59], v[230:233], v[172:175], v[56:59]
	v_mfma_f32_16x16x32_bf16 v[44:47], v[222:225], v[180:183], v[44:47]
	v_mfma_f32_16x16x32_bf16 v[40:43], v[230:233], v[180:183], v[40:43]
	v_mfma_f32_16x16x32_bf16 v[28:31], v[222:225], v[206:209], v[28:31]
	v_mfma_f32_16x16x32_bf16 v[24:27], v[230:233], v[206:209], v[24:27]
	v_mfma_f32_16x16x32_bf16 v[12:15], v[222:225], v[214:217], v[12:15]
	v_mfma_f32_16x16x32_bf16 v[8:11], v[230:233], v[214:217], v[8:11]
	s_setprio 0
	s_cbranch_scc0 .Lrot_1668
	s_barrier

;     DI size_t aoff(const Unit& u, size_t tstep) const { return (size_t)u.pm * tstep; }
;     DI size_t boff(const Unit& u, size_t tstep) const { return (size_t)u.pn * tstep; }
;     DI bool next(int i, Unit& u) const { const long L = (long)i * G + c; if (L >= np) return false; u.pm = pmv; u.pn = (int)(L % nN); u.ks = (int)(L / nN); return true; }
;     DI size_t aoff(const Unit& u, size_t) const { return (size_t)u.ks * kbytes; }
;     DI size_t boff(const Unit& u, size_t tstep) const { return (size_t)u.pn * tstep + (size_t)u.ks * kbytes; }
;     DI bool next(int i, Unit& u) const { Unit t; if (!S.next(i / 3, t)) return false; u.pm = t.pm; u.pn = t.pn; u.ks = i % 3; return true; }
;     DI size_t aoff(const Unit& u, size_t tstep) const { return (u.ks < 2 ? offU : offOA) + (size_t)u.pm * tstep; }
; #define PG8_WAIT_V(n) asm volatile("s_waitcnt vmcnt(" #n ")" ::: "memory")
; template <class Epi, class Sched>
; DI void gemm_phase(LAS unsigned char* lds, const Gemm g, const Sched& S, const Epi& E) {
;     ...
;         const bool has_next = S.next(ui + 1, nxt);
;         const char* nA = has_next ? (const char*)g.A + S.aoff(nxt, tstep) : cA; const char* nB = has_next ? (const char*)g.Bt + S.boff(nxt, tstep) : cB;
;         for (int t = 0; t < nt; t += 2) {
;             if constexpr (Epi::HAS_MID) { if (t == E.mid_t(nt)) { int fr3 = fr, fq3 = fq; asm volatile("" : "+v"(fr3), "+v"(fq3)); E.mid(acc, cur, wr, wc, fr3, fq3); } }
;             const bool last = (t == nt - 2);
;             const char* a1 = cA + (size_t)(t + 1) * kstep;
;             const char* a2 = last ? nA : cA + (size_t)(t + 2) * kstep; const char* b2 = last ? nB : cB + (size_t)(t + 2) * kstep;
;             const char* a3 = a2 + kstep; const char* b3 = b2 + kstep;
;             PG8_LDB(B0, 0, 0); PG8_SCHED; PG8_LDA(At, 0, 0); PG8_STAGE(PG8_SA(1, 1), a1 + hstep, voffA);
;             PG8_WAIT_L(8); PG8_BAR; PG8_WAIT_L(0); PG8_MMA(0, 0, At, B0); PG8_BAR; PG8_SCHED;
;             PG8_LDB(B1, 0, 1); PG8_STAGE(PG8_SB(0, 0), b2, voffB);
;             PG8_BAR; PG8_WAIT_L(0); PG8_MMA(0, 1, At, B1); PG8_BAR;
;             PG8_LDA(At, 0, 1); PG8_STAGE(PG8_SA(0, 0), a2, voffA);
;             PG8_BAR; PG8_WAIT_L(0); PG8_MMA(1, 0, At, B0); PG8_BAR; PG8_SCHED;
;             PG8_STAGE(PG8_SB(0, 1), b2 + hstep, voffB);
;             PG8_WAIT_V(6); PG8_BAR; PG8_MMA(1, 1, At, B1); PG8_BAR;
.LBB0_1745:
	s_add_u32 s38, s38, 0x160080
	s_addc_u32 s39, s39, 0
	s_add_u32 s35, s40, 0x100
	v_mov_b32_e32 v0, 0
	s_addc_u32 s67, s41, 0
	s_mov_b32 s68, -2
	s_waitcnt lgkmcnt(0)
	ds_read_b128 v[144:147], v155
	ds_read_b128 v[160:163], v155 offset:1024
	ds_read_b128 v[164:167], v155 offset:2048
	ds_read_b128 v[168:171], v155 offset:3072
	s_add_u32 s0, s38, 0xffea0080
	s_addc_u32 s1, s39, -1
	s_cmpk_eq_i32 s68, 0x54
	s_cselect_b32 s43, s9, s1
	s_cselect_b32 s42, s8, s0
	s_cselect_b32 s41, s11, s67
	s_cselect_b32 s40, s10, s35
	s_add_i32 m0, s52, 0xc000
	ds_read_b128 v[172:175], v156
	ds_read_b128 v[176:179], v156 offset:1024
	ds_read_b128 v[180:183], v156 offset:2048
	ds_read_b128 v[188:191], v156 offset:3072
	ds_read_b128 v[206:209], v156 offset:4096
	ds_read_b128 v[210:213], v156 offset:5120
	ds_read_b128 v[214:217], v156 offset:6144
	global_load_lds_dwordx4 v136, s[38:39]
	s_add_i32 m0, s52, 0xe000
	ds_read_b128 v[218:221], v156 offset:7168
	global_load_lds_dwordx4 v138, s[38:39]
	s_waitcnt lgkmcnt(8)
	s_barrier
	s_waitcnt lgkmcnt(0)
	s_setprio 1
	v_mfma_f32_16x16x32_bf16 v[124:127], v[144:147], v[172:175], 0
	v_mfma_f32_16x16x32_bf16 v[120:123], v[164:167], v[172:175], 0
	v_mfma_f32_16x16x32_bf16 v[108:111], v[144:147], v[180:183], 0
	v_mfma_f32_16x16x32_bf16 v[104:107], v[164:167], v[180:183], 0
	v_mfma_f32_16x16x32_bf16 v[92:95], v[144:147], v[206:209], 0
	v_mfma_f32_16x16x32_bf16 v[88:91], v[164:167], v[206:209], 0
	v_mfma_f32_16x16x32_bf16 v[76:79], v[144:147], v[214:217], 0
	v_mfma_f32_16x16x32_bf16 v[72:75], v[164:167], v[214:217], 0
	v_mfma_f32_16x16x32_bf16 v[124:127], v[160:163], v[176:179], v[124:127]
	v_mfma_f32_16x16x32_bf16 v[120:123], v[168:171], v[176:179], v[120:123]
	v_mfma_f32_16x16x32_bf16 v[108:111], v[160:163], v[188:191], v[108:111]
	v_mfma_f32_16x16x32_bf16 v[104:107], v[168:171], v[188:191], v[104:107]
	v_mfma_f32_16x16x32_bf16 v[92:95], v[160:163], v[210:213], v[92:95]
	v_mfma_f32_16x16x32_bf16 v[88:91], v[168:171], v[210:213], v[88:91]
	v_mfma_f32_16x16x32_bf16 v[76:79], v[160:163], v[218:221], v[76:79]
	v_mfma_f32_16x16x32_bf16 v[72:75], v[168:171], v[218:221], v[72:75]
	s_setprio 0
	s_barrier
	s_add_i32 s0, s61, s51
	s_mov_b32 m0, s0
	ds_read_b128 v[222:225], v157
	ds_read_b128 v[226:229], v157 offset:1024
	ds_read_b128 v[230:233], v157 offset:2048
	global_load_lds_dwordx4 v130, s[40:41]
	s_add_i32 m0, s0, 0x2000
	ds_read_b128 v[234:237], v157 offset:3072
	global_load_lds_dwordx4 v134, s[40:41]
	s_barrier
	s_waitcnt lgkmcnt(0)
	s_setprio 1
	v_mfma_f32_16x16x32_bf16 v[116:119], v[222:225], v[172:175], 0
	v_mfma_f32_16x16x32_bf16 v[112:115], v[230:233], v[172:175], 0
	v_mfma_f32_16x16x32_bf16 v[100:103], v[222:225], v[180:183], 0
	v_mfma_f32_16x16x32_bf16 v[96:99], v[230:233], v[180:183], 0
	v_mfma_f32_16x16x32_bf16 v[84:87], v[222:225], v[206:209], 0
	v_mfma_f32_16x16x32_bf16 v[80:83], v[230:233], v[206:209], 0
	v_mfma_f32_16x16x32_bf16 v[68:71], v[222:225], v[214:217], 0
	v_mfma_f32_16x16x32_bf16 v[64:67], v[230:233], v[214:217], 0
	v_mfma_f32_16x16x32_bf16 v[116:119], v[226:229], v[176:179], v[116:119]
	v_mfma_f32_16x16x32_bf16 v[112:115], v[234:237], v[176:179], v[112:115]
	v_mfma_f32_16x16x32_bf16 v[100:103], v[226:229], v[188:191], v[100:103]
	v_mfma_f32_16x16x32_bf16 v[96:99], v[234:237], v[188:191], v[96:99]
	v_mfma_f32_16x16x32_bf16 v[84:87], v[226:229], v[210:213], v[84:87]
	v_mfma_f32_16x16x32_bf16 v[80:83], v[234:237], v[210:213], v[80:83]
	v_mfma_f32_16x16x32_bf16 v[68:71], v[226:229], v[218:221], v[68:71]
	v_mfma_f32_16x16x32_bf16 v[64:67], v[234:237], v[218:221], v[64:67]
	s_setprio 0
	s_mov_b32 m0, s52
	s_barrier
	ds_read_b128 v[172:175], v156 offset:16384
	ds_read_b128 v[176:179], v156 offset:17408
	ds_read_b128 v[180:183], v156 offset:18432
	ds_read_b128 v[188:191], v156 offset:19456
	ds_read_b128 v[206:209], v156 offset:20480
	ds_read_b128 v[210:213], v156 offset:21504
	ds_read_b128 v[214:217], v156 offset:22528
	global_load_lds_dwordx4 v128, s[42:43]
	s_mov_b32 m0, s53
	ds_read_b128 v[218:221], v156 offset:23552
	global_load_lds_dwordx4 v132, s[42:43]
	s_barrier
	s_waitcnt lgkmcnt(0)
	s_setprio 1
	v_mfma_f32_16x16x32_bf16 v[60:63], v[144:147], v[172:175], 0
	v_mfma_f32_16x16x32_bf16 v[56:59], v[164:167], v[172:175], 0
	v_mfma_f32_16x16x32_bf16 v[44:47], v[144:147], v[180:183], 0
	v_mfma_f32_16x16x32_bf16 v[40:43], v[164:167], v[180:183], 0
	v_mfma_f32_16x16x32_bf16 v[28:31], v[144:147], v[206:209], 0
	v_mfma_f32_16x16x32_bf16 v[24:27], v[164:167], v[206:209], 0
	v_mfma_f32_16x16x32_bf16 v[12:15], v[144:147], v[214:217], 0
	v_mfma_f32_16x16x32_bf16 v[8:11], v[164:167], v[214:217], 0
	v_mfma_f32_16x16x32_bf16 v[60:63], v[160:163], v[176:179], v[60:63]
	v_mfma_f32_16x16x32_bf16 v[56:59], v[168:171], v[176:179], v[56:59]
	v_mfma_f32_16x16x32_bf16 v[44:47], v[160:163], v[188:191], v[44:47]
	v_mfma_f32_16x16x32_bf16 v[40:43], v[168:171], v[188:191], v[40:43]
	v_mfma_f32_16x16x32_bf16 v[28:31], v[160:163], v[210:213], v[28:31]
	v_mfma_f32_16x16x32_bf16 v[24:27], v[168:171], v[210:213], v[24:27]
	v_mfma_f32_16x16x32_bf16 v[12:15], v[160:163], v[218:221], v[12:15]
	v_mfma_f32_16x16x32_bf16 v[8:11], v[168:171], v[218:221], v[8:11]
	s_setprio 0
	s_barrier
	s_add_i32 s4, s62, s51
	s_mov_b32 m0, s4
	s_add_u32 s0, s40, 0x160000
	s_addc_u32 s1, s41, 0
	global_load_lds_dwordx4 v130, s[0:1]
	s_add_i32 m0, s4, 0x2000
	s_nop 0
	global_load_lds_dwordx4 v134, s[0:1]
	s_waitcnt vmcnt(6)
	s_barrier
; #define PG8_STAGE(bufoff, gbase, voff) do { _Pragma("unroll") for (int _i = 0; _i < 2; ++_i) \
;         __builtin_amdgcn_global_load_lds((const unsigned*)((const char*)(gbase) + (voff)[_i]), (LAS unsigned*)(lds + (bufoff) + ldsw + _i * 8192), 16, 0, 0); } while (0)
; #define PG8_LDA(dst, b, h) do { _Pragma("unroll") for (int m = 0; m < 4; ++m) _Pragma("unroll") for (int k = 0; k < 2; ++k) dst[m][k] = *(const LAS bf16x8*)(lds + PG8_SA(b, h) + aoff + m * 2048 + k * 1024); } while (0)
; #define PG8_LDB(dst, b, h) do { _Pragma("unroll") for (int n = 0; n < 2; ++n) _Pragma("unroll") for (int k = 0; k < 2; ++k) dst[n][k] = *(const LAS bf16x8*)(lds + PG8_SB(b, h) + boff + n * 2048 + k * 1024); } while (0)
; #define PG8_MMA(ai, bj, At, Bt) do { __builtin_amdgcn_s_setprio(1); _Pragma("unroll") for (int m = 0; m < 4; ++m) _Pragma("unroll") for (int n = 0; n < 2; ++n) _Pragma("unroll") for (int k = 0; k < 2; ++k) \
;         acc[ai][bj][m][n] = __builtin_amdgcn_mfma_f32_16x16x32_bf16(Bt[n][k], At[m][k], acc[ai][bj][m][n], 0, 0, 0); __builtin_amdgcn_s_setprio(0); } while (0)
; #define PG8_WAIT_V(n) asm volatile("s_waitcnt vmcnt(" #n ")" ::: "memory")
; #define PG8_WAIT_L(n) asm volatile("s_waitcnt lgkmcnt(" #n ")" ::: "memory")
; #define PG8_BAR __builtin_amdgcn_s_barrier()
; #define PG8_SCHED __builtin_amdgcn_sched_barrier(0)
; template <class Epi, class Sched>
; DI void gemm_phase(LAS unsigned char* lds, const Gemm g, const Sched& S, const Epi& E) {
;     ...
;             PG8_WAIT_V(6); PG8_BAR; PG8_MMA(1, 1, At, B1); PG8_BAR;
;             PG8_LDB(B0, 1, 0); PG8_SCHED; PG8_LDA(At, 1, 0); PG8_STAGE(PG8_SA(0, 1), a2 + hstep, voffA);
;             PG8_WAIT_L(8); PG8_BAR; PG8_WAIT_L(0); PG8_MMA(0, 0, At, B0); PG8_BAR; PG8_SCHED;
;             PG8_LDB(B1, 1, 1); PG8_STAGE(PG8_SB(1, 0), b3, voffB);
	s_setprio 1
	v_mfma_f32_16x16x32_bf16 v[52:55], v[222:225], v[172:175], 0
	v_mfma_f32_16x16x32_bf16 v[48:51], v[230:233], v[172:175], 0
	v_mfma_f32_16x16x32_bf16 v[36:39], v[222:225], v[180:183], 0
	v_mfma_f32_16x16x32_bf16 v[32:35], v[230:233], v[180:183], 0
	v_mfma_f32_16x16x32_bf16 v[20:23], v[222:225], v[206:209], 0
	v_mfma_f32_16x16x32_bf16 v[16:19], v[230:233], v[206:209], 0
	v_mfma_f32_16x16x32_bf16 v[4:7], v[222:225], v[214:217], 0
	v_mfma_f32_16x16x32_bf16 v[0:3], v[230:233], v[214:217], 0
	v_mfma_f32_16x16x32_bf16 v[52:55], v[226:229], v[176:179], v[52:55]
	v_mfma_f32_16x16x32_bf16 v[48:51], v[234:237], v[176:179], v[48:51]
	v_mfma_f32_16x16x32_bf16 v[36:39], v[226:229], v[188:191], v[36:39]
	v_mfma_f32_16x16x32_bf16 v[32:35], v[234:237], v[188:191], v[32:35]
	v_mfma_f32_16x16x32_bf16 v[20:23], v[226:229], v[210:213], v[20:23]
	v_mfma_f32_16x16x32_bf16 v[16:19], v[234:237], v[210:213], v[16:19]
	v_mfma_f32_16x16x32_bf16 v[4:7], v[226:229], v[218:221], v[4:7]
	v_mfma_f32_16x16x32_bf16 v[0:3], v[234:237], v[218:221], v[0:3]
	s_setprio 0
	s_add_i32 s4, 0, 0x18000
	v_add_u32_e32 v202, s4, v154
	s_barrier
	ds_read_b128 v[144:147], v202
	ds_read_b128 v[160:163], v202 offset:1024
	ds_read_b128 v[164:167], v202 offset:2048
	ds_read_b128 v[168:171], v202 offset:3072
	s_add_u32 s0, s42, 0x160000
	s_addc_u32 s1, s43, 0
	s_mov_b32 m0, s54
	ds_read_b128 v[172:175], v156 offset:32768
	ds_read_b128 v[176:179], v156 offset:33792
	ds_read_b128 v[180:183], v156 offset:34816
	ds_read_b128 v[188:191], v156 offset:35840
	ds_read_b128 v[206:209], v156 offset:36864
	ds_read_b128 v[210:213], v156 offset:37888
	ds_read_b128 v[214:217], v156 offset:38912
	global_load_lds_dwordx4 v128, s[0:1]
	s_mov_b32 m0, s55
	ds_read_b128 v[218:221], v156 offset:39936
	global_load_lds_dwordx4 v132, s[0:1]
	s_waitcnt lgkmcnt(8)
	s_barrier
	s_waitcnt lgkmcnt(0)
	s_setprio 1
	v_mfma_f32_16x16x32_bf16 v[124:127], v[144:147], v[172:175], v[124:127]
	v_mfma_f32_16x16x32_bf16 v[120:123], v[164:167], v[172:175], v[120:123]
	v_mfma_f32_16x16x32_bf16 v[108:111], v[144:147], v[180:183], v[108:111]
	v_mfma_f32_16x16x32_bf16 v[104:107], v[164:167], v[180:183], v[104:107]
	v_mfma_f32_16x16x32_bf16 v[92:95], v[144:147], v[206:209], v[92:95]
	v_mfma_f32_16x16x32_bf16 v[88:91], v[164:167], v[206:209], v[88:91]
	v_mfma_f32_16x16x32_bf16 v[76:79], v[144:147], v[214:217], v[76:79]
	v_mfma_f32_16x16x32_bf16 v[72:75], v[164:167], v[214:217], v[72:75]
	v_mfma_f32_16x16x32_bf16 v[124:127], v[160:163], v[176:179], v[124:127]
	v_mfma_f32_16x16x32_bf16 v[120:123], v[168:171], v[176:179], v[120:123]
	v_mfma_f32_16x16x32_bf16 v[108:111], v[160:163], v[188:191], v[108:111]
	v_mfma_f32_16x16x32_bf16 v[104:107], v[168:171], v[188:191], v[104:107]
	v_mfma_f32_16x16x32_bf16 v[92:95], v[160:163], v[210:213], v[92:95]
	v_mfma_f32_16x16x32_bf16 v[88:91], v[168:171], v[210:213], v[88:91]
	v_mfma_f32_16x16x32_bf16 v[76:79], v[160:163], v[218:221], v[76:79]
	v_mfma_f32_16x16x32_bf16 v[72:75], v[168:171], v[218:221], v[72:75]
	s_setprio 0
	s_barrier
	s_add_i32 s5, 0, 0x1c000
	s_add_i32 s0, s4, s51
	v_add_u32_e32 v203, s5, v154
	s_add_i32 m0, s0, 0xffffff80
	ds_read_b128 v[222:225], v203
	ds_read_b128 v[226:229], v203 offset:1024
	ds_read_b128 v[230:233], v203 offset:2048
	global_load_lds_dwordx4 v130, s[40:41] offset:128
	s_add_i32 m0, s0, 0x1f80
	ds_read_b128 v[234:237], v203 offset:3072
	global_load_lds_dwordx4 v134, s[40:41] offset:128
	s_barrier
; #define PG8_STAGE(bufoff, gbase, voff) do { _Pragma("unroll") for (int _i = 0; _i < 2; ++_i) \
;         __builtin_amdgcn_global_load_lds((const unsigned*)((const char*)(gbase) + (voff)[_i]), (LAS unsigned*)(lds + (bufoff) + ldsw + _i * 8192), 16, 0, 0); } while (0)
; #define PG8_LDA(dst, b, h) do { _Pragma("unroll") for (int m = 0; m < 4; ++m) _Pragma("unroll") for (int k = 0; k < 2; ++k) dst[m][k] = *(const LAS bf16x8*)(lds + PG8_SA(b, h) + aoff + m * 2048 + k * 1024); } while (0)
; #define PG8_MMA(ai, bj, At, Bt) do { __builtin_amdgcn_s_setprio(1); _Pragma("unroll") for (int m = 0; m < 4; ++m) _Pragma("unroll") for (int n = 0; n < 2; ++n) _Pragma("unroll") for (int k = 0; k < 2; ++k) \
;         acc[ai][bj][m][n] = __builtin_amdgcn_mfma_f32_16x16x32_bf16(Bt[n][k], At[m][k], acc[ai][bj][m][n], 0, 0, 0); __builtin_amdgcn_s_setprio(0); } while (0)
; #define PG8_WAIT_V(n) asm volatile("s_waitcnt vmcnt(" #n ")" ::: "memory")
; #define PG8_WAIT_L(n) asm volatile("s_waitcnt lgkmcnt(" #n ")" ::: "memory")
; #define PG8_BAR __builtin_amdgcn_s_barrier()
; #define PG8_SCHED __builtin_amdgcn_sched_barrier(0)
; template <class Epi, class Sched>
; DI void gemm_phase(LAS unsigned char* lds, const Gemm g, const Sched& S, const Epi& E) {
;     ...
;             PG8_BAR; PG8_WAIT_L(0); PG8_MMA(0, 1, At, B1); PG8_BAR;
;             PG8_LDA(At, 1, 1); PG8_STAGE(PG8_SA(1, 0), a3, voffA);
;             PG8_BAR; PG8_WAIT_L(0); PG8_MMA(1, 0, At, B0); PG8_BAR; PG8_SCHED;
;             PG8_STAGE(PG8_SB(1, 1), b3 + hstep, voffB);
;             PG8_WAIT_V(6); PG8_BAR; PG8_MMA(1, 1, At, B1); PG8_BAR;
;         }
	s_waitcnt lgkmcnt(0)
	s_setprio 1
	v_mfma_f32_16x16x32_bf16 v[116:119], v[222:225], v[172:175], v[116:119]
	v_mfma_f32_16x16x32_bf16 v[112:115], v[230:233], v[172:175], v[112:115]
	v_mfma_f32_16x16x32_bf16 v[100:103], v[222:225], v[180:183], v[100:103]
	v_mfma_f32_16x16x32_bf16 v[96:99], v[230:233], v[180:183], v[96:99]
	v_mfma_f32_16x16x32_bf16 v[84:87], v[222:225], v[206:209], v[84:87]
	v_mfma_f32_16x16x32_bf16 v[80:83], v[230:233], v[206:209], v[80:83]
	v_mfma_f32_16x16x32_bf16 v[68:71], v[222:225], v[214:217], v[68:71]
	v_mfma_f32_16x16x32_bf16 v[64:67], v[230:233], v[214:217], v[64:67]
	v_mfma_f32_16x16x32_bf16 v[116:119], v[226:229], v[176:179], v[116:119]
	v_mfma_f32_16x16x32_bf16 v[112:115], v[234:237], v[176:179], v[112:115]
	v_mfma_f32_16x16x32_bf16 v[100:103], v[226:229], v[188:191], v[100:103]
	v_mfma_f32_16x16x32_bf16 v[96:99], v[234:237], v[188:191], v[96:99]
	v_mfma_f32_16x16x32_bf16 v[84:87], v[226:229], v[210:213], v[84:87]
	v_mfma_f32_16x16x32_bf16 v[80:83], v[234:237], v[210:213], v[80:83]
	v_mfma_f32_16x16x32_bf16 v[68:71], v[226:229], v[218:221], v[68:71]
	v_mfma_f32_16x16x32_bf16 v[64:67], v[234:237], v[218:221], v[64:67]
	s_setprio 0
	s_add_i32 m0, s59, 0xffffff80
	s_barrier
	ds_read_b128 v[172:175], v156 offset:49152
	ds_read_b128 v[176:179], v156 offset:50176
	ds_read_b128 v[180:183], v156 offset:51200
	ds_read_b128 v[188:191], v156 offset:52224
	ds_read_b128 v[206:209], v156 offset:53248
	ds_read_b128 v[210:213], v156 offset:54272
	ds_read_b128 v[214:217], v156 offset:55296
	global_load_lds_dwordx4 v128, s[42:43] offset:128
	s_add_i32 m0, s60, 0xffffff80
	ds_read_b128 v[218:221], v156 offset:56320
	global_load_lds_dwordx4 v132, s[42:43] offset:128
	s_barrier
	s_waitcnt lgkmcnt(0)
	s_setprio 1
	v_mfma_f32_16x16x32_bf16 v[60:63], v[144:147], v[172:175], v[60:63]
	v_mfma_f32_16x16x32_bf16 v[56:59], v[164:167], v[172:175], v[56:59]
	v_mfma_f32_16x16x32_bf16 v[44:47], v[144:147], v[180:183], v[44:47]
	v_mfma_f32_16x16x32_bf16 v[40:43], v[164:167], v[180:183], v[40:43]
	v_mfma_f32_16x16x32_bf16 v[28:31], v[144:147], v[206:209], v[28:31]
	v_mfma_f32_16x16x32_bf16 v[24:27], v[164:167], v[206:209], v[24:27]
	v_mfma_f32_16x16x32_bf16 v[12:15], v[144:147], v[214:217], v[12:15]
	v_mfma_f32_16x16x32_bf16 v[8:11], v[164:167], v[214:217], v[8:11]
	v_mfma_f32_16x16x32_bf16 v[60:63], v[160:163], v[176:179], v[60:63]
	v_mfma_f32_16x16x32_bf16 v[56:59], v[168:171], v[176:179], v[56:59]
	v_mfma_f32_16x16x32_bf16 v[44:47], v[160:163], v[188:191], v[44:47]
	v_mfma_f32_16x16x32_bf16 v[40:43], v[168:171], v[188:191], v[40:43]
	v_mfma_f32_16x16x32_bf16 v[28:31], v[160:163], v[210:213], v[28:31]
	v_mfma_f32_16x16x32_bf16 v[24:27], v[168:171], v[210:213], v[24:27]
	v_mfma_f32_16x16x32_bf16 v[12:15], v[160:163], v[218:221], v[12:15]
	v_mfma_f32_16x16x32_bf16 v[8:11], v[168:171], v[218:221], v[8:11]
	s_setprio 0
	s_barrier
	s_add_i32 s4, s5, s51
	s_mov_b32 m0, s4
	s_add_u32 s0, s40, 0x160080
	s_addc_u32 s1, s41, 0
	global_load_lds_dwordx4 v130, s[0:1]
	s_add_i32 m0, s4, 0x2000
	s_nop 0
	global_load_lds_dwordx4 v134, s[0:1]
	s_waitcnt vmcnt(6)
	s_barrier
	s_setprio 1
	v_mfma_f32_16x16x32_bf16 v[52:55], v[222:225], v[172:175], v[52:55]
	v_mfma_f32_16x16x32_bf16 v[48:51], v[230:233], v[172:175], v[48:51]
	v_mfma_f32_16x16x32_bf16 v[36:39], v[222:225], v[180:183], v[36:39]
	v_mfma_f32_16x16x32_bf16 v[32:35], v[230:233], v[180:183], v[32:35]
	v_mfma_f32_16x16x32_bf16 v[20:23], v[222:225], v[206:209], v[20:23]
	v_mfma_f32_16x16x32_bf16 v[16:19], v[230:233], v[206:209], v[16:19]
	v_mfma_f32_16x16x32_bf16 v[4:7], v[222:225], v[214:217], v[4:7]
	v_mfma_f32_16x16x32_bf16 v[0:3], v[230:233], v[214:217], v[0:3]
	v_mfma_f32_16x16x32_bf16 v[52:55], v[226:229], v[176:179], v[52:55]
	v_mfma_f32_16x16x32_bf16 v[48:51], v[234:237], v[176:179], v[48:51]
	v_mfma_f32_16x16x32_bf16 v[36:39], v[226:229], v[188:191], v[36:39]
	v_mfma_f32_16x16x32_bf16 v[32:35], v[234:237], v[188:191], v[32:35]
	v_mfma_f32_16x16x32_bf16 v[20:23], v[226:229], v[210:213], v[20:23]
	v_mfma_f32_16x16x32_bf16 v[16:19], v[234:237], v[210:213], v[16:19]
	v_mfma_f32_16x16x32_bf16 v[4:7], v[226:229], v[218:221], v[4:7]
	v_mfma_f32_16x16x32_bf16 v[0:3], v[234:237], v[218:221], v[0:3]
	s_setprio 0
	s_add_i32 s68, s68, 2
	s_add_u32 s38, s38, 0x100
	s_addc_u32 s39, s39, 0
	s_add_u32 s35, s35, 0x100
	s_addc_u32 s67, s67, 0
	s_cmpk_gt_u32 s68, 0x55
	s_cbranch_scc0 .Lrot_1746
	s_barrier
	s_branch .Lpeel_done_1746

; #define PG8_STAGE(bufoff, gbase, voff) do { _Pragma("unroll") for (int _i = 0; _i < 2; ++_i) \
;         __builtin_amdgcn_global_load_lds((const unsigned*)((const char*)(gbase) + (voff)[_i]), (LAS unsigned*)(lds + (bufoff) + ldsw + _i * 8192), 16, 0, 0); } while (0)
; #define PG8_LDA(dst, b, h) do { _Pragma("unroll") for (int m = 0; m < 4; ++m) _Pragma("unroll") for (int k = 0; k < 2; ++k) dst[m][k] = *(const LAS bf16x8*)(lds + PG8_SA(b, h) + aoff + m * 2048 + k * 1024); } while (0)
; #define PG8_LDB(dst, b, h) do { _Pragma("unroll") for (int n = 0; n < 2; ++n) _Pragma("unroll") for (int k = 0; k < 2; ++k) dst[n][k] = *(const LAS bf16x8*)(lds + PG8_SB(b, h) + boff + n * 2048 + k * 1024); } while (0)
; #define PG8_MMA(ai, bj, At, Bt) do { __builtin_amdgcn_s_setprio(1); _Pragma("unroll") for (int m = 0; m < 4; ++m) _Pragma("unroll") for (int n = 0; n < 2; ++n) _Pragma("unroll") for (int k = 0; k < 2; ++k) \
;         acc[ai][bj][m][n] = __builtin_amdgcn_mfma_f32_16x16x32_bf16(Bt[n][k], At[m][k], acc[ai][bj][m][n], 0, 0, 0); __builtin_amdgcn_s_setprio(0); } while (0)
; #define PG8_WAIT_V(n) asm volatile("s_waitcnt vmcnt(" #n ")" ::: "memory")
; #define PG8_WAIT_L(n) asm volatile("s_waitcnt lgkmcnt(" #n ")" ::: "memory")
; #define PG8_BAR __builtin_amdgcn_s_barrier()
; #define PG8_SCHED __builtin_amdgcn_sched_barrier(0)
; template <class Epi, class Sched>
; DI void gemm_phase(LAS unsigned char* lds, const Gemm g, const Sched& S, const Epi& E) {
;     ...
;             PG8_LDB(B0, 0, 0); PG8_SCHED; PG8_LDA(At, 0, 0); PG8_STAGE(PG8_SA(1, 1), a1 + hstep, voffA);
;             PG8_WAIT_L(8); PG8_BAR; PG8_WAIT_L(0); PG8_MMA(0, 0, At, B0); PG8_BAR; PG8_SCHED;
;             PG8_LDB(B1, 0, 1); PG8_STAGE(PG8_SB(0, 0), b2, voffB);
;             PG8_BAR; PG8_WAIT_L(0); PG8_MMA(0, 1, At, B1); PG8_BAR;
;             PG8_LDA(At, 0, 1); PG8_STAGE(PG8_SA(0, 0), a2, voffA);
;             PG8_BAR; PG8_WAIT_L(0); PG8_MMA(1, 0, At, B0); PG8_BAR; PG8_SCHED;
;             PG8_STAGE(PG8_SB(0, 1), b2 + hstep, voffB);
;             PG8_WAIT_V(6); PG8_BAR; PG8_MMA(1, 1, At, B1); PG8_BAR;
.LBB0_1746:
	ds_read_b128 v[144:147], v155
	ds_read_b128 v[160:163], v155 offset:1024
	ds_read_b128 v[164:167], v155 offset:2048
	ds_read_b128 v[168:171], v155 offset:3072
	s_add_u32 s0, s38, 0xffea0080
	s_addc_u32 s1, s39, -1
	s_cmpk_eq_i32 s68, 0x54
	s_cselect_b32 s43, s9, s1
	s_cselect_b32 s42, s8, s0
	s_cselect_b32 s41, s11, s67
	s_cselect_b32 s40, s10, s35
	s_add_i32 m0, s52, 0xc000
	ds_read_b128 v[172:175], v156
	ds_read_b128 v[176:179], v156 offset:1024
	ds_read_b128 v[180:183], v156 offset:2048
	ds_read_b128 v[188:191], v156 offset:3072
	ds_read_b128 v[206:209], v156 offset:4096
	ds_read_b128 v[210:213], v156 offset:5120
	ds_read_b128 v[214:217], v156 offset:6144
	global_load_lds_dwordx4 v136, s[38:39]
	s_add_i32 m0, s52, 0xe000
	ds_read_b128 v[218:221], v156 offset:7168
	global_load_lds_dwordx4 v138, s[38:39]
	s_waitcnt lgkmcnt(8)
	s_barrier
	s_waitcnt lgkmcnt(0)
	s_setprio 1
	v_mfma_f32_16x16x32_bf16 v[124:127], v[144:147], v[172:175], v[124:127]
	v_mfma_f32_16x16x32_bf16 v[120:123], v[164:167], v[172:175], v[120:123]
	v_mfma_f32_16x16x32_bf16 v[108:111], v[144:147], v[180:183], v[108:111]
	v_mfma_f32_16x16x32_bf16 v[104:107], v[164:167], v[180:183], v[104:107]
	v_mfma_f32_16x16x32_bf16 v[92:95], v[144:147], v[206:209], v[92:95]
	v_mfma_f32_16x16x32_bf16 v[88:91], v[164:167], v[206:209], v[88:91]
	v_mfma_f32_16x16x32_bf16 v[76:79], v[144:147], v[214:217], v[76:79]
	v_mfma_f32_16x16x32_bf16 v[72:75], v[164:167], v[214:217], v[72:75]
	v_mfma_f32_16x16x32_bf16 v[124:127], v[160:163], v[176:179], v[124:127]
	v_mfma_f32_16x16x32_bf16 v[120:123], v[168:171], v[176:179], v[120:123]
	v_mfma_f32_16x16x32_bf16 v[108:111], v[160:163], v[188:191], v[108:111]
	v_mfma_f32_16x16x32_bf16 v[104:107], v[168:171], v[188:191], v[104:107]
	v_mfma_f32_16x16x32_bf16 v[92:95], v[160:163], v[210:213], v[92:95]
	v_mfma_f32_16x16x32_bf16 v[88:91], v[168:171], v[210:213], v[88:91]
	v_mfma_f32_16x16x32_bf16 v[76:79], v[160:163], v[218:221], v[76:79]
	v_mfma_f32_16x16x32_bf16 v[72:75], v[168:171], v[218:221], v[72:75]
	s_setprio 0
	s_barrier
	s_add_i32 s0, s61, s51
	s_mov_b32 m0, s0
	ds_read_b128 v[222:225], v157
	ds_read_b128 v[226:229], v157 offset:1024
	ds_read_b128 v[230:233], v157 offset:2048
	global_load_lds_dwordx4 v130, s[40:41]
	s_add_i32 m0, s0, 0x2000
	ds_read_b128 v[234:237], v157 offset:3072
	global_load_lds_dwordx4 v134, s[40:41]
	s_barrier
	s_waitcnt lgkmcnt(0)
	s_setprio 1
	v_mfma_f32_16x16x32_bf16 v[116:119], v[222:225], v[172:175], v[116:119]
	v_mfma_f32_16x16x32_bf16 v[112:115], v[230:233], v[172:175], v[112:115]
	v_mfma_f32_16x16x32_bf16 v[100:103], v[222:225], v[180:183], v[100:103]
	v_mfma_f32_16x16x32_bf16 v[96:99], v[230:233], v[180:183], v[96:99]
	v_mfma_f32_16x16x32_bf16 v[84:87], v[222:225], v[206:209], v[84:87]
	v_mfma_f32_16x16x32_bf16 v[80:83], v[230:233], v[206:209], v[80:83]
	v_mfma_f32_16x16x32_bf16 v[68:71], v[222:225], v[214:217], v[68:71]
	v_mfma_f32_16x16x32_bf16 v[64:67], v[230:233], v[214:217], v[64:67]
	v_mfma_f32_16x16x32_bf16 v[116:119], v[226:229], v[176:179], v[116:119]
	v_mfma_f32_16x16x32_bf16 v[112:115], v[234:237], v[176:179], v[112:115]
	v_mfma_f32_16x16x32_bf16 v[100:103], v[226:229], v[188:191], v[100:103]
	v_mfma_f32_16x16x32_bf16 v[96:99], v[234:237], v[188:191], v[96:99]
	v_mfma_f32_16x16x32_bf16 v[84:87], v[226:229], v[210:213], v[84:87]
	v_mfma_f32_16x16x32_bf16 v[80:83], v[234:237], v[210:213], v[80:83]
	v_mfma_f32_16x16x32_bf16 v[68:71], v[226:229], v[218:221], v[68:71]
	v_mfma_f32_16x16x32_bf16 v[64:67], v[234:237], v[218:221], v[64:67]
	s_setprio 0
	s_mov_b32 m0, s52
	s_barrier
	ds_read_b128 v[172:175], v156 offset:16384
	ds_read_b128 v[176:179], v156 offset:17408
	ds_read_b128 v[180:183], v156 offset:18432
	ds_read_b128 v[188:191], v156 offset:19456
	ds_read_b128 v[206:209], v156 offset:20480
	ds_read_b128 v[210:213], v156 offset:21504
	ds_read_b128 v[214:217], v156 offset:22528
	global_load_lds_dwordx4 v128, s[42:43]
	s_mov_b32 m0, s53
	ds_read_b128 v[218:221], v156 offset:23552
	global_load_lds_dwordx4 v132, s[42:43]
	s_barrier
	s_waitcnt lgkmcnt(0)
	s_setprio 1
	v_mfma_f32_16x16x32_bf16 v[60:63], v[144:147], v[172:175], v[60:63]
	v_mfma_f32_16x16x32_bf16 v[56:59], v[164:167], v[172:175], v[56:59]
	v_mfma_f32_16x16x32_bf16 v[44:47], v[144:147], v[180:183], v[44:47]
	v_mfma_f32_16x16x32_bf16 v[40:43], v[164:167], v[180:183], v[40:43]
	v_mfma_f32_16x16x32_bf16 v[28:31], v[144:147], v[206:209], v[28:31]
	v_mfma_f32_16x16x32_bf16 v[24:27], v[164:167], v[206:209], v[24:27]
	v_mfma_f32_16x16x32_bf16 v[12:15], v[144:147], v[214:217], v[12:15]
	v_mfma_f32_16x16x32_bf16 v[8:11], v[164:167], v[214:217], v[8:11]
	v_mfma_f32_16x16x32_bf16 v[60:63], v[160:163], v[176:179], v[60:63]
	v_mfma_f32_16x16x32_bf16 v[56:59], v[168:171], v[176:179], v[56:59]
	v_mfma_f32_16x16x32_bf16 v[44:47], v[160:163], v[188:191], v[44:47]
	v_mfma_f32_16x16x32_bf16 v[40:43], v[168:171], v[188:191], v[40:43]
	v_mfma_f32_16x16x32_bf16 v[28:31], v[160:163], v[210:213], v[28:31]
	v_mfma_f32_16x16x32_bf16 v[24:27], v[168:171], v[210:213], v[24:27]
	v_mfma_f32_16x16x32_bf16 v[12:15], v[160:163], v[218:221], v[12:15]
	v_mfma_f32_16x16x32_bf16 v[8:11], v[168:171], v[218:221], v[8:11]
	s_setprio 0
	s_barrier
	s_add_i32 s4, s62, s51
	s_mov_b32 m0, s4
	s_add_u32 s0, s40, 0x160000
	s_addc_u32 s1, s41, 0
	global_load_lds_dwordx4 v130, s[0:1]
	s_add_i32 m0, s4, 0x2000
	s_nop 0
	global_load_lds_dwordx4 v134, s[0:1]
	s_waitcnt vmcnt(6)
	s_barrier
; #define PG8_STAGE(bufoff, gbase, voff) do { _Pragma("unroll") for (int _i = 0; _i < 2; ++_i) \
;         __builtin_amdgcn_global_load_lds((const unsigned*)((const char*)(gbase) + (voff)[_i]), (LAS unsigned*)(lds + (bufoff) + ldsw + _i * 8192), 16, 0, 0); } while (0)
; #define PG8_LDA(dst, b, h) do { _Pragma("unroll") for (int m = 0; m < 4; ++m) _Pragma("unroll") for (int k = 0; k < 2; ++k) dst[m][k] = *(const LAS bf16x8*)(lds + PG8_SA(b, h) + aoff + m * 2048 + k * 1024); } while (0)
; #define PG8_LDB(dst, b, h) do { _Pragma("unroll") for (int n = 0; n < 2; ++n) _Pragma("unroll") for (int k = 0; k < 2; ++k) dst[n][k] = *(const LAS bf16x8*)(lds + PG8_SB(b, h) + boff + n * 2048 + k * 1024); } while (0)
; #define PG8_MMA(ai, bj, At, Bt) do { __builtin_amdgcn_s_setprio(1); _Pragma("unroll") for (int m = 0; m < 4; ++m) _Pragma("unroll") for (int n = 0; n < 2; ++n) _Pragma("unroll") for (int k = 0; k < 2; ++k) \
;         acc[ai][bj][m][n] = __builtin_amdgcn_mfma_f32_16x16x32_bf16(Bt[n][k], At[m][k], acc[ai][bj][m][n], 0, 0, 0); __builtin_amdgcn_s_setprio(0); } while (0)
; #define PG8_WAIT_V(n) asm volatile("s_waitcnt vmcnt(" #n ")" ::: "memory")
; #define PG8_WAIT_L(n) asm volatile("s_waitcnt lgkmcnt(" #n ")" ::: "memory")
; #define PG8_BAR __builtin_amdgcn_s_barrier()
; #define PG8_SCHED __builtin_amdgcn_sched_barrier(0)
; template <class Epi, class Sched>
; DI void gemm_phase(LAS unsigned char* lds, const Gemm g, const Sched& S, const Epi& E) {
;     ...
;             PG8_WAIT_V(6); PG8_BAR; PG8_MMA(1, 1, At, B1); PG8_BAR;
;             PG8_LDB(B0, 1, 0); PG8_SCHED; PG8_LDA(At, 1, 0); PG8_STAGE(PG8_SA(0, 1), a2 + hstep, voffA);
;             PG8_WAIT_L(8); PG8_BAR; PG8_WAIT_L(0); PG8_MMA(0, 0, At, B0); PG8_BAR; PG8_SCHED;
;             PG8_LDB(B1, 1, 1); PG8_STAGE(PG8_SB(1, 0), b3, voffB);
	s_setprio 1
	v_mfma_f32_16x16x32_bf16 v[52:55], v[222:225], v[172:175], v[52:55]
	v_mfma_f32_16x16x32_bf16 v[48:51], v[230:233], v[172:175], v[48:51]
	v_mfma_f32_16x16x32_bf16 v[36:39], v[222:225], v[180:183], v[36:39]
	v_mfma_f32_16x16x32_bf16 v[32:35], v[230:233], v[180:183], v[32:35]
	v_mfma_f32_16x16x32_bf16 v[20:23], v[222:225], v[206:209], v[20:23]
	v_mfma_f32_16x16x32_bf16 v[16:19], v[230:233], v[206:209], v[16:19]
	v_mfma_f32_16x16x32_bf16 v[4:7], v[222:225], v[214:217], v[4:7]
	v_mfma_f32_16x16x32_bf16 v[0:3], v[230:233], v[214:217], v[0:3]
	v_mfma_f32_16x16x32_bf16 v[52:55], v[226:229], v[176:179], v[52:55]
	v_mfma_f32_16x16x32_bf16 v[48:51], v[234:237], v[176:179], v[48:51]
	v_mfma_f32_16x16x32_bf16 v[36:39], v[226:229], v[188:191], v[36:39]
	v_mfma_f32_16x16x32_bf16 v[32:35], v[234:237], v[188:191], v[32:35]
	v_mfma_f32_16x16x32_bf16 v[20:23], v[226:229], v[210:213], v[20:23]
	v_mfma_f32_16x16x32_bf16 v[16:19], v[234:237], v[210:213], v[16:19]
	v_mfma_f32_16x16x32_bf16 v[4:7], v[226:229], v[218:221], v[4:7]
	v_mfma_f32_16x16x32_bf16 v[0:3], v[234:237], v[218:221], v[0:3]
	s_setprio 0
	s_add_i32 s4, 0, 0x18000
	s_barrier
	ds_read_b128 v[144:147], v202
	ds_read_b128 v[160:163], v202 offset:1024
	ds_read_b128 v[164:167], v202 offset:2048
	ds_read_b128 v[168:171], v202 offset:3072
	s_add_u32 s0, s42, 0x160000
	s_addc_u32 s1, s43, 0
	s_mov_b32 m0, s54
	ds_read_b128 v[172:175], v156 offset:32768
	ds_read_b128 v[176:179], v156 offset:33792
	ds_read_b128 v[180:183], v156 offset:34816
	ds_read_b128 v[188:191], v156 offset:35840
	ds_read_b128 v[206:209], v156 offset:36864
	ds_read_b128 v[210:213], v156 offset:37888
	ds_read_b128 v[214:217], v156 offset:38912
	global_load_lds_dwordx4 v128, s[0:1]
	s_mov_b32 m0, s55
	ds_read_b128 v[218:221], v156 offset:39936
	global_load_lds_dwordx4 v132, s[0:1]
	s_waitcnt lgkmcnt(8)
	s_barrier
	s_waitcnt lgkmcnt(0)
	s_setprio 1
	v_mfma_f32_16x16x32_bf16 v[124:127], v[144:147], v[172:175], v[124:127]
	v_mfma_f32_16x16x32_bf16 v[120:123], v[164:167], v[172:175], v[120:123]
	v_mfma_f32_16x16x32_bf16 v[108:111], v[144:147], v[180:183], v[108:111]
	v_mfma_f32_16x16x32_bf16 v[104:107], v[164:167], v[180:183], v[104:107]
	v_mfma_f32_16x16x32_bf16 v[92:95], v[144:147], v[206:209], v[92:95]
	v_mfma_f32_16x16x32_bf16 v[88:91], v[164:167], v[206:209], v[88:91]
	v_mfma_f32_16x16x32_bf16 v[76:79], v[144:147], v[214:217], v[76:79]
	v_mfma_f32_16x16x32_bf16 v[72:75], v[164:167], v[214:217], v[72:75]
	v_mfma_f32_16x16x32_bf16 v[124:127], v[160:163], v[176:179], v[124:127]
	v_mfma_f32_16x16x32_bf16 v[120:123], v[168:171], v[176:179], v[120:123]
	v_mfma_f32_16x16x32_bf16 v[108:111], v[160:163], v[188:191], v[108:111]
	v_mfma_f32_16x16x32_bf16 v[104:107], v[168:171], v[188:191], v[104:107]
	v_mfma_f32_16x16x32_bf16 v[92:95], v[160:163], v[210:213], v[92:95]
	v_mfma_f32_16x16x32_bf16 v[88:91], v[168:171], v[210:213], v[88:91]
	v_mfma_f32_16x16x32_bf16 v[76:79], v[160:163], v[218:221], v[76:79]
	v_mfma_f32_16x16x32_bf16 v[72:75], v[168:171], v[218:221], v[72:75]
	s_setprio 0
	s_barrier
	s_add_i32 s5, 0, 0x1c000
	s_add_i32 s0, s4, s51
	s_add_i32 m0, s0, 0xffffff80
	ds_read_b128 v[222:225], v203
	ds_read_b128 v[226:229], v203 offset:1024
	ds_read_b128 v[230:233], v203 offset:2048
	global_load_lds_dwordx4 v130, s[40:41] offset:128
	s_add_i32 m0, s0, 0x1f80
	ds_read_b128 v[234:237], v203 offset:3072
	global_load_lds_dwordx4 v134, s[40:41] offset:128
	s_barrier
; #define PG8_STAGE(bufoff, gbase, voff) do { _Pragma("unroll") for (int _i = 0; _i < 2; ++_i) \
;         __builtin_amdgcn_global_load_lds((const unsigned*)((const char*)(gbase) + (voff)[_i]), (LAS unsigned*)(lds + (bufoff) + ldsw + _i * 8192), 16, 0, 0); } while (0)
; #define PG8_LDA(dst, b, h) do { _Pragma("unroll") for (int m = 0; m < 4; ++m) _Pragma("unroll") for (int k = 0; k < 2; ++k) dst[m][k] = *(const LAS bf16x8*)(lds + PG8_SA(b, h) + aoff + m * 2048 + k * 1024); } while (0)
; #define PG8_MMA(ai, bj, At, Bt) do { __builtin_amdgcn_s_setprio(1); _Pragma("unroll") for (int m = 0; m < 4; ++m) _Pragma("unroll") for (int n = 0; n < 2; ++n) _Pragma("unroll") for (int k = 0; k < 2; ++k) \
;         acc[ai][bj][m][n] = __builtin_amdgcn_mfma_f32_16x16x32_bf16(Bt[n][k], At[m][k], acc[ai][bj][m][n], 0, 0, 0); __builtin_amdgcn_s_setprio(0); } while (0)
; #define PG8_WAIT_V(n) asm volatile("s_waitcnt vmcnt(" #n ")" ::: "memory")
; #define PG8_WAIT_L(n) asm volatile("s_waitcnt lgkmcnt(" #n ")" ::: "memory")
; #define PG8_BAR __builtin_amdgcn_s_barrier()
; #define PG8_SCHED __builtin_amdgcn_sched_barrier(0)
; template <class Epi, class Sched>
; DI void gemm_phase(LAS unsigned char* lds, const Gemm g, const Sched& S, const Epi& E) {
;     ...
;             PG8_BAR; PG8_WAIT_L(0); PG8_MMA(0, 1, At, B1); PG8_BAR;
;             PG8_LDA(At, 1, 1); PG8_STAGE(PG8_SA(1, 0), a3, voffA);
;             PG8_BAR; PG8_WAIT_L(0); PG8_MMA(1, 0, At, B0); PG8_BAR; PG8_SCHED;
;             PG8_STAGE(PG8_SB(1, 1), b3 + hstep, voffB);
;             PG8_WAIT_V(6); PG8_BAR; PG8_MMA(1, 1, At, B1); PG8_BAR;
;         }
	s_waitcnt lgkmcnt(0)
	s_setprio 1
	v_mfma_f32_16x16x32_bf16 v[116:119], v[222:225], v[172:175], v[116:119]
	v_mfma_f32_16x16x32_bf16 v[112:115], v[230:233], v[172:175], v[112:115]
	v_mfma_f32_16x16x32_bf16 v[100:103], v[222:225], v[180:183], v[100:103]
	v_mfma_f32_16x16x32_bf16 v[96:99], v[230:233], v[180:183], v[96:99]
	v_mfma_f32_16x16x32_bf16 v[84:87], v[222:225], v[206:209], v[84:87]
	v_mfma_f32_16x16x32_bf16 v[80:83], v[230:233], v[206:209], v[80:83]
	v_mfma_f32_16x16x32_bf16 v[68:71], v[222:225], v[214:217], v[68:71]
	v_mfma_f32_16x16x32_bf16 v[64:67], v[230:233], v[214:217], v[64:67]
	v_mfma_f32_16x16x32_bf16 v[116:119], v[226:229], v[176:179], v[116:119]
	v_mfma_f32_16x16x32_bf16 v[112:115], v[234:237], v[176:179], v[112:115]
	v_mfma_f32_16x16x32_bf16 v[100:103], v[226:229], v[188:191], v[100:103]
	v_mfma_f32_16x16x32_bf16 v[96:99], v[234:237], v[188:191], v[96:99]
	v_mfma_f32_16x16x32_bf16 v[84:87], v[226:229], v[210:213], v[84:87]
	v_mfma_f32_16x16x32_bf16 v[80:83], v[234:237], v[210:213], v[80:83]
	v_mfma_f32_16x16x32_bf16 v[68:71], v[226:229], v[218:221], v[68:71]
	v_mfma_f32_16x16x32_bf16 v[64:67], v[234:237], v[218:221], v[64:67]
	s_setprio 0
	s_add_i32 m0, s59, 0xffffff80
	s_barrier
	ds_read_b128 v[172:175], v156 offset:49152
	ds_read_b128 v[176:179], v156 offset:50176
	ds_read_b128 v[180:183], v156 offset:51200
	ds_read_b128 v[188:191], v156 offset:52224
	ds_read_b128 v[206:209], v156 offset:53248
	ds_read_b128 v[210:213], v156 offset:54272
	ds_read_b128 v[214:217], v156 offset:55296
	global_load_lds_dwordx4 v128, s[42:43] offset:128
	s_add_i32 m0, s60, 0xffffff80
	ds_read_b128 v[218:221], v156 offset:56320
	global_load_lds_dwordx4 v132, s[42:43] offset:128
	s_barrier
	s_waitcnt lgkmcnt(0)
	s_setprio 1
	v_mfma_f32_16x16x32_bf16 v[60:63], v[144:147], v[172:175], v[60:63]
	v_mfma_f32_16x16x32_bf16 v[56:59], v[164:167], v[172:175], v[56:59]
	v_mfma_f32_16x16x32_bf16 v[44:47], v[144:147], v[180:183], v[44:47]
	v_mfma_f32_16x16x32_bf16 v[40:43], v[164:167], v[180:183], v[40:43]
	v_mfma_f32_16x16x32_bf16 v[28:31], v[144:147], v[206:209], v[28:31]
	v_mfma_f32_16x16x32_bf16 v[24:27], v[164:167], v[206:209], v[24:27]
	v_mfma_f32_16x16x32_bf16 v[12:15], v[144:147], v[214:217], v[12:15]
	v_mfma_f32_16x16x32_bf16 v[8:11], v[164:167], v[214:217], v[8:11]
	v_mfma_f32_16x16x32_bf16 v[60:63], v[160:163], v[176:179], v[60:63]
	v_mfma_f32_16x16x32_bf16 v[56:59], v[168:171], v[176:179], v[56:59]
	v_mfma_f32_16x16x32_bf16 v[44:47], v[160:163], v[188:191], v[44:47]
	v_mfma_f32_16x16x32_bf16 v[40:43], v[168:171], v[188:191], v[40:43]
	v_mfma_f32_16x16x32_bf16 v[28:31], v[160:163], v[210:213], v[28:31]
	v_mfma_f32_16x16x32_bf16 v[24:27], v[168:171], v[210:213], v[24:27]
	v_mfma_f32_16x16x32_bf16 v[12:15], v[160:163], v[218:221], v[12:15]
	v_mfma_f32_16x16x32_bf16 v[8:11], v[168:171], v[218:221], v[8:11]
	s_setprio 0
	s_barrier
	s_add_i32 s4, s5, s51
	s_mov_b32 m0, s4
	s_add_u32 s0, s40, 0x160080
	s_addc_u32 s1, s41, 0
	global_load_lds_dwordx4 v130, s[0:1]
	s_add_i32 m0, s4, 0x2000
	s_nop 0
	global_load_lds_dwordx4 v134, s[0:1]
	s_waitcnt vmcnt(6)
	s_barrier
	s_setprio 1
	v_mfma_f32_16x16x32_bf16 v[52:55], v[222:225], v[172:175], v[52:55]
	v_mfma_f32_16x16x32_bf16 v[48:51], v[230:233], v[172:175], v[48:51]
	v_mfma_f32_16x16x32_bf16 v[36:39], v[222:225], v[180:183], v[36:39]
	v_mfma_f32_16x16x32_bf16 v[32:35], v[230:233], v[180:183], v[32:35]
	v_mfma_f32_16x16x32_bf16 v[20:23], v[222:225], v[206:209], v[20:23]
	v_mfma_f32_16x16x32_bf16 v[16:19], v[230:233], v[206:209], v[16:19]
	v_mfma_f32_16x16x32_bf16 v[4:7], v[222:225], v[214:217], v[4:7]
	v_mfma_f32_16x16x32_bf16 v[0:3], v[230:233], v[214:217], v[0:3]
	v_mfma_f32_16x16x32_bf16 v[52:55], v[226:229], v[176:179], v[52:55]
	v_mfma_f32_16x16x32_bf16 v[48:51], v[234:237], v[176:179], v[48:51]
	v_mfma_f32_16x16x32_bf16 v[36:39], v[226:229], v[188:191], v[36:39]
	v_mfma_f32_16x16x32_bf16 v[32:35], v[234:237], v[188:191], v[32:35]
	v_mfma_f32_16x16x32_bf16 v[20:23], v[226:229], v[210:213], v[20:23]
	v_mfma_f32_16x16x32_bf16 v[16:19], v[234:237], v[210:213], v[16:19]
	v_mfma_f32_16x16x32_bf16 v[4:7], v[226:229], v[218:221], v[4:7]
	v_mfma_f32_16x16x32_bf16 v[0:3], v[234:237], v[218:221], v[0:3]
	s_setprio 0
	s_add_i32 s68, s68, 2
	s_add_u32 s38, s38, 0x100
	s_addc_u32 s39, s39, 0
	s_add_u32 s35, s35, 0x100
	s_addc_u32 s67, s67, 0
	s_cmpk_gt_u32 s68, 0x55
	s_cbranch_scc0 .Lrot_1746
	s_barrier

;     DI size_t aoff(const Unit& u, size_t tstep) const { return (size_t)u.pm * tstep; }
;     DI size_t boff(const Unit& u, size_t tstep) const { return (size_t)u.pn * tstep; }
;     DI bool next(int i, Unit& u) const { const long L = (long)i * G + c; if (L >= np) return false; u.pm = pmv; u.pn = (int)(L % nN); u.ks = (int)(L / nN); return true; }
;     DI size_t aoff(const Unit& u, size_t) const { return (size_t)u.ks * kbytes; }
;     DI size_t boff(const Unit& u, size_t tstep) const { return (size_t)u.pn * tstep + (size_t)u.ks * kbytes; }
;     DI bool next(int i, Unit& u) const { Unit t; if (!S.next(i / 3, t)) return false; u.pm = t.pm; u.pn = t.pn; u.ks = i % 3; return true; }
;     DI size_t aoff(const Unit& u, size_t tstep) const { return (u.ks < 2 ? offU : offOA) + (size_t)u.pm * tstep; }
; #define PG8_WAIT_V(n) asm volatile("s_waitcnt vmcnt(" #n ")" ::: "memory")
; template <class Epi, class Sched>
; DI void gemm_phase(LAS unsigned char* lds, const Gemm g, const Sched& S, const Epi& E) {
;     ...
;         const bool has_next = S.next(ui + 1, nxt);
;         const char* nA = has_next ? (const char*)g.A + S.aoff(nxt, tstep) : cA; const char* nB = has_next ? (const char*)g.Bt + S.boff(nxt, tstep) : cB;
;         for (int t = 0; t < nt; t += 2) {
;             if constexpr (Epi::HAS_MID) { if (t == E.mid_t(nt)) { int fr3 = fr, fq3 = fq; asm volatile("" : "+v"(fr3), "+v"(fq3)); E.mid(acc, cur, wr, wc, fr3, fq3); } }
;             const bool last = (t == nt - 2);
;             const char* a1 = cA + (size_t)(t + 1) * kstep;
;             const char* a2 = last ? nA : cA + (size_t)(t + 2) * kstep; const char* b2 = last ? nB : cB + (size_t)(t + 2) * kstep;
;             const char* a3 = a2 + kstep; const char* b3 = b2 + kstep;
;             PG8_LDB(B0, 0, 0); PG8_SCHED; PG8_LDA(At, 0, 0); PG8_STAGE(PG8_SA(1, 1), a1 + hstep, voffA);
;             PG8_WAIT_L(8); PG8_BAR; PG8_WAIT_L(0); PG8_MMA(0, 0, At, B0); PG8_BAR; PG8_SCHED;
;             PG8_LDB(B1, 0, 1); PG8_STAGE(PG8_SB(0, 0), b2, voffB);
;             PG8_BAR; PG8_WAIT_L(0); PG8_MMA(0, 1, At, B1); PG8_BAR;
;             PG8_LDA(At, 0, 1); PG8_STAGE(PG8_SA(0, 0), a2, voffA);
;             PG8_BAR; PG8_WAIT_L(0); PG8_MMA(1, 0, At, B0); PG8_BAR; PG8_SCHED;
;             PG8_STAGE(PG8_SB(0, 1), b2 + hstep, voffB);
;             PG8_WAIT_V(6); PG8_BAR; PG8_MMA(1, 1, At, B1); PG8_BAR;
.LBB0_1774:
	s_add_u32 s28, s38, s28
	s_addc_u32 s29, s39, s29
	s_and_b64 s[0:1], s[8:9], exec
	s_cselect_b32 s15, s29, s37
	s_cselect_b32 s17, s28, s36
	s_add_u32 s8, s36, 0x160080
	s_addc_u32 s9, s37, 0
	s_add_u32 s64, s30, 0x100
	v_mov_b32_e32 v0, 0
	s_addc_u32 s65, s31, 0
	s_mov_b32 s66, -2
	ds_read_b128 v[146:149], v141
	ds_read_b128 v[154:157], v141 offset:1024
	ds_read_b128 v[158:161], v141 offset:2048
	ds_read_b128 v[162:165], v141 offset:3072
	s_mov_b32 m0, s56
	ds_read_b128 v[166:169], v142
	ds_read_b128 v[170:173], v142 offset:1024
	ds_read_b128 v[174:177], v142 offset:2048
	ds_read_b128 v[178:181], v142 offset:3072
	ds_read_b128 v[188:191], v142 offset:4096
	ds_read_b128 v[206:209], v142 offset:5120
	ds_read_b128 v[210:213], v142 offset:6144
	global_load_lds_dwordx4 v132, s[8:9]
	s_mov_b32 m0, s57
	ds_read_b128 v[214:217], v142 offset:7168
	global_load_lds_dwordx4 v134, s[8:9]
	s_add_u32 s0, s8, 0xffea0080
	s_addc_u32 s1, s9, -1
	s_cmp_eq_u32 s66, 4
	s_cselect_b32 s37, s15, s1
	s_cselect_b32 s36, s17, s0
	s_cselect_b32 s31, s19, s65
	s_cselect_b32 s30, s18, s64
	s_waitcnt lgkmcnt(8)
	s_barrier
	s_waitcnt lgkmcnt(0)
	s_setprio 1
	v_mfma_f32_16x16x32_bf16 v[124:127], v[146:149], v[166:169], 0
	v_mfma_f32_16x16x32_bf16 v[120:123], v[158:161], v[166:169], 0
	v_mfma_f32_16x16x32_bf16 v[116:119], v[146:149], v[174:177], 0
	v_mfma_f32_16x16x32_bf16 v[112:115], v[158:161], v[174:177], 0
	v_mfma_f32_16x16x32_bf16 v[104:107], v[146:149], v[188:191], 0
	v_mfma_f32_16x16x32_bf16 v[96:99], v[158:161], v[188:191], 0
	v_mfma_f32_16x16x32_bf16 v[88:91], v[146:149], v[210:213], 0
	v_mfma_f32_16x16x32_bf16 v[80:83], v[158:161], v[210:213], 0
	v_mfma_f32_16x16x32_bf16 v[124:127], v[154:157], v[170:173], v[124:127]
	v_mfma_f32_16x16x32_bf16 v[120:123], v[162:165], v[170:173], v[120:123]
	v_mfma_f32_16x16x32_bf16 v[116:119], v[154:157], v[178:181], v[116:119]
	v_mfma_f32_16x16x32_bf16 v[112:115], v[162:165], v[178:181], v[112:115]
	v_mfma_f32_16x16x32_bf16 v[104:107], v[154:157], v[206:209], v[104:107]
	v_mfma_f32_16x16x32_bf16 v[96:99], v[162:165], v[206:209], v[96:99]
	v_mfma_f32_16x16x32_bf16 v[88:91], v[154:157], v[214:217], v[88:91]
	v_mfma_f32_16x16x32_bf16 v[80:83], v[162:165], v[214:217], v[80:83]
	s_setprio 0
	s_barrier
	s_mov_b32 m0, s58
	ds_read_b128 v[218:221], v143
	ds_read_b128 v[222:225], v143 offset:1024
	ds_read_b128 v[226:229], v143 offset:2048
	global_load_lds_dwordx4 v130, s[30:31]
	s_mov_b32 m0, s59
	ds_read_b128 v[230:233], v143 offset:3072
	global_load_lds_dwordx4 v128, s[30:31]
	s_barrier
	s_waitcnt lgkmcnt(0)
	s_setprio 1
	v_mfma_f32_16x16x32_bf16 v[108:111], v[218:221], v[166:169], 0
	v_mfma_f32_16x16x32_bf16 v[100:103], v[226:229], v[166:169], 0
	v_mfma_f32_16x16x32_bf16 v[92:95], v[218:221], v[174:177], 0
	v_mfma_f32_16x16x32_bf16 v[84:87], v[226:229], v[174:177], 0
	v_mfma_f32_16x16x32_bf16 v[76:79], v[218:221], v[188:191], 0
	v_mfma_f32_16x16x32_bf16 v[72:75], v[226:229], v[188:191], 0
	v_mfma_f32_16x16x32_bf16 v[68:71], v[218:221], v[210:213], 0
	v_mfma_f32_16x16x32_bf16 v[64:67], v[226:229], v[210:213], 0
	v_mfma_f32_16x16x32_bf16 v[108:111], v[222:225], v[170:173], v[108:111]
	v_mfma_f32_16x16x32_bf16 v[100:103], v[230:233], v[170:173], v[100:103]
	v_mfma_f32_16x16x32_bf16 v[92:95], v[222:225], v[178:181], v[92:95]
	v_mfma_f32_16x16x32_bf16 v[84:87], v[230:233], v[178:181], v[84:87]
	v_mfma_f32_16x16x32_bf16 v[76:79], v[222:225], v[206:209], v[76:79]
	v_mfma_f32_16x16x32_bf16 v[72:75], v[230:233], v[206:209], v[72:75]
	v_mfma_f32_16x16x32_bf16 v[68:71], v[222:225], v[214:217], v[68:71]
	v_mfma_f32_16x16x32_bf16 v[64:67], v[230:233], v[214:217], v[64:67]
	s_setprio 0
	s_mov_b32 m0, s40
	s_barrier
	ds_read_b128 v[166:169], v142 offset:16384
	ds_read_b128 v[170:173], v142 offset:17408
	ds_read_b128 v[174:177], v142 offset:18432
	ds_read_b128 v[178:181], v142 offset:19456
	ds_read_b128 v[188:191], v142 offset:20480
	ds_read_b128 v[206:209], v142 offset:21504
	ds_read_b128 v[210:213], v142 offset:22528
	global_load_lds_dwordx4 v130, s[36:37]
	s_mov_b32 m0, s41
	ds_read_b128 v[214:217], v142 offset:23552
	global_load_lds_dwordx4 v128, s[36:37]
	s_barrier
	s_waitcnt lgkmcnt(0)
	s_setprio 1
	v_mfma_f32_16x16x32_bf16 v[60:63], v[146:149], v[166:169], 0
	v_mfma_f32_16x16x32_bf16 v[56:59], v[158:161], v[166:169], 0
	v_mfma_f32_16x16x32_bf16 v[52:55], v[146:149], v[174:177], 0
	v_mfma_f32_16x16x32_bf16 v[48:51], v[158:161], v[174:177], 0
	v_mfma_f32_16x16x32_bf16 v[40:43], v[146:149], v[188:191], 0
	v_mfma_f32_16x16x32_bf16 v[32:35], v[158:161], v[188:191], 0
	v_mfma_f32_16x16x32_bf16 v[24:27], v[146:149], v[210:213], 0
	v_mfma_f32_16x16x32_bf16 v[16:19], v[158:161], v[210:213], 0
	v_mfma_f32_16x16x32_bf16 v[60:63], v[154:157], v[170:173], v[60:63]
	v_mfma_f32_16x16x32_bf16 v[56:59], v[162:165], v[170:173], v[56:59]
	v_mfma_f32_16x16x32_bf16 v[52:55], v[154:157], v[178:181], v[52:55]
	v_mfma_f32_16x16x32_bf16 v[48:51], v[162:165], v[178:181], v[48:51]
	v_mfma_f32_16x16x32_bf16 v[40:43], v[154:157], v[206:209], v[40:43]
	v_mfma_f32_16x16x32_bf16 v[32:35], v[162:165], v[206:209], v[32:35]
	v_mfma_f32_16x16x32_bf16 v[24:27], v[154:157], v[214:217], v[24:27]
	v_mfma_f32_16x16x32_bf16 v[16:19], v[162:165], v[214:217], v[16:19]
	s_setprio 0
	s_barrier
	s_add_u32 s0, s30, 0x160000
	s_addc_u32 s1, s31, 0
	s_mov_b32 m0, s60
	s_nop 0
	global_load_lds_dwordx4 v130, s[0:1]
	s_mov_b32 m0, s61
	s_nop 0
	global_load_lds_dwordx4 v128, s[0:1]
	s_waitcnt vmcnt(6)
	s_barrier
; #define PG8_STAGE(bufoff, gbase, voff) do { _Pragma("unroll") for (int _i = 0; _i < 2; ++_i) \
;         __builtin_amdgcn_global_load_lds((const unsigned*)((const char*)(gbase) + (voff)[_i]), (LAS unsigned*)(lds + (bufoff) + ldsw + _i * 8192), 16, 0, 0); } while (0)
; #define PG8_LDA(dst, b, h) do { _Pragma("unroll") for (int m = 0; m < 4; ++m) _Pragma("unroll") for (int k = 0; k < 2; ++k) dst[m][k] = *(const LAS bf16x8*)(lds + PG8_SA(b, h) + aoff + m * 2048 + k * 1024); } while (0)
; #define PG8_LDB(dst, b, h) do { _Pragma("unroll") for (int n = 0; n < 2; ++n) _Pragma("unroll") for (int k = 0; k < 2; ++k) dst[n][k] = *(const LAS bf16x8*)(lds + PG8_SB(b, h) + boff + n * 2048 + k * 1024); } while (0)
; #define PG8_MMA(ai, bj, At, Bt) do { __builtin_amdgcn_s_setprio(1); _Pragma("unroll") for (int m = 0; m < 4; ++m) _Pragma("unroll") for (int n = 0; n < 2; ++n) _Pragma("unroll") for (int k = 0; k < 2; ++k) \
;         acc[ai][bj][m][n] = __builtin_amdgcn_mfma_f32_16x16x32_bf16(Bt[n][k], At[m][k], acc[ai][bj][m][n], 0, 0, 0); __builtin_amdgcn_s_setprio(0); } while (0)
; #define PG8_WAIT_V(n) asm volatile("s_waitcnt vmcnt(" #n ")" ::: "memory")
; #define PG8_WAIT_L(n) asm volatile("s_waitcnt lgkmcnt(" #n ")" ::: "memory")
; #define PG8_BAR __builtin_amdgcn_s_barrier()
; #define PG8_SCHED __builtin_amdgcn_sched_barrier(0)
; template <class Epi, class Sched>
; DI void gemm_phase(LAS unsigned char* lds, const Gemm g, const Sched& S, const Epi& E) {
;     ...
;             PG8_WAIT_V(6); PG8_BAR; PG8_MMA(1, 1, At, B1); PG8_BAR;
;             PG8_LDB(B0, 1, 0); PG8_SCHED; PG8_LDA(At, 1, 0); PG8_STAGE(PG8_SA(0, 1), a2 + hstep, voffA);
;             PG8_WAIT_L(8); PG8_BAR; PG8_WAIT_L(0); PG8_MMA(0, 0, At, B0); PG8_BAR; PG8_SCHED;
;             PG8_LDB(B1, 1, 1); PG8_STAGE(PG8_SB(1, 0), b3, voffB);
	s_setprio 1
	v_mfma_f32_16x16x32_bf16 v[44:47], v[218:221], v[166:169], 0
	v_mfma_f32_16x16x32_bf16 v[36:39], v[226:229], v[166:169], 0
	v_mfma_f32_16x16x32_bf16 v[28:31], v[218:221], v[174:177], 0
	v_mfma_f32_16x16x32_bf16 v[20:23], v[226:229], v[174:177], 0
	v_mfma_f32_16x16x32_bf16 v[12:15], v[218:221], v[188:191], 0
	v_mfma_f32_16x16x32_bf16 v[8:11], v[226:229], v[188:191], 0
	v_mfma_f32_16x16x32_bf16 v[4:7], v[218:221], v[210:213], 0
	v_mfma_f32_16x16x32_bf16 v[0:3], v[226:229], v[210:213], 0
	v_mfma_f32_16x16x32_bf16 v[44:47], v[222:225], v[170:173], v[44:47]
	v_mfma_f32_16x16x32_bf16 v[36:39], v[230:233], v[170:173], v[36:39]
	v_mfma_f32_16x16x32_bf16 v[28:31], v[222:225], v[178:181], v[28:31]
	v_mfma_f32_16x16x32_bf16 v[20:23], v[230:233], v[178:181], v[20:23]
	v_mfma_f32_16x16x32_bf16 v[12:15], v[222:225], v[206:209], v[12:15]
	v_mfma_f32_16x16x32_bf16 v[8:11], v[230:233], v[206:209], v[8:11]
	v_mfma_f32_16x16x32_bf16 v[4:7], v[222:225], v[214:217], v[4:7]
	v_mfma_f32_16x16x32_bf16 v[0:3], v[230:233], v[214:217], v[0:3]
	s_setprio 0
	s_barrier
	ds_read_b128 v[146:149], v144
	ds_read_b128 v[154:157], v144 offset:1024
	ds_read_b128 v[158:161], v144 offset:2048
	ds_read_b128 v[162:165], v144 offset:3072
	s_add_u32 s0, s36, 0x160000
	s_addc_u32 s1, s37, 0
	s_mov_b32 m0, s42
	ds_read_b128 v[166:169], v142 offset:32768
	ds_read_b128 v[170:173], v142 offset:33792
	ds_read_b128 v[174:177], v142 offset:34816
	ds_read_b128 v[178:181], v142 offset:35840
	ds_read_b128 v[188:191], v142 offset:36864
	ds_read_b128 v[206:209], v142 offset:37888
	ds_read_b128 v[210:213], v142 offset:38912
	global_load_lds_dwordx4 v130, s[0:1]
	s_mov_b32 m0, s43
	ds_read_b128 v[214:217], v142 offset:39936
	global_load_lds_dwordx4 v128, s[0:1]
	s_waitcnt lgkmcnt(8)
	s_barrier
	s_waitcnt lgkmcnt(0)
	s_setprio 1
	v_mfma_f32_16x16x32_bf16 v[124:127], v[146:149], v[166:169], v[124:127]
	v_mfma_f32_16x16x32_bf16 v[120:123], v[158:161], v[166:169], v[120:123]
	v_mfma_f32_16x16x32_bf16 v[116:119], v[146:149], v[174:177], v[116:119]
	v_mfma_f32_16x16x32_bf16 v[112:115], v[158:161], v[174:177], v[112:115]
	v_mfma_f32_16x16x32_bf16 v[104:107], v[146:149], v[188:191], v[104:107]
	v_mfma_f32_16x16x32_bf16 v[96:99], v[158:161], v[188:191], v[96:99]
	v_mfma_f32_16x16x32_bf16 v[88:91], v[146:149], v[210:213], v[88:91]
	v_mfma_f32_16x16x32_bf16 v[80:83], v[158:161], v[210:213], v[80:83]
	v_mfma_f32_16x16x32_bf16 v[124:127], v[154:157], v[170:173], v[124:127]
	v_mfma_f32_16x16x32_bf16 v[120:123], v[162:165], v[170:173], v[120:123]
	v_mfma_f32_16x16x32_bf16 v[116:119], v[154:157], v[178:181], v[116:119]
	v_mfma_f32_16x16x32_bf16 v[112:115], v[162:165], v[178:181], v[112:115]
	v_mfma_f32_16x16x32_bf16 v[104:107], v[154:157], v[206:209], v[104:107]
	v_mfma_f32_16x16x32_bf16 v[96:99], v[162:165], v[206:209], v[96:99]
	v_mfma_f32_16x16x32_bf16 v[88:91], v[154:157], v[214:217], v[88:91]
	v_mfma_f32_16x16x32_bf16 v[80:83], v[162:165], v[214:217], v[80:83]
	s_setprio 0
	s_barrier
	s_add_i32 s4, 0, 0x1c000
	s_add_i32 s0, s62, s35
	v_add_u32_e32 v145, s4, v140
	s_add_i32 m0, s0, 0xffffff80
	ds_read_b128 v[218:221], v145
	ds_read_b128 v[222:225], v145 offset:1024
	ds_read_b128 v[226:229], v145 offset:2048
	global_load_lds_dwordx4 v130, s[30:31] offset:128
	s_add_i32 m0, s0, 0x1f80
	ds_read_b128 v[230:233], v145 offset:3072
	global_load_lds_dwordx4 v128, s[30:31] offset:128
	s_barrier
; #define PG8_STAGE(bufoff, gbase, voff) do { _Pragma("unroll") for (int _i = 0; _i < 2; ++_i) \
;         __builtin_amdgcn_global_load_lds((const unsigned*)((const char*)(gbase) + (voff)[_i]), (LAS unsigned*)(lds + (bufoff) + ldsw + _i * 8192), 16, 0, 0); } while (0)
; #define PG8_LDA(dst, b, h) do { _Pragma("unroll") for (int m = 0; m < 4; ++m) _Pragma("unroll") for (int k = 0; k < 2; ++k) dst[m][k] = *(const LAS bf16x8*)(lds + PG8_SA(b, h) + aoff + m * 2048 + k * 1024); } while (0)
; #define PG8_MMA(ai, bj, At, Bt) do { __builtin_amdgcn_s_setprio(1); _Pragma("unroll") for (int m = 0; m < 4; ++m) _Pragma("unroll") for (int n = 0; n < 2; ++n) _Pragma("unroll") for (int k = 0; k < 2; ++k) \
;         acc[ai][bj][m][n] = __builtin_amdgcn_mfma_f32_16x16x32_bf16(Bt[n][k], At[m][k], acc[ai][bj][m][n], 0, 0, 0); __builtin_amdgcn_s_setprio(0); } while (0)
; #define PG8_WAIT_V(n) asm volatile("s_waitcnt vmcnt(" #n ")" ::: "memory")
; #define PG8_WAIT_L(n) asm volatile("s_waitcnt lgkmcnt(" #n ")" ::: "memory")
; #define PG8_BAR __builtin_amdgcn_s_barrier()
; #define PG8_SCHED __builtin_amdgcn_sched_barrier(0)
; template <class Epi, class Sched>
; DI void gemm_phase(LAS unsigned char* lds, const Gemm g, const Sched& S, const Epi& E) {
;     ...
;             PG8_BAR; PG8_WAIT_L(0); PG8_MMA(0, 1, At, B1); PG8_BAR;
;             PG8_LDA(At, 1, 1); PG8_STAGE(PG8_SA(1, 0), a3, voffA);
;             PG8_BAR; PG8_WAIT_L(0); PG8_MMA(1, 0, At, B0); PG8_BAR; PG8_SCHED;
;             PG8_STAGE(PG8_SB(1, 1), b3 + hstep, voffB);
;             PG8_WAIT_V(6); PG8_BAR; PG8_MMA(1, 1, At, B1); PG8_BAR;
;         }
	s_waitcnt lgkmcnt(0)
	s_setprio 1
	v_mfma_f32_16x16x32_bf16 v[108:111], v[218:221], v[166:169], v[108:111]
	v_mfma_f32_16x16x32_bf16 v[100:103], v[226:229], v[166:169], v[100:103]
	v_mfma_f32_16x16x32_bf16 v[92:95], v[218:221], v[174:177], v[92:95]
	v_mfma_f32_16x16x32_bf16 v[84:87], v[226:229], v[174:177], v[84:87]
	v_mfma_f32_16x16x32_bf16 v[76:79], v[218:221], v[188:191], v[76:79]
	v_mfma_f32_16x16x32_bf16 v[72:75], v[226:229], v[188:191], v[72:75]
	v_mfma_f32_16x16x32_bf16 v[68:71], v[218:221], v[210:213], v[68:71]
	v_mfma_f32_16x16x32_bf16 v[64:67], v[226:229], v[210:213], v[64:67]
	v_mfma_f32_16x16x32_bf16 v[108:111], v[222:225], v[170:173], v[108:111]
	v_mfma_f32_16x16x32_bf16 v[100:103], v[230:233], v[170:173], v[100:103]
	v_mfma_f32_16x16x32_bf16 v[92:95], v[222:225], v[178:181], v[92:95]
	v_mfma_f32_16x16x32_bf16 v[84:87], v[230:233], v[178:181], v[84:87]
	v_mfma_f32_16x16x32_bf16 v[76:79], v[222:225], v[206:209], v[76:79]
	v_mfma_f32_16x16x32_bf16 v[72:75], v[230:233], v[206:209], v[72:75]
	v_mfma_f32_16x16x32_bf16 v[68:71], v[222:225], v[214:217], v[68:71]
	v_mfma_f32_16x16x32_bf16 v[64:67], v[230:233], v[214:217], v[64:67]
	s_setprio 0
	s_add_i32 m0, s54, 0xffffff80
	s_barrier
	ds_read_b128 v[166:169], v142 offset:49152
	ds_read_b128 v[170:173], v142 offset:50176
	ds_read_b128 v[174:177], v142 offset:51200
	ds_read_b128 v[178:181], v142 offset:52224
	ds_read_b128 v[188:191], v142 offset:53248
	ds_read_b128 v[206:209], v142 offset:54272
	ds_read_b128 v[210:213], v142 offset:55296
	global_load_lds_dwordx4 v130, s[36:37] offset:128
	s_add_i32 m0, s55, 0xffffff80
	ds_read_b128 v[214:217], v142 offset:56320
	global_load_lds_dwordx4 v128, s[36:37] offset:128
	s_barrier
	s_waitcnt lgkmcnt(0)
	s_setprio 1
	v_mfma_f32_16x16x32_bf16 v[60:63], v[146:149], v[166:169], v[60:63]
	v_mfma_f32_16x16x32_bf16 v[56:59], v[158:161], v[166:169], v[56:59]
	v_mfma_f32_16x16x32_bf16 v[52:55], v[146:149], v[174:177], v[52:55]
	v_mfma_f32_16x16x32_bf16 v[48:51], v[158:161], v[174:177], v[48:51]
	v_mfma_f32_16x16x32_bf16 v[40:43], v[146:149], v[188:191], v[40:43]
	v_mfma_f32_16x16x32_bf16 v[32:35], v[158:161], v[188:191], v[32:35]
	v_mfma_f32_16x16x32_bf16 v[24:27], v[146:149], v[210:213], v[24:27]
	v_mfma_f32_16x16x32_bf16 v[16:19], v[158:161], v[210:213], v[16:19]
	v_mfma_f32_16x16x32_bf16 v[60:63], v[154:157], v[170:173], v[60:63]
	v_mfma_f32_16x16x32_bf16 v[56:59], v[162:165], v[170:173], v[56:59]
	v_mfma_f32_16x16x32_bf16 v[52:55], v[154:157], v[178:181], v[52:55]
	v_mfma_f32_16x16x32_bf16 v[48:51], v[162:165], v[178:181], v[48:51]
	v_mfma_f32_16x16x32_bf16 v[40:43], v[154:157], v[206:209], v[40:43]
	v_mfma_f32_16x16x32_bf16 v[32:35], v[162:165], v[206:209], v[32:35]
	v_mfma_f32_16x16x32_bf16 v[24:27], v[154:157], v[214:217], v[24:27]
	v_mfma_f32_16x16x32_bf16 v[16:19], v[162:165], v[214:217], v[16:19]
	s_setprio 0
	s_barrier
	s_add_i32 s4, s4, s35
	s_mov_b32 m0, s4
	s_add_u32 s0, s30, 0x160080
	s_addc_u32 s1, s31, 0
	global_load_lds_dwordx4 v130, s[0:1]
	s_add_i32 m0, s4, 0x2000
	s_nop 0
	global_load_lds_dwordx4 v128, s[0:1]
	s_add_i32 s66, s66, 2
	s_add_u32 s8, s8, 0x100
	s_addc_u32 s9, s9, 0
	s_add_u32 s64, s64, 0x100
	s_addc_u32 s65, s65, 0
	s_cmp_gt_u32 s66, 5
	s_waitcnt vmcnt(6)
	s_barrier
	s_setprio 1
	v_mfma_f32_16x16x32_bf16 v[44:47], v[218:221], v[166:169], v[44:47]
	v_mfma_f32_16x16x32_bf16 v[36:39], v[226:229], v[166:169], v[36:39]
	v_mfma_f32_16x16x32_bf16 v[28:31], v[218:221], v[174:177], v[28:31]
	v_mfma_f32_16x16x32_bf16 v[20:23], v[226:229], v[174:177], v[20:23]
	v_mfma_f32_16x16x32_bf16 v[12:15], v[218:221], v[188:191], v[12:15]
	v_mfma_f32_16x16x32_bf16 v[8:11], v[226:229], v[188:191], v[8:11]
	v_mfma_f32_16x16x32_bf16 v[4:7], v[218:221], v[210:213], v[4:7]
	v_mfma_f32_16x16x32_bf16 v[0:3], v[226:229], v[210:213], v[0:3]
	v_mfma_f32_16x16x32_bf16 v[44:47], v[222:225], v[170:173], v[44:47]
	v_mfma_f32_16x16x32_bf16 v[36:39], v[230:233], v[170:173], v[36:39]
	v_mfma_f32_16x16x32_bf16 v[28:31], v[222:225], v[178:181], v[28:31]
	v_mfma_f32_16x16x32_bf16 v[20:23], v[230:233], v[178:181], v[20:23]
	v_mfma_f32_16x16x32_bf16 v[12:15], v[222:225], v[206:209], v[12:15]
	v_mfma_f32_16x16x32_bf16 v[8:11], v[230:233], v[206:209], v[8:11]
	v_mfma_f32_16x16x32_bf16 v[4:7], v[222:225], v[214:217], v[4:7]
	v_mfma_f32_16x16x32_bf16 v[0:3], v[230:233], v[214:217], v[0:3]
	s_setprio 0
	s_cbranch_scc0 .Lrot_1775
	s_barrier
	s_branch .Lpeel_done_1775

; #define PG8_STAGE(bufoff, gbase, voff) do { _Pragma("unroll") for (int _i = 0; _i < 2; ++_i) \
;         __builtin_amdgcn_global_load_lds((const unsigned*)((const char*)(gbase) + (voff)[_i]), (LAS unsigned*)(lds + (bufoff) + ldsw + _i * 8192), 16, 0, 0); } while (0)
; #define PG8_LDA(dst, b, h) do { _Pragma("unroll") for (int m = 0; m < 4; ++m) _Pragma("unroll") for (int k = 0; k < 2; ++k) dst[m][k] = *(const LAS bf16x8*)(lds + PG8_SA(b, h) + aoff + m * 2048 + k * 1024); } while (0)
; #define PG8_LDB(dst, b, h) do { _Pragma("unroll") for (int n = 0; n < 2; ++n) _Pragma("unroll") for (int k = 0; k < 2; ++k) dst[n][k] = *(const LAS bf16x8*)(lds + PG8_SB(b, h) + boff + n * 2048 + k * 1024); } while (0)
; #define PG8_MMA(ai, bj, At, Bt) do { __builtin_amdgcn_s_setprio(1); _Pragma("unroll") for (int m = 0; m < 4; ++m) _Pragma("unroll") for (int n = 0; n < 2; ++n) _Pragma("unroll") for (int k = 0; k < 2; ++k) \
;         acc[ai][bj][m][n] = __builtin_amdgcn_mfma_f32_16x16x32_bf16(Bt[n][k], At[m][k], acc[ai][bj][m][n], 0, 0, 0); __builtin_amdgcn_s_setprio(0); } while (0)
; #define PG8_WAIT_V(n) asm volatile("s_waitcnt vmcnt(" #n ")" ::: "memory")
; #define PG8_WAIT_L(n) asm volatile("s_waitcnt lgkmcnt(" #n ")" ::: "memory")
; #define PG8_BAR __builtin_amdgcn_s_barrier()
; #define PG8_SCHED __builtin_amdgcn_sched_barrier(0)
; template <class Epi, class Sched>
; DI void gemm_phase(LAS unsigned char* lds, const Gemm g, const Sched& S, const Epi& E) {
;     ...
;             PG8_LDB(B0, 0, 0); PG8_SCHED; PG8_LDA(At, 0, 0); PG8_STAGE(PG8_SA(1, 1), a1 + hstep, voffA);
;             PG8_WAIT_L(8); PG8_BAR; PG8_WAIT_L(0); PG8_MMA(0, 0, At, B0); PG8_BAR; PG8_SCHED;
;             PG8_LDB(B1, 0, 1); PG8_STAGE(PG8_SB(0, 0), b2, voffB);
;             PG8_BAR; PG8_WAIT_L(0); PG8_MMA(0, 1, At, B1); PG8_BAR;
;             PG8_LDA(At, 0, 1); PG8_STAGE(PG8_SA(0, 0), a2, voffA);
;             PG8_BAR; PG8_WAIT_L(0); PG8_MMA(1, 0, At, B0); PG8_BAR; PG8_SCHED;
;             PG8_STAGE(PG8_SB(0, 1), b2 + hstep, voffB);
;             PG8_WAIT_V(6); PG8_BAR; PG8_MMA(1, 1, At, B1); PG8_BAR;
.LBB0_1775:
	ds_read_b128 v[146:149], v141
	ds_read_b128 v[154:157], v141 offset:1024
	ds_read_b128 v[158:161], v141 offset:2048
	ds_read_b128 v[162:165], v141 offset:3072
	s_mov_b32 m0, s56
	ds_read_b128 v[166:169], v142
	ds_read_b128 v[170:173], v142 offset:1024
	ds_read_b128 v[174:177], v142 offset:2048
	ds_read_b128 v[178:181], v142 offset:3072
	ds_read_b128 v[188:191], v142 offset:4096
	ds_read_b128 v[206:209], v142 offset:5120
	ds_read_b128 v[210:213], v142 offset:6144
	global_load_lds_dwordx4 v132, s[8:9]
	s_mov_b32 m0, s57
	ds_read_b128 v[214:217], v142 offset:7168
	global_load_lds_dwordx4 v134, s[8:9]
	s_add_u32 s0, s8, 0xffea0080
	s_addc_u32 s1, s9, -1
	s_cmp_eq_u32 s66, 4
	s_cselect_b32 s37, s15, s1
	s_cselect_b32 s36, s17, s0
	s_cselect_b32 s31, s19, s65
	s_cselect_b32 s30, s18, s64
	s_waitcnt lgkmcnt(8)
	s_barrier
	s_waitcnt lgkmcnt(0)
	s_setprio 1
	v_mfma_f32_16x16x32_bf16 v[124:127], v[146:149], v[166:169], v[124:127]
	v_mfma_f32_16x16x32_bf16 v[120:123], v[158:161], v[166:169], v[120:123]
	v_mfma_f32_16x16x32_bf16 v[116:119], v[146:149], v[174:177], v[116:119]
	v_mfma_f32_16x16x32_bf16 v[112:115], v[158:161], v[174:177], v[112:115]
	v_mfma_f32_16x16x32_bf16 v[104:107], v[146:149], v[188:191], v[104:107]
	v_mfma_f32_16x16x32_bf16 v[96:99], v[158:161], v[188:191], v[96:99]
	v_mfma_f32_16x16x32_bf16 v[88:91], v[146:149], v[210:213], v[88:91]
	v_mfma_f32_16x16x32_bf16 v[80:83], v[158:161], v[210:213], v[80:83]
	v_mfma_f32_16x16x32_bf16 v[124:127], v[154:157], v[170:173], v[124:127]
	v_mfma_f32_16x16x32_bf16 v[120:123], v[162:165], v[170:173], v[120:123]
	v_mfma_f32_16x16x32_bf16 v[116:119], v[154:157], v[178:181], v[116:119]
	v_mfma_f32_16x16x32_bf16 v[112:115], v[162:165], v[178:181], v[112:115]
	v_mfma_f32_16x16x32_bf16 v[104:107], v[154:157], v[206:209], v[104:107]
	v_mfma_f32_16x16x32_bf16 v[96:99], v[162:165], v[206:209], v[96:99]
	v_mfma_f32_16x16x32_bf16 v[88:91], v[154:157], v[214:217], v[88:91]
	v_mfma_f32_16x16x32_bf16 v[80:83], v[162:165], v[214:217], v[80:83]
	s_setprio 0
	s_barrier
	s_mov_b32 m0, s58
	ds_read_b128 v[218:221], v143
	ds_read_b128 v[222:225], v143 offset:1024
	ds_read_b128 v[226:229], v143 offset:2048
	global_load_lds_dwordx4 v130, s[30:31]
	s_mov_b32 m0, s59
	ds_read_b128 v[230:233], v143 offset:3072
	global_load_lds_dwordx4 v128, s[30:31]
	s_barrier
	s_waitcnt lgkmcnt(0)
	s_setprio 1
	v_mfma_f32_16x16x32_bf16 v[108:111], v[218:221], v[166:169], v[108:111]
	v_mfma_f32_16x16x32_bf16 v[100:103], v[226:229], v[166:169], v[100:103]
	v_mfma_f32_16x16x32_bf16 v[92:95], v[218:221], v[174:177], v[92:95]
	v_mfma_f32_16x16x32_bf16 v[84:87], v[226:229], v[174:177], v[84:87]
	v_mfma_f32_16x16x32_bf16 v[76:79], v[218:221], v[188:191], v[76:79]
	v_mfma_f32_16x16x32_bf16 v[72:75], v[226:229], v[188:191], v[72:75]
	v_mfma_f32_16x16x32_bf16 v[68:71], v[218:221], v[210:213], v[68:71]
	v_mfma_f32_16x16x32_bf16 v[64:67], v[226:229], v[210:213], v[64:67]
	v_mfma_f32_16x16x32_bf16 v[108:111], v[222:225], v[170:173], v[108:111]
	v_mfma_f32_16x16x32_bf16 v[100:103], v[230:233], v[170:173], v[100:103]
	v_mfma_f32_16x16x32_bf16 v[92:95], v[222:225], v[178:181], v[92:95]
	v_mfma_f32_16x16x32_bf16 v[84:87], v[230:233], v[178:181], v[84:87]
	v_mfma_f32_16x16x32_bf16 v[76:79], v[222:225], v[206:209], v[76:79]
	v_mfma_f32_16x16x32_bf16 v[72:75], v[230:233], v[206:209], v[72:75]
	v_mfma_f32_16x16x32_bf16 v[68:71], v[222:225], v[214:217], v[68:71]
	v_mfma_f32_16x16x32_bf16 v[64:67], v[230:233], v[214:217], v[64:67]
	s_setprio 0
	s_mov_b32 m0, s40
	s_barrier
	ds_read_b128 v[166:169], v142 offset:16384
	ds_read_b128 v[170:173], v142 offset:17408
	ds_read_b128 v[174:177], v142 offset:18432
	ds_read_b128 v[178:181], v142 offset:19456
	ds_read_b128 v[188:191], v142 offset:20480
	ds_read_b128 v[206:209], v142 offset:21504
	ds_read_b128 v[210:213], v142 offset:22528
	global_load_lds_dwordx4 v130, s[36:37]
	s_mov_b32 m0, s41
	ds_read_b128 v[214:217], v142 offset:23552
	global_load_lds_dwordx4 v128, s[36:37]
	s_barrier
	s_waitcnt lgkmcnt(0)
	s_setprio 1
	v_mfma_f32_16x16x32_bf16 v[60:63], v[146:149], v[166:169], v[60:63]
	v_mfma_f32_16x16x32_bf16 v[56:59], v[158:161], v[166:169], v[56:59]
	v_mfma_f32_16x16x32_bf16 v[52:55], v[146:149], v[174:177], v[52:55]
	v_mfma_f32_16x16x32_bf16 v[48:51], v[158:161], v[174:177], v[48:51]
	v_mfma_f32_16x16x32_bf16 v[40:43], v[146:149], v[188:191], v[40:43]
	v_mfma_f32_16x16x32_bf16 v[32:35], v[158:161], v[188:191], v[32:35]
	v_mfma_f32_16x16x32_bf16 v[24:27], v[146:149], v[210:213], v[24:27]
	v_mfma_f32_16x16x32_bf16 v[16:19], v[158:161], v[210:213], v[16:19]
	v_mfma_f32_16x16x32_bf16 v[60:63], v[154:157], v[170:173], v[60:63]
	v_mfma_f32_16x16x32_bf16 v[56:59], v[162:165], v[170:173], v[56:59]
	v_mfma_f32_16x16x32_bf16 v[52:55], v[154:157], v[178:181], v[52:55]
	v_mfma_f32_16x16x32_bf16 v[48:51], v[162:165], v[178:181], v[48:51]
	v_mfma_f32_16x16x32_bf16 v[40:43], v[154:157], v[206:209], v[40:43]
	v_mfma_f32_16x16x32_bf16 v[32:35], v[162:165], v[206:209], v[32:35]
	v_mfma_f32_16x16x32_bf16 v[24:27], v[154:157], v[214:217], v[24:27]
	v_mfma_f32_16x16x32_bf16 v[16:19], v[162:165], v[214:217], v[16:19]
	s_setprio 0
	s_barrier
	s_add_u32 s0, s30, 0x160000
	s_addc_u32 s1, s31, 0
	s_mov_b32 m0, s60
	s_nop 0
	global_load_lds_dwordx4 v130, s[0:1]
	s_mov_b32 m0, s61
	s_nop 0
	global_load_lds_dwordx4 v128, s[0:1]
	s_waitcnt vmcnt(6)
	s_barrier
; #define PG8_STAGE(bufoff, gbase, voff) do { _Pragma("unroll") for (int _i = 0; _i < 2; ++_i) \
;         __builtin_amdgcn_global_load_lds((const unsigned*)((const char*)(gbase) + (voff)[_i]), (LAS unsigned*)(lds + (bufoff) + ldsw + _i * 8192), 16, 0, 0); } while (0)
; #define PG8_LDA(dst, b, h) do { _Pragma("unroll") for (int m = 0; m < 4; ++m) _Pragma("unroll") for (int k = 0; k < 2; ++k) dst[m][k] = *(const LAS bf16x8*)(lds + PG8_SA(b, h) + aoff + m * 2048 + k * 1024); } while (0)
; #define PG8_LDB(dst, b, h) do { _Pragma("unroll") for (int n = 0; n < 2; ++n) _Pragma("unroll") for (int k = 0; k < 2; ++k) dst[n][k] = *(const LAS bf16x8*)(lds + PG8_SB(b, h) + boff + n * 2048 + k * 1024); } while (0)
; #define PG8_MMA(ai, bj, At, Bt) do { __builtin_amdgcn_s_setprio(1); _Pragma("unroll") for (int m = 0; m < 4; ++m) _Pragma("unroll") for (int n = 0; n < 2; ++n) _Pragma("unroll") for (int k = 0; k < 2; ++k) \
;         acc[ai][bj][m][n] = __builtin_amdgcn_mfma_f32_16x16x32_bf16(Bt[n][k], At[m][k], acc[ai][bj][m][n], 0, 0, 0); __builtin_amdgcn_s_setprio(0); } while (0)
; #define PG8_WAIT_V(n) asm volatile("s_waitcnt vmcnt(" #n ")" ::: "memory")
; #define PG8_WAIT_L(n) asm volatile("s_waitcnt lgkmcnt(" #n ")" ::: "memory")
; #define PG8_BAR __builtin_amdgcn_s_barrier()
; #define PG8_SCHED __builtin_amdgcn_sched_barrier(0)
; template <class Epi, class Sched>
; DI void gemm_phase(LAS unsigned char* lds, const Gemm g, const Sched& S, const Epi& E) {
;     ...
;             PG8_WAIT_V(6); PG8_BAR; PG8_MMA(1, 1, At, B1); PG8_BAR;
;             PG8_LDB(B0, 1, 0); PG8_SCHED; PG8_LDA(At, 1, 0); PG8_STAGE(PG8_SA(0, 1), a2 + hstep, voffA);
;             PG8_WAIT_L(8); PG8_BAR; PG8_WAIT_L(0); PG8_MMA(0, 0, At, B0); PG8_BAR; PG8_SCHED;
;             PG8_LDB(B1, 1, 1); PG8_STAGE(PG8_SB(1, 0), b3, voffB);
	s_setprio 1
	v_mfma_f32_16x16x32_bf16 v[44:47], v[218:221], v[166:169], v[44:47]
	v_mfma_f32_16x16x32_bf16 v[36:39], v[226:229], v[166:169], v[36:39]
	v_mfma_f32_16x16x32_bf16 v[28:31], v[218:221], v[174:177], v[28:31]
	v_mfma_f32_16x16x32_bf16 v[20:23], v[226:229], v[174:177], v[20:23]
	v_mfma_f32_16x16x32_bf16 v[12:15], v[218:221], v[188:191], v[12:15]
	v_mfma_f32_16x16x32_bf16 v[8:11], v[226:229], v[188:191], v[8:11]
	v_mfma_f32_16x16x32_bf16 v[4:7], v[218:221], v[210:213], v[4:7]
	v_mfma_f32_16x16x32_bf16 v[0:3], v[226:229], v[210:213], v[0:3]
	v_mfma_f32_16x16x32_bf16 v[44:47], v[222:225], v[170:173], v[44:47]
	v_mfma_f32_16x16x32_bf16 v[36:39], v[230:233], v[170:173], v[36:39]
	v_mfma_f32_16x16x32_bf16 v[28:31], v[222:225], v[178:181], v[28:31]
	v_mfma_f32_16x16x32_bf16 v[20:23], v[230:233], v[178:181], v[20:23]
	v_mfma_f32_16x16x32_bf16 v[12:15], v[222:225], v[206:209], v[12:15]
	v_mfma_f32_16x16x32_bf16 v[8:11], v[230:233], v[206:209], v[8:11]
	v_mfma_f32_16x16x32_bf16 v[4:7], v[222:225], v[214:217], v[4:7]
	v_mfma_f32_16x16x32_bf16 v[0:3], v[230:233], v[214:217], v[0:3]
	s_setprio 0
	s_barrier
	ds_read_b128 v[146:149], v144
	ds_read_b128 v[154:157], v144 offset:1024
	ds_read_b128 v[158:161], v144 offset:2048
	ds_read_b128 v[162:165], v144 offset:3072
	s_add_u32 s0, s36, 0x160000
	s_addc_u32 s1, s37, 0
	s_mov_b32 m0, s42
	ds_read_b128 v[166:169], v142 offset:32768
	ds_read_b128 v[170:173], v142 offset:33792
	ds_read_b128 v[174:177], v142 offset:34816
	ds_read_b128 v[178:181], v142 offset:35840
	ds_read_b128 v[188:191], v142 offset:36864
	ds_read_b128 v[206:209], v142 offset:37888
	ds_read_b128 v[210:213], v142 offset:38912
	global_load_lds_dwordx4 v130, s[0:1]
	s_mov_b32 m0, s43
	ds_read_b128 v[214:217], v142 offset:39936
	global_load_lds_dwordx4 v128, s[0:1]
	s_waitcnt lgkmcnt(8)
	s_barrier
	s_waitcnt lgkmcnt(0)
	s_setprio 1
	v_mfma_f32_16x16x32_bf16 v[124:127], v[146:149], v[166:169], v[124:127]
	v_mfma_f32_16x16x32_bf16 v[120:123], v[158:161], v[166:169], v[120:123]
	v_mfma_f32_16x16x32_bf16 v[116:119], v[146:149], v[174:177], v[116:119]
	v_mfma_f32_16x16x32_bf16 v[112:115], v[158:161], v[174:177], v[112:115]
	v_mfma_f32_16x16x32_bf16 v[104:107], v[146:149], v[188:191], v[104:107]
	v_mfma_f32_16x16x32_bf16 v[96:99], v[158:161], v[188:191], v[96:99]
	v_mfma_f32_16x16x32_bf16 v[88:91], v[146:149], v[210:213], v[88:91]
	v_mfma_f32_16x16x32_bf16 v[80:83], v[158:161], v[210:213], v[80:83]
	v_mfma_f32_16x16x32_bf16 v[124:127], v[154:157], v[170:173], v[124:127]
	v_mfma_f32_16x16x32_bf16 v[120:123], v[162:165], v[170:173], v[120:123]
	v_mfma_f32_16x16x32_bf16 v[116:119], v[154:157], v[178:181], v[116:119]
	v_mfma_f32_16x16x32_bf16 v[112:115], v[162:165], v[178:181], v[112:115]
	v_mfma_f32_16x16x32_bf16 v[104:107], v[154:157], v[206:209], v[104:107]
	v_mfma_f32_16x16x32_bf16 v[96:99], v[162:165], v[206:209], v[96:99]
	v_mfma_f32_16x16x32_bf16 v[88:91], v[154:157], v[214:217], v[88:91]
	v_mfma_f32_16x16x32_bf16 v[80:83], v[162:165], v[214:217], v[80:83]
	s_setprio 0
	s_barrier
	s_add_i32 s4, 0, 0x1c000
	s_add_i32 s0, s62, s35
	v_add_u32_e32 v145, s4, v140
	s_add_i32 m0, s0, 0xffffff80
	ds_read_b128 v[218:221], v145
	ds_read_b128 v[222:225], v145 offset:1024
	ds_read_b128 v[226:229], v145 offset:2048
	global_load_lds_dwordx4 v130, s[30:31] offset:128
	s_add_i32 m0, s0, 0x1f80
	ds_read_b128 v[230:233], v145 offset:3072
	global_load_lds_dwordx4 v128, s[30:31] offset:128
	s_barrier
; #define PG8_STAGE(bufoff, gbase, voff) do { _Pragma("unroll") for (int _i = 0; _i < 2; ++_i) \
;         __builtin_amdgcn_global_load_lds((const unsigned*)((const char*)(gbase) + (voff)[_i]), (LAS unsigned*)(lds + (bufoff) + ldsw + _i * 8192), 16, 0, 0); } while (0)
; #define PG8_LDA(dst, b, h) do { _Pragma("unroll") for (int m = 0; m < 4; ++m) _Pragma("unroll") for (int k = 0; k < 2; ++k) dst[m][k] = *(const LAS bf16x8*)(lds + PG8_SA(b, h) + aoff + m * 2048 + k * 1024); } while (0)
; #define PG8_MMA(ai, bj, At, Bt) do { __builtin_amdgcn_s_setprio(1); _Pragma("unroll") for (int m = 0; m < 4; ++m) _Pragma("unroll") for (int n = 0; n < 2; ++n) _Pragma("unroll") for (int k = 0; k < 2; ++k) \
;         acc[ai][bj][m][n] = __builtin_amdgcn_mfma_f32_16x16x32_bf16(Bt[n][k], At[m][k], acc[ai][bj][m][n], 0, 0, 0); __builtin_amdgcn_s_setprio(0); } while (0)
; #define PG8_WAIT_V(n) asm volatile("s_waitcnt vmcnt(" #n ")" ::: "memory")
; #define PG8_WAIT_L(n) asm volatile("s_waitcnt lgkmcnt(" #n ")" ::: "memory")
; #define PG8_BAR __builtin_amdgcn_s_barrier()
; #define PG8_SCHED __builtin_amdgcn_sched_barrier(0)
; template <class Epi, class Sched>
; DI void gemm_phase(LAS unsigned char* lds, const Gemm g, const Sched& S, const Epi& E) {
;     ...
;             PG8_BAR; PG8_WAIT_L(0); PG8_MMA(0, 1, At, B1); PG8_BAR;
;             PG8_LDA(At, 1, 1); PG8_STAGE(PG8_SA(1, 0), a3, voffA);
;             PG8_BAR; PG8_WAIT_L(0); PG8_MMA(1, 0, At, B0); PG8_BAR; PG8_SCHED;
;             PG8_STAGE(PG8_SB(1, 1), b3 + hstep, voffB);
;             PG8_WAIT_V(6); PG8_BAR; PG8_MMA(1, 1, At, B1); PG8_BAR;
;         }
	s_waitcnt lgkmcnt(0)
	s_setprio 1
	v_mfma_f32_16x16x32_bf16 v[108:111], v[218:221], v[166:169], v[108:111]
	v_mfma_f32_16x16x32_bf16 v[100:103], v[226:229], v[166:169], v[100:103]
	v_mfma_f32_16x16x32_bf16 v[92:95], v[218:221], v[174:177], v[92:95]
	v_mfma_f32_16x16x32_bf16 v[84:87], v[226:229], v[174:177], v[84:87]
	v_mfma_f32_16x16x32_bf16 v[76:79], v[218:221], v[188:191], v[76:79]
	v_mfma_f32_16x16x32_bf16 v[72:75], v[226:229], v[188:191], v[72:75]
	v_mfma_f32_16x16x32_bf16 v[68:71], v[218:221], v[210:213], v[68:71]
	v_mfma_f32_16x16x32_bf16 v[64:67], v[226:229], v[210:213], v[64:67]
	v_mfma_f32_16x16x32_bf16 v[108:111], v[222:225], v[170:173], v[108:111]
	v_mfma_f32_16x16x32_bf16 v[100:103], v[230:233], v[170:173], v[100:103]
	v_mfma_f32_16x16x32_bf16 v[92:95], v[222:225], v[178:181], v[92:95]
	v_mfma_f32_16x16x32_bf16 v[84:87], v[230:233], v[178:181], v[84:87]
	v_mfma_f32_16x16x32_bf16 v[76:79], v[222:225], v[206:209], v[76:79]
	v_mfma_f32_16x16x32_bf16 v[72:75], v[230:233], v[206:209], v[72:75]
	v_mfma_f32_16x16x32_bf16 v[68:71], v[222:225], v[214:217], v[68:71]
	v_mfma_f32_16x16x32_bf16 v[64:67], v[230:233], v[214:217], v[64:67]
	s_setprio 0
	s_add_i32 m0, s54, 0xffffff80
	s_barrier
	ds_read_b128 v[166:169], v142 offset:49152
	ds_read_b128 v[170:173], v142 offset:50176
	ds_read_b128 v[174:177], v142 offset:51200
	ds_read_b128 v[178:181], v142 offset:52224
	ds_read_b128 v[188:191], v142 offset:53248
	ds_read_b128 v[206:209], v142 offset:54272
	ds_read_b128 v[210:213], v142 offset:55296
	global_load_lds_dwordx4 v130, s[36:37] offset:128
	s_add_i32 m0, s55, 0xffffff80
	ds_read_b128 v[214:217], v142 offset:56320
	global_load_lds_dwordx4 v128, s[36:37] offset:128
	s_barrier
	s_waitcnt lgkmcnt(0)
	s_setprio 1
	v_mfma_f32_16x16x32_bf16 v[60:63], v[146:149], v[166:169], v[60:63]
	v_mfma_f32_16x16x32_bf16 v[56:59], v[158:161], v[166:169], v[56:59]
	v_mfma_f32_16x16x32_bf16 v[52:55], v[146:149], v[174:177], v[52:55]
	v_mfma_f32_16x16x32_bf16 v[48:51], v[158:161], v[174:177], v[48:51]
	v_mfma_f32_16x16x32_bf16 v[40:43], v[146:149], v[188:191], v[40:43]
	v_mfma_f32_16x16x32_bf16 v[32:35], v[158:161], v[188:191], v[32:35]
	v_mfma_f32_16x16x32_bf16 v[24:27], v[146:149], v[210:213], v[24:27]
	v_mfma_f32_16x16x32_bf16 v[16:19], v[158:161], v[210:213], v[16:19]
	v_mfma_f32_16x16x32_bf16 v[60:63], v[154:157], v[170:173], v[60:63]
	v_mfma_f32_16x16x32_bf16 v[56:59], v[162:165], v[170:173], v[56:59]
	v_mfma_f32_16x16x32_bf16 v[52:55], v[154:157], v[178:181], v[52:55]
	v_mfma_f32_16x16x32_bf16 v[48:51], v[162:165], v[178:181], v[48:51]
	v_mfma_f32_16x16x32_bf16 v[40:43], v[154:157], v[206:209], v[40:43]
	v_mfma_f32_16x16x32_bf16 v[32:35], v[162:165], v[206:209], v[32:35]
	v_mfma_f32_16x16x32_bf16 v[24:27], v[154:157], v[214:217], v[24:27]
	v_mfma_f32_16x16x32_bf16 v[16:19], v[162:165], v[214:217], v[16:19]
	s_setprio 0
	s_barrier
	s_add_i32 s4, s4, s35
	s_mov_b32 m0, s4
	s_add_u32 s0, s30, 0x160080
	s_addc_u32 s1, s31, 0
	global_load_lds_dwordx4 v130, s[0:1]
	s_add_i32 m0, s4, 0x2000
	s_nop 0
	global_load_lds_dwordx4 v128, s[0:1]
	s_add_i32 s66, s66, 2
	s_add_u32 s8, s8, 0x100
	s_addc_u32 s9, s9, 0
	s_add_u32 s64, s64, 0x100
	s_addc_u32 s65, s65, 0
	s_cmp_gt_u32 s66, 5
	s_waitcnt vmcnt(6)
	s_barrier
	s_setprio 1
	v_mfma_f32_16x16x32_bf16 v[44:47], v[218:221], v[166:169], v[44:47]
	v_mfma_f32_16x16x32_bf16 v[36:39], v[226:229], v[166:169], v[36:39]
	v_mfma_f32_16x16x32_bf16 v[28:31], v[218:221], v[174:177], v[28:31]
	v_mfma_f32_16x16x32_bf16 v[20:23], v[226:229], v[174:177], v[20:23]
	v_mfma_f32_16x16x32_bf16 v[12:15], v[218:221], v[188:191], v[12:15]
	v_mfma_f32_16x16x32_bf16 v[8:11], v[226:229], v[188:191], v[8:11]
	v_mfma_f32_16x16x32_bf16 v[4:7], v[218:221], v[210:213], v[4:7]
	v_mfma_f32_16x16x32_bf16 v[0:3], v[226:229], v[210:213], v[0:3]
	v_mfma_f32_16x16x32_bf16 v[44:47], v[222:225], v[170:173], v[44:47]
	v_mfma_f32_16x16x32_bf16 v[36:39], v[230:233], v[170:173], v[36:39]
	v_mfma_f32_16x16x32_bf16 v[28:31], v[222:225], v[178:181], v[28:31]
	v_mfma_f32_16x16x32_bf16 v[20:23], v[230:233], v[178:181], v[20:23]
	v_mfma_f32_16x16x32_bf16 v[12:15], v[222:225], v[206:209], v[12:15]
	v_mfma_f32_16x16x32_bf16 v[8:11], v[230:233], v[206:209], v[8:11]
	v_mfma_f32_16x16x32_bf16 v[4:7], v[222:225], v[214:217], v[4:7]
	v_mfma_f32_16x16x32_bf16 v[0:3], v[230:233], v[214:217], v[0:3]
	s_setprio 0
	s_cbranch_scc0 .Lrot_1775
	s_barrier
